# speedup vs baseline: 1.0350x; 1.0350x over previous
; #define BJOB(C, POS, W1) for (int kc = lbid(); kc < 16; kc += gridDim.x) { const int n = ltid(); float s = 0.f; \
;     for (int k = kc * 128; k < kc * 128 + 128; ++k) s += (POS)[k] * (W1)[(long)k * 256 + n]; p.bias_part[((C) * 16 + kc) * 256 + n] = s; }
; DI void prep_phase(const Params& p, char* smem) {
;     ...
;   BJOB(0, p.a_pos_k, p.a_w1_k)
.LBB0_130:
	s_mov_b32 s15, s43
	s_cmp_gt_i32 s15, 15
	s_cbranch_scc1 .LBB0_135
	s_load_dwordx2 s[0:1], s[56:57], 0x28
	s_load_dwordx2 s[4:5], s[56:57], 0x38
	s_load_dwordx2 s[6:7], s[56:57], 0xf8
	s_lshl_b32 s8, s15, 7
	s_add_i32 s16, s8, -1
	s_lshl_b32 s17, s14, 7
	v_mov_b32_e32 v4, 0
	s_mov_b64 s[10:11], 0x1000

.LBB0_133:
	global_load_dword v65, v4, s[12:13]
	global_load_dword v66, v4, s[12:13] offset:4
	global_load_dword v67, v4, s[12:13] offset:8
	global_load_dword v68, v4, s[12:13] offset:12
	global_load_dword v69, v4, s[12:13] offset:16
	global_load_dword v70, v4, s[12:13] offset:20
	global_load_dword v71, v4, s[12:13] offset:24
	global_load_dword v72, v4, s[12:13] offset:28
	global_load_dword v73, v4, s[12:13] offset:32
	global_load_dword v74, v4, s[12:13] offset:36
	global_load_dword v75, v4, s[12:13] offset:40
	global_load_dword v76, v4, s[12:13] offset:44
	global_load_dword v77, v4, s[12:13] offset:48
	global_load_dword v78, v4, s[12:13] offset:52
	global_load_dword v79, v4, s[12:13] offset:56
	global_load_dword v80, v4, s[12:13] offset:60
	global_load_dword v81, v[2:3], off
	global_load_dword v82, v[2:3], off offset:1024
	global_load_dword v83, v[2:3], off offset:2048
	global_load_dword v84, v[2:3], off offset:3072
	v_lshl_add_u64 v[2:3], v[2:3], 0, s[10:11]
	global_load_dword v85, v[2:3], off
	global_load_dword v86, v[2:3], off offset:1024
	global_load_dword v87, v[2:3], off offset:2048
	global_load_dword v88, v[2:3], off offset:3072
	v_lshl_add_u64 v[2:3], v[2:3], 0, s[10:11]
	global_load_dword v89, v[2:3], off
	global_load_dword v90, v[2:3], off offset:1024
	global_load_dword v91, v[2:3], off offset:2048
	global_load_dword v92, v[2:3], off offset:3072
	v_lshl_add_u64 v[2:3], v[2:3], 0, s[10:11]
	global_load_dword v93, v[2:3], off
	global_load_dword v94, v[2:3], off offset:1024
	global_load_dword v95, v[2:3], off offset:2048
	global_load_dword v96, v[2:3], off offset:3072
	v_lshl_add_u64 v[2:3], v[2:3], 0, s[10:11]
	s_add_i32 s18, s18, 16
	s_add_u32 s12, s12, 64
	s_addc_u32 s13, s13, 0
	s_cmp_ge_i32 s18, s9
	s_waitcnt vmcnt(15)
	v_fmac_f32_e32 v1, v65, v81
	s_waitcnt vmcnt(14)
	v_fmac_f32_e32 v1, v66, v82
	s_waitcnt vmcnt(13)
	v_fmac_f32_e32 v1, v67, v83
	s_waitcnt vmcnt(12)
	v_fmac_f32_e32 v1, v68, v84
	s_waitcnt vmcnt(11)
	v_fmac_f32_e32 v1, v69, v85
	s_waitcnt vmcnt(10)
	v_fmac_f32_e32 v1, v70, v86
	s_waitcnt vmcnt(9)
	v_fmac_f32_e32 v1, v71, v87
	s_waitcnt vmcnt(8)
	v_fmac_f32_e32 v1, v72, v88
	s_waitcnt vmcnt(7)
	v_fmac_f32_e32 v1, v73, v89
	s_waitcnt vmcnt(6)
	v_fmac_f32_e32 v1, v74, v90
	s_waitcnt vmcnt(5)
	v_fmac_f32_e32 v1, v75, v91
	s_waitcnt vmcnt(4)
	v_fmac_f32_e32 v1, v76, v92
	s_waitcnt vmcnt(3)
	v_fmac_f32_e32 v1, v77, v93
	s_waitcnt vmcnt(2)
	v_fmac_f32_e32 v1, v78, v94
	s_waitcnt vmcnt(1)
	v_fmac_f32_e32 v1, v79, v95
	s_waitcnt vmcnt(0)
	v_fmac_f32_e32 v1, v80, v96
	s_cbranch_scc0 .LBB0_133
	v_lshl_add_u32 v2, s15, 8, v0
	v_ashrrev_i32_e32 v3, 31, v2
	s_add_i32 s15, s15, s14
	s_add_i32 s16, s16, s17
	s_add_i32 s8, s8, s17
	v_lshl_add_u64 v[2:3], v[2:3], 2, s[6:7]
	s_cmp_gt_i32 s15, 15
	global_store_dword v[2:3], v1, off
	s_cbranch_scc0 .LBB0_132
.LBB0_135:
	s_mov_b32 s15, s43
	s_cmp_gt_i32 s15, 15
	s_cbranch_scc1 .LBB0_140
	s_load_dwordx2 s[0:1], s[56:57], 0x30
	s_load_dwordx2 s[4:5], s[56:57], 0x48
	s_load_dwordx2 s[6:7], s[56:57], 0xf8
	s_lshl_b32 s8, s15, 7
	s_add_i32 s16, s8, -1
	s_lshl_b32 s17, s14, 7
	v_mov_b32_e32 v4, 0
	s_mov_b64 s[10:11], 0x1000

; #define BJOB(C, POS, W1) for (int kc = lbid(); kc < 16; kc += gridDim.x) { const int n = ltid(); float s = 0.f; \
;     for (int k = kc * 128; k < kc * 128 + 128; ++k) s += (POS)[k] * (W1)[(long)k * 256 + n]; p.bias_part[((C) * 16 + kc) * 256 + n] = s; }
; DI void prep_phase(const Params& p, char* smem) {
;     ...
;   BJOB(0, p.a_pos_k, p.a_w1_k)
;   BJOB(1, p.a_pos_v, p.a_w1_v)
.LBB0_138:
	global_load_dword v65, v4, s[12:13]
	global_load_dword v66, v4, s[12:13] offset:4
	global_load_dword v67, v4, s[12:13] offset:8
	global_load_dword v68, v4, s[12:13] offset:12
	global_load_dword v69, v4, s[12:13] offset:16
	global_load_dword v70, v4, s[12:13] offset:20
	global_load_dword v71, v4, s[12:13] offset:24
	global_load_dword v72, v4, s[12:13] offset:28
	global_load_dword v73, v4, s[12:13] offset:32
	global_load_dword v74, v4, s[12:13] offset:36
	global_load_dword v75, v4, s[12:13] offset:40
	global_load_dword v76, v4, s[12:13] offset:44
	global_load_dword v77, v4, s[12:13] offset:48
	global_load_dword v78, v4, s[12:13] offset:52
	global_load_dword v79, v4, s[12:13] offset:56
	global_load_dword v80, v4, s[12:13] offset:60
	global_load_dword v81, v[2:3], off
	global_load_dword v82, v[2:3], off offset:1024
	global_load_dword v83, v[2:3], off offset:2048
	global_load_dword v84, v[2:3], off offset:3072
	v_lshl_add_u64 v[2:3], v[2:3], 0, s[10:11]
	global_load_dword v85, v[2:3], off
	global_load_dword v86, v[2:3], off offset:1024
	global_load_dword v87, v[2:3], off offset:2048
	global_load_dword v88, v[2:3], off offset:3072
	v_lshl_add_u64 v[2:3], v[2:3], 0, s[10:11]
	global_load_dword v89, v[2:3], off
	global_load_dword v90, v[2:3], off offset:1024
	global_load_dword v91, v[2:3], off offset:2048
	global_load_dword v92, v[2:3], off offset:3072
	v_lshl_add_u64 v[2:3], v[2:3], 0, s[10:11]
	global_load_dword v93, v[2:3], off
	global_load_dword v94, v[2:3], off offset:1024
	global_load_dword v95, v[2:3], off offset:2048
	global_load_dword v96, v[2:3], off offset:3072
	v_lshl_add_u64 v[2:3], v[2:3], 0, s[10:11]
	s_add_i32 s18, s18, 16
	s_add_u32 s12, s12, 64
	s_addc_u32 s13, s13, 0
	s_cmp_ge_i32 s18, s9
	s_waitcnt vmcnt(15)
	v_fmac_f32_e32 v1, v65, v81
	s_waitcnt vmcnt(14)
	v_fmac_f32_e32 v1, v66, v82
	s_waitcnt vmcnt(13)
	v_fmac_f32_e32 v1, v67, v83
	s_waitcnt vmcnt(12)
	v_fmac_f32_e32 v1, v68, v84
	s_waitcnt vmcnt(11)
	v_fmac_f32_e32 v1, v69, v85
	s_waitcnt vmcnt(10)
	v_fmac_f32_e32 v1, v70, v86
	s_waitcnt vmcnt(9)
	v_fmac_f32_e32 v1, v71, v87
	s_waitcnt vmcnt(8)
	v_fmac_f32_e32 v1, v72, v88
	s_waitcnt vmcnt(7)
	v_fmac_f32_e32 v1, v73, v89
	s_waitcnt vmcnt(6)
	v_fmac_f32_e32 v1, v74, v90
	s_waitcnt vmcnt(5)
	v_fmac_f32_e32 v1, v75, v91
	s_waitcnt vmcnt(4)
	v_fmac_f32_e32 v1, v76, v92
	s_waitcnt vmcnt(3)
	v_fmac_f32_e32 v1, v77, v93
	s_waitcnt vmcnt(2)
	v_fmac_f32_e32 v1, v78, v94
	s_waitcnt vmcnt(1)
	v_fmac_f32_e32 v1, v79, v95
	s_waitcnt vmcnt(0)
	v_fmac_f32_e32 v1, v80, v96
	s_cbranch_scc0 .LBB0_138
	s_lshl_b32 s9, s15, 8
	s_addk_i32 s9, 0x1000
	v_add_u32_e32 v2, s9, v0
	v_ashrrev_i32_e32 v3, 31, v2
	s_add_i32 s15, s15, s14
	s_add_i32 s16, s16, s17
	s_add_i32 s8, s8, s17
	v_lshl_add_u64 v[2:3], v[2:3], 2, s[6:7]
	s_cmp_gt_i32 s15, 15
	global_store_dword v[2:3], v1, off
	s_cbranch_scc0 .LBB0_137

; template <class ARow, class Epi>
; DI void gemm_tile(const ARow& arow, long a_kstride, const u16* __restrict__ Bt, long ldb, int K, int m0, int n0,
;                   const Epi& epi, char* smem) {
;     ...
;   const int fr = lane & 15, fq = lane >> 4;
;   int foff[2];
; #pragma unroll
;   for (int ks = 0; ks < 2; ++ks) foff[ks] = fr * 128 + ((((4 * ks + fq) ^ ((fr >> 1) & 7))) << 4);
;   f32x4 acc[4][4];
; #pragma unroll
;   for (int a = 0; a < 4; ++a)
; #pragma unroll
;     for (int b = 0; b < 4; ++b) acc[a][b] = (f32x4){0.f, 0.f, 0.f, 0.f};
;   const int KT = K >> 6;
;   GEMM_STAGE(0, 0);
;   asm volatile("s_waitcnt vmcnt(0)" ::: "memory");
;   __syncthreads();
;   for (int kt = 0; kt < KT; ++kt) {
;     const int cur = kt & 1;
;     if (kt + 1 < KT) GEMM_STAGE(cur ^ 1, kt + 1);
;     const char* sa = smem + cur * 32768 + wm * 64 * 128;
;     const char* sb = smem + cur * 32768 + 16384 + wn * 64 * 128;
; #pragma unroll
;     for (int ks = 0; ks < 2; ++ks) {
;       bf16x8 wf[4], af[4];
; #pragma unroll
;       for (int j = 0; j < 4; ++j) {
;         wf[j] = *(const bf16x8*)(sb + j * 2048 + foff[ks]);
;         af[j] = *(const bf16x8*)(sa + j * 2048 + foff[ks]);
;       }
; #pragma unroll
;       for (int ni = 0; ni < 4; ++ni)
; #pragma unroll
;         for (int mi = 0; mi < 4; ++mi) acc[ni][mi] = __builtin_amdgcn_mfma_f32_16x16x32_bf16(wf[ni], af[mi], acc[ni][mi], 0, 0, 0);
;     }
;     asm volatile("s_waitcnt vmcnt(0)" ::: "memory");
;     __syncthreads();
;   }
.LBB0_217:
	s_and_b32 s6, s1, 0x8000
	s_xor_b32 s7, s6, 0x8000
	v_add_u32_e32 v108, s7, v91
	v_add_u32_e32 v116, s6, v89
	v_or_b32_e32 v117, s6, v90
	v_readfirstlane_b32 s6, v108
	v_add_u32_e32 v109, 0x4000, v108
	v_lshl_add_u64 v[92:93], v[66:67], 0, s[4:5]
	v_add_u32_e32 v110, 0x400, v108
	v_readfirstlane_b32 s7, v109
	s_mov_b32 m0, s6
	v_lshl_add_u64 v[94:95], v[68:69], 0, s[4:5]
	v_add_u32_e32 v111, 0x4400, v108
	v_readfirstlane_b32 s8, v110
	global_load_lds_dwordx4 v[92:93], off
	s_mov_b32 m0, s7
	v_lshl_add_u64 v[96:97], v[70:71], 0, s[4:5]
	v_add_u32_e32 v113, 0x800, v108
	v_readfirstlane_b32 s9, v111
	global_load_lds_dwordx4 v[94:95], off
	s_mov_b32 m0, s8
	v_lshl_add_u64 v[98:99], v[72:73], 0, s[4:5]
	v_add_u32_e32 v114, 0x4800, v108
	v_readfirstlane_b32 s10, v113
	global_load_lds_dwordx4 v[96:97], off
	s_mov_b32 m0, s9
	v_lshl_add_u64 v[100:101], v[74:75], 0, s[4:5]
	v_add_u32_e32 v115, 0xc00, v108
	v_readfirstlane_b32 s11, v114
	global_load_lds_dwordx4 v[98:99], off
	s_mov_b32 m0, s10
	v_lshl_add_u64 v[102:103], v[76:77], 0, s[4:5]
	v_add_u32_e32 v108, 0x4c00, v108
	v_readfirstlane_b32 s12, v115
	global_load_lds_dwordx4 v[100:101], off
	s_mov_b32 m0, s11
	v_lshl_add_u64 v[104:105], v[78:79], 0, s[4:5]
	v_readfirstlane_b32 s13, v108
	global_load_lds_dwordx4 v[102:103], off
	s_mov_b32 m0, s12
	v_lshl_add_u64 v[106:107], v[80:81], 0, s[4:5]
	global_load_lds_dwordx4 v[104:105], off
	s_mov_b32 m0, s13
	v_add_u32_e32 v118, v117, v88
	global_load_lds_dwordx4 v[106:107], off
	v_add_u32_e32 v112, v116, v88
	ds_read_b128 v[92:95], v118 offset:16384
	ds_read_b128 v[96:99], v112
	ds_read_b128 v[100:103], v118 offset:18432
	ds_read_b128 v[104:107], v112 offset:2048
	ds_read_b128 v[108:111], v112 offset:4096
	ds_read_b128 v[112:115], v112 offset:6144
	s_waitcnt lgkmcnt(0)
	v_mfma_f32_16x16x32_bf16 v[60:63], v[92:95], v[96:99], v[60:63]
	v_add_u32_e32 v117, v117, v87
	v_add_u32_e32 v116, v116, v87
	s_add_i32 s1, s1, 0x8000
	v_mfma_f32_16x16x32_bf16 v[56:59], v[92:95], v[104:107], v[56:59]
	s_add_u32 s4, s4, 0x80
	s_addc_u32 s5, s5, 0
	s_cmpk_eq_i32 s4, 0x780
	v_mfma_f32_16x16x32_bf16 v[48:51], v[92:95], v[108:111], v[48:51]
	v_mfma_f32_16x16x32_bf16 v[40:43], v[92:95], v[112:115], v[40:43]
	v_mfma_f32_16x16x32_bf16 v[36:39], v[100:103], v[96:99], v[36:39]
	v_mfma_f32_16x16x32_bf16 v[32:35], v[100:103], v[104:107], v[32:35]
	v_mfma_f32_16x16x32_bf16 v[28:31], v[100:103], v[108:111], v[28:31]
	v_mfma_f32_16x16x32_bf16 v[24:27], v[100:103], v[112:115], v[24:27]
	ds_read_b128 v[92:95], v118 offset:20480
	ds_read_b128 v[100:103], v118 offset:22528
	s_waitcnt lgkmcnt(0)
	v_mfma_f32_16x16x32_bf16 v[20:23], v[92:95], v[96:99], v[20:23]
	v_mfma_f32_16x16x32_bf16 v[16:19], v[92:95], v[104:107], v[16:19]
	v_mfma_f32_16x16x32_bf16 v[12:15], v[92:95], v[108:111], v[12:15]
	v_mfma_f32_16x16x32_bf16 v[8:11], v[92:95], v[112:115], v[8:11]
	ds_read_b128 v[92:95], v117 offset:16384
	v_mfma_f32_16x16x32_bf16 v[4:7], v[100:103], v[96:99], v[4:7]
	v_mfma_f32_16x16x32_bf16 v[0:3], v[100:103], v[104:107], v[0:3]
	v_mfma_f32_16x16x32_bf16 v[52:55], v[100:103], v[108:111], v[52:55]
	v_mfma_f32_16x16x32_bf16 v[44:47], v[100:103], v[112:115], v[44:47]
	ds_read_b128 v[96:99], v116
	ds_read_b128 v[100:103], v117 offset:18432
	ds_read_b128 v[104:107], v116 offset:2048
	ds_read_b128 v[108:111], v116 offset:4096
	ds_read_b128 v[112:115], v116 offset:6144
	s_waitcnt lgkmcnt(0)
	v_mfma_f32_16x16x32_bf16 v[60:63], v[92:95], v[96:99], v[60:63]
	v_mfma_f32_16x16x32_bf16 v[56:59], v[92:95], v[104:107], v[56:59]
	v_mfma_f32_16x16x32_bf16 v[48:51], v[92:95], v[108:111], v[48:51]
	v_mfma_f32_16x16x32_bf16 v[40:43], v[92:95], v[112:115], v[40:43]
	v_mfma_f32_16x16x32_bf16 v[36:39], v[100:103], v[96:99], v[36:39]
	v_mfma_f32_16x16x32_bf16 v[32:35], v[100:103], v[104:107], v[32:35]
	v_mfma_f32_16x16x32_bf16 v[28:31], v[100:103], v[108:111], v[28:31]
	v_mfma_f32_16x16x32_bf16 v[24:27], v[100:103], v[112:115], v[24:27]
	ds_read_b128 v[92:95], v117 offset:20480
	ds_read_b128 v[100:103], v117 offset:22528
	s_waitcnt vmcnt(0)
	s_waitcnt vmcnt(0) lgkmcnt(0)
	v_mfma_f32_16x16x32_bf16 v[20:23], v[92:95], v[96:99], v[20:23]
	s_barrier
	v_mfma_f32_16x16x32_bf16 v[16:19], v[92:95], v[104:107], v[16:19]
	v_mfma_f32_16x16x32_bf16 v[12:15], v[92:95], v[108:111], v[12:15]
	v_mfma_f32_16x16x32_bf16 v[8:11], v[92:95], v[112:115], v[8:11]
	v_mfma_f32_16x16x32_bf16 v[4:7], v[100:103], v[96:99], v[4:7]
	v_mfma_f32_16x16x32_bf16 v[0:3], v[100:103], v[104:107], v[0:3]
	v_mfma_f32_16x16x32_bf16 v[52:55], v[100:103], v[108:111], v[52:55]
	v_mfma_f32_16x16x32_bf16 v[44:47], v[100:103], v[112:115], v[44:47]
	s_cbranch_scc0 .LBB0_217
; DI float silu_f(float v) { return v / (1.f + fexp(-v)); }
; DI float sigmoid_f(float v) { return 1.f / (1.f + fexp(-v)); }
;   DI void operator()(int m, int n, float a, float b, float c, float d, float& ss) const { u32x2 v; v.x = pack2(a, b); v.y = pack2(c, d); *(u32x2*)(y + (long)m * 1024 + n) = v; }
; template <class ARow, class Epi>
; DI void gemm_tile(const ARow& arow, long a_kstride, const u16* __restrict__ Bt, long ldb, int K, int m0, int n0,
;                   const Epi& epi, char* smem) {
;     ...
;     for (int ks = 0; ks < 2; ++ks) {
;       bf16x8 wf[4], af[4];
; #pragma unroll
;       for (int j = 0; j < 4; ++j) {
;         wf[j] = *(const bf16x8*)(sb + j * 2048 + foff[ks]);
;         af[j] = *(const bf16x8*)(sa + j * 2048 + foff[ks]);
;       }
; #pragma unroll
;       for (int ni = 0; ni < 4; ++ni)
; #pragma unroll
;         for (int mi = 0; mi < 4; ++mi) acc[ni][mi] = __builtin_amdgcn_mfma_f32_16x16x32_bf16(wf[ni], af[mi], acc[ni][mi], 0, 0, 0);
;     }
;     asm volatile("s_waitcnt vmcnt(0)" ::: "memory");
;     __syncthreads();
;   }
;   DI void operator()(int m, int n, float a, float b, float c, float d, float& ss) const {
;     if (n >= gl_start) {
;       const int j = n - gl_start;
;       if (j < 48) { float* g = gates + (long)m * 48 + j; g[0] = sigmoid_f(a); g[1] = sigmoid_f(b); g[2] = sigmoid_f(c); g[3] = sigmoid_f(d); }
;       return;
;     }
;     if (n < q_end) { a *= qscale; b *= qscale; c *= qscale; d *= qscale; }
;     else if (n >= z_start) { a = silu_f(a); b = silu_f(b); c = silu_f(c); d = silu_f(d); }
	v_add_u32_e32 v91, v90, v88
	ds_read_b128 v[66:69], v91 offset:49152
	v_add_u32_e32 v88, v89, v88
	ds_read_b128 v[70:73], v88 offset:32768
	ds_read_b128 v[74:77], v88 offset:34816
	ds_read_b128 v[78:81], v88 offset:36864
	ds_read_b128 v[92:95], v88 offset:38912
	v_add_u32_e32 v116, v90, v87
	s_waitcnt lgkmcnt(3)
	v_mfma_f32_16x16x32_bf16 v[60:63], v[66:69], v[70:73], v[60:63]
	s_waitcnt lgkmcnt(2)
	v_mfma_f32_16x16x32_bf16 v[56:59], v[66:69], v[74:77], v[56:59]
	s_waitcnt lgkmcnt(1)
	v_mfma_f32_16x16x32_bf16 v[48:51], v[66:69], v[78:81], v[48:51]
	s_waitcnt lgkmcnt(0)
	v_mfma_f32_16x16x32_bf16 v[40:43], v[66:69], v[92:95], v[40:43]
	ds_read_b128 v[66:69], v91 offset:51200
	s_waitcnt lgkmcnt(0)
	v_mfma_f32_16x16x32_bf16 v[36:39], v[66:69], v[70:73], v[36:39]
	v_mfma_f32_16x16x32_bf16 v[32:35], v[66:69], v[74:77], v[32:35]
	v_mfma_f32_16x16x32_bf16 v[96:99], v[66:69], v[78:81], v[28:31]
	v_mfma_f32_16x16x32_bf16 v[66:69], v[66:69], v[92:95], v[24:27]
	s_nop 2
	ds_read_b128 v[24:27], v91 offset:53248
	s_waitcnt lgkmcnt(0)
	v_mfma_f32_16x16x32_bf16 v[104:107], v[24:27], v[92:95], v[8:11]
	s_nop 2
	ds_read_b128 v[8:11], v91 offset:55296
	v_mfma_f32_16x16x32_bf16 v[20:23], v[24:27], v[70:73], v[20:23]
	s_waitcnt lgkmcnt(0)
	v_mfma_f32_16x16x32_bf16 v[70:73], v[8:11], v[70:73], v[4:7]
	s_nop 2
	ds_read_b128 v[4:7], v116 offset:49152
	v_mfma_f32_16x16x32_bf16 v[100:103], v[24:27], v[78:81], v[12:15]
	s_nop 2
	v_add_u32_e32 v12, v89, v87
	v_mfma_f32_16x16x32_bf16 v[16:19], v[24:27], v[74:77], v[16:19]
	ds_read_b128 v[88:91], v12 offset:32768
	ds_read_b128 v[108:111], v12 offset:36864
	ds_read_b128 v[112:115], v12 offset:38912
	v_mfma_f32_16x16x32_bf16 v[0:3], v[8:11], v[74:77], v[0:3]
	v_mfma_f32_16x16x32_bf16 v[74:77], v[8:11], v[78:81], v[52:55]
	v_mfma_f32_16x16x32_bf16 v[78:81], v[8:11], v[92:95], v[44:47]
	ds_read_b128 v[92:95], v12 offset:34816
	s_waitcnt lgkmcnt(3)
	v_mfma_f32_16x16x32_bf16 v[60:63], v[4:7], v[88:91], v[60:63]
	s_waitcnt lgkmcnt(0)
	v_mfma_f32_16x16x32_bf16 v[44:47], v[4:7], v[92:95], v[56:59]
	v_mfma_f32_16x16x32_bf16 v[28:31], v[4:7], v[108:111], v[48:51]
	v_mfma_f32_16x16x32_bf16 v[12:15], v[4:7], v[112:115], v[40:43]
	ds_read_b128 v[4:7], v116 offset:51200
	s_waitcnt lgkmcnt(0)
	v_mfma_f32_16x16x32_bf16 v[56:59], v[4:7], v[88:91], v[36:39]
	v_mfma_f32_16x16x32_bf16 v[40:43], v[4:7], v[92:95], v[32:35]
	v_mfma_f32_16x16x32_bf16 v[24:27], v[4:7], v[108:111], v[96:99]
	v_mfma_f32_16x16x32_bf16 v[8:11], v[4:7], v[112:115], v[66:69]
	ds_read_b128 v[4:7], v116 offset:53248
	s_nop 0
	ds_read_b128 v[96:99], v116 offset:55296
	s_waitcnt vmcnt(0)
	s_waitcnt lgkmcnt(0)
	v_mfma_f32_16x16x32_bf16 v[32:35], v[96:99], v[92:95], v[0:3]
	s_nop 2
	v_or_b32_e32 v0, s0, v64
	v_lshl_or_b32 v66, v85, 6, s42
	v_cmp_lt_i32_e32 vcc, s33, v66
	v_mfma_f32_16x16x32_bf16 v[52:55], v[4:7], v[88:91], v[20:23]
	s_barrier
	v_mfma_f32_16x16x32_bf16 v[36:39], v[4:7], v[92:95], v[16:19]
	v_mfma_f32_16x16x32_bf16 v[20:23], v[4:7], v[108:111], v[100:103]
	v_mfma_f32_16x16x32_bf16 v[4:7], v[4:7], v[112:115], v[104:107]
	v_mfma_f32_16x16x32_bf16 v[48:51], v[96:99], v[88:91], v[70:73]
	v_mfma_f32_16x16x32_bf16 v[16:19], v[96:99], v[108:111], v[74:77]
	s_nop 1
	v_lshlrev_b32_e32 v70, 2, v84
	v_or_b32_e32 v64, v66, v70
	v_lshl_add_u32 v74, v86, 6, v0
	v_mfma_f32_16x16x32_bf16 v[0:3], v[96:99], v[112:115], v[78:81]
	s_and_saveexec_b64 s[0:1], vcc
	s_xor_b64 s[12:13], exec, s[0:1]
	s_cbranch_execz .LBB0_364
	v_mad_i64_i32 v[68:69], s[0:1], v74, s38, 0
	v_cmp_lt_i32_e64 s[4:5], s33, v64
	v_add_u32_e32 v66, 0xfffff200, v64
	s_and_saveexec_b64 s[0:1], s[4:5]
	s_xor_b64 s[0:1], exec, s[0:1]
	s_cbranch_execz .LBB0_223
	v_cmp_gt_u32_e32 vcc, 48, v66
	s_and_saveexec_b64 s[6:7], vcc
	s_cbranch_execz .LBB0_222
	v_mul_f32_e32 v60, 0xbfb8aa3b, v60
	v_mul_f32_e32 v61, 0xbfb8aa3b, v61
	v_exp_f32_e32 v60, v60
	v_exp_f32_e32 v61, v61
	v_lshl_add_u64 v[70:71], s[2:3], 0, v[68:69]
	v_mov_b32_e32 v67, v65
	v_lshl_add_u64 v[70:71], v[66:67], 2, v[70:71]
	v_pk_add_f32 v[60:61], v[60:61], 1.0 op_sel_hi:[1,0]
	v_mul_f32_e32 v62, 0xbfb8aa3b, v62
	v_mul_f32_e32 v63, 0xbfb8aa3b, v63
	v_exp_f32_e32 v62, v62
	v_exp_f32_e32 v63, v63
	v_rcp_f32_e32 v67, v61
	s_nop 0
	v_mul_f32_e32 v61, 1.0, v67
	v_pk_add_f32 v[62:63], v[62:63], 1.0 op_sel_hi:[1,0]
	v_rcp_f32_e32 v67, v60
	s_nop 0
	v_mul_f32_e32 v60, 1.0, v67
	v_rcp_f32_e32 v67, v63
	s_nop 0
	v_mul_f32_e32 v63, 1.0, v67
	v_rcp_f32_e32 v67, v62
	s_nop 0
	v_mul_f32_e32 v62, 1.0, v67
	global_store_dwordx4 v[70:71], v[60:63], off

; DI unsigned pack2(float a, float b) { v2f f = {a, b}; return __builtin_bit_cast(unsigned, __builtin_convertvector(f, v2bf)); }
; DI float fexp(float x) { return __builtin_amdgcn_exp2f(x * LOG2E); }
; DI float silu_f(float v) { return v / (1.f + fexp(-v)); }
;   DI void operator()(int m, int n, float a, float b, float c, float d, float& ss) const {
;     ...
;     if (n < q_end) { a *= qscale; b *= qscale; c *= qscale; d *= qscale; }
;     else if (n >= z_start) { a = silu_f(a); b = silu_f(b); c = silu_f(c); d = silu_f(d); }
;     ss += a * a + b * b + c * c + d * d;
;     u32x2 v; v.x = pack2(a, b); v.y = pack2(c, d);
;     *(u32x2*)(dst + (long)m * ld + n) = v;
.LBB0_223:
	s_andn2_saveexec_b64 s[0:1], s[0:1]
	s_cbranch_execz .LBB0_229
	v_cmp_lt_i32_e32 vcc, s39, v64
	s_and_saveexec_b64 s[6:7], vcc
	s_xor_b64 s[6:7], exec, s[6:7]
	s_cbranch_execz .LBB0_226
	v_mul_f32_e32 v67, 0xbfb8aa3b, v60
	v_exp_f32_e32 v70, v67
	v_mul_f32_e32 v67, 0xbfb8aa3b, v61
	v_exp_f32_e32 v71, v67
	s_nop 0
	v_pk_add_f32 v[70:71], v[70:71], 1.0 op_sel_hi:[1,0]
	s_nop 0
	v_rcp_f32_e32 v67, v71
	v_mul_f32_e32 v72, 0xbfb8aa3b, v62
	v_mul_f32_e32 v73, 0xbfb8aa3b, v63
	v_exp_f32_e32 v72, v72
	v_exp_f32_e32 v73, v73
	v_mul_f32_e32 v71, v61, v67
	v_pk_add_f32 v[72:73], v[72:73], 1.0 op_sel_hi:[1,0]
	v_rcp_f32_e32 v61, v70
	s_nop 0
	v_mul_f32_e32 v70, v60, v61
	v_rcp_f32_e32 v60, v73
	s_nop 0
	v_mul_f32_e32 v73, v63, v60
	v_rcp_f32_e32 v60, v72
	s_nop 0
	v_mul_f32_e32 v72, v62, v60

; DI float fexp(float x) { return __builtin_amdgcn_exp2f(x * LOG2E); }
; DI float sigmoid_f(float v) { return 1.f / (1.f + fexp(-v)); }
;   DI void operator()(int m, int n, float a, float b, float c, float d, float& ss) const {
;     if (n >= gl_start) {
;       const int j = n - gl_start;
;       if (j < 48) { float* g = gates + (long)m * 48 + j; g[0] = sigmoid_f(a); g[1] = sigmoid_f(b); g[2] = sigmoid_f(c); g[3] = sigmoid_f(d); }
;       return;
.LBB0_229:
	s_or_b64 exec, exec, s[0:1]
	v_or_b32_e32 v72, 16, v64
	v_cmp_lt_i32_e64 s[6:7], s33, v72
	v_add_u32_e32 v60, 0xfffff210, v64
	s_and_saveexec_b64 s[0:1], s[6:7]
	s_xor_b64 s[0:1], exec, s[0:1]
	s_cbranch_execz .LBB0_233
	v_cmp_gt_u32_e32 vcc, 48, v60
	s_and_saveexec_b64 s[8:9], vcc
	s_cbranch_execz .LBB0_232
	v_mul_f32_e32 v56, 0xbfb8aa3b, v56
	v_mul_f32_e32 v57, 0xbfb8aa3b, v57
	v_exp_f32_e32 v56, v56
	v_exp_f32_e32 v57, v57
	v_lshl_add_u64 v[62:63], s[2:3], 0, v[68:69]
	v_mov_b32_e32 v61, v65
	v_lshl_add_u64 v[62:63], v[60:61], 2, v[62:63]
	v_pk_add_f32 v[56:57], v[56:57], 1.0 op_sel_hi:[1,0]
	v_mul_f32_e32 v58, 0xbfb8aa3b, v58
	v_mul_f32_e32 v59, 0xbfb8aa3b, v59
	v_exp_f32_e32 v58, v58
	v_exp_f32_e32 v59, v59
	v_rcp_f32_e32 v61, v57
	s_nop 0
	v_mul_f32_e32 v57, 1.0, v61
	v_pk_add_f32 v[58:59], v[58:59], 1.0 op_sel_hi:[1,0]
	v_rcp_f32_e32 v61, v56
	s_nop 0
	v_mul_f32_e32 v56, 1.0, v61
	v_rcp_f32_e32 v61, v59
	s_nop 0
	v_mul_f32_e32 v59, 1.0, v61
	v_rcp_f32_e32 v61, v58
	s_nop 0
	v_mul_f32_e32 v58, 1.0, v61
	global_store_dwordx4 v[62:63], v[56:59], off

; DI unsigned pack2(float a, float b) { v2f f = {a, b}; return __builtin_bit_cast(unsigned, __builtin_convertvector(f, v2bf)); }
; DI float fexp(float x) { return __builtin_amdgcn_exp2f(x * LOG2E); }
; DI float silu_f(float v) { return v / (1.f + fexp(-v)); }
;   DI void operator()(int m, int n, float a, float b, float c, float d, float& ss) const {
;     ...
;     if (n < q_end) { a *= qscale; b *= qscale; c *= qscale; d *= qscale; }
;     else if (n >= z_start) { a = silu_f(a); b = silu_f(b); c = silu_f(c); d = silu_f(d); }
;     ss += a * a + b * b + c * c + d * d;
;     u32x2 v; v.x = pack2(a, b); v.y = pack2(c, d);
;     *(u32x2*)(dst + (long)m * ld + n) = v;
.LBB0_233:
	s_andn2_saveexec_b64 s[0:1], s[0:1]
	s_cbranch_execz .LBB0_239
	v_cmp_lt_i32_e32 vcc, s39, v72
	s_and_saveexec_b64 s[8:9], vcc
	s_xor_b64 s[8:9], exec, s[8:9]
	s_cbranch_execz .LBB0_236
	v_mul_f32_e32 v61, 0xbfb8aa3b, v56
	v_exp_f32_e32 v62, v61
	v_mul_f32_e32 v61, 0xbfb8aa3b, v57
	v_exp_f32_e32 v63, v61
	s_nop 0
	v_pk_add_f32 v[62:63], v[62:63], 1.0 op_sel_hi:[1,0]
	s_nop 0
	v_rcp_f32_e32 v61, v63
	v_mul_f32_e32 v67, 0xbfb8aa3b, v58
	v_exp_f32_e32 v70, v67
	v_mul_f32_e32 v67, 0xbfb8aa3b, v59
	v_exp_f32_e32 v71, v67
	v_mul_f32_e32 v63, v57, v61
	v_pk_add_f32 v[70:71], v[70:71], 1.0 op_sel_hi:[1,0]
	v_rcp_f32_e32 v57, v62
	s_nop 0
	v_mul_f32_e32 v62, v56, v57
	v_rcp_f32_e32 v56, v71
	s_nop 0
	v_mul_f32_e32 v71, v59, v56
	v_rcp_f32_e32 v56, v70
	s_nop 0
	v_mul_f32_e32 v70, v58, v56

; DI float fexp(float x) { return __builtin_amdgcn_exp2f(x * LOG2E); }
; DI float sigmoid_f(float v) { return 1.f / (1.f + fexp(-v)); }
;   DI void operator()(int m, int n, float a, float b, float c, float d, float& ss) const {
;     if (n >= gl_start) {
;       const int j = n - gl_start;
;       if (j < 48) { float* g = gates + (long)m * 48 + j; g[0] = sigmoid_f(a); g[1] = sigmoid_f(b); g[2] = sigmoid_f(c); g[3] = sigmoid_f(d); }
;       return;
.LBB0_239:
	s_or_b64 exec, exec, s[0:1]
	v_or_b32_e32 v70, 32, v64
	v_cmp_lt_i32_e64 s[8:9], s33, v70
	v_add_u32_e32 v56, 0xfffff220, v64
	s_and_saveexec_b64 s[0:1], s[8:9]
	s_xor_b64 s[0:1], exec, s[0:1]
	s_cbranch_execz .LBB0_243
	v_cmp_gt_u32_e32 vcc, 48, v56
	s_and_saveexec_b64 s[10:11], vcc
	s_cbranch_execz .LBB0_242
	v_mul_f32_e32 v52, 0xbfb8aa3b, v52
	v_mul_f32_e32 v53, 0xbfb8aa3b, v53
	v_exp_f32_e32 v52, v52
	v_exp_f32_e32 v53, v53
	v_lshl_add_u64 v[58:59], s[2:3], 0, v[68:69]
	v_mov_b32_e32 v57, v65
	v_lshl_add_u64 v[58:59], v[56:57], 2, v[58:59]
	v_pk_add_f32 v[52:53], v[52:53], 1.0 op_sel_hi:[1,0]
	v_mul_f32_e32 v54, 0xbfb8aa3b, v54
	v_mul_f32_e32 v55, 0xbfb8aa3b, v55
	v_exp_f32_e32 v54, v54
	v_exp_f32_e32 v55, v55
	v_rcp_f32_e32 v57, v53
	s_nop 0
	v_mul_f32_e32 v53, 1.0, v57
	v_pk_add_f32 v[54:55], v[54:55], 1.0 op_sel_hi:[1,0]
	v_rcp_f32_e32 v57, v52
	s_nop 0
	v_mul_f32_e32 v52, 1.0, v57
	v_rcp_f32_e32 v57, v55
	s_nop 0
	v_mul_f32_e32 v55, 1.0, v57
	v_rcp_f32_e32 v57, v54
	s_nop 0
	v_mul_f32_e32 v54, 1.0, v57
	global_store_dwordx4 v[58:59], v[52:55], off

; DI unsigned pack2(float a, float b) { v2f f = {a, b}; return __builtin_bit_cast(unsigned, __builtin_convertvector(f, v2bf)); }
; DI float fexp(float x) { return __builtin_amdgcn_exp2f(x * LOG2E); }
; DI float silu_f(float v) { return v / (1.f + fexp(-v)); }
;   DI void operator()(int m, int n, float a, float b, float c, float d, float& ss) const {
;     ...
;     if (n < q_end) { a *= qscale; b *= qscale; c *= qscale; d *= qscale; }
;     else if (n >= z_start) { a = silu_f(a); b = silu_f(b); c = silu_f(c); d = silu_f(d); }
;     ss += a * a + b * b + c * c + d * d;
;     u32x2 v; v.x = pack2(a, b); v.y = pack2(c, d);
;     *(u32x2*)(dst + (long)m * ld + n) = v;
.LBB0_243:
	s_andn2_saveexec_b64 s[0:1], s[0:1]
	s_cbranch_execz .LBB0_249
	v_cmp_lt_i32_e32 vcc, s39, v70
	s_and_saveexec_b64 s[10:11], vcc
	s_xor_b64 s[10:11], exec, s[10:11]
	s_cbranch_execz .LBB0_246
	v_mul_f32_e32 v57, 0xbfb8aa3b, v52
	v_exp_f32_e32 v58, v57
	v_mul_f32_e32 v57, 0xbfb8aa3b, v53
	v_exp_f32_e32 v59, v57
	s_nop 0
	v_pk_add_f32 v[58:59], v[58:59], 1.0 op_sel_hi:[1,0]
	s_nop 0
	v_rcp_f32_e32 v57, v59
	v_mul_f32_e32 v61, 0xbfb8aa3b, v54
	v_exp_f32_e32 v62, v61
	v_mul_f32_e32 v61, 0xbfb8aa3b, v55
	v_exp_f32_e32 v63, v61
	v_mul_f32_e32 v59, v53, v57
	v_pk_add_f32 v[62:63], v[62:63], 1.0 op_sel_hi:[1,0]
	v_rcp_f32_e32 v53, v58
	s_nop 0
	v_mul_f32_e32 v58, v52, v53
	v_rcp_f32_e32 v52, v63
	s_nop 0
	v_mul_f32_e32 v63, v55, v52
	v_rcp_f32_e32 v52, v62
	s_nop 0
	v_mul_f32_e32 v62, v54, v52

; DI unsigned pack2(float a, float b) { v2f f = {a, b}; return __builtin_bit_cast(unsigned, __builtin_convertvector(f, v2bf)); }
; DI float fexp(float x) { return __builtin_amdgcn_exp2f(x * LOG2E); }
; DI float silu_f(float v) { return v / (1.f + fexp(-v)); }
;   DI void operator()(int m, int n, float a, float b, float c, float d, float& ss) const {
;     ...
;     if (n < q_end) { a *= qscale; b *= qscale; c *= qscale; d *= qscale; }
;     else if (n >= z_start) { a = silu_f(a); b = silu_f(b); c = silu_f(c); d = silu_f(d); }
;     ss += a * a + b * b + c * c + d * d;
;     u32x2 v; v.x = pack2(a, b); v.y = pack2(c, d);
;     *(u32x2*)(dst + (long)m * ld + n) = v;
.LBB0_249:
	s_or_b64 exec, exec, s[0:1]
	v_or_b32_e32 v58, 48, v64
	v_cmp_gt_i32_e64 s[10:11], s41, v58
	s_and_saveexec_b64 s[0:1], s[10:11]
	s_cbranch_execz .LBB0_255
	v_cmp_lt_i32_e32 vcc, s39, v58
	s_and_saveexec_b64 s[34:35], vcc
	s_xor_b64 s[34:35], exec, s[34:35]
	s_cbranch_execz .LBB0_252
	v_mul_f32_e32 v52, 0xbfb8aa3b, v48
	v_mul_f32_e32 v53, 0xbfb8aa3b, v49
	v_exp_f32_e32 v52, v52
	v_exp_f32_e32 v53, v53
	s_nop 0
	v_pk_add_f32 v[52:53], v[52:53], 1.0 op_sel_hi:[1,0]
	s_nop 0
	v_rcp_f32_e32 v54, v53
	s_nop 0
	v_mul_f32_e32 v53, v49, v54
	v_mul_f32_e32 v54, 0xbfb8aa3b, v50
	v_mul_f32_e32 v55, 0xbfb8aa3b, v51
	v_exp_f32_e32 v54, v54
	v_exp_f32_e32 v55, v55
	s_nop 0
	v_pk_add_f32 v[54:55], v[54:55], 1.0 op_sel_hi:[1,0]
	v_rcp_f32_e32 v49, v52
	s_nop 0
	v_mul_f32_e32 v52, v48, v49
	v_rcp_f32_e32 v48, v55
	s_nop 0
	v_mul_f32_e32 v55, v51, v48
	v_rcp_f32_e32 v48, v54
	s_nop 0
	v_mul_f32_e32 v54, v50, v48

; DI float fexp(float x) { return __builtin_amdgcn_exp2f(x * LOG2E); }
; DI float sigmoid_f(float v) { return 1.f / (1.f + fexp(-v)); }
;   DI void operator()(int m, int n, float a, float b, float c, float d, float& ss) const {
;     if (n >= gl_start) {
;       const int j = n - gl_start;
;       if (j < 48) { float* g = gates + (long)m * 48 + j; g[0] = sigmoid_f(a); g[1] = sigmoid_f(b); g[2] = sigmoid_f(c); g[3] = sigmoid_f(d); }
;       return;
.LBB0_262:
	v_cmp_gt_u32_e32 vcc, 48, v66
	s_and_saveexec_b64 s[34:35], vcc
	s_cbranch_execz .LBB0_264
	v_mul_f32_e32 v44, 0xbfb8aa3b, v44
	v_mul_f32_e32 v45, 0xbfb8aa3b, v45
	v_exp_f32_e32 v44, v44
	v_exp_f32_e32 v45, v45
	v_mul_f32_e32 v46, 0xbfb8aa3b, v46
	v_mul_f32_e32 v47, 0xbfb8aa3b, v47
	v_exp_f32_e32 v46, v46
	v_pk_add_f32 v[44:45], v[44:45], 1.0 op_sel_hi:[1,0]
	v_exp_f32_e32 v47, v47
	s_nop 0
	v_pk_add_f32 v[46:47], v[46:47], 1.0 op_sel_hi:[1,0]
	v_lshl_add_u64 v[50:51], s[2:3], 0, v[48:49]
	v_mov_b32_e32 v67, v65
	v_rcp_f32_e32 v52, v45
	s_nop 0
	v_mul_f32_e32 v45, 1.0, v52
	v_lshl_add_u64 v[50:51], v[66:67], 2, v[50:51]
	v_rcp_f32_e32 v52, v44
	s_nop 0
	v_mul_f32_e32 v44, 1.0, v52
	v_rcp_f32_e32 v52, v47
	s_nop 0
	v_mul_f32_e32 v47, 1.0, v52
	v_rcp_f32_e32 v52, v46
	s_nop 0
	v_mul_f32_e32 v46, 1.0, v52
	global_store_dwordx4 v[50:51], v[44:47], off

; DI unsigned pack2(float a, float b) { v2f f = {a, b}; return __builtin_bit_cast(unsigned, __builtin_convertvector(f, v2bf)); }
; DI float fexp(float x) { return __builtin_amdgcn_exp2f(x * LOG2E); }
; DI float silu_f(float v) { return v / (1.f + fexp(-v)); }
;   DI void operator()(int m, int n, float a, float b, float c, float d, float& ss) const {
;     ...
;     if (n < q_end) { a *= qscale; b *= qscale; c *= qscale; d *= qscale; }
;     else if (n >= z_start) { a = silu_f(a); b = silu_f(b); c = silu_f(c); d = silu_f(d); }
;     ss += a * a + b * b + c * c + d * d;
;     u32x2 v; v.x = pack2(a, b); v.y = pack2(c, d);
;     *(u32x2*)(dst + (long)m * ld + n) = v;
.LBB0_265:
	v_cmp_lt_i32_e32 vcc, s39, v64
	s_and_saveexec_b64 s[34:35], vcc
	s_xor_b64 s[34:35], exec, s[34:35]
	s_cbranch_execz .LBB0_267
	v_mul_f32_e32 v50, 0xbfb8aa3b, v44
	v_mul_f32_e32 v51, 0xbfb8aa3b, v45
	v_exp_f32_e32 v50, v50
	v_exp_f32_e32 v51, v51
	s_nop 0
	v_pk_add_f32 v[50:51], v[50:51], 1.0 op_sel_hi:[1,0]
	s_nop 0
	v_rcp_f32_e32 v52, v51
	s_nop 0
	v_mul_f32_e32 v51, v45, v52
	v_mul_f32_e32 v52, 0xbfb8aa3b, v46
	v_mul_f32_e32 v53, 0xbfb8aa3b, v47
	v_exp_f32_e32 v52, v52
	v_exp_f32_e32 v53, v53
	s_nop 0
	v_pk_add_f32 v[52:53], v[52:53], 1.0 op_sel_hi:[1,0]
	v_rcp_f32_e32 v45, v50
	s_nop 0
	v_mul_f32_e32 v50, v44, v45
	v_rcp_f32_e32 v44, v53
	s_nop 0
	v_mul_f32_e32 v53, v47, v44
	v_rcp_f32_e32 v44, v52
	s_nop 0
	v_mul_f32_e32 v52, v46, v44

; DI float fexp(float x) { return __builtin_amdgcn_exp2f(x * LOG2E); }
; DI float sigmoid_f(float v) { return 1.f / (1.f + fexp(-v)); }
;   DI void operator()(int m, int n, float a, float b, float c, float d, float& ss) const {
;     if (n >= gl_start) {
;       const int j = n - gl_start;
;       if (j < 48) { float* g = gates + (long)m * 48 + j; g[0] = sigmoid_f(a); g[1] = sigmoid_f(b); g[2] = sigmoid_f(c); g[3] = sigmoid_f(d); }
;       return;
.LBB0_270:
	v_cmp_gt_u32_e32 vcc, 48, v60
	s_and_saveexec_b64 s[34:35], vcc
	s_cbranch_execz .LBB0_272
	v_mul_f32_e32 v40, 0xbfb8aa3b, v40
	v_mul_f32_e32 v41, 0xbfb8aa3b, v41
	v_exp_f32_e32 v40, v40
	v_exp_f32_e32 v41, v41
	v_mul_f32_e32 v42, 0xbfb8aa3b, v42
	v_mul_f32_e32 v43, 0xbfb8aa3b, v43
	v_exp_f32_e32 v42, v42
	v_pk_add_f32 v[40:41], v[40:41], 1.0 op_sel_hi:[1,0]
	v_exp_f32_e32 v43, v43
	s_nop 0
	v_pk_add_f32 v[42:43], v[42:43], 1.0 op_sel_hi:[1,0]
	v_lshl_add_u64 v[44:45], s[2:3], 0, v[48:49]
	v_mov_b32_e32 v61, v65
	v_rcp_f32_e32 v46, v41
	s_nop 0
	v_mul_f32_e32 v41, 1.0, v46
	v_lshl_add_u64 v[44:45], v[60:61], 2, v[44:45]
	v_rcp_f32_e32 v46, v40
	s_nop 0
	v_mul_f32_e32 v40, 1.0, v46
	v_rcp_f32_e32 v46, v43
	s_nop 0
	v_mul_f32_e32 v43, 1.0, v46
	v_rcp_f32_e32 v46, v42
	s_nop 0
	v_mul_f32_e32 v42, 1.0, v46
	global_store_dwordx4 v[44:45], v[40:43], off

; DI unsigned pack2(float a, float b) { v2f f = {a, b}; return __builtin_bit_cast(unsigned, __builtin_convertvector(f, v2bf)); }
; DI float fexp(float x) { return __builtin_amdgcn_exp2f(x * LOG2E); }
; DI float silu_f(float v) { return v / (1.f + fexp(-v)); }
;   DI void operator()(int m, int n, float a, float b, float c, float d, float& ss) const {
;     ...
;     if (n < q_end) { a *= qscale; b *= qscale; c *= qscale; d *= qscale; }
;     else if (n >= z_start) { a = silu_f(a); b = silu_f(b); c = silu_f(c); d = silu_f(d); }
;     ss += a * a + b * b + c * c + d * d;
;     u32x2 v; v.x = pack2(a, b); v.y = pack2(c, d);
;     *(u32x2*)(dst + (long)m * ld + n) = v;
.LBB0_273:
	v_cmp_lt_i32_e32 vcc, s39, v72
	s_and_saveexec_b64 s[34:35], vcc
	s_xor_b64 s[34:35], exec, s[34:35]
	s_cbranch_execz .LBB0_275
	v_mul_f32_e32 v44, 0xbfb8aa3b, v40
	v_mul_f32_e32 v45, 0xbfb8aa3b, v41
	v_exp_f32_e32 v44, v44
	v_exp_f32_e32 v45, v45
	s_nop 0
	v_pk_add_f32 v[44:45], v[44:45], 1.0 op_sel_hi:[1,0]
	s_nop 0
	v_rcp_f32_e32 v46, v45
	s_nop 0
	v_mul_f32_e32 v45, v41, v46
	v_mul_f32_e32 v46, 0xbfb8aa3b, v42
	v_mul_f32_e32 v47, 0xbfb8aa3b, v43
	v_exp_f32_e32 v46, v46
	v_exp_f32_e32 v47, v47
	s_nop 0
	v_pk_add_f32 v[46:47], v[46:47], 1.0 op_sel_hi:[1,0]
	v_rcp_f32_e32 v41, v44
	s_nop 0
	v_mul_f32_e32 v44, v40, v41
	v_rcp_f32_e32 v40, v47
	s_nop 0
	v_mul_f32_e32 v47, v43, v40
	v_rcp_f32_e32 v40, v46
	s_nop 0
	v_mul_f32_e32 v46, v42, v40

; DI float fexp(float x) { return __builtin_amdgcn_exp2f(x * LOG2E); }
; DI float sigmoid_f(float v) { return 1.f / (1.f + fexp(-v)); }
;   DI void operator()(int m, int n, float a, float b, float c, float d, float& ss) const {
;     if (n >= gl_start) {
;       const int j = n - gl_start;
;       if (j < 48) { float* g = gates + (long)m * 48 + j; g[0] = sigmoid_f(a); g[1] = sigmoid_f(b); g[2] = sigmoid_f(c); g[3] = sigmoid_f(d); }
;       return;
.LBB0_278:
	v_cmp_gt_u32_e32 vcc, 48, v56
	s_and_saveexec_b64 s[34:35], vcc
	s_cbranch_execz .LBB0_280
	v_mul_f32_e32 v36, 0xbfb8aa3b, v36
	v_mul_f32_e32 v37, 0xbfb8aa3b, v37
	v_exp_f32_e32 v36, v36
	v_exp_f32_e32 v37, v37
	v_mul_f32_e32 v38, 0xbfb8aa3b, v38
	v_mul_f32_e32 v39, 0xbfb8aa3b, v39
	v_exp_f32_e32 v38, v38
	v_pk_add_f32 v[36:37], v[36:37], 1.0 op_sel_hi:[1,0]
	v_exp_f32_e32 v39, v39
	s_nop 0
	v_pk_add_f32 v[38:39], v[38:39], 1.0 op_sel_hi:[1,0]
	v_lshl_add_u64 v[40:41], s[2:3], 0, v[48:49]
	v_mov_b32_e32 v57, v65
	v_rcp_f32_e32 v42, v37
	s_nop 0
	v_mul_f32_e32 v37, 1.0, v42
	v_lshl_add_u64 v[40:41], v[56:57], 2, v[40:41]
	v_rcp_f32_e32 v42, v36
	s_nop 0
	v_mul_f32_e32 v36, 1.0, v42
	v_rcp_f32_e32 v42, v39
	s_nop 0
	v_mul_f32_e32 v39, 1.0, v42
	v_rcp_f32_e32 v42, v38
	s_nop 0
	v_mul_f32_e32 v38, 1.0, v42
	global_store_dwordx4 v[40:41], v[36:39], off

; DI unsigned pack2(float a, float b) { v2f f = {a, b}; return __builtin_bit_cast(unsigned, __builtin_convertvector(f, v2bf)); }
; DI float fexp(float x) { return __builtin_amdgcn_exp2f(x * LOG2E); }
; DI float silu_f(float v) { return v / (1.f + fexp(-v)); }
;   DI void operator()(int m, int n, float a, float b, float c, float d, float& ss) const {
;     ...
;     if (n < q_end) { a *= qscale; b *= qscale; c *= qscale; d *= qscale; }
;     else if (n >= z_start) { a = silu_f(a); b = silu_f(b); c = silu_f(c); d = silu_f(d); }
;     ss += a * a + b * b + c * c + d * d;
;     u32x2 v; v.x = pack2(a, b); v.y = pack2(c, d);
;     *(u32x2*)(dst + (long)m * ld + n) = v;
.LBB0_281:
	v_cmp_lt_i32_e32 vcc, s39, v70
	s_and_saveexec_b64 s[34:35], vcc
	s_xor_b64 s[34:35], exec, s[34:35]
	s_cbranch_execz .LBB0_283
	v_mul_f32_e32 v40, 0xbfb8aa3b, v36
	v_mul_f32_e32 v41, 0xbfb8aa3b, v37
	v_exp_f32_e32 v40, v40
	v_exp_f32_e32 v41, v41
	s_nop 0
	v_pk_add_f32 v[40:41], v[40:41], 1.0 op_sel_hi:[1,0]
	s_nop 0
	v_rcp_f32_e32 v42, v41
	s_nop 0
	v_mul_f32_e32 v41, v37, v42
	v_mul_f32_e32 v42, 0xbfb8aa3b, v38
	v_mul_f32_e32 v43, 0xbfb8aa3b, v39
	v_exp_f32_e32 v42, v42
	v_exp_f32_e32 v43, v43
	s_nop 0
	v_pk_add_f32 v[42:43], v[42:43], 1.0 op_sel_hi:[1,0]
	v_rcp_f32_e32 v37, v40
	s_nop 0
	v_mul_f32_e32 v40, v36, v37
	v_rcp_f32_e32 v36, v43
	s_nop 0
	v_mul_f32_e32 v43, v39, v36
	v_rcp_f32_e32 v36, v42
	s_nop 0
	v_mul_f32_e32 v42, v38, v36

; DI unsigned pack2(float a, float b) { v2f f = {a, b}; return __builtin_bit_cast(unsigned, __builtin_convertvector(f, v2bf)); }
; DI float fexp(float x) { return __builtin_amdgcn_exp2f(x * LOG2E); }
; DI float silu_f(float v) { return v / (1.f + fexp(-v)); }
;   DI void operator()(int m, int n, float a, float b, float c, float d, float& ss) const {
;     ...
;     if (n < q_end) { a *= qscale; b *= qscale; c *= qscale; d *= qscale; }
;     else if (n >= z_start) { a = silu_f(a); b = silu_f(b); c = silu_f(c); d = silu_f(d); }
;     ss += a * a + b * b + c * c + d * d;
;     u32x2 v; v.x = pack2(a, b); v.y = pack2(c, d);
;     *(u32x2*)(dst + (long)m * ld + n) = v;
.LBB0_286:
	v_cmp_lt_i32_e32 vcc, s39, v58
	s_and_saveexec_b64 s[34:35], vcc
	s_xor_b64 s[34:35], exec, s[34:35]
	s_cbranch_execz .LBB0_288
	v_mul_f32_e32 v36, 0xbfb8aa3b, v32
	v_mul_f32_e32 v37, 0xbfb8aa3b, v33
	v_exp_f32_e32 v36, v36
	v_exp_f32_e32 v37, v37
	s_nop 0
	v_pk_add_f32 v[36:37], v[36:37], 1.0 op_sel_hi:[1,0]
	s_nop 0
	v_rcp_f32_e32 v38, v37
	s_nop 0
	v_mul_f32_e32 v37, v33, v38
	v_mul_f32_e32 v38, 0xbfb8aa3b, v34
	v_mul_f32_e32 v39, 0xbfb8aa3b, v35
	v_exp_f32_e32 v38, v38
	v_exp_f32_e32 v39, v39
	s_nop 0
	v_pk_add_f32 v[38:39], v[38:39], 1.0 op_sel_hi:[1,0]
	v_rcp_f32_e32 v33, v36
	s_nop 0
	v_mul_f32_e32 v36, v32, v33
	v_rcp_f32_e32 v32, v39
	s_nop 0
	v_mul_f32_e32 v39, v35, v32
	v_rcp_f32_e32 v32, v38
	s_nop 0
	v_mul_f32_e32 v38, v34, v32

; DI float fexp(float x) { return __builtin_amdgcn_exp2f(x * LOG2E); }
; DI float sigmoid_f(float v) { return 1.f / (1.f + fexp(-v)); }
;   DI void operator()(int m, int n, float a, float b, float c, float d, float& ss) const {
;     if (n >= gl_start) {
;       const int j = n - gl_start;
;       if (j < 48) { float* g = gates + (long)m * 48 + j; g[0] = sigmoid_f(a); g[1] = sigmoid_f(b); g[2] = sigmoid_f(c); g[3] = sigmoid_f(d); }
;       return;
.LBB0_298:
	v_cmp_gt_u32_e32 vcc, 48, v66
	s_and_saveexec_b64 s[34:35], vcc
	s_cbranch_execz .LBB0_300
	v_mul_f32_e32 v28, 0xbfb8aa3b, v28
	v_mul_f32_e32 v29, 0xbfb8aa3b, v29
	v_exp_f32_e32 v28, v28
	v_exp_f32_e32 v29, v29
	v_mul_f32_e32 v30, 0xbfb8aa3b, v30
	v_mul_f32_e32 v31, 0xbfb8aa3b, v31
	v_exp_f32_e32 v30, v30
	v_pk_add_f32 v[28:29], v[28:29], 1.0 op_sel_hi:[1,0]
	v_exp_f32_e32 v31, v31
	s_nop 0
	v_pk_add_f32 v[30:31], v[30:31], 1.0 op_sel_hi:[1,0]
	v_lshl_add_u64 v[34:35], s[2:3], 0, v[32:33]
	v_mov_b32_e32 v67, v65
	v_rcp_f32_e32 v36, v29
	s_nop 0
	v_mul_f32_e32 v29, 1.0, v36
	v_lshl_add_u64 v[34:35], v[66:67], 2, v[34:35]
	v_rcp_f32_e32 v36, v28
	s_nop 0
	v_mul_f32_e32 v28, 1.0, v36
	v_rcp_f32_e32 v36, v31
	s_nop 0
	v_mul_f32_e32 v31, 1.0, v36
	v_rcp_f32_e32 v36, v30
	s_nop 0
	v_mul_f32_e32 v30, 1.0, v36
	global_store_dwordx4 v[34:35], v[28:31], off

; DI unsigned pack2(float a, float b) { v2f f = {a, b}; return __builtin_bit_cast(unsigned, __builtin_convertvector(f, v2bf)); }
; DI float fexp(float x) { return __builtin_amdgcn_exp2f(x * LOG2E); }
; DI float silu_f(float v) { return v / (1.f + fexp(-v)); }
;   DI void operator()(int m, int n, float a, float b, float c, float d, float& ss) const {
;     ...
;     if (n < q_end) { a *= qscale; b *= qscale; c *= qscale; d *= qscale; }
;     else if (n >= z_start) { a = silu_f(a); b = silu_f(b); c = silu_f(c); d = silu_f(d); }
;     ss += a * a + b * b + c * c + d * d;
;     u32x2 v; v.x = pack2(a, b); v.y = pack2(c, d);
;     *(u32x2*)(dst + (long)m * ld + n) = v;
.LBB0_301:
	v_cmp_lt_i32_e32 vcc, s39, v64
	s_and_saveexec_b64 s[34:35], vcc
	s_xor_b64 s[34:35], exec, s[34:35]
	s_cbranch_execz .LBB0_303
	v_mul_f32_e32 v34, 0xbfb8aa3b, v28
	v_mul_f32_e32 v35, 0xbfb8aa3b, v29
	v_exp_f32_e32 v34, v34
	v_exp_f32_e32 v35, v35
	s_nop 0
	v_pk_add_f32 v[34:35], v[34:35], 1.0 op_sel_hi:[1,0]
	s_nop 0
	v_rcp_f32_e32 v36, v35
	s_nop 0
	v_mul_f32_e32 v35, v29, v36
	v_mul_f32_e32 v36, 0xbfb8aa3b, v30
	v_mul_f32_e32 v37, 0xbfb8aa3b, v31
	v_exp_f32_e32 v36, v36
	v_exp_f32_e32 v37, v37
	s_nop 0
	v_pk_add_f32 v[36:37], v[36:37], 1.0 op_sel_hi:[1,0]
	v_rcp_f32_e32 v29, v34
	s_nop 0
	v_mul_f32_e32 v34, v28, v29
	v_rcp_f32_e32 v28, v37
	s_nop 0
	v_mul_f32_e32 v37, v31, v28
	v_rcp_f32_e32 v28, v36
	s_nop 0
	v_mul_f32_e32 v36, v30, v28

; DI float fexp(float x) { return __builtin_amdgcn_exp2f(x * LOG2E); }
; DI float sigmoid_f(float v) { return 1.f / (1.f + fexp(-v)); }
;   DI void operator()(int m, int n, float a, float b, float c, float d, float& ss) const {
;     if (n >= gl_start) {
;       const int j = n - gl_start;
;       if (j < 48) { float* g = gates + (long)m * 48 + j; g[0] = sigmoid_f(a); g[1] = sigmoid_f(b); g[2] = sigmoid_f(c); g[3] = sigmoid_f(d); }
;       return;
.LBB0_306:
	v_cmp_gt_u32_e32 vcc, 48, v60
	s_and_saveexec_b64 s[34:35], vcc
	s_cbranch_execz .LBB0_308
	v_mul_f32_e32 v24, 0xbfb8aa3b, v24
	v_mul_f32_e32 v25, 0xbfb8aa3b, v25
	v_exp_f32_e32 v24, v24
	v_exp_f32_e32 v25, v25
	v_mul_f32_e32 v26, 0xbfb8aa3b, v26
	v_mul_f32_e32 v27, 0xbfb8aa3b, v27
	v_exp_f32_e32 v26, v26
	v_pk_add_f32 v[24:25], v[24:25], 1.0 op_sel_hi:[1,0]
	v_exp_f32_e32 v27, v27
	s_nop 0
	v_pk_add_f32 v[26:27], v[26:27], 1.0 op_sel_hi:[1,0]
	v_lshl_add_u64 v[28:29], s[2:3], 0, v[32:33]
	v_mov_b32_e32 v61, v65
	v_rcp_f32_e32 v30, v25
	s_nop 0
	v_mul_f32_e32 v25, 1.0, v30
	v_lshl_add_u64 v[28:29], v[60:61], 2, v[28:29]
	v_rcp_f32_e32 v30, v24
	s_nop 0
	v_mul_f32_e32 v24, 1.0, v30
	v_rcp_f32_e32 v30, v27
	s_nop 0
	v_mul_f32_e32 v27, 1.0, v30
	v_rcp_f32_e32 v30, v26
	s_nop 0
	v_mul_f32_e32 v26, 1.0, v30
	global_store_dwordx4 v[28:29], v[24:27], off

; DI unsigned pack2(float a, float b) { v2f f = {a, b}; return __builtin_bit_cast(unsigned, __builtin_convertvector(f, v2bf)); }
; DI float fexp(float x) { return __builtin_amdgcn_exp2f(x * LOG2E); }
; DI float silu_f(float v) { return v / (1.f + fexp(-v)); }
;   DI void operator()(int m, int n, float a, float b, float c, float d, float& ss) const {
;     ...
;     if (n < q_end) { a *= qscale; b *= qscale; c *= qscale; d *= qscale; }
;     else if (n >= z_start) { a = silu_f(a); b = silu_f(b); c = silu_f(c); d = silu_f(d); }
;     ss += a * a + b * b + c * c + d * d;
;     u32x2 v; v.x = pack2(a, b); v.y = pack2(c, d);
;     *(u32x2*)(dst + (long)m * ld + n) = v;
.LBB0_309:
	v_cmp_lt_i32_e32 vcc, s39, v72
	s_and_saveexec_b64 s[34:35], vcc
	s_xor_b64 s[34:35], exec, s[34:35]
	s_cbranch_execz .LBB0_311
	v_mul_f32_e32 v28, 0xbfb8aa3b, v24
	v_mul_f32_e32 v29, 0xbfb8aa3b, v25
	v_exp_f32_e32 v28, v28
	v_exp_f32_e32 v29, v29
	s_nop 0
	v_pk_add_f32 v[28:29], v[28:29], 1.0 op_sel_hi:[1,0]
	s_nop 0
	v_rcp_f32_e32 v30, v29
	s_nop 0
	v_mul_f32_e32 v29, v25, v30
	v_mul_f32_e32 v30, 0xbfb8aa3b, v26
	v_mul_f32_e32 v31, 0xbfb8aa3b, v27
	v_exp_f32_e32 v30, v30
	v_exp_f32_e32 v31, v31
	s_nop 0
	v_pk_add_f32 v[30:31], v[30:31], 1.0 op_sel_hi:[1,0]
	v_rcp_f32_e32 v25, v28
	s_nop 0
	v_mul_f32_e32 v28, v24, v25
	v_rcp_f32_e32 v24, v31
	s_nop 0
	v_mul_f32_e32 v31, v27, v24
	v_rcp_f32_e32 v24, v30
	s_nop 0
	v_mul_f32_e32 v30, v26, v24

; DI float fexp(float x) { return __builtin_amdgcn_exp2f(x * LOG2E); }
; DI float sigmoid_f(float v) { return 1.f / (1.f + fexp(-v)); }
;   DI void operator()(int m, int n, float a, float b, float c, float d, float& ss) const {
;     if (n >= gl_start) {
;       const int j = n - gl_start;
;       if (j < 48) { float* g = gates + (long)m * 48 + j; g[0] = sigmoid_f(a); g[1] = sigmoid_f(b); g[2] = sigmoid_f(c); g[3] = sigmoid_f(d); }
;       return;
.LBB0_314:
	v_cmp_gt_u32_e32 vcc, 48, v56
	s_and_saveexec_b64 s[34:35], vcc
	s_cbranch_execz .LBB0_316
	v_mul_f32_e32 v20, 0xbfb8aa3b, v20
	v_mul_f32_e32 v21, 0xbfb8aa3b, v21
	v_exp_f32_e32 v20, v20
	v_exp_f32_e32 v21, v21
	v_mul_f32_e32 v22, 0xbfb8aa3b, v22
	v_mul_f32_e32 v23, 0xbfb8aa3b, v23
	v_exp_f32_e32 v22, v22
	v_pk_add_f32 v[20:21], v[20:21], 1.0 op_sel_hi:[1,0]
	v_exp_f32_e32 v23, v23
	s_nop 0
	v_pk_add_f32 v[22:23], v[22:23], 1.0 op_sel_hi:[1,0]
	v_lshl_add_u64 v[24:25], s[2:3], 0, v[32:33]
	v_mov_b32_e32 v57, v65
	v_rcp_f32_e32 v26, v21
	s_nop 0
	v_mul_f32_e32 v21, 1.0, v26
	v_lshl_add_u64 v[24:25], v[56:57], 2, v[24:25]
	v_rcp_f32_e32 v26, v20
	s_nop 0
	v_mul_f32_e32 v20, 1.0, v26
	v_rcp_f32_e32 v26, v23
	s_nop 0
	v_mul_f32_e32 v23, 1.0, v26
	v_rcp_f32_e32 v26, v22
	s_nop 0
	v_mul_f32_e32 v22, 1.0, v26
	global_store_dwordx4 v[24:25], v[20:23], off

; DI unsigned pack2(float a, float b) { v2f f = {a, b}; return __builtin_bit_cast(unsigned, __builtin_convertvector(f, v2bf)); }
; DI float fexp(float x) { return __builtin_amdgcn_exp2f(x * LOG2E); }
; DI float silu_f(float v) { return v / (1.f + fexp(-v)); }
;   DI void operator()(int m, int n, float a, float b, float c, float d, float& ss) const {
;     ...
;     if (n < q_end) { a *= qscale; b *= qscale; c *= qscale; d *= qscale; }
;     else if (n >= z_start) { a = silu_f(a); b = silu_f(b); c = silu_f(c); d = silu_f(d); }
;     ss += a * a + b * b + c * c + d * d;
;     u32x2 v; v.x = pack2(a, b); v.y = pack2(c, d);
;     *(u32x2*)(dst + (long)m * ld + n) = v;
.LBB0_317:
	v_cmp_lt_i32_e32 vcc, s39, v70
	s_and_saveexec_b64 s[34:35], vcc
	s_xor_b64 s[34:35], exec, s[34:35]
	s_cbranch_execz .LBB0_319
	v_mul_f32_e32 v24, 0xbfb8aa3b, v20
	v_mul_f32_e32 v25, 0xbfb8aa3b, v21
	v_exp_f32_e32 v24, v24
	v_exp_f32_e32 v25, v25
	s_nop 0
	v_pk_add_f32 v[24:25], v[24:25], 1.0 op_sel_hi:[1,0]
	s_nop 0
	v_rcp_f32_e32 v26, v25
	s_nop 0
	v_mul_f32_e32 v25, v21, v26
	v_mul_f32_e32 v26, 0xbfb8aa3b, v22
	v_mul_f32_e32 v27, 0xbfb8aa3b, v23
	v_exp_f32_e32 v26, v26
	v_exp_f32_e32 v27, v27
	s_nop 0
	v_pk_add_f32 v[26:27], v[26:27], 1.0 op_sel_hi:[1,0]
	v_rcp_f32_e32 v21, v24
	s_nop 0
	v_mul_f32_e32 v24, v20, v21
	v_rcp_f32_e32 v20, v27
	s_nop 0
	v_mul_f32_e32 v27, v23, v20
	v_rcp_f32_e32 v20, v26
	s_nop 0
	v_mul_f32_e32 v26, v22, v20

; DI unsigned pack2(float a, float b) { v2f f = {a, b}; return __builtin_bit_cast(unsigned, __builtin_convertvector(f, v2bf)); }
; DI float fexp(float x) { return __builtin_amdgcn_exp2f(x * LOG2E); }
; DI float silu_f(float v) { return v / (1.f + fexp(-v)); }
;   DI void operator()(int m, int n, float a, float b, float c, float d, float& ss) const {
;     ...
;     if (n < q_end) { a *= qscale; b *= qscale; c *= qscale; d *= qscale; }
;     else if (n >= z_start) { a = silu_f(a); b = silu_f(b); c = silu_f(c); d = silu_f(d); }
;     ss += a * a + b * b + c * c + d * d;
;     u32x2 v; v.x = pack2(a, b); v.y = pack2(c, d);
;     *(u32x2*)(dst + (long)m * ld + n) = v;
.LBB0_322:
	v_cmp_lt_i32_e32 vcc, s39, v58
	s_and_saveexec_b64 s[34:35], vcc
	s_xor_b64 s[34:35], exec, s[34:35]
	s_cbranch_execz .LBB0_324
	v_mul_f32_e32 v20, 0xbfb8aa3b, v16
	v_mul_f32_e32 v21, 0xbfb8aa3b, v17
	v_exp_f32_e32 v20, v20
	v_exp_f32_e32 v21, v21
	s_nop 0
	v_pk_add_f32 v[20:21], v[20:21], 1.0 op_sel_hi:[1,0]
	s_nop 0
	v_rcp_f32_e32 v22, v21
	s_nop 0
	v_mul_f32_e32 v21, v17, v22
	v_mul_f32_e32 v22, 0xbfb8aa3b, v18
	v_mul_f32_e32 v23, 0xbfb8aa3b, v19
	v_exp_f32_e32 v22, v22
	v_exp_f32_e32 v23, v23
	s_nop 0
	v_pk_add_f32 v[22:23], v[22:23], 1.0 op_sel_hi:[1,0]
	v_rcp_f32_e32 v17, v20
	s_nop 0
	v_mul_f32_e32 v20, v16, v17
	v_rcp_f32_e32 v16, v23
	s_nop 0
	v_mul_f32_e32 v23, v19, v16
	v_rcp_f32_e32 v16, v22
	s_nop 0
	v_mul_f32_e32 v22, v18, v16

; DI float fexp(float x) { return __builtin_amdgcn_exp2f(x * LOG2E); }
; DI float sigmoid_f(float v) { return 1.f / (1.f + fexp(-v)); }
;   DI void operator()(int m, int n, float a, float b, float c, float d, float& ss) const {
;     if (n >= gl_start) {
;       const int j = n - gl_start;
;       if (j < 48) { float* g = gates + (long)m * 48 + j; g[0] = sigmoid_f(a); g[1] = sigmoid_f(b); g[2] = sigmoid_f(c); g[3] = sigmoid_f(d); }
;       return;
.LBB0_334:
	v_cmp_gt_u32_e32 vcc, 48, v66
	s_and_saveexec_b64 s[4:5], vcc
	s_cbranch_execz .LBB0_336
	v_mul_f32_e32 v12, 0xbfb8aa3b, v12
	v_mul_f32_e32 v13, 0xbfb8aa3b, v13
	v_exp_f32_e32 v12, v12
	v_exp_f32_e32 v13, v13
	v_mul_f32_e32 v14, 0xbfb8aa3b, v14
	v_mul_f32_e32 v15, 0xbfb8aa3b, v15
	v_exp_f32_e32 v14, v14
	v_pk_add_f32 v[12:13], v[12:13], 1.0 op_sel_hi:[1,0]
	v_exp_f32_e32 v15, v15
	s_nop 0
	v_pk_add_f32 v[14:15], v[14:15], 1.0 op_sel_hi:[1,0]
	v_lshl_add_u64 v[18:19], s[2:3], 0, v[16:17]
	v_mov_b32_e32 v67, v65
	v_rcp_f32_e32 v20, v13
	s_nop 0
	v_mul_f32_e32 v13, 1.0, v20
	v_lshl_add_u64 v[18:19], v[66:67], 2, v[18:19]
	v_rcp_f32_e32 v20, v12
	s_nop 0
	v_mul_f32_e32 v12, 1.0, v20
	v_rcp_f32_e32 v20, v15
	s_nop 0
	v_mul_f32_e32 v15, 1.0, v20
	v_rcp_f32_e32 v20, v14
	s_nop 0
	v_mul_f32_e32 v14, 1.0, v20
	global_store_dwordx4 v[18:19], v[12:15], off

; DI unsigned pack2(float a, float b) { v2f f = {a, b}; return __builtin_bit_cast(unsigned, __builtin_convertvector(f, v2bf)); }
; DI float fexp(float x) { return __builtin_amdgcn_exp2f(x * LOG2E); }
; DI float silu_f(float v) { return v / (1.f + fexp(-v)); }
;   DI void operator()(int m, int n, float a, float b, float c, float d, float& ss) const {
;     ...
;     if (n < q_end) { a *= qscale; b *= qscale; c *= qscale; d *= qscale; }
;     else if (n >= z_start) { a = silu_f(a); b = silu_f(b); c = silu_f(c); d = silu_f(d); }
;     ss += a * a + b * b + c * c + d * d;
;     u32x2 v; v.x = pack2(a, b); v.y = pack2(c, d);
;     *(u32x2*)(dst + (long)m * ld + n) = v;
.LBB0_337:
	v_cmp_lt_i32_e32 vcc, s39, v64
	s_and_saveexec_b64 s[4:5], vcc
	s_xor_b64 s[4:5], exec, s[4:5]
	s_cbranch_execz .LBB0_339
	v_mul_f32_e32 v18, 0xbfb8aa3b, v12
	v_mul_f32_e32 v19, 0xbfb8aa3b, v13
	v_exp_f32_e32 v18, v18
	v_exp_f32_e32 v19, v19
	s_nop 0
	v_pk_add_f32 v[18:19], v[18:19], 1.0 op_sel_hi:[1,0]
	s_nop 0
	v_rcp_f32_e32 v20, v19
	s_nop 0
	v_mul_f32_e32 v19, v13, v20
	v_mul_f32_e32 v20, 0xbfb8aa3b, v14
	v_mul_f32_e32 v21, 0xbfb8aa3b, v15
	v_exp_f32_e32 v20, v20
	v_exp_f32_e32 v21, v21
	s_nop 0
	v_pk_add_f32 v[20:21], v[20:21], 1.0 op_sel_hi:[1,0]
	v_rcp_f32_e32 v13, v18
	s_nop 0
	v_mul_f32_e32 v18, v12, v13
	v_rcp_f32_e32 v12, v21
	s_nop 0
	v_mul_f32_e32 v21, v15, v12
	v_rcp_f32_e32 v12, v20
	s_nop 0
	v_mul_f32_e32 v20, v14, v12

; DI float fexp(float x) { return __builtin_amdgcn_exp2f(x * LOG2E); }
; DI float sigmoid_f(float v) { return 1.f / (1.f + fexp(-v)); }
;   DI void operator()(int m, int n, float a, float b, float c, float d, float& ss) const {
;     if (n >= gl_start) {
;       const int j = n - gl_start;
;       if (j < 48) { float* g = gates + (long)m * 48 + j; g[0] = sigmoid_f(a); g[1] = sigmoid_f(b); g[2] = sigmoid_f(c); g[3] = sigmoid_f(d); }
;       return;
.LBB0_342:
	v_cmp_gt_u32_e32 vcc, 48, v60
	s_and_saveexec_b64 s[4:5], vcc
	s_cbranch_execz .LBB0_344
	v_mul_f32_e32 v8, 0xbfb8aa3b, v8
	v_mul_f32_e32 v9, 0xbfb8aa3b, v9
	v_exp_f32_e32 v8, v8
	v_exp_f32_e32 v9, v9
	v_mul_f32_e32 v10, 0xbfb8aa3b, v10
	v_mul_f32_e32 v11, 0xbfb8aa3b, v11
	v_exp_f32_e32 v10, v10
	v_pk_add_f32 v[8:9], v[8:9], 1.0 op_sel_hi:[1,0]
	v_exp_f32_e32 v11, v11
	s_nop 0
	v_pk_add_f32 v[10:11], v[10:11], 1.0 op_sel_hi:[1,0]
	v_lshl_add_u64 v[12:13], s[2:3], 0, v[16:17]
	v_mov_b32_e32 v61, v65
	v_rcp_f32_e32 v14, v9
	s_nop 0
	v_mul_f32_e32 v9, 1.0, v14
	v_lshl_add_u64 v[12:13], v[60:61], 2, v[12:13]
	v_rcp_f32_e32 v14, v8
	s_nop 0
	v_mul_f32_e32 v8, 1.0, v14
	v_rcp_f32_e32 v14, v11
	s_nop 0
	v_mul_f32_e32 v11, 1.0, v14
	v_rcp_f32_e32 v14, v10
	s_nop 0
	v_mul_f32_e32 v10, 1.0, v14
	global_store_dwordx4 v[12:13], v[8:11], off

; DI unsigned pack2(float a, float b) { v2f f = {a, b}; return __builtin_bit_cast(unsigned, __builtin_convertvector(f, v2bf)); }
; DI float fexp(float x) { return __builtin_amdgcn_exp2f(x * LOG2E); }
; DI float silu_f(float v) { return v / (1.f + fexp(-v)); }
;   DI void operator()(int m, int n, float a, float b, float c, float d, float& ss) const {
;     ...
;     if (n < q_end) { a *= qscale; b *= qscale; c *= qscale; d *= qscale; }
;     else if (n >= z_start) { a = silu_f(a); b = silu_f(b); c = silu_f(c); d = silu_f(d); }
;     ss += a * a + b * b + c * c + d * d;
;     u32x2 v; v.x = pack2(a, b); v.y = pack2(c, d);
;     *(u32x2*)(dst + (long)m * ld + n) = v;
.LBB0_345:
	v_cmp_lt_i32_e32 vcc, s39, v72
	s_and_saveexec_b64 s[4:5], vcc
	s_xor_b64 s[4:5], exec, s[4:5]
	s_cbranch_execz .LBB0_347
	v_mul_f32_e32 v12, 0xbfb8aa3b, v8
	v_mul_f32_e32 v13, 0xbfb8aa3b, v9
	v_exp_f32_e32 v12, v12
	v_exp_f32_e32 v13, v13
	s_nop 0
	v_pk_add_f32 v[12:13], v[12:13], 1.0 op_sel_hi:[1,0]
	s_nop 0
	v_rcp_f32_e32 v14, v13
	s_nop 0
	v_mul_f32_e32 v13, v9, v14
	v_mul_f32_e32 v14, 0xbfb8aa3b, v10
	v_mul_f32_e32 v15, 0xbfb8aa3b, v11
	v_exp_f32_e32 v14, v14
	v_exp_f32_e32 v15, v15
	s_nop 0
	v_pk_add_f32 v[14:15], v[14:15], 1.0 op_sel_hi:[1,0]
	v_rcp_f32_e32 v9, v12
	s_nop 0
	v_mul_f32_e32 v12, v8, v9
	v_rcp_f32_e32 v8, v15
	s_nop 0
	v_mul_f32_e32 v15, v11, v8
	v_rcp_f32_e32 v8, v14
	s_nop 0
	v_mul_f32_e32 v14, v10, v8

; DI float fexp(float x) { return __builtin_amdgcn_exp2f(x * LOG2E); }
; DI float sigmoid_f(float v) { return 1.f / (1.f + fexp(-v)); }
;   DI void operator()(int m, int n, float a, float b, float c, float d, float& ss) const {
;     if (n >= gl_start) {
;       const int j = n - gl_start;
;       if (j < 48) { float* g = gates + (long)m * 48 + j; g[0] = sigmoid_f(a); g[1] = sigmoid_f(b); g[2] = sigmoid_f(c); g[3] = sigmoid_f(d); }
;       return;
.LBB0_350:
	v_cmp_gt_u32_e32 vcc, 48, v56
	s_and_saveexec_b64 s[4:5], vcc
	s_cbranch_execz .LBB0_352
	v_mul_f32_e32 v4, 0xbfb8aa3b, v4
	v_mul_f32_e32 v5, 0xbfb8aa3b, v5
	v_exp_f32_e32 v4, v4
	v_exp_f32_e32 v5, v5
	v_mul_f32_e32 v6, 0xbfb8aa3b, v6
	v_mul_f32_e32 v7, 0xbfb8aa3b, v7
	v_exp_f32_e32 v6, v6
	v_pk_add_f32 v[4:5], v[4:5], 1.0 op_sel_hi:[1,0]
	v_exp_f32_e32 v7, v7
	s_nop 0
	v_pk_add_f32 v[6:7], v[6:7], 1.0 op_sel_hi:[1,0]
	v_lshl_add_u64 v[8:9], s[2:3], 0, v[16:17]
	v_mov_b32_e32 v57, v65
	v_rcp_f32_e32 v10, v5
	s_nop 0
	v_mul_f32_e32 v5, 1.0, v10
	v_lshl_add_u64 v[8:9], v[56:57], 2, v[8:9]
	v_rcp_f32_e32 v10, v4
	s_nop 0
	v_mul_f32_e32 v4, 1.0, v10
	v_rcp_f32_e32 v10, v7
	s_nop 0
	v_mul_f32_e32 v7, 1.0, v10
	v_rcp_f32_e32 v10, v6
	s_nop 0
	v_mul_f32_e32 v6, 1.0, v10
	global_store_dwordx4 v[8:9], v[4:7], off

; DI unsigned pack2(float a, float b) { v2f f = {a, b}; return __builtin_bit_cast(unsigned, __builtin_convertvector(f, v2bf)); }
; DI float fexp(float x) { return __builtin_amdgcn_exp2f(x * LOG2E); }
; DI float silu_f(float v) { return v / (1.f + fexp(-v)); }
;   DI void operator()(int m, int n, float a, float b, float c, float d, float& ss) const {
;     ...
;     if (n < q_end) { a *= qscale; b *= qscale; c *= qscale; d *= qscale; }
;     else if (n >= z_start) { a = silu_f(a); b = silu_f(b); c = silu_f(c); d = silu_f(d); }
;     ss += a * a + b * b + c * c + d * d;
;     u32x2 v; v.x = pack2(a, b); v.y = pack2(c, d);
;     *(u32x2*)(dst + (long)m * ld + n) = v;
.LBB0_353:
	v_cmp_lt_i32_e32 vcc, s39, v70
	s_and_saveexec_b64 s[4:5], vcc
	s_xor_b64 s[4:5], exec, s[4:5]
	s_cbranch_execz .LBB0_355
	v_mul_f32_e32 v8, 0xbfb8aa3b, v4
	v_mul_f32_e32 v9, 0xbfb8aa3b, v5
	v_exp_f32_e32 v8, v8
	v_exp_f32_e32 v9, v9
	s_nop 0
	v_pk_add_f32 v[8:9], v[8:9], 1.0 op_sel_hi:[1,0]
	s_nop 0
	v_rcp_f32_e32 v10, v9
	s_nop 0
	v_mul_f32_e32 v9, v5, v10
	v_mul_f32_e32 v10, 0xbfb8aa3b, v6
	v_mul_f32_e32 v11, 0xbfb8aa3b, v7
	v_exp_f32_e32 v10, v10
	v_exp_f32_e32 v11, v11
	s_nop 0
	v_pk_add_f32 v[10:11], v[10:11], 1.0 op_sel_hi:[1,0]
	v_rcp_f32_e32 v5, v8
	s_nop 0
	v_mul_f32_e32 v8, v4, v5
	v_rcp_f32_e32 v4, v11
	s_nop 0
	v_mul_f32_e32 v11, v7, v4
	v_rcp_f32_e32 v4, v10
	s_nop 0
	v_mul_f32_e32 v10, v6, v4

; DI unsigned pack2(float a, float b) { v2f f = {a, b}; return __builtin_bit_cast(unsigned, __builtin_convertvector(f, v2bf)); }
; DI float fexp(float x) { return __builtin_amdgcn_exp2f(x * LOG2E); }
; DI float silu_f(float v) { return v / (1.f + fexp(-v)); }
;   DI void operator()(int m, int n, float a, float b, float c, float d, float& ss) const {
;     ...
;     if (n < q_end) { a *= qscale; b *= qscale; c *= qscale; d *= qscale; }
;     else if (n >= z_start) { a = silu_f(a); b = silu_f(b); c = silu_f(c); d = silu_f(d); }
;     ss += a * a + b * b + c * c + d * d;
;     u32x2 v; v.x = pack2(a, b); v.y = pack2(c, d);
;     *(u32x2*)(dst + (long)m * ld + n) = v;
.LBB0_358:
	v_cmp_lt_i32_e32 vcc, s39, v58
	s_and_saveexec_b64 s[4:5], vcc
	s_xor_b64 s[4:5], exec, s[4:5]
	s_cbranch_execz .LBB0_360
	v_mul_f32_e32 v4, 0xbfb8aa3b, v0
	v_mul_f32_e32 v5, 0xbfb8aa3b, v1
	v_exp_f32_e32 v4, v4
	v_exp_f32_e32 v5, v5
	s_nop 0
	v_pk_add_f32 v[4:5], v[4:5], 1.0 op_sel_hi:[1,0]
	s_nop 0
	v_rcp_f32_e32 v6, v5
	s_nop 0
	v_mul_f32_e32 v5, v1, v6
	v_mul_f32_e32 v6, 0xbfb8aa3b, v2
	v_mul_f32_e32 v7, 0xbfb8aa3b, v3
	v_exp_f32_e32 v6, v6
	v_exp_f32_e32 v7, v7
	s_nop 0
	v_pk_add_f32 v[6:7], v[6:7], 1.0 op_sel_hi:[1,0]
	v_rcp_f32_e32 v1, v4
	s_nop 0
	v_mul_f32_e32 v4, v0, v1
	v_rcp_f32_e32 v0, v7
	s_nop 0
	v_mul_f32_e32 v7, v3, v0
	v_rcp_f32_e32 v0, v6
	s_nop 0
	v_mul_f32_e32 v6, v2, v0

; DI unsigned pack2(float a, float b) { v2f f = {a, b}; return __builtin_bit_cast(unsigned, __builtin_convertvector(f, v2bf)); }
; DI float fexp(float x) { return __builtin_amdgcn_exp2f(x * LOG2E); }
;   DI u32x2 pack(int, int, float a, float b, float c, float d, float&) const { u32x2 v; v.x = pack2(a, b); v.y = pack2(c, d); return v; }
; DI float silu_f(float v) { return v / (1.f + fexp(-v)); }
;   DI u32x2 pack(int m, int n, float a, float b, float c, float d, float& ss) const {
;     if (n < q_end) { a *= qscale; b *= qscale; c *= qscale; d *= qscale; }
;     else if (n >= z_start) { a = silu_f(a); b = silu_f(b); c = silu_f(c); d = silu_f(d); }
;     ss += a * a + b * b + c * c + d * d;
;     u32x2 v; v.x = pack2(a, b); v.y = pack2(c, d);
;     return v;
.LBB0_364:
	s_andn2_saveexec_b64 s[34:35], s[12:13]
	s_cbranch_execz .LBB0_215
	v_cmp_lt_i32_e64 s[4:5], s39, v64
	s_and_saveexec_b64 s[0:1], s[4:5]
	s_xor_b64 s[0:1], exec, s[0:1]
	s_cbranch_execz .LBB0_368
	s_cmpk_lt_u32 s42, 0xa00
	s_cbranch_scc1 .LBB0_368
	v_mul_f32_e32 v67, 0xbfb8aa3b, v60
	v_exp_f32_e32 v68, v67
	v_mul_f32_e32 v67, 0xbfb8aa3b, v61
	v_exp_f32_e32 v69, v67
	s_nop 0
	v_pk_add_f32 v[68:69], v[68:69], 1.0 op_sel_hi:[1,0]
	s_nop 0
	v_rcp_f32_e32 v67, v68
	v_mul_f32_e32 v71, 0xbfb8aa3b, v62
	v_exp_f32_e32 v72, v71
	v_mul_f32_e32 v71, 0xbfb8aa3b, v63
	v_exp_f32_e32 v73, v71
	v_mul_f32_e32 v60, v60, v67
	v_pk_add_f32 v[72:73], v[72:73], 1.0 op_sel_hi:[1,0]
	v_rcp_f32_e32 v67, v69
	s_nop 0
	v_mul_f32_e32 v61, v61, v67
	v_rcp_f32_e32 v67, v72
	s_nop 0
	v_mul_f32_e32 v62, v62, v67
	v_rcp_f32_e32 v67, v73
	s_nop 0
	v_mul_f32_e32 v63, v63, v67
.LBB0_368:
	s_andn2_saveexec_b64 s[0:1], s[0:1]
	v_pk_mul_f32 v[60:61], v[60:61], s[30:31] op_sel_hi:[1,0]
	v_pk_mul_f32 v[62:63], v[62:63], s[30:31] op_sel_hi:[1,0]
	s_or_b64 exec, exec, s[0:1]
	v_or_b32_e32 v67, 16, v64
	v_cmp_lt_i32_e64 s[6:7], s39, v67
	s_and_saveexec_b64 s[0:1], s[6:7]
	s_xor_b64 s[0:1], exec, s[0:1]
	s_cbranch_execz .LBB0_373
	s_cmpk_lt_u32 s42, 0xa00
	s_cbranch_scc1 .LBB0_373
	v_mul_f32_e32 v67, 0xbfb8aa3b, v56
	v_exp_f32_e32 v68, v67
	v_mul_f32_e32 v67, 0xbfb8aa3b, v57
	v_exp_f32_e32 v69, v67
	s_nop 0
	v_pk_add_f32 v[68:69], v[68:69], 1.0 op_sel_hi:[1,0]
	s_nop 0
	v_rcp_f32_e32 v67, v68
	v_mul_f32_e32 v71, 0xbfb8aa3b, v58
	v_exp_f32_e32 v72, v71
	v_mul_f32_e32 v71, 0xbfb8aa3b, v59
	v_exp_f32_e32 v73, v71
	v_mul_f32_e32 v56, v56, v67
	v_pk_add_f32 v[72:73], v[72:73], 1.0 op_sel_hi:[1,0]
	v_rcp_f32_e32 v67, v69
	s_nop 0
	v_mul_f32_e32 v57, v57, v67
	v_rcp_f32_e32 v67, v72
	s_nop 0
	v_mul_f32_e32 v58, v58, v67
	v_rcp_f32_e32 v67, v73
	s_nop 0
	v_mul_f32_e32 v59, v59, v67
.LBB0_373:
	s_andn2_saveexec_b64 s[0:1], s[0:1]
	v_pk_mul_f32 v[56:57], v[56:57], s[30:31] op_sel_hi:[1,0]
	v_pk_mul_f32 v[58:59], v[58:59], s[30:31] op_sel_hi:[1,0]
	s_or_b64 exec, exec, s[0:1]
	v_or_b32_e32 v67, 32, v64
	v_cmp_lt_i32_e64 s[8:9], s39, v67
	s_and_saveexec_b64 s[0:1], s[8:9]
	s_xor_b64 s[0:1], exec, s[0:1]
	s_cbranch_execz .LBB0_378
	s_cmpk_lt_u32 s42, 0xa00
	s_cbranch_scc1 .LBB0_378
	v_mul_f32_e32 v67, 0xbfb8aa3b, v52
	v_exp_f32_e32 v68, v67
	v_mul_f32_e32 v67, 0xbfb8aa3b, v53
	v_exp_f32_e32 v69, v67
	s_nop 0
	v_pk_add_f32 v[68:69], v[68:69], 1.0 op_sel_hi:[1,0]
	s_nop 0
	v_rcp_f32_e32 v67, v68
	v_mul_f32_e32 v71, 0xbfb8aa3b, v54
	v_exp_f32_e32 v72, v71
	v_mul_f32_e32 v71, 0xbfb8aa3b, v55
	v_exp_f32_e32 v73, v71
	v_mul_f32_e32 v52, v52, v67
	v_pk_add_f32 v[72:73], v[72:73], 1.0 op_sel_hi:[1,0]
	v_rcp_f32_e32 v67, v69
	s_nop 0
	v_mul_f32_e32 v53, v53, v67
	v_rcp_f32_e32 v67, v72
	s_nop 0
	v_mul_f32_e32 v54, v54, v67
	v_rcp_f32_e32 v67, v73
	s_nop 0
	v_mul_f32_e32 v55, v55, v67
.LBB0_378:
	s_andn2_saveexec_b64 s[0:1], s[0:1]
	v_pk_mul_f32 v[52:53], v[52:53], s[30:31] op_sel_hi:[1,0]
	v_pk_mul_f32 v[54:55], v[54:55], s[30:31] op_sel_hi:[1,0]
	s_or_b64 exec, exec, s[0:1]
	v_or_b32_e32 v64, 48, v64
	v_cmp_lt_i32_e64 s[10:11], s39, v64
	s_and_saveexec_b64 s[0:1], s[10:11]
	s_xor_b64 s[0:1], exec, s[0:1]
	s_cbranch_execz .LBB0_383
	s_cmpk_lt_u32 s42, 0xa00
	s_cbranch_scc1 .LBB0_383
	v_mul_f32_e32 v64, 0xbfb8aa3b, v48
	v_exp_f32_e32 v68, v64
	v_mul_f32_e32 v64, 0xbfb8aa3b, v49
	v_exp_f32_e32 v69, v64
	s_nop 0
	v_pk_add_f32 v[68:69], v[68:69], 1.0 op_sel_hi:[1,0]
	s_nop 0
	v_rcp_f32_e32 v64, v68
	s_nop 0
	v_mul_f32_e32 v48, v48, v64
	v_mul_f32_e32 v68, 0xbfb8aa3b, v50
	v_exp_f32_e32 v72, v68
	v_mul_f32_e32 v68, 0xbfb8aa3b, v51
	v_exp_f32_e32 v73, v68
	s_nop 0
	v_pk_add_f32 v[72:73], v[72:73], 1.0 op_sel_hi:[1,0]
	v_rcp_f32_e32 v64, v69
	s_nop 0
	v_mul_f32_e32 v49, v49, v64
	v_rcp_f32_e32 v64, v72
	s_nop 0
	v_mul_f32_e32 v50, v50, v64
	v_rcp_f32_e32 v64, v73
	s_nop 0
	v_mul_f32_e32 v51, v51, v64

; DI float silu_f(float v) { return v / (1.f + fexp(-v)); }
;   DI u32x2 pack(int, int, float a, float b, float c, float d, float&) const { u32x2 v; v.x = pack2(a, b); v.y = pack2(c, d); return v; }
; template <class ARow, class Epi>
; DI void gemm_tile(const ARow& arow, long a_kstride, const u16* __restrict__ Bt, long ldb, int K, int m0, int n0,
;                   const Epi& epi, char* smem) {
;     ...
;     for (int mi = 0; mi < 4; ++mi) {
;       const int m = m0 + wm * 64 + mi * 16 + fr;
;       float ss = 0.f;
;       u32x2 pk[4];
; #pragma unroll
;       for (int ni = 0; ni < 4; ++ni) pk[ni] = epi.pack(m, nh + ni * 16 + fq * 4, acc[ni][mi][0], acc[ni][mi][1], acc[ni][mi][2], acc[ni][mi][3], ss);
;       epi.finish16(m, nh, ss);
;       u16* rp = epi.rowp(m) + nh;
; #pragma unroll
;       for (int pp = 0; pp < 2; ++pp) {
;         u32x2 a = pk[2 * pp], b = pk[2 * pp + 1];
;         const u32x2 rx = __builtin_amdgcn_permlane16_swap(a.x, b.x, false, false);
;         const u32x2 ry = __builtin_amdgcn_permlane16_swap(a.y, b.y, false, false);
;         const int nst = (fq & 1) ? ((2 * pp + 1) * 16 + (fq - 1) * 4) : ((2 * pp) * 16 + fq * 4);
;         *(u32x4*)(rp + nst) = (u32x4){rx[0], ry[0], rx[1], ry[1]};
;   DI u32x2 pack(int m, int n, float a, float b, float c, float d, float& ss) const {
;     if (n < q_end) { a *= qscale; b *= qscale; c *= qscale; d *= qscale; }
;     else if (n >= z_start) { a = silu_f(a); b = silu_f(b); c = silu_f(c); d = silu_f(d); }
;     ss += a * a + b * b + c * c + d * d;
.LBB0_389:
	v_cvt_pk_bf16_f32 v77, v54, v55
	v_and_b32_e32 v54, 16, v83
	v_cvt_pk_bf16_f32 v76, v52, v53
	v_mov_b64_e32 v[52:53], s[18:19]
	v_add_u32_e32 v55, 12, v70
	v_cmp_eq_u32_e32 vcc, 0, v54
	s_waitcnt lgkmcnt(0)
	v_ashrrev_i32_e32 v67, 31, v66
	v_mad_i64_i32 v[52:53], s[0:1], v74, s40, v[52:53]
	v_cndmask_b32_e32 v54, v55, v70, vcc
	v_cvt_pk_bf16_f32 v78, v48, v49
	v_cvt_pk_bf16_f32 v79, v50, v51
	v_cvt_pk_bf16_f32 v50, v56, v57
	v_cvt_pk_bf16_f32 v51, v58, v59
	v_cvt_pk_bf16_f32 v48, v60, v61
	v_cvt_pk_bf16_f32 v49, v62, v63
	v_lshl_add_u64 v[52:53], v[66:67], 1, v[52:53]
	v_lshlrev_b32_e32 v64, 1, v54
	v_permlane16_swap_b32_e32 v48, v50
	v_permlane16_swap_b32_e32 v49, v51
	v_lshl_add_u64 v[54:55], v[52:53], 0, v[64:65]
	global_store_dwordx4 v[54:55], v[48:51], off
	v_permlane16_swap_b32_e32 v76, v78
	s_nop 0
	v_add_u32_e32 v48, 44, v70
	v_or_b32_e32 v49, 32, v70
	v_cndmask_b32_e32 v48, v48, v49, vcc
	v_lshlrev_b32_e32 v48, 1, v48
	v_mov_b32_e32 v49, v65
	v_permlane16_swap_b32_e32 v77, v79
	v_lshl_add_u64 v[50:51], v[52:53], 0, v[48:49]
	global_store_dwordx4 v[50:51], v[76:79], off
	s_and_saveexec_b64 s[0:1], s[4:5]
	s_xor_b64 s[0:1], exec, s[0:1]
	s_cbranch_execz .LBB0_392
	s_cmpk_lt_u32 s42, 0xa00
	s_cbranch_scc1 .LBB0_392
	v_mul_f32_e32 v49, 0xbfb8aa3b, v44
	v_exp_f32_e32 v50, v49
	v_mul_f32_e32 v49, 0xbfb8aa3b, v45
	v_exp_f32_e32 v51, v49
	s_nop 0
	v_pk_add_f32 v[50:51], v[50:51], 1.0 op_sel_hi:[1,0]
	s_nop 0
	v_rcp_f32_e32 v49, v50
	v_mul_f32_e32 v52, 0xbfb8aa3b, v46
	v_mul_f32_e32 v53, 0xbfb8aa3b, v47
	v_exp_f32_e32 v52, v52
	v_exp_f32_e32 v53, v53
	v_mul_f32_e32 v44, v44, v49
	v_pk_add_f32 v[52:53], v[52:53], 1.0 op_sel_hi:[1,0]
	v_rcp_f32_e32 v49, v51
	s_nop 0
	v_mul_f32_e32 v45, v45, v49
	v_rcp_f32_e32 v49, v52
	s_nop 0
	v_mul_f32_e32 v46, v46, v49
	v_rcp_f32_e32 v49, v53
	s_nop 0
	v_mul_f32_e32 v47, v47, v49
.LBB0_392:
	s_andn2_saveexec_b64 s[0:1], s[0:1]
	v_pk_mul_f32 v[44:45], v[44:45], s[30:31] op_sel_hi:[1,0]
	v_pk_mul_f32 v[46:47], v[46:47], s[30:31] op_sel_hi:[1,0]
	s_or_b64 exec, exec, s[0:1]
	s_and_saveexec_b64 s[0:1], s[6:7]
	s_xor_b64 s[0:1], exec, s[0:1]
	s_cbranch_execz .LBB0_397
	s_cmpk_lt_u32 s42, 0xa00
	s_cbranch_scc1 .LBB0_397
	v_mul_f32_e32 v49, 0xbfb8aa3b, v40
	v_exp_f32_e32 v50, v49
	v_mul_f32_e32 v49, 0xbfb8aa3b, v41
	v_exp_f32_e32 v51, v49
	s_nop 0
	v_pk_add_f32 v[50:51], v[50:51], 1.0 op_sel_hi:[1,0]
	s_nop 0
	v_rcp_f32_e32 v49, v50
	v_mul_f32_e32 v52, 0xbfb8aa3b, v42
	v_mul_f32_e32 v53, 0xbfb8aa3b, v43
	v_exp_f32_e32 v52, v52
	v_exp_f32_e32 v53, v53
	v_mul_f32_e32 v40, v40, v49
	v_pk_add_f32 v[52:53], v[52:53], 1.0 op_sel_hi:[1,0]
	v_rcp_f32_e32 v49, v51
	s_nop 0
	v_mul_f32_e32 v41, v41, v49
	v_rcp_f32_e32 v49, v52
	s_nop 0
	v_mul_f32_e32 v42, v42, v49
	v_rcp_f32_e32 v49, v53
	s_nop 0
	v_mul_f32_e32 v43, v43, v49
.LBB0_397:
	s_andn2_saveexec_b64 s[0:1], s[0:1]
	v_pk_mul_f32 v[40:41], v[40:41], s[30:31] op_sel_hi:[1,0]
	v_pk_mul_f32 v[42:43], v[42:43], s[30:31] op_sel_hi:[1,0]
	s_or_b64 exec, exec, s[0:1]
	s_and_saveexec_b64 s[0:1], s[8:9]
	s_xor_b64 s[0:1], exec, s[0:1]
	s_cbranch_execz .LBB0_402
	s_cmpk_lt_u32 s42, 0xa00
	s_cbranch_scc1 .LBB0_402
	v_mul_f32_e32 v49, 0xbfb8aa3b, v36
	v_exp_f32_e32 v50, v49
	v_mul_f32_e32 v49, 0xbfb8aa3b, v37
	v_exp_f32_e32 v51, v49
	s_nop 0
	v_pk_add_f32 v[50:51], v[50:51], 1.0 op_sel_hi:[1,0]
	s_nop 0
	v_rcp_f32_e32 v49, v50
	v_mul_f32_e32 v52, 0xbfb8aa3b, v38
	v_mul_f32_e32 v53, 0xbfb8aa3b, v39
	v_exp_f32_e32 v52, v52
	v_exp_f32_e32 v53, v53
	v_mul_f32_e32 v36, v36, v49
	v_pk_add_f32 v[52:53], v[52:53], 1.0 op_sel_hi:[1,0]
	v_rcp_f32_e32 v49, v51
	s_nop 0
	v_mul_f32_e32 v37, v37, v49
	v_rcp_f32_e32 v49, v52
	s_nop 0
	v_mul_f32_e32 v38, v38, v49
	v_rcp_f32_e32 v49, v53
	s_nop 0
	v_mul_f32_e32 v39, v39, v49
.LBB0_402:
	s_andn2_saveexec_b64 s[0:1], s[0:1]
	v_pk_mul_f32 v[36:37], v[36:37], s[30:31] op_sel_hi:[1,0]
	v_pk_mul_f32 v[38:39], v[38:39], s[30:31] op_sel_hi:[1,0]
	s_or_b64 exec, exec, s[0:1]
	s_and_saveexec_b64 s[0:1], s[10:11]
	s_xor_b64 s[0:1], exec, s[0:1]
	s_cbranch_execz .LBB0_407
	s_cmpk_lt_u32 s42, 0xa00
	s_cbranch_scc1 .LBB0_407
	v_mul_f32_e32 v49, 0xbfb8aa3b, v32
	v_exp_f32_e32 v50, v49
	v_mul_f32_e32 v49, 0xbfb8aa3b, v33
	v_exp_f32_e32 v51, v49
	s_nop 0
	v_pk_add_f32 v[50:51], v[50:51], 1.0 op_sel_hi:[1,0]
	s_nop 0
	v_rcp_f32_e32 v49, v50
	v_mul_f32_e32 v52, 0xbfb8aa3b, v34
	v_mul_f32_e32 v53, 0xbfb8aa3b, v35
	v_exp_f32_e32 v52, v52
	v_exp_f32_e32 v53, v53
	v_mul_f32_e32 v32, v32, v49
	v_pk_add_f32 v[52:53], v[52:53], 1.0 op_sel_hi:[1,0]
	v_rcp_f32_e32 v49, v51
	s_nop 0
	v_mul_f32_e32 v33, v33, v49
	v_rcp_f32_e32 v49, v52
	s_nop 0
	v_mul_f32_e32 v34, v34, v49
	v_rcp_f32_e32 v49, v53
	s_nop 0
	v_mul_f32_e32 v35, v35, v49

; DI float silu_f(float v) { return v / (1.f + fexp(-v)); }
;   DI u32x2 pack(int, int, float a, float b, float c, float d, float&) const { u32x2 v; v.x = pack2(a, b); v.y = pack2(c, d); return v; }
; template <class ARow, class Epi>
; DI void gemm_tile(const ARow& arow, long a_kstride, const u16* __restrict__ Bt, long ldb, int K, int m0, int n0,
;                   const Epi& epi, char* smem) {
;     ...
;     for (int mi = 0; mi < 4; ++mi) {
;       const int m = m0 + wm * 64 + mi * 16 + fr;
;       float ss = 0.f;
;       u32x2 pk[4];
; #pragma unroll
;       for (int ni = 0; ni < 4; ++ni) pk[ni] = epi.pack(m, nh + ni * 16 + fq * 4, acc[ni][mi][0], acc[ni][mi][1], acc[ni][mi][2], acc[ni][mi][3], ss);
;       epi.finish16(m, nh, ss);
;       u16* rp = epi.rowp(m) + nh;
; #pragma unroll
;       for (int pp = 0; pp < 2; ++pp) {
;         u32x2 a = pk[2 * pp], b = pk[2 * pp + 1];
;         const u32x2 rx = __builtin_amdgcn_permlane16_swap(a.x, b.x, false, false);
;         const u32x2 ry = __builtin_amdgcn_permlane16_swap(a.y, b.y, false, false);
;         const int nst = (fq & 1) ? ((2 * pp + 1) * 16 + (fq - 1) * 4) : ((2 * pp) * 16 + fq * 4);
;         *(u32x4*)(rp + nst) = (u32x4){rx[0], ry[0], rx[1], ry[1]};
;   DI u32x2 pack(int m, int n, float a, float b, float c, float d, float& ss) const {
;     if (n < q_end) { a *= qscale; b *= qscale; c *= qscale; d *= qscale; }
;     else if (n >= z_start) { a = silu_f(a); b = silu_f(b); c = silu_f(c); d = silu_f(d); }
;     ss += a * a + b * b + c * c + d * d;
.LBB0_413:
	v_or_b32_e32 v49, 16, v74
	s_waitcnt lgkmcnt(0)
	v_cvt_pk_bf16_f32 v50, v36, v37
	v_mov_b64_e32 v[36:37], s[18:19]
	v_mad_i64_i32 v[36:37], s[0:1], v49, s40, v[36:37]
	v_cvt_pk_bf16_f32 v52, v32, v33
	v_cvt_pk_bf16_f32 v53, v34, v35
	v_cvt_pk_bf16_f32 v34, v40, v41
	v_cvt_pk_bf16_f32 v35, v42, v43
	v_cvt_pk_bf16_f32 v32, v44, v45
	v_cvt_pk_bf16_f32 v33, v46, v47
	v_lshl_add_u64 v[36:37], v[66:67], 1, v[36:37]
	v_cvt_pk_bf16_f32 v51, v38, v39
	v_permlane16_swap_b32_e32 v32, v34
	v_permlane16_swap_b32_e32 v33, v35
	v_lshl_add_u64 v[38:39], v[36:37], 0, v[64:65]
	v_mov_b32_e32 v49, v65
	global_store_dwordx4 v[38:39], v[32:35], off
	v_permlane16_swap_b32_e32 v50, v52
	v_permlane16_swap_b32_e32 v51, v53
	v_lshl_add_u64 v[32:33], v[36:37], 0, v[48:49]
	global_store_dwordx4 v[32:33], v[50:53], off
	s_and_saveexec_b64 s[0:1], s[4:5]
	s_xor_b64 s[0:1], exec, s[0:1]
	s_cbranch_execz .LBB0_416
	s_cmpk_lt_u32 s42, 0xa00
	s_cbranch_scc1 .LBB0_416
	v_mul_f32_e32 v32, 0xbfb8aa3b, v28
	v_mul_f32_e32 v33, 0xbfb8aa3b, v29
	v_exp_f32_e32 v32, v32
	v_exp_f32_e32 v33, v33
	s_nop 0
	v_pk_add_f32 v[32:33], v[32:33], 1.0 op_sel_hi:[1,0]
	s_nop 0
	v_rcp_f32_e32 v34, v32
	s_nop 0
	v_mul_f32_e32 v28, v28, v34
	v_mul_f32_e32 v34, 0xbfb8aa3b, v30
	v_mul_f32_e32 v35, 0xbfb8aa3b, v31
	v_exp_f32_e32 v34, v34
	v_exp_f32_e32 v35, v35
	s_nop 0
	v_pk_add_f32 v[34:35], v[34:35], 1.0 op_sel_hi:[1,0]
	v_rcp_f32_e32 v32, v33
	s_nop 0
	v_mul_f32_e32 v29, v29, v32
	v_rcp_f32_e32 v32, v34
	s_nop 0
	v_mul_f32_e32 v30, v30, v32
	v_rcp_f32_e32 v32, v35
	s_nop 0
	v_mul_f32_e32 v31, v31, v32
.LBB0_416:
	s_andn2_saveexec_b64 s[0:1], s[0:1]
	v_pk_mul_f32 v[28:29], v[28:29], s[30:31] op_sel_hi:[1,0]
	v_pk_mul_f32 v[30:31], v[30:31], s[30:31] op_sel_hi:[1,0]
	s_or_b64 exec, exec, s[0:1]
	s_and_saveexec_b64 s[0:1], s[6:7]
	s_xor_b64 s[0:1], exec, s[0:1]
	s_cbranch_execz .LBB0_421
	s_cmpk_lt_u32 s42, 0xa00
	s_cbranch_scc1 .LBB0_421
	v_mul_f32_e32 v32, 0xbfb8aa3b, v24
	v_mul_f32_e32 v33, 0xbfb8aa3b, v25
	v_exp_f32_e32 v32, v32
	v_exp_f32_e32 v33, v33
	s_nop 0
	v_pk_add_f32 v[32:33], v[32:33], 1.0 op_sel_hi:[1,0]
	s_nop 0
	v_rcp_f32_e32 v34, v32
	s_nop 0
	v_mul_f32_e32 v24, v24, v34
	v_mul_f32_e32 v34, 0xbfb8aa3b, v26
	v_mul_f32_e32 v35, 0xbfb8aa3b, v27
	v_exp_f32_e32 v34, v34
	v_exp_f32_e32 v35, v35
	s_nop 0
	v_pk_add_f32 v[34:35], v[34:35], 1.0 op_sel_hi:[1,0]
	v_rcp_f32_e32 v32, v33
	s_nop 0
	v_mul_f32_e32 v25, v25, v32
	v_rcp_f32_e32 v32, v34
	s_nop 0
	v_mul_f32_e32 v26, v26, v32
	v_rcp_f32_e32 v32, v35
	s_nop 0
	v_mul_f32_e32 v27, v27, v32
.LBB0_421:
	s_andn2_saveexec_b64 s[0:1], s[0:1]
	v_pk_mul_f32 v[24:25], v[24:25], s[30:31] op_sel_hi:[1,0]
	v_pk_mul_f32 v[26:27], v[26:27], s[30:31] op_sel_hi:[1,0]
	s_or_b64 exec, exec, s[0:1]
	s_and_saveexec_b64 s[0:1], s[8:9]
	s_xor_b64 s[0:1], exec, s[0:1]
	s_cbranch_execz .LBB0_426
	s_cmpk_lt_u32 s42, 0xa00
	s_cbranch_scc1 .LBB0_426
	v_mul_f32_e32 v32, 0xbfb8aa3b, v20
	v_mul_f32_e32 v33, 0xbfb8aa3b, v21
	v_exp_f32_e32 v32, v32
	v_exp_f32_e32 v33, v33
	s_nop 0
	v_pk_add_f32 v[32:33], v[32:33], 1.0 op_sel_hi:[1,0]
	s_nop 0
	v_rcp_f32_e32 v34, v32
	s_nop 0
	v_mul_f32_e32 v20, v20, v34
	v_mul_f32_e32 v34, 0xbfb8aa3b, v22
	v_mul_f32_e32 v35, 0xbfb8aa3b, v23
	v_exp_f32_e32 v34, v34
	v_exp_f32_e32 v35, v35
	s_nop 0
	v_pk_add_f32 v[34:35], v[34:35], 1.0 op_sel_hi:[1,0]
	v_rcp_f32_e32 v32, v33
	s_nop 0
	v_mul_f32_e32 v21, v21, v32
	v_rcp_f32_e32 v32, v34
	s_nop 0
	v_mul_f32_e32 v22, v22, v32
	v_rcp_f32_e32 v32, v35
	s_nop 0
	v_mul_f32_e32 v23, v23, v32
.LBB0_426:
	s_andn2_saveexec_b64 s[0:1], s[0:1]
	v_pk_mul_f32 v[20:21], v[20:21], s[30:31] op_sel_hi:[1,0]
	v_pk_mul_f32 v[22:23], v[22:23], s[30:31] op_sel_hi:[1,0]
	s_or_b64 exec, exec, s[0:1]
	s_and_saveexec_b64 s[0:1], s[10:11]
	s_xor_b64 s[0:1], exec, s[0:1]
	s_cbranch_execz .LBB0_431
	s_cmpk_lt_u32 s42, 0xa00
	s_cbranch_scc1 .LBB0_431
	v_mul_f32_e32 v32, 0xbfb8aa3b, v16
	v_mul_f32_e32 v33, 0xbfb8aa3b, v17
	v_exp_f32_e32 v32, v32
	v_exp_f32_e32 v33, v33
	s_nop 0
	v_pk_add_f32 v[32:33], v[32:33], 1.0 op_sel_hi:[1,0]
	s_nop 0
	v_rcp_f32_e32 v34, v32
	s_nop 0
	v_mul_f32_e32 v16, v16, v34
	v_mul_f32_e32 v34, 0xbfb8aa3b, v18
	v_mul_f32_e32 v35, 0xbfb8aa3b, v19
	v_exp_f32_e32 v34, v34
	v_exp_f32_e32 v35, v35
	s_nop 0
	v_pk_add_f32 v[34:35], v[34:35], 1.0 op_sel_hi:[1,0]
	v_rcp_f32_e32 v32, v33
	s_nop 0
	v_mul_f32_e32 v17, v17, v32
	v_rcp_f32_e32 v32, v34
	s_nop 0
	v_mul_f32_e32 v18, v18, v32
	v_rcp_f32_e32 v32, v35
	s_nop 0
	v_mul_f32_e32 v19, v19, v32

; DI float silu_f(float v) { return v / (1.f + fexp(-v)); }
;   DI u32x2 pack(int, int, float a, float b, float c, float d, float&) const { u32x2 v; v.x = pack2(a, b); v.y = pack2(c, d); return v; }
; template <class ARow, class Epi>
; DI void gemm_tile(const ARow& arow, long a_kstride, const u16* __restrict__ Bt, long ldb, int K, int m0, int n0,
;                   const Epi& epi, char* smem) {
;     ...
;     for (int mi = 0; mi < 4; ++mi) {
;       const int m = m0 + wm * 64 + mi * 16 + fr;
;       float ss = 0.f;
;       u32x2 pk[4];
; #pragma unroll
;       for (int ni = 0; ni < 4; ++ni) pk[ni] = epi.pack(m, nh + ni * 16 + fq * 4, acc[ni][mi][0], acc[ni][mi][1], acc[ni][mi][2], acc[ni][mi][3], ss);
;       epi.finish16(m, nh, ss);
;       u16* rp = epi.rowp(m) + nh;
; #pragma unroll
;       for (int pp = 0; pp < 2; ++pp) {
;         u32x2 a = pk[2 * pp], b = pk[2 * pp + 1];
;         const u32x2 rx = __builtin_amdgcn_permlane16_swap(a.x, b.x, false, false);
;         const u32x2 ry = __builtin_amdgcn_permlane16_swap(a.y, b.y, false, false);
;         const int nst = (fq & 1) ? ((2 * pp + 1) * 16 + (fq - 1) * 4) : ((2 * pp) * 16 + fq * 4);
;         *(u32x4*)(rp + nst) = (u32x4){rx[0], ry[0], rx[1], ry[1]};
;   DI u32x2 pack(int m, int n, float a, float b, float c, float d, float& ss) const {
;     if (n < q_end) { a *= qscale; b *= qscale; c *= qscale; d *= qscale; }
;     else if (n >= z_start) { a = silu_f(a); b = silu_f(b); c = silu_f(c); d = silu_f(d); }
;     ss += a * a + b * b + c * c + d * d;
.LBB0_437:
	v_or_b32_e32 v36, 32, v74
	v_cvt_pk_bf16_f32 v32, v20, v21
	v_mov_b64_e32 v[20:21], s[18:19]
	v_mad_i64_i32 v[20:21], s[0:1], v36, s40, v[20:21]
	v_cvt_pk_bf16_f32 v34, v16, v17
	v_cvt_pk_bf16_f32 v35, v18, v19
	v_cvt_pk_bf16_f32 v18, v24, v25
	v_cvt_pk_bf16_f32 v19, v26, v27
	v_cvt_pk_bf16_f32 v16, v28, v29
	v_cvt_pk_bf16_f32 v17, v30, v31
	v_lshl_add_u64 v[20:21], v[66:67], 1, v[20:21]
	s_waitcnt lgkmcnt(0)
	v_cvt_pk_bf16_f32 v33, v22, v23
	v_permlane16_swap_b32_e32 v16, v18
	v_permlane16_swap_b32_e32 v17, v19
	v_lshl_add_u64 v[22:23], v[20:21], 0, v[64:65]
	v_mov_b32_e32 v49, v65
	global_store_dwordx4 v[22:23], v[16:19], off
	v_permlane16_swap_b32_e32 v32, v34
	v_permlane16_swap_b32_e32 v33, v35
	v_lshl_add_u64 v[16:17], v[20:21], 0, v[48:49]
	global_store_dwordx4 v[16:17], v[32:35], off
	s_and_saveexec_b64 s[0:1], s[4:5]
	s_xor_b64 s[0:1], exec, s[0:1]
	s_cbranch_execz .LBB0_440
	s_cmpk_lt_u32 s42, 0xa00
	s_cbranch_scc1 .LBB0_440
	v_mul_f32_e32 v16, 0xbfb8aa3b, v12
	v_mul_f32_e32 v17, 0xbfb8aa3b, v13
	v_exp_f32_e32 v16, v16
	v_exp_f32_e32 v17, v17
	s_nop 0
	v_pk_add_f32 v[16:17], v[16:17], 1.0 op_sel_hi:[1,0]
	s_nop 0
	v_rcp_f32_e32 v18, v16
	s_nop 0
	v_mul_f32_e32 v12, v12, v18
	v_mul_f32_e32 v18, 0xbfb8aa3b, v14
	v_mul_f32_e32 v19, 0xbfb8aa3b, v15
	v_exp_f32_e32 v18, v18
	v_exp_f32_e32 v19, v19
	s_nop 0
	v_pk_add_f32 v[18:19], v[18:19], 1.0 op_sel_hi:[1,0]
	v_rcp_f32_e32 v16, v17
	s_nop 0
	v_mul_f32_e32 v13, v13, v16
	v_rcp_f32_e32 v16, v18
	s_nop 0
	v_mul_f32_e32 v14, v14, v16
	v_rcp_f32_e32 v16, v19
	s_nop 0
	v_mul_f32_e32 v15, v15, v16
.LBB0_440:
	s_andn2_saveexec_b64 s[0:1], s[0:1]
	v_pk_mul_f32 v[12:13], v[12:13], s[30:31] op_sel_hi:[1,0]
	v_pk_mul_f32 v[14:15], v[14:15], s[30:31] op_sel_hi:[1,0]
	s_or_b64 exec, exec, s[0:1]
	s_and_saveexec_b64 s[0:1], s[6:7]
	s_xor_b64 s[0:1], exec, s[0:1]
	s_cbranch_execz .LBB0_445
	s_cmpk_lt_u32 s42, 0xa00
	s_cbranch_scc1 .LBB0_445
	v_mul_f32_e32 v16, 0xbfb8aa3b, v8
	v_mul_f32_e32 v17, 0xbfb8aa3b, v9
	v_exp_f32_e32 v16, v16
	v_exp_f32_e32 v17, v17
	s_nop 0
	v_pk_add_f32 v[16:17], v[16:17], 1.0 op_sel_hi:[1,0]
	s_nop 0
	v_rcp_f32_e32 v18, v16
	s_nop 0
	v_mul_f32_e32 v8, v8, v18
	v_mul_f32_e32 v18, 0xbfb8aa3b, v10
	v_mul_f32_e32 v19, 0xbfb8aa3b, v11
	v_exp_f32_e32 v18, v18
	v_exp_f32_e32 v19, v19
	s_nop 0
	v_pk_add_f32 v[18:19], v[18:19], 1.0 op_sel_hi:[1,0]
	v_rcp_f32_e32 v16, v17
	s_nop 0
	v_mul_f32_e32 v9, v9, v16
	v_rcp_f32_e32 v16, v18
	s_nop 0
	v_mul_f32_e32 v10, v10, v16
	v_rcp_f32_e32 v16, v19
	s_nop 0
	v_mul_f32_e32 v11, v11, v16
.LBB0_445:
	s_andn2_saveexec_b64 s[0:1], s[0:1]
	v_pk_mul_f32 v[8:9], v[8:9], s[30:31] op_sel_hi:[1,0]
	v_pk_mul_f32 v[10:11], v[10:11], s[30:31] op_sel_hi:[1,0]
	s_or_b64 exec, exec, s[0:1]
	s_and_saveexec_b64 s[0:1], s[8:9]
	s_xor_b64 s[0:1], exec, s[0:1]
	s_cbranch_execz .LBB0_450
	s_cmpk_lt_u32 s42, 0xa00
	s_cbranch_scc1 .LBB0_450
	v_mul_f32_e32 v16, 0xbfb8aa3b, v4
	v_mul_f32_e32 v17, 0xbfb8aa3b, v5
	v_exp_f32_e32 v16, v16
	v_exp_f32_e32 v17, v17
	s_nop 0
	v_pk_add_f32 v[16:17], v[16:17], 1.0 op_sel_hi:[1,0]
	s_nop 0
	v_rcp_f32_e32 v18, v16
	s_nop 0
	v_mul_f32_e32 v4, v4, v18
	v_mul_f32_e32 v18, 0xbfb8aa3b, v6
	v_mul_f32_e32 v19, 0xbfb8aa3b, v7
	v_exp_f32_e32 v18, v18
	v_exp_f32_e32 v19, v19
	s_nop 0
	v_pk_add_f32 v[18:19], v[18:19], 1.0 op_sel_hi:[1,0]
	v_rcp_f32_e32 v16, v17
	s_nop 0
	v_mul_f32_e32 v5, v5, v16
	v_rcp_f32_e32 v16, v18
	s_nop 0
	v_mul_f32_e32 v6, v6, v16
	v_rcp_f32_e32 v16, v19
	s_nop 0
	v_mul_f32_e32 v7, v7, v16
.LBB0_450:
	s_andn2_saveexec_b64 s[0:1], s[0:1]
	v_pk_mul_f32 v[4:5], v[4:5], s[30:31] op_sel_hi:[1,0]
	v_pk_mul_f32 v[6:7], v[6:7], s[30:31] op_sel_hi:[1,0]
	s_or_b64 exec, exec, s[0:1]
	s_and_saveexec_b64 s[0:1], s[10:11]
	s_xor_b64 s[0:1], exec, s[0:1]
	s_cbranch_execz .LBB0_455
	s_cmpk_lt_u32 s42, 0xa00
	s_cbranch_scc1 .LBB0_455
	v_mul_f32_e32 v16, 0xbfb8aa3b, v0
	v_mul_f32_e32 v17, 0xbfb8aa3b, v1
	v_exp_f32_e32 v16, v16
	v_exp_f32_e32 v17, v17
	s_nop 0
	v_pk_add_f32 v[16:17], v[16:17], 1.0 op_sel_hi:[1,0]
	s_nop 0
	v_rcp_f32_e32 v18, v16
	s_nop 0
	v_mul_f32_e32 v0, v0, v18
	v_mul_f32_e32 v18, 0xbfb8aa3b, v2
	v_mul_f32_e32 v19, 0xbfb8aa3b, v3
	v_exp_f32_e32 v18, v18
	v_exp_f32_e32 v19, v19
	s_nop 0
	v_pk_add_f32 v[18:19], v[18:19], 1.0 op_sel_hi:[1,0]
	v_rcp_f32_e32 v16, v17
	s_nop 0
	v_mul_f32_e32 v1, v1, v16
	v_rcp_f32_e32 v16, v18
	s_nop 0
	v_mul_f32_e32 v2, v2, v16
	v_rcp_f32_e32 v16, v19
	s_nop 0
	v_mul_f32_e32 v3, v3, v16

; template <class ARow, class Epi>
; DI void gemm_tile(const ARow& arow, long a_kstride, const u16* __restrict__ Bt, long ldb, int K, int m0, int n0,
;                   const Epi& epi, char* smem) {
;     ...
;   for (int kt = 0; kt < KT; ++kt) {
;     const int cur = kt & 1;
;     if (kt + 1 < KT) GEMM_STAGE(cur ^ 1, kt + 1);
;     const char* sa = smem + cur * 32768 + wm * 64 * 128;
;     const char* sb = smem + cur * 32768 + 16384 + wn * 64 * 128;
; #pragma unroll
;     for (int ks = 0; ks < 2; ++ks) {
;       bf16x8 wf[4], af[4];
; #pragma unroll
;       for (int j = 0; j < 4; ++j) {
;         wf[j] = *(const bf16x8*)(sb + j * 2048 + foff[ks]);
;         af[j] = *(const bf16x8*)(sa + j * 2048 + foff[ks]);
;       }
; #pragma unroll
;       for (int ni = 0; ni < 4; ++ni)
; #pragma unroll
;         for (int mi = 0; mi < 4; ++mi) acc[ni][mi] = __builtin_amdgcn_mfma_f32_16x16x32_bf16(wf[ni], af[mi], acc[ni][mi], 0, 0, 0);
;     }
;     asm volatile("s_waitcnt vmcnt(0)" ::: "memory");
;     __syncthreads();
;   }
.LBB0_1173:
	s_and_b32 s6, s1, 0x8000
	s_xor_b32 s7, s6, 0x8000
	v_add_u32_e32 v108, s7, v91
	v_add_u32_e32 v116, s6, v89
	v_or_b32_e32 v117, s6, v90
	v_readfirstlane_b32 s6, v108
	v_add_u32_e32 v109, 0x4000, v108
	v_lshl_add_u64 v[92:93], v[66:67], 0, s[4:5]
	v_add_u32_e32 v110, 0x400, v108
	v_readfirstlane_b32 s7, v109
	s_mov_b32 m0, s6
	v_lshl_add_u64 v[94:95], v[68:69], 0, s[4:5]
	v_add_u32_e32 v111, 0x4400, v108
	v_readfirstlane_b32 s8, v110
	global_load_lds_dwordx4 v[92:93], off
	s_mov_b32 m0, s7
	v_lshl_add_u64 v[96:97], v[70:71], 0, s[4:5]
	v_add_u32_e32 v113, 0x800, v108
	v_readfirstlane_b32 s9, v111
	global_load_lds_dwordx4 v[94:95], off
	s_mov_b32 m0, s8
	v_lshl_add_u64 v[98:99], v[72:73], 0, s[4:5]
	v_add_u32_e32 v114, 0x4800, v108
	v_readfirstlane_b32 s10, v113
	global_load_lds_dwordx4 v[96:97], off
	s_mov_b32 m0, s9
	v_lshl_add_u64 v[100:101], v[74:75], 0, s[4:5]
	v_add_u32_e32 v115, 0xc00, v108
	v_readfirstlane_b32 s11, v114
	global_load_lds_dwordx4 v[98:99], off
	s_mov_b32 m0, s10
	v_lshl_add_u64 v[102:103], v[76:77], 0, s[4:5]
	v_add_u32_e32 v108, 0x4c00, v108
	v_readfirstlane_b32 s12, v115
	global_load_lds_dwordx4 v[100:101], off
	s_mov_b32 m0, s11
	v_lshl_add_u64 v[104:105], v[78:79], 0, s[4:5]
	v_readfirstlane_b32 s13, v108
	global_load_lds_dwordx4 v[102:103], off
	s_mov_b32 m0, s12
	v_lshl_add_u64 v[106:107], v[80:81], 0, s[4:5]
	global_load_lds_dwordx4 v[104:105], off
	s_mov_b32 m0, s13
	v_add_u32_e32 v118, v117, v88
	global_load_lds_dwordx4 v[106:107], off
	v_add_u32_e32 v112, v116, v88
	ds_read_b128 v[92:95], v118 offset:16384
	ds_read_b128 v[96:99], v112
	ds_read_b128 v[100:103], v118 offset:18432
	ds_read_b128 v[104:107], v112 offset:2048
	ds_read_b128 v[108:111], v112 offset:4096
	ds_read_b128 v[112:115], v112 offset:6144
	s_waitcnt lgkmcnt(0)
	v_mfma_f32_16x16x32_bf16 v[60:63], v[92:95], v[96:99], v[60:63]
	v_add_u32_e32 v117, v117, v87
	v_add_u32_e32 v116, v116, v87
	s_add_i32 s1, s1, 0x8000
	v_mfma_f32_16x16x32_bf16 v[56:59], v[92:95], v[104:107], v[56:59]
	s_add_u32 s4, s4, 0x80
	s_addc_u32 s5, s5, 0
	s_cmpk_eq_i32 s4, 0x780
	v_mfma_f32_16x16x32_bf16 v[48:51], v[92:95], v[108:111], v[48:51]
	v_mfma_f32_16x16x32_bf16 v[40:43], v[92:95], v[112:115], v[40:43]
	v_mfma_f32_16x16x32_bf16 v[36:39], v[100:103], v[96:99], v[36:39]
	v_mfma_f32_16x16x32_bf16 v[32:35], v[100:103], v[104:107], v[32:35]
	v_mfma_f32_16x16x32_bf16 v[28:31], v[100:103], v[108:111], v[28:31]
	v_mfma_f32_16x16x32_bf16 v[24:27], v[100:103], v[112:115], v[24:27]
	ds_read_b128 v[92:95], v118 offset:20480
	ds_read_b128 v[100:103], v118 offset:22528
	s_waitcnt lgkmcnt(0)
	v_mfma_f32_16x16x32_bf16 v[20:23], v[92:95], v[96:99], v[20:23]
	v_mfma_f32_16x16x32_bf16 v[16:19], v[92:95], v[104:107], v[16:19]
	v_mfma_f32_16x16x32_bf16 v[12:15], v[92:95], v[108:111], v[12:15]
	v_mfma_f32_16x16x32_bf16 v[8:11], v[92:95], v[112:115], v[8:11]
	ds_read_b128 v[92:95], v117 offset:16384
	v_mfma_f32_16x16x32_bf16 v[4:7], v[100:103], v[96:99], v[4:7]
	v_mfma_f32_16x16x32_bf16 v[0:3], v[100:103], v[104:107], v[0:3]
	v_mfma_f32_16x16x32_bf16 v[52:55], v[100:103], v[108:111], v[52:55]
	v_mfma_f32_16x16x32_bf16 v[44:47], v[100:103], v[112:115], v[44:47]
	ds_read_b128 v[96:99], v116
	ds_read_b128 v[100:103], v117 offset:18432
	ds_read_b128 v[104:107], v116 offset:2048
	ds_read_b128 v[108:111], v116 offset:4096
	ds_read_b128 v[112:115], v116 offset:6144
	s_waitcnt lgkmcnt(0)
	v_mfma_f32_16x16x32_bf16 v[60:63], v[92:95], v[96:99], v[60:63]
	v_mfma_f32_16x16x32_bf16 v[56:59], v[92:95], v[104:107], v[56:59]
	v_mfma_f32_16x16x32_bf16 v[48:51], v[92:95], v[108:111], v[48:51]
	v_mfma_f32_16x16x32_bf16 v[40:43], v[92:95], v[112:115], v[40:43]
	v_mfma_f32_16x16x32_bf16 v[36:39], v[100:103], v[96:99], v[36:39]
	v_mfma_f32_16x16x32_bf16 v[32:35], v[100:103], v[104:107], v[32:35]
	v_mfma_f32_16x16x32_bf16 v[28:31], v[100:103], v[108:111], v[28:31]
	v_mfma_f32_16x16x32_bf16 v[24:27], v[100:103], v[112:115], v[24:27]
	ds_read_b128 v[92:95], v117 offset:20480
	ds_read_b128 v[100:103], v117 offset:22528
	s_waitcnt vmcnt(0)
	s_waitcnt vmcnt(0) lgkmcnt(0)
	v_mfma_f32_16x16x32_bf16 v[20:23], v[92:95], v[96:99], v[20:23]
	s_barrier
	v_mfma_f32_16x16x32_bf16 v[16:19], v[92:95], v[104:107], v[16:19]
	v_mfma_f32_16x16x32_bf16 v[12:15], v[92:95], v[108:111], v[12:15]
	v_mfma_f32_16x16x32_bf16 v[8:11], v[92:95], v[112:115], v[8:11]
	v_mfma_f32_16x16x32_bf16 v[4:7], v[100:103], v[96:99], v[4:7]
	v_mfma_f32_16x16x32_bf16 v[0:3], v[100:103], v[104:107], v[0:3]
	v_mfma_f32_16x16x32_bf16 v[52:55], v[100:103], v[108:111], v[52:55]
	v_mfma_f32_16x16x32_bf16 v[44:47], v[100:103], v[112:115], v[44:47]
	s_cbranch_scc0 .LBB0_1173
; DI float sigmoid_f(float v) { return 1.f / (1.f + fexp(-v)); }
;   DI void operator()(int m, int n, float a, float b, float c, float d, float& ss) const { u32x2 v; v.x = pack2(a, b); v.y = pack2(c, d); *(u32x2*)(y + (long)m * 1024 + n) = v; }
; template <class ARow, class Epi>
; DI void gemm_tile(const ARow& arow, long a_kstride, const u16* __restrict__ Bt, long ldb, int K, int m0, int n0,
;                   const Epi& epi, char* smem) {
;     ...
;   for (int kt = 0; kt < KT; ++kt) {
;     const int cur = kt & 1;
;     if (kt + 1 < KT) GEMM_STAGE(cur ^ 1, kt + 1);
;     const char* sa = smem + cur * 32768 + wm * 64 * 128;
;     const char* sb = smem + cur * 32768 + 16384 + wn * 64 * 128;
; #pragma unroll
;     for (int ks = 0; ks < 2; ++ks) {
;       bf16x8 wf[4], af[4];
; #pragma unroll
;       for (int j = 0; j < 4; ++j) {
;         wf[j] = *(const bf16x8*)(sb + j * 2048 + foff[ks]);
;         af[j] = *(const bf16x8*)(sa + j * 2048 + foff[ks]);
;       }
; #pragma unroll
;       for (int ni = 0; ni < 4; ++ni)
; #pragma unroll
;         for (int mi = 0; mi < 4; ++mi) acc[ni][mi] = __builtin_amdgcn_mfma_f32_16x16x32_bf16(wf[ni], af[mi], acc[ni][mi], 0, 0, 0);
;     }
;     asm volatile("s_waitcnt vmcnt(0)" ::: "memory");
;     __syncthreads();
;   }
;     ...
;   const int nh = n0 + wn * 64;
;   if (epi.packed(nh)) {
;   DI void operator()(int m, int n, float a, float b, float c, float d, float& ss) const {
;     if (n >= gl_start) {
;       const int j = n - gl_start;
;       if (j < 48) { float* g = gates + (long)m * 48 + j; g[0] = sigmoid_f(a); g[1] = sigmoid_f(b); g[2] = sigmoid_f(c); g[3] = sigmoid_f(d); }
;       return;
	v_add_u32_e32 v91, v90, v88
	ds_read_b128 v[66:69], v91 offset:49152
	v_add_u32_e32 v88, v89, v88
	ds_read_b128 v[70:73], v88 offset:32768
	ds_read_b128 v[74:77], v88 offset:34816
	ds_read_b128 v[78:81], v88 offset:36864
	ds_read_b128 v[92:95], v88 offset:38912
	v_add_u32_e32 v116, v90, v87
	s_waitcnt lgkmcnt(3)
	v_mfma_f32_16x16x32_bf16 v[60:63], v[66:69], v[70:73], v[60:63]
	s_waitcnt lgkmcnt(2)
	v_mfma_f32_16x16x32_bf16 v[56:59], v[66:69], v[74:77], v[56:59]
	s_waitcnt lgkmcnt(1)
	v_mfma_f32_16x16x32_bf16 v[48:51], v[66:69], v[78:81], v[48:51]
	s_waitcnt lgkmcnt(0)
	v_mfma_f32_16x16x32_bf16 v[40:43], v[66:69], v[92:95], v[40:43]
	ds_read_b128 v[66:69], v91 offset:51200
	s_waitcnt lgkmcnt(0)
	v_mfma_f32_16x16x32_bf16 v[36:39], v[66:69], v[70:73], v[36:39]
	v_mfma_f32_16x16x32_bf16 v[32:35], v[66:69], v[74:77], v[32:35]
	v_mfma_f32_16x16x32_bf16 v[96:99], v[66:69], v[78:81], v[28:31]
	v_mfma_f32_16x16x32_bf16 v[66:69], v[66:69], v[92:95], v[24:27]
	s_nop 2
	ds_read_b128 v[24:27], v91 offset:53248
	s_waitcnt lgkmcnt(0)
	v_mfma_f32_16x16x32_bf16 v[104:107], v[24:27], v[92:95], v[8:11]
	s_nop 2
	ds_read_b128 v[8:11], v91 offset:55296
	v_mfma_f32_16x16x32_bf16 v[20:23], v[24:27], v[70:73], v[20:23]
	s_waitcnt lgkmcnt(0)
	v_mfma_f32_16x16x32_bf16 v[70:73], v[8:11], v[70:73], v[4:7]
	s_nop 2
	ds_read_b128 v[4:7], v116 offset:49152
	v_mfma_f32_16x16x32_bf16 v[100:103], v[24:27], v[78:81], v[12:15]
	s_nop 2
	v_add_u32_e32 v12, v89, v87
	v_mfma_f32_16x16x32_bf16 v[16:19], v[24:27], v[74:77], v[16:19]
	ds_read_b128 v[88:91], v12 offset:32768
	ds_read_b128 v[108:111], v12 offset:36864
	ds_read_b128 v[112:115], v12 offset:38912
	v_mfma_f32_16x16x32_bf16 v[0:3], v[8:11], v[74:77], v[0:3]
	v_mfma_f32_16x16x32_bf16 v[74:77], v[8:11], v[78:81], v[52:55]
	v_mfma_f32_16x16x32_bf16 v[78:81], v[8:11], v[92:95], v[44:47]
	ds_read_b128 v[92:95], v12 offset:34816
	s_waitcnt lgkmcnt(3)
	v_mfma_f32_16x16x32_bf16 v[60:63], v[4:7], v[88:91], v[60:63]
	s_waitcnt lgkmcnt(0)
	v_mfma_f32_16x16x32_bf16 v[44:47], v[4:7], v[92:95], v[56:59]
	v_mfma_f32_16x16x32_bf16 v[28:31], v[4:7], v[108:111], v[48:51]
	v_mfma_f32_16x16x32_bf16 v[12:15], v[4:7], v[112:115], v[40:43]
	ds_read_b128 v[4:7], v116 offset:51200
	s_waitcnt lgkmcnt(0)
	v_mfma_f32_16x16x32_bf16 v[56:59], v[4:7], v[88:91], v[36:39]
	v_mfma_f32_16x16x32_bf16 v[40:43], v[4:7], v[92:95], v[32:35]
	v_mfma_f32_16x16x32_bf16 v[24:27], v[4:7], v[108:111], v[96:99]
	v_mfma_f32_16x16x32_bf16 v[8:11], v[4:7], v[112:115], v[66:69]
	ds_read_b128 v[4:7], v116 offset:53248
	s_nop 0
	ds_read_b128 v[96:99], v116 offset:55296
	s_waitcnt vmcnt(0)
	s_waitcnt lgkmcnt(0)
	v_mfma_f32_16x16x32_bf16 v[32:35], v[96:99], v[92:95], v[0:3]
	s_nop 2
	v_or_b32_e32 v0, s0, v64
	v_lshl_add_u32 v66, v86, 6, v0
	v_lshl_or_b32 v68, v85, 6, s38
	v_mfma_f32_16x16x32_bf16 v[52:55], v[4:7], v[88:91], v[20:23]
	v_cmp_lt_i32_e32 vcc, s33, v68
	s_barrier
	v_mfma_f32_16x16x32_bf16 v[36:39], v[4:7], v[92:95], v[16:19]
	v_mfma_f32_16x16x32_bf16 v[20:23], v[4:7], v[108:111], v[100:103]
	v_mfma_f32_16x16x32_bf16 v[4:7], v[4:7], v[112:115], v[104:107]
	v_mfma_f32_16x16x32_bf16 v[48:51], v[96:99], v[88:91], v[70:73]
	v_mfma_f32_16x16x32_bf16 v[16:19], v[96:99], v[108:111], v[74:77]
	s_nop 1
	v_lshlrev_b32_e32 v72, 2, v84
	v_or_b32_e32 v64, v68, v72
	v_mfma_f32_16x16x32_bf16 v[0:3], v[96:99], v[112:115], v[78:81]
	s_and_saveexec_b64 s[0:1], vcc
	s_xor_b64 s[12:13], exec, s[0:1]
	s_cbranch_execz .LBB0_1320
	v_mad_i64_i32 v[70:71], s[0:1], v66, s36, 0
	v_cmp_lt_i32_e64 s[4:5], s33, v64
	v_add_u32_e32 v68, -2.0, v64
	s_and_saveexec_b64 s[0:1], s[4:5]
	s_xor_b64 s[0:1], exec, s[0:1]
	s_cbranch_execz .LBB0_1179
	v_cmp_gt_u32_e32 vcc, 48, v68
	s_and_saveexec_b64 s[6:7], vcc
	s_cbranch_execz .LBB0_1178
	v_mul_f32_e32 v60, 0xbfb8aa3b, v60
	v_mul_f32_e32 v61, 0xbfb8aa3b, v61
	v_exp_f32_e32 v60, v60
	v_exp_f32_e32 v61, v61
	v_mov_b32_e32 v69, v65
	v_lshl_add_u64 v[72:73], v[68:69], 2, v[70:71]
	v_mul_f32_e32 v62, 0xbfb8aa3b, v62
	v_pk_add_f32 v[60:61], v[60:61], 1.0 op_sel_hi:[1,0]
	v_mul_f32_e32 v63, 0xbfb8aa3b, v63
	v_exp_f32_e32 v62, v62
	v_exp_f32_e32 v63, v63
	v_rcp_f32_e32 v67, v61
	s_nop 0
	v_mul_f32_e32 v61, 1.0, v67
	v_pk_add_f32 v[62:63], v[62:63], 1.0 op_sel_hi:[1,0]
	v_rcp_f32_e32 v67, v60
	s_nop 0
	v_mul_f32_e32 v60, 1.0, v67
	v_rcp_f32_e32 v67, v63
	s_nop 0
	v_mul_f32_e32 v63, 1.0, v67
	v_rcp_f32_e32 v67, v62
	s_nop 0
	v_mul_f32_e32 v62, 1.0, v67
	flat_store_dwordx4 v[72:73], v[60:63]

; DI unsigned pack2(float a, float b) { v2f f = {a, b}; return __builtin_bit_cast(unsigned, __builtin_convertvector(f, v2bf)); }
; DI float fexp(float x) { return __builtin_amdgcn_exp2f(x * LOG2E); }
; DI float silu_f(float v) { return v / (1.f + fexp(-v)); }
;   DI void operator()(int m, int n, float a, float b, float c, float d, float& ss) const {
;     ...
;     if (n < q_end) { a *= qscale; b *= qscale; c *= qscale; d *= qscale; }
;     else if (n >= z_start) { a = silu_f(a); b = silu_f(b); c = silu_f(c); d = silu_f(d); }
;     ss += a * a + b * b + c * c + d * d;
;     u32x2 v; v.x = pack2(a, b); v.y = pack2(c, d);
;     *(u32x2*)(dst + (long)m * ld + n) = v;
.LBB0_1179:
	s_or_saveexec_b64 s[0:1], s[0:1]
	v_ashrrev_i32_e32 v67, 31, v66
	s_xor_b64 exec, exec, s[0:1]
	s_cbranch_execz .LBB0_1185
	v_cmp_lt_i32_e32 vcc, s37, v64
	s_and_saveexec_b64 s[6:7], vcc
	s_xor_b64 s[6:7], exec, s[6:7]
	s_cbranch_execz .LBB0_1182
	v_mul_f32_e32 v69, 0xbfb8aa3b, v60
	v_exp_f32_e32 v72, v69
	v_mul_f32_e32 v69, 0xbfb8aa3b, v61
	v_exp_f32_e32 v73, v69
	s_nop 0
	v_pk_add_f32 v[72:73], v[72:73], 1.0 op_sel_hi:[1,0]
	s_nop 0
	v_rcp_f32_e32 v69, v73
	v_mul_f32_e32 v74, 0xbfb8aa3b, v62
	v_mul_f32_e32 v75, 0xbfb8aa3b, v63
	v_exp_f32_e32 v74, v74
	v_exp_f32_e32 v75, v75
	v_mul_f32_e32 v73, v61, v69
	v_pk_add_f32 v[74:75], v[74:75], 1.0 op_sel_hi:[1,0]
	v_rcp_f32_e32 v61, v72
	s_nop 0
	v_mul_f32_e32 v72, v60, v61
	v_rcp_f32_e32 v60, v75
	s_nop 0
	v_mul_f32_e32 v75, v63, v60
	v_rcp_f32_e32 v60, v74
	s_nop 0
	v_mul_f32_e32 v74, v62, v60

; DI float fexp(float x) { return __builtin_amdgcn_exp2f(x * LOG2E); }
; DI float sigmoid_f(float v) { return 1.f / (1.f + fexp(-v)); }
;   DI void operator()(int m, int n, float a, float b, float c, float d, float& ss) const {
;     if (n >= gl_start) {
;       const int j = n - gl_start;
;       if (j < 48) { float* g = gates + (long)m * 48 + j; g[0] = sigmoid_f(a); g[1] = sigmoid_f(b); g[2] = sigmoid_f(c); g[3] = sigmoid_f(d); }
;       return;
.LBB0_1185:
	s_or_b64 exec, exec, s[0:1]
	v_or_b32_e32 v74, 16, v64
	v_cmp_lt_i32_e64 s[6:7], s33, v74
	v_add_u32_e32 v60, 0xc0000010, v64
	s_and_saveexec_b64 s[0:1], s[6:7]
	s_xor_b64 s[0:1], exec, s[0:1]
	s_cbranch_execz .LBB0_1189
	v_cmp_gt_u32_e32 vcc, 48, v60
	s_and_saveexec_b64 s[8:9], vcc
	s_cbranch_execz .LBB0_1188
	v_mul_f32_e32 v56, 0xbfb8aa3b, v56
	v_mul_f32_e32 v57, 0xbfb8aa3b, v57
	v_exp_f32_e32 v56, v56
	v_exp_f32_e32 v57, v57
	v_mov_b32_e32 v61, v65
	v_lshl_add_u64 v[62:63], v[60:61], 2, v[70:71]
	v_mul_f32_e32 v58, 0xbfb8aa3b, v58
	v_pk_add_f32 v[56:57], v[56:57], 1.0 op_sel_hi:[1,0]
	v_mul_f32_e32 v59, 0xbfb8aa3b, v59
	v_exp_f32_e32 v58, v58
	v_exp_f32_e32 v59, v59
	v_rcp_f32_e32 v61, v57
	s_nop 0
	v_mul_f32_e32 v57, 1.0, v61
	v_pk_add_f32 v[58:59], v[58:59], 1.0 op_sel_hi:[1,0]
	v_rcp_f32_e32 v61, v56
	s_nop 0
	v_mul_f32_e32 v56, 1.0, v61
	v_rcp_f32_e32 v61, v59
	s_nop 0
	v_mul_f32_e32 v59, 1.0, v61
	v_rcp_f32_e32 v61, v58
	s_nop 0
	v_mul_f32_e32 v58, 1.0, v61
	flat_store_dwordx4 v[62:63], v[56:59]

; DI unsigned pack2(float a, float b) { v2f f = {a, b}; return __builtin_bit_cast(unsigned, __builtin_convertvector(f, v2bf)); }
; DI float fexp(float x) { return __builtin_amdgcn_exp2f(x * LOG2E); }
; DI float silu_f(float v) { return v / (1.f + fexp(-v)); }
;   DI void operator()(int m, int n, float a, float b, float c, float d, float& ss) const {
;     ...
;     if (n < q_end) { a *= qscale; b *= qscale; c *= qscale; d *= qscale; }
;     else if (n >= z_start) { a = silu_f(a); b = silu_f(b); c = silu_f(c); d = silu_f(d); }
;     ss += a * a + b * b + c * c + d * d;
;     u32x2 v; v.x = pack2(a, b); v.y = pack2(c, d);
;     *(u32x2*)(dst + (long)m * ld + n) = v;
.LBB0_1189:
	s_andn2_saveexec_b64 s[0:1], s[0:1]
	s_cbranch_execz .LBB0_1195
	v_cmp_lt_i32_e32 vcc, s37, v74
	s_and_saveexec_b64 s[8:9], vcc
	s_xor_b64 s[8:9], exec, s[8:9]
	s_cbranch_execz .LBB0_1192
	v_mul_f32_e32 v61, 0xbfb8aa3b, v56
	v_exp_f32_e32 v62, v61
	v_mul_f32_e32 v61, 0xbfb8aa3b, v57
	v_exp_f32_e32 v63, v61
	s_nop 0
	v_pk_add_f32 v[62:63], v[62:63], 1.0 op_sel_hi:[1,0]
	s_nop 0
	v_rcp_f32_e32 v61, v63
	v_mul_f32_e32 v69, 0xbfb8aa3b, v58
	v_exp_f32_e32 v72, v69
	v_mul_f32_e32 v69, 0xbfb8aa3b, v59
	v_exp_f32_e32 v73, v69
	v_mul_f32_e32 v63, v57, v61
	v_pk_add_f32 v[72:73], v[72:73], 1.0 op_sel_hi:[1,0]
	v_rcp_f32_e32 v57, v62
	s_nop 0
	v_mul_f32_e32 v62, v56, v57
	v_rcp_f32_e32 v56, v73
	s_nop 0
	v_mul_f32_e32 v73, v59, v56
	v_rcp_f32_e32 v56, v72
	s_nop 0
	v_mul_f32_e32 v72, v58, v56

; DI float fexp(float x) { return __builtin_amdgcn_exp2f(x * LOG2E); }
; DI float sigmoid_f(float v) { return 1.f / (1.f + fexp(-v)); }
;   DI void operator()(int m, int n, float a, float b, float c, float d, float& ss) const {
;     if (n >= gl_start) {
;       const int j = n - gl_start;
;       if (j < 48) { float* g = gates + (long)m * 48 + j; g[0] = sigmoid_f(a); g[1] = sigmoid_f(b); g[2] = sigmoid_f(c); g[3] = sigmoid_f(d); }
;       return;
.LBB0_1195:
	s_or_b64 exec, exec, s[0:1]
	v_or_b32_e32 v72, 32, v64
	v_cmp_lt_i32_e64 s[8:9], s33, v72
	v_add_u32_e32 v56, 0xc0000020, v64
	s_and_saveexec_b64 s[0:1], s[8:9]
	s_xor_b64 s[0:1], exec, s[0:1]
	s_cbranch_execz .LBB0_1199
	v_cmp_gt_u32_e32 vcc, 48, v56
	s_and_saveexec_b64 s[10:11], vcc
	s_cbranch_execz .LBB0_1198
	v_mul_f32_e32 v52, 0xbfb8aa3b, v52
	v_mul_f32_e32 v53, 0xbfb8aa3b, v53
	v_exp_f32_e32 v52, v52
	v_exp_f32_e32 v53, v53
	v_mov_b32_e32 v57, v65
	v_lshl_add_u64 v[58:59], v[56:57], 2, v[70:71]
	v_mul_f32_e32 v54, 0xbfb8aa3b, v54
	v_pk_add_f32 v[52:53], v[52:53], 1.0 op_sel_hi:[1,0]
	v_mul_f32_e32 v55, 0xbfb8aa3b, v55
	v_exp_f32_e32 v54, v54
	v_exp_f32_e32 v55, v55
	v_rcp_f32_e32 v57, v53
	s_nop 0
	v_mul_f32_e32 v53, 1.0, v57
	v_pk_add_f32 v[54:55], v[54:55], 1.0 op_sel_hi:[1,0]
	v_rcp_f32_e32 v57, v52
	s_nop 0
	v_mul_f32_e32 v52, 1.0, v57
	v_rcp_f32_e32 v57, v55
	s_nop 0
	v_mul_f32_e32 v55, 1.0, v57
	v_rcp_f32_e32 v57, v54
	s_nop 0
	v_mul_f32_e32 v54, 1.0, v57
	flat_store_dwordx4 v[58:59], v[52:55]

; DI unsigned pack2(float a, float b) { v2f f = {a, b}; return __builtin_bit_cast(unsigned, __builtin_convertvector(f, v2bf)); }
; DI float fexp(float x) { return __builtin_amdgcn_exp2f(x * LOG2E); }
; DI float silu_f(float v) { return v / (1.f + fexp(-v)); }
;   DI void operator()(int m, int n, float a, float b, float c, float d, float& ss) const {
;     ...
;     if (n < q_end) { a *= qscale; b *= qscale; c *= qscale; d *= qscale; }
;     else if (n >= z_start) { a = silu_f(a); b = silu_f(b); c = silu_f(c); d = silu_f(d); }
;     ss += a * a + b * b + c * c + d * d;
;     u32x2 v; v.x = pack2(a, b); v.y = pack2(c, d);
;     *(u32x2*)(dst + (long)m * ld + n) = v;
.LBB0_1199:
	s_andn2_saveexec_b64 s[0:1], s[0:1]
	s_cbranch_execz .LBB0_1205
	v_cmp_lt_i32_e32 vcc, s37, v72
	s_and_saveexec_b64 s[10:11], vcc
	s_xor_b64 s[10:11], exec, s[10:11]
	s_cbranch_execz .LBB0_1202
	v_mul_f32_e32 v57, 0xbfb8aa3b, v52
	v_exp_f32_e32 v58, v57
	v_mul_f32_e32 v57, 0xbfb8aa3b, v53
	v_exp_f32_e32 v59, v57
	s_nop 0
	v_pk_add_f32 v[58:59], v[58:59], 1.0 op_sel_hi:[1,0]
	s_nop 0
	v_rcp_f32_e32 v57, v59
	v_mul_f32_e32 v61, 0xbfb8aa3b, v54
	v_exp_f32_e32 v62, v61
	v_mul_f32_e32 v61, 0xbfb8aa3b, v55
	v_exp_f32_e32 v63, v61
	v_mul_f32_e32 v59, v53, v57
	v_pk_add_f32 v[62:63], v[62:63], 1.0 op_sel_hi:[1,0]
	v_rcp_f32_e32 v53, v58
	s_nop 0
	v_mul_f32_e32 v58, v52, v53
	v_rcp_f32_e32 v52, v63
	s_nop 0
	v_mul_f32_e32 v63, v55, v52
	v_rcp_f32_e32 v52, v62
	s_nop 0
	v_mul_f32_e32 v62, v54, v52

; DI unsigned pack2(float a, float b) { v2f f = {a, b}; return __builtin_bit_cast(unsigned, __builtin_convertvector(f, v2bf)); }
; DI float fexp(float x) { return __builtin_amdgcn_exp2f(x * LOG2E); }
; DI float silu_f(float v) { return v / (1.f + fexp(-v)); }
;   DI void operator()(int m, int n, float a, float b, float c, float d, float& ss) const {
;     ...
;     if (n < q_end) { a *= qscale; b *= qscale; c *= qscale; d *= qscale; }
;     else if (n >= z_start) { a = silu_f(a); b = silu_f(b); c = silu_f(c); d = silu_f(d); }
;     ss += a * a + b * b + c * c + d * d;
;     u32x2 v; v.x = pack2(a, b); v.y = pack2(c, d);
;     *(u32x2*)(dst + (long)m * ld + n) = v;
.LBB0_1205:
	s_or_b64 exec, exec, s[0:1]
	v_or_b32_e32 v58, 48, v64
	v_cmp_gt_i32_e64 s[10:11], 2.0, v58
	s_and_saveexec_b64 s[0:1], s[10:11]
	s_cbranch_execz .LBB0_1211
	v_cmp_lt_i32_e32 vcc, s37, v58
	s_and_saveexec_b64 s[30:31], vcc
	s_xor_b64 s[30:31], exec, s[30:31]
	s_cbranch_execz .LBB0_1208
	v_mul_f32_e32 v52, 0xbfb8aa3b, v48
	v_mul_f32_e32 v53, 0xbfb8aa3b, v49
	v_exp_f32_e32 v52, v52
	v_exp_f32_e32 v53, v53
	s_nop 0
	v_pk_add_f32 v[52:53], v[52:53], 1.0 op_sel_hi:[1,0]
	s_nop 0
	v_rcp_f32_e32 v54, v53
	s_nop 0
	v_mul_f32_e32 v53, v49, v54
	v_mul_f32_e32 v54, 0xbfb8aa3b, v50
	v_mul_f32_e32 v55, 0xbfb8aa3b, v51
	v_exp_f32_e32 v54, v54
	v_exp_f32_e32 v55, v55
	s_nop 0
	v_pk_add_f32 v[54:55], v[54:55], 1.0 op_sel_hi:[1,0]
	v_rcp_f32_e32 v49, v52
	s_nop 0
	v_mul_f32_e32 v52, v48, v49
	v_rcp_f32_e32 v48, v55
	s_nop 0
	v_mul_f32_e32 v55, v51, v48
	v_rcp_f32_e32 v48, v54
	s_nop 0
	v_mul_f32_e32 v54, v50, v48

; DI float fexp(float x) { return __builtin_amdgcn_exp2f(x * LOG2E); }
; DI float sigmoid_f(float v) { return 1.f / (1.f + fexp(-v)); }
;   DI void operator()(int m, int n, float a, float b, float c, float d, float& ss) const {
;     if (n >= gl_start) {
;       const int j = n - gl_start;
;       if (j < 48) { float* g = gates + (long)m * 48 + j; g[0] = sigmoid_f(a); g[1] = sigmoid_f(b); g[2] = sigmoid_f(c); g[3] = sigmoid_f(d); }
;       return;
.LBB0_1218:
	v_cmp_gt_u32_e32 vcc, 48, v68
	s_and_saveexec_b64 s[30:31], vcc
	s_cbranch_execz .LBB0_1220
	v_mul_f32_e32 v44, 0xbfb8aa3b, v44
	v_mul_f32_e32 v45, 0xbfb8aa3b, v45
	v_exp_f32_e32 v44, v44
	v_exp_f32_e32 v45, v45
	v_mul_f32_e32 v46, 0xbfb8aa3b, v46
	v_mul_f32_e32 v47, 0xbfb8aa3b, v47
	v_exp_f32_e32 v46, v46
	v_pk_add_f32 v[44:45], v[44:45], 1.0 op_sel_hi:[1,0]
	v_exp_f32_e32 v47, v47
	s_nop 0
	v_pk_add_f32 v[46:47], v[46:47], 1.0 op_sel_hi:[1,0]
	v_mov_b32_e32 v69, v65
	v_lshl_add_u64 v[52:53], v[68:69], 2, v[50:51]
	v_rcp_f32_e32 v49, v45
	s_nop 0
	v_mul_f32_e32 v45, 1.0, v49
	v_rcp_f32_e32 v49, v44
	s_nop 0
	v_mul_f32_e32 v44, 1.0, v49
	v_rcp_f32_e32 v49, v47
	s_nop 0
	v_mul_f32_e32 v47, 1.0, v49
	v_rcp_f32_e32 v49, v46
	s_nop 0
	v_mul_f32_e32 v46, 1.0, v49
	flat_store_dwordx4 v[52:53], v[44:47]

; DI unsigned pack2(float a, float b) { v2f f = {a, b}; return __builtin_bit_cast(unsigned, __builtin_convertvector(f, v2bf)); }
; DI float fexp(float x) { return __builtin_amdgcn_exp2f(x * LOG2E); }
; DI float silu_f(float v) { return v / (1.f + fexp(-v)); }
;   DI void operator()(int m, int n, float a, float b, float c, float d, float& ss) const {
;     ...
;     if (n < q_end) { a *= qscale; b *= qscale; c *= qscale; d *= qscale; }
;     else if (n >= z_start) { a = silu_f(a); b = silu_f(b); c = silu_f(c); d = silu_f(d); }
;     ss += a * a + b * b + c * c + d * d;
;     u32x2 v; v.x = pack2(a, b); v.y = pack2(c, d);
;     *(u32x2*)(dst + (long)m * ld + n) = v;
.LBB0_1221:
	v_cmp_lt_i32_e32 vcc, s37, v64
	s_and_saveexec_b64 s[30:31], vcc
	s_xor_b64 s[30:31], exec, s[30:31]
	s_cbranch_execz .LBB0_1223
	v_mul_f32_e32 v52, 0xbfb8aa3b, v44
	v_mul_f32_e32 v53, 0xbfb8aa3b, v45
	v_exp_f32_e32 v52, v52
	v_exp_f32_e32 v53, v53
	s_nop 0
	v_pk_add_f32 v[52:53], v[52:53], 1.0 op_sel_hi:[1,0]
	s_nop 0
	v_rcp_f32_e32 v54, v53
	s_nop 0
	v_mul_f32_e32 v53, v45, v54
	v_mul_f32_e32 v54, 0xbfb8aa3b, v46
	v_mul_f32_e32 v55, 0xbfb8aa3b, v47
	v_exp_f32_e32 v54, v54
	v_exp_f32_e32 v55, v55
	s_nop 0
	v_pk_add_f32 v[54:55], v[54:55], 1.0 op_sel_hi:[1,0]
	v_rcp_f32_e32 v45, v52
	s_nop 0
	v_mul_f32_e32 v52, v44, v45
	v_rcp_f32_e32 v44, v55
	s_nop 0
	v_mul_f32_e32 v55, v47, v44
	v_rcp_f32_e32 v44, v54
	s_nop 0
	v_mul_f32_e32 v54, v46, v44

; DI float fexp(float x) { return __builtin_amdgcn_exp2f(x * LOG2E); }
; DI float sigmoid_f(float v) { return 1.f / (1.f + fexp(-v)); }
;   DI void operator()(int m, int n, float a, float b, float c, float d, float& ss) const {
;     if (n >= gl_start) {
;       const int j = n - gl_start;
;       if (j < 48) { float* g = gates + (long)m * 48 + j; g[0] = sigmoid_f(a); g[1] = sigmoid_f(b); g[2] = sigmoid_f(c); g[3] = sigmoid_f(d); }
;       return;
.LBB0_1226:
	v_cmp_gt_u32_e32 vcc, 48, v60
	s_and_saveexec_b64 s[30:31], vcc
	s_cbranch_execz .LBB0_1228
	v_mul_f32_e32 v40, 0xbfb8aa3b, v40
	v_mul_f32_e32 v41, 0xbfb8aa3b, v41
	v_exp_f32_e32 v40, v40
	v_exp_f32_e32 v41, v41
	v_mul_f32_e32 v42, 0xbfb8aa3b, v42
	v_mul_f32_e32 v43, 0xbfb8aa3b, v43
	v_exp_f32_e32 v42, v42
	v_pk_add_f32 v[40:41], v[40:41], 1.0 op_sel_hi:[1,0]
	v_exp_f32_e32 v43, v43
	s_nop 0
	v_pk_add_f32 v[42:43], v[42:43], 1.0 op_sel_hi:[1,0]
	v_mov_b32_e32 v61, v65
	v_lshl_add_u64 v[44:45], v[60:61], 2, v[50:51]
	v_rcp_f32_e32 v46, v41
	s_nop 0
	v_mul_f32_e32 v41, 1.0, v46
	v_rcp_f32_e32 v46, v40
	s_nop 0
	v_mul_f32_e32 v40, 1.0, v46
	v_rcp_f32_e32 v46, v43
	s_nop 0
	v_mul_f32_e32 v43, 1.0, v46
	v_rcp_f32_e32 v46, v42
	s_nop 0
	v_mul_f32_e32 v42, 1.0, v46
	flat_store_dwordx4 v[44:45], v[40:43]

; DI unsigned pack2(float a, float b) { v2f f = {a, b}; return __builtin_bit_cast(unsigned, __builtin_convertvector(f, v2bf)); }
; DI float fexp(float x) { return __builtin_amdgcn_exp2f(x * LOG2E); }
; DI float silu_f(float v) { return v / (1.f + fexp(-v)); }
;   DI void operator()(int m, int n, float a, float b, float c, float d, float& ss) const {
;     ...
;     if (n < q_end) { a *= qscale; b *= qscale; c *= qscale; d *= qscale; }
;     else if (n >= z_start) { a = silu_f(a); b = silu_f(b); c = silu_f(c); d = silu_f(d); }
;     ss += a * a + b * b + c * c + d * d;
;     u32x2 v; v.x = pack2(a, b); v.y = pack2(c, d);
;     *(u32x2*)(dst + (long)m * ld + n) = v;
.LBB0_1229:
	v_cmp_lt_i32_e32 vcc, s37, v74
	s_and_saveexec_b64 s[30:31], vcc
	s_xor_b64 s[30:31], exec, s[30:31]
	s_cbranch_execz .LBB0_1231
	v_mul_f32_e32 v44, 0xbfb8aa3b, v40
	v_mul_f32_e32 v45, 0xbfb8aa3b, v41
	v_exp_f32_e32 v44, v44
	v_exp_f32_e32 v45, v45
	s_nop 0
	v_pk_add_f32 v[44:45], v[44:45], 1.0 op_sel_hi:[1,0]
	s_nop 0
	v_rcp_f32_e32 v46, v45
	s_nop 0
	v_mul_f32_e32 v45, v41, v46
	v_mul_f32_e32 v46, 0xbfb8aa3b, v42
	v_mul_f32_e32 v47, 0xbfb8aa3b, v43
	v_exp_f32_e32 v46, v46
	v_exp_f32_e32 v47, v47
	s_nop 0
	v_pk_add_f32 v[46:47], v[46:47], 1.0 op_sel_hi:[1,0]
	v_rcp_f32_e32 v41, v44
	s_nop 0
	v_mul_f32_e32 v44, v40, v41
	v_rcp_f32_e32 v40, v47
	s_nop 0
	v_mul_f32_e32 v47, v43, v40
	v_rcp_f32_e32 v40, v46
	s_nop 0
	v_mul_f32_e32 v46, v42, v40

; DI float fexp(float x) { return __builtin_amdgcn_exp2f(x * LOG2E); }
; DI float sigmoid_f(float v) { return 1.f / (1.f + fexp(-v)); }
;   DI void operator()(int m, int n, float a, float b, float c, float d, float& ss) const {
;     if (n >= gl_start) {
;       const int j = n - gl_start;
;       if (j < 48) { float* g = gates + (long)m * 48 + j; g[0] = sigmoid_f(a); g[1] = sigmoid_f(b); g[2] = sigmoid_f(c); g[3] = sigmoid_f(d); }
;       return;
.LBB0_1234:
	v_cmp_gt_u32_e32 vcc, 48, v56
	s_and_saveexec_b64 s[30:31], vcc
	s_cbranch_execz .LBB0_1236
	v_mul_f32_e32 v36, 0xbfb8aa3b, v36
	v_mul_f32_e32 v37, 0xbfb8aa3b, v37
	v_exp_f32_e32 v36, v36
	v_exp_f32_e32 v37, v37
	v_mul_f32_e32 v38, 0xbfb8aa3b, v38
	v_mul_f32_e32 v39, 0xbfb8aa3b, v39
	v_exp_f32_e32 v38, v38
	v_pk_add_f32 v[36:37], v[36:37], 1.0 op_sel_hi:[1,0]
	v_exp_f32_e32 v39, v39
	s_nop 0
	v_pk_add_f32 v[38:39], v[38:39], 1.0 op_sel_hi:[1,0]
	v_mov_b32_e32 v57, v65
	v_lshl_add_u64 v[40:41], v[56:57], 2, v[50:51]
	v_rcp_f32_e32 v42, v37
	s_nop 0
	v_mul_f32_e32 v37, 1.0, v42
	v_rcp_f32_e32 v42, v36
	s_nop 0
	v_mul_f32_e32 v36, 1.0, v42
	v_rcp_f32_e32 v42, v39
	s_nop 0
	v_mul_f32_e32 v39, 1.0, v42
	v_rcp_f32_e32 v42, v38
	s_nop 0
	v_mul_f32_e32 v38, 1.0, v42
	flat_store_dwordx4 v[40:41], v[36:39]

; DI unsigned pack2(float a, float b) { v2f f = {a, b}; return __builtin_bit_cast(unsigned, __builtin_convertvector(f, v2bf)); }
; DI float fexp(float x) { return __builtin_amdgcn_exp2f(x * LOG2E); }
; DI float silu_f(float v) { return v / (1.f + fexp(-v)); }
;   DI void operator()(int m, int n, float a, float b, float c, float d, float& ss) const {
;     ...
;     if (n < q_end) { a *= qscale; b *= qscale; c *= qscale; d *= qscale; }
;     else if (n >= z_start) { a = silu_f(a); b = silu_f(b); c = silu_f(c); d = silu_f(d); }
;     ss += a * a + b * b + c * c + d * d;
;     u32x2 v; v.x = pack2(a, b); v.y = pack2(c, d);
;     *(u32x2*)(dst + (long)m * ld + n) = v;
.LBB0_1237:
	v_cmp_lt_i32_e32 vcc, s37, v72
	s_and_saveexec_b64 s[30:31], vcc
	s_xor_b64 s[30:31], exec, s[30:31]
	s_cbranch_execz .LBB0_1239
	v_mul_f32_e32 v40, 0xbfb8aa3b, v36
	v_mul_f32_e32 v41, 0xbfb8aa3b, v37
	v_exp_f32_e32 v40, v40
	v_exp_f32_e32 v41, v41
	s_nop 0
	v_pk_add_f32 v[40:41], v[40:41], 1.0 op_sel_hi:[1,0]
	s_nop 0
	v_rcp_f32_e32 v42, v41
	s_nop 0
	v_mul_f32_e32 v41, v37, v42
	v_mul_f32_e32 v42, 0xbfb8aa3b, v38
	v_mul_f32_e32 v43, 0xbfb8aa3b, v39
	v_exp_f32_e32 v42, v42
	v_exp_f32_e32 v43, v43
	s_nop 0
	v_pk_add_f32 v[42:43], v[42:43], 1.0 op_sel_hi:[1,0]
	v_rcp_f32_e32 v37, v40
	s_nop 0
	v_mul_f32_e32 v40, v36, v37
	v_rcp_f32_e32 v36, v43
	s_nop 0
	v_mul_f32_e32 v43, v39, v36
	v_rcp_f32_e32 v36, v42
	s_nop 0
	v_mul_f32_e32 v42, v38, v36

; DI unsigned pack2(float a, float b) { v2f f = {a, b}; return __builtin_bit_cast(unsigned, __builtin_convertvector(f, v2bf)); }
; DI float fexp(float x) { return __builtin_amdgcn_exp2f(x * LOG2E); }
; DI float silu_f(float v) { return v / (1.f + fexp(-v)); }
;   DI void operator()(int m, int n, float a, float b, float c, float d, float& ss) const {
;     ...
;     if (n < q_end) { a *= qscale; b *= qscale; c *= qscale; d *= qscale; }
;     else if (n >= z_start) { a = silu_f(a); b = silu_f(b); c = silu_f(c); d = silu_f(d); }
;     ss += a * a + b * b + c * c + d * d;
;     u32x2 v; v.x = pack2(a, b); v.y = pack2(c, d);
;     *(u32x2*)(dst + (long)m * ld + n) = v;
.LBB0_1242:
	v_cmp_lt_i32_e32 vcc, s37, v58
	s_and_saveexec_b64 s[30:31], vcc
	s_xor_b64 s[30:31], exec, s[30:31]
	s_cbranch_execz .LBB0_1244
	v_mul_f32_e32 v36, 0xbfb8aa3b, v32
	v_mul_f32_e32 v37, 0xbfb8aa3b, v33
	v_exp_f32_e32 v36, v36
	v_exp_f32_e32 v37, v37
	s_nop 0
	v_pk_add_f32 v[36:37], v[36:37], 1.0 op_sel_hi:[1,0]
	s_nop 0
	v_rcp_f32_e32 v38, v37
	s_nop 0
	v_mul_f32_e32 v37, v33, v38
	v_mul_f32_e32 v38, 0xbfb8aa3b, v34
	v_mul_f32_e32 v39, 0xbfb8aa3b, v35
	v_exp_f32_e32 v38, v38
	v_exp_f32_e32 v39, v39
	s_nop 0
	v_pk_add_f32 v[38:39], v[38:39], 1.0 op_sel_hi:[1,0]
	v_rcp_f32_e32 v33, v36
	s_nop 0
	v_mul_f32_e32 v36, v32, v33
	v_rcp_f32_e32 v32, v39
	s_nop 0
	v_mul_f32_e32 v39, v35, v32
	v_rcp_f32_e32 v32, v38
	s_nop 0
	v_mul_f32_e32 v38, v34, v32

; DI float fexp(float x) { return __builtin_amdgcn_exp2f(x * LOG2E); }
; DI float sigmoid_f(float v) { return 1.f / (1.f + fexp(-v)); }
;   DI void operator()(int m, int n, float a, float b, float c, float d, float& ss) const {
;     if (n >= gl_start) {
;       const int j = n - gl_start;
;       if (j < 48) { float* g = gates + (long)m * 48 + j; g[0] = sigmoid_f(a); g[1] = sigmoid_f(b); g[2] = sigmoid_f(c); g[3] = sigmoid_f(d); }
;       return;
.LBB0_1254:
	v_cmp_gt_u32_e32 vcc, 48, v68
	s_and_saveexec_b64 s[30:31], vcc
	s_cbranch_execz .LBB0_1256
	v_mul_f32_e32 v28, 0xbfb8aa3b, v28
	v_mul_f32_e32 v29, 0xbfb8aa3b, v29
	v_exp_f32_e32 v28, v28
	v_exp_f32_e32 v29, v29
	v_mul_f32_e32 v30, 0xbfb8aa3b, v30
	v_mul_f32_e32 v31, 0xbfb8aa3b, v31
	v_exp_f32_e32 v30, v30
	v_pk_add_f32 v[28:29], v[28:29], 1.0 op_sel_hi:[1,0]
	v_exp_f32_e32 v31, v31
	s_nop 0
	v_pk_add_f32 v[30:31], v[30:31], 1.0 op_sel_hi:[1,0]
	v_mov_b32_e32 v69, v65
	v_lshl_add_u64 v[36:37], v[68:69], 2, v[34:35]
	v_rcp_f32_e32 v33, v29
	s_nop 0
	v_mul_f32_e32 v29, 1.0, v33
	v_rcp_f32_e32 v33, v28
	s_nop 0
	v_mul_f32_e32 v28, 1.0, v33
	v_rcp_f32_e32 v33, v31
	s_nop 0
	v_mul_f32_e32 v31, 1.0, v33
	v_rcp_f32_e32 v33, v30
	s_nop 0
	v_mul_f32_e32 v30, 1.0, v33
	flat_store_dwordx4 v[36:37], v[28:31]

; DI unsigned pack2(float a, float b) { v2f f = {a, b}; return __builtin_bit_cast(unsigned, __builtin_convertvector(f, v2bf)); }
; DI float fexp(float x) { return __builtin_amdgcn_exp2f(x * LOG2E); }
; DI float silu_f(float v) { return v / (1.f + fexp(-v)); }
;   DI void operator()(int m, int n, float a, float b, float c, float d, float& ss) const {
;     ...
;     if (n < q_end) { a *= qscale; b *= qscale; c *= qscale; d *= qscale; }
;     else if (n >= z_start) { a = silu_f(a); b = silu_f(b); c = silu_f(c); d = silu_f(d); }
;     ss += a * a + b * b + c * c + d * d;
;     u32x2 v; v.x = pack2(a, b); v.y = pack2(c, d);
;     *(u32x2*)(dst + (long)m * ld + n) = v;
.LBB0_1257:
	v_cmp_lt_i32_e32 vcc, s37, v64
	s_and_saveexec_b64 s[30:31], vcc
	s_xor_b64 s[30:31], exec, s[30:31]
	s_cbranch_execz .LBB0_1259
	v_mul_f32_e32 v36, 0xbfb8aa3b, v28
	v_mul_f32_e32 v37, 0xbfb8aa3b, v29
	v_exp_f32_e32 v36, v36
	v_exp_f32_e32 v37, v37
	s_nop 0
	v_pk_add_f32 v[36:37], v[36:37], 1.0 op_sel_hi:[1,0]
	s_nop 0
	v_rcp_f32_e32 v38, v37
	s_nop 0
	v_mul_f32_e32 v37, v29, v38
	v_mul_f32_e32 v38, 0xbfb8aa3b, v30
	v_mul_f32_e32 v39, 0xbfb8aa3b, v31
	v_exp_f32_e32 v38, v38
	v_exp_f32_e32 v39, v39
	s_nop 0
	v_pk_add_f32 v[38:39], v[38:39], 1.0 op_sel_hi:[1,0]
	v_rcp_f32_e32 v29, v36
	s_nop 0
	v_mul_f32_e32 v36, v28, v29
	v_rcp_f32_e32 v28, v39
	s_nop 0
	v_mul_f32_e32 v39, v31, v28
	v_rcp_f32_e32 v28, v38
	s_nop 0
	v_mul_f32_e32 v38, v30, v28

; DI float fexp(float x) { return __builtin_amdgcn_exp2f(x * LOG2E); }
; DI float sigmoid_f(float v) { return 1.f / (1.f + fexp(-v)); }
;   DI void operator()(int m, int n, float a, float b, float c, float d, float& ss) const {
;     if (n >= gl_start) {
;       const int j = n - gl_start;
;       if (j < 48) { float* g = gates + (long)m * 48 + j; g[0] = sigmoid_f(a); g[1] = sigmoid_f(b); g[2] = sigmoid_f(c); g[3] = sigmoid_f(d); }
;       return;
.LBB0_1262:
	v_cmp_gt_u32_e32 vcc, 48, v60
	s_and_saveexec_b64 s[30:31], vcc
	s_cbranch_execz .LBB0_1264
	v_mul_f32_e32 v24, 0xbfb8aa3b, v24
	v_mul_f32_e32 v25, 0xbfb8aa3b, v25
	v_exp_f32_e32 v24, v24
	v_exp_f32_e32 v25, v25
	v_mul_f32_e32 v26, 0xbfb8aa3b, v26
	v_mul_f32_e32 v27, 0xbfb8aa3b, v27
	v_exp_f32_e32 v26, v26
	v_pk_add_f32 v[24:25], v[24:25], 1.0 op_sel_hi:[1,0]
	v_exp_f32_e32 v27, v27
	s_nop 0
	v_pk_add_f32 v[26:27], v[26:27], 1.0 op_sel_hi:[1,0]
	v_mov_b32_e32 v61, v65
	v_lshl_add_u64 v[28:29], v[60:61], 2, v[34:35]
	v_rcp_f32_e32 v30, v25
	s_nop 0
	v_mul_f32_e32 v25, 1.0, v30
	v_rcp_f32_e32 v30, v24
	s_nop 0
	v_mul_f32_e32 v24, 1.0, v30
	v_rcp_f32_e32 v30, v27
	s_nop 0
	v_mul_f32_e32 v27, 1.0, v30
	v_rcp_f32_e32 v30, v26
	s_nop 0
	v_mul_f32_e32 v26, 1.0, v30
	flat_store_dwordx4 v[28:29], v[24:27]

; DI unsigned pack2(float a, float b) { v2f f = {a, b}; return __builtin_bit_cast(unsigned, __builtin_convertvector(f, v2bf)); }
; DI float fexp(float x) { return __builtin_amdgcn_exp2f(x * LOG2E); }
; DI float silu_f(float v) { return v / (1.f + fexp(-v)); }
;   DI void operator()(int m, int n, float a, float b, float c, float d, float& ss) const {
;     ...
;     if (n < q_end) { a *= qscale; b *= qscale; c *= qscale; d *= qscale; }
;     else if (n >= z_start) { a = silu_f(a); b = silu_f(b); c = silu_f(c); d = silu_f(d); }
;     ss += a * a + b * b + c * c + d * d;
;     u32x2 v; v.x = pack2(a, b); v.y = pack2(c, d);
;     *(u32x2*)(dst + (long)m * ld + n) = v;
.LBB0_1265:
	v_cmp_lt_i32_e32 vcc, s37, v74
	s_and_saveexec_b64 s[30:31], vcc
	s_xor_b64 s[30:31], exec, s[30:31]
	s_cbranch_execz .LBB0_1267
	v_mul_f32_e32 v28, 0xbfb8aa3b, v24
	v_mul_f32_e32 v29, 0xbfb8aa3b, v25
	v_exp_f32_e32 v28, v28
	v_exp_f32_e32 v29, v29
	s_nop 0
	v_pk_add_f32 v[28:29], v[28:29], 1.0 op_sel_hi:[1,0]
	s_nop 0
	v_rcp_f32_e32 v30, v29
	s_nop 0
	v_mul_f32_e32 v29, v25, v30
	v_mul_f32_e32 v30, 0xbfb8aa3b, v26
	v_mul_f32_e32 v31, 0xbfb8aa3b, v27
	v_exp_f32_e32 v30, v30
	v_exp_f32_e32 v31, v31
	s_nop 0
	v_pk_add_f32 v[30:31], v[30:31], 1.0 op_sel_hi:[1,0]
	v_rcp_f32_e32 v25, v28
	s_nop 0
	v_mul_f32_e32 v28, v24, v25
	v_rcp_f32_e32 v24, v31
	s_nop 0
	v_mul_f32_e32 v31, v27, v24
	v_rcp_f32_e32 v24, v30
	s_nop 0
	v_mul_f32_e32 v30, v26, v24

; DI float fexp(float x) { return __builtin_amdgcn_exp2f(x * LOG2E); }
; DI float sigmoid_f(float v) { return 1.f / (1.f + fexp(-v)); }
;   DI void operator()(int m, int n, float a, float b, float c, float d, float& ss) const {
;     if (n >= gl_start) {
;       const int j = n - gl_start;
;       if (j < 48) { float* g = gates + (long)m * 48 + j; g[0] = sigmoid_f(a); g[1] = sigmoid_f(b); g[2] = sigmoid_f(c); g[3] = sigmoid_f(d); }
;       return;
.LBB0_1270:
	v_cmp_gt_u32_e32 vcc, 48, v56
	s_and_saveexec_b64 s[30:31], vcc
	s_cbranch_execz .LBB0_1272
	v_mul_f32_e32 v20, 0xbfb8aa3b, v20
	v_mul_f32_e32 v21, 0xbfb8aa3b, v21
	v_exp_f32_e32 v20, v20
	v_exp_f32_e32 v21, v21
	v_mul_f32_e32 v22, 0xbfb8aa3b, v22
	v_mul_f32_e32 v23, 0xbfb8aa3b, v23
	v_exp_f32_e32 v22, v22
	v_pk_add_f32 v[20:21], v[20:21], 1.0 op_sel_hi:[1,0]
	v_exp_f32_e32 v23, v23
	s_nop 0
	v_pk_add_f32 v[22:23], v[22:23], 1.0 op_sel_hi:[1,0]
	v_mov_b32_e32 v57, v65
	v_lshl_add_u64 v[24:25], v[56:57], 2, v[34:35]
	v_rcp_f32_e32 v26, v21
	s_nop 0
	v_mul_f32_e32 v21, 1.0, v26
	v_rcp_f32_e32 v26, v20
	s_nop 0
	v_mul_f32_e32 v20, 1.0, v26
	v_rcp_f32_e32 v26, v23
	s_nop 0
	v_mul_f32_e32 v23, 1.0, v26
	v_rcp_f32_e32 v26, v22
	s_nop 0
	v_mul_f32_e32 v22, 1.0, v26
	flat_store_dwordx4 v[24:25], v[20:23]

; DI unsigned pack2(float a, float b) { v2f f = {a, b}; return __builtin_bit_cast(unsigned, __builtin_convertvector(f, v2bf)); }
; DI float fexp(float x) { return __builtin_amdgcn_exp2f(x * LOG2E); }
; DI float silu_f(float v) { return v / (1.f + fexp(-v)); }
;   DI void operator()(int m, int n, float a, float b, float c, float d, float& ss) const {
;     ...
;     if (n < q_end) { a *= qscale; b *= qscale; c *= qscale; d *= qscale; }
;     else if (n >= z_start) { a = silu_f(a); b = silu_f(b); c = silu_f(c); d = silu_f(d); }
;     ss += a * a + b * b + c * c + d * d;
;     u32x2 v; v.x = pack2(a, b); v.y = pack2(c, d);
;     *(u32x2*)(dst + (long)m * ld + n) = v;
.LBB0_1273:
	v_cmp_lt_i32_e32 vcc, s37, v72
	s_and_saveexec_b64 s[30:31], vcc
	s_xor_b64 s[30:31], exec, s[30:31]
	s_cbranch_execz .LBB0_1275
	v_mul_f32_e32 v24, 0xbfb8aa3b, v20
	v_mul_f32_e32 v25, 0xbfb8aa3b, v21
	v_exp_f32_e32 v24, v24
	v_exp_f32_e32 v25, v25
	s_nop 0
	v_pk_add_f32 v[24:25], v[24:25], 1.0 op_sel_hi:[1,0]
	s_nop 0
	v_rcp_f32_e32 v26, v25
	s_nop 0
	v_mul_f32_e32 v25, v21, v26
	v_mul_f32_e32 v26, 0xbfb8aa3b, v22
	v_mul_f32_e32 v27, 0xbfb8aa3b, v23
	v_exp_f32_e32 v26, v26
	v_exp_f32_e32 v27, v27
	s_nop 0
	v_pk_add_f32 v[26:27], v[26:27], 1.0 op_sel_hi:[1,0]
	v_rcp_f32_e32 v21, v24
	s_nop 0
	v_mul_f32_e32 v24, v20, v21
	v_rcp_f32_e32 v20, v27
	s_nop 0
	v_mul_f32_e32 v27, v23, v20
	v_rcp_f32_e32 v20, v26
	s_nop 0
	v_mul_f32_e32 v26, v22, v20

; DI unsigned pack2(float a, float b) { v2f f = {a, b}; return __builtin_bit_cast(unsigned, __builtin_convertvector(f, v2bf)); }
; DI float fexp(float x) { return __builtin_amdgcn_exp2f(x * LOG2E); }
; DI float silu_f(float v) { return v / (1.f + fexp(-v)); }
;   DI void operator()(int m, int n, float a, float b, float c, float d, float& ss) const {
;     ...
;     if (n < q_end) { a *= qscale; b *= qscale; c *= qscale; d *= qscale; }
;     else if (n >= z_start) { a = silu_f(a); b = silu_f(b); c = silu_f(c); d = silu_f(d); }
;     ss += a * a + b * b + c * c + d * d;
;     u32x2 v; v.x = pack2(a, b); v.y = pack2(c, d);
;     *(u32x2*)(dst + (long)m * ld + n) = v;
.LBB0_1278:
	v_cmp_lt_i32_e32 vcc, s37, v58
	s_and_saveexec_b64 s[30:31], vcc
	s_xor_b64 s[30:31], exec, s[30:31]
	s_cbranch_execz .LBB0_1280
	v_mul_f32_e32 v20, 0xbfb8aa3b, v16
	v_mul_f32_e32 v21, 0xbfb8aa3b, v17
	v_exp_f32_e32 v20, v20
	v_exp_f32_e32 v21, v21
	s_nop 0
	v_pk_add_f32 v[20:21], v[20:21], 1.0 op_sel_hi:[1,0]
	s_nop 0
	v_rcp_f32_e32 v22, v21
	s_nop 0
	v_mul_f32_e32 v21, v17, v22
	v_mul_f32_e32 v22, 0xbfb8aa3b, v18
	v_mul_f32_e32 v23, 0xbfb8aa3b, v19
	v_exp_f32_e32 v22, v22
	v_exp_f32_e32 v23, v23
	s_nop 0
	v_pk_add_f32 v[22:23], v[22:23], 1.0 op_sel_hi:[1,0]
	v_rcp_f32_e32 v17, v20
	s_nop 0
	v_mul_f32_e32 v20, v16, v17
	v_rcp_f32_e32 v16, v23
	s_nop 0
	v_mul_f32_e32 v23, v19, v16
	v_rcp_f32_e32 v16, v22
	s_nop 0
	v_mul_f32_e32 v22, v18, v16

; DI float fexp(float x) { return __builtin_amdgcn_exp2f(x * LOG2E); }
; DI float sigmoid_f(float v) { return 1.f / (1.f + fexp(-v)); }
;   DI void operator()(int m, int n, float a, float b, float c, float d, float& ss) const {
;     if (n >= gl_start) {
;       const int j = n - gl_start;
;       if (j < 48) { float* g = gates + (long)m * 48 + j; g[0] = sigmoid_f(a); g[1] = sigmoid_f(b); g[2] = sigmoid_f(c); g[3] = sigmoid_f(d); }
;       return;
.LBB0_1290:
	v_cmp_gt_u32_e32 vcc, 48, v68
	s_and_saveexec_b64 s[4:5], vcc
	s_cbranch_execz .LBB0_1292
	v_mul_f32_e32 v12, 0xbfb8aa3b, v12
	v_mul_f32_e32 v13, 0xbfb8aa3b, v13
	v_exp_f32_e32 v12, v12
	v_exp_f32_e32 v13, v13
	v_mul_f32_e32 v14, 0xbfb8aa3b, v14
	v_mul_f32_e32 v15, 0xbfb8aa3b, v15
	v_exp_f32_e32 v14, v14
	v_pk_add_f32 v[12:13], v[12:13], 1.0 op_sel_hi:[1,0]
	v_exp_f32_e32 v15, v15
	s_nop 0
	v_pk_add_f32 v[14:15], v[14:15], 1.0 op_sel_hi:[1,0]
	v_mov_b32_e32 v69, v65
	v_lshl_add_u64 v[20:21], v[68:69], 2, v[18:19]
	v_rcp_f32_e32 v17, v13
	s_nop 0
	v_mul_f32_e32 v13, 1.0, v17
	v_rcp_f32_e32 v17, v12
	s_nop 0
	v_mul_f32_e32 v12, 1.0, v17
	v_rcp_f32_e32 v17, v15
	s_nop 0
	v_mul_f32_e32 v15, 1.0, v17
	v_rcp_f32_e32 v17, v14
	s_nop 0
	v_mul_f32_e32 v14, 1.0, v17
	flat_store_dwordx4 v[20:21], v[12:15]

; DI unsigned pack2(float a, float b) { v2f f = {a, b}; return __builtin_bit_cast(unsigned, __builtin_convertvector(f, v2bf)); }
; DI float fexp(float x) { return __builtin_amdgcn_exp2f(x * LOG2E); }
; DI float silu_f(float v) { return v / (1.f + fexp(-v)); }
;   DI void operator()(int m, int n, float a, float b, float c, float d, float& ss) const {
;     ...
;     if (n < q_end) { a *= qscale; b *= qscale; c *= qscale; d *= qscale; }
;     else if (n >= z_start) { a = silu_f(a); b = silu_f(b); c = silu_f(c); d = silu_f(d); }
;     ss += a * a + b * b + c * c + d * d;
;     u32x2 v; v.x = pack2(a, b); v.y = pack2(c, d);
;     *(u32x2*)(dst + (long)m * ld + n) = v;
.LBB0_1293:
	v_cmp_lt_i32_e32 vcc, s37, v64
	s_and_saveexec_b64 s[4:5], vcc
	s_xor_b64 s[4:5], exec, s[4:5]
	s_cbranch_execz .LBB0_1295
	v_mul_f32_e32 v20, 0xbfb8aa3b, v12
	v_mul_f32_e32 v21, 0xbfb8aa3b, v13
	v_exp_f32_e32 v20, v20
	v_exp_f32_e32 v21, v21
	s_nop 0
	v_pk_add_f32 v[20:21], v[20:21], 1.0 op_sel_hi:[1,0]
	s_nop 0
	v_rcp_f32_e32 v22, v21
	s_nop 0
	v_mul_f32_e32 v21, v13, v22
	v_mul_f32_e32 v22, 0xbfb8aa3b, v14
	v_mul_f32_e32 v23, 0xbfb8aa3b, v15
	v_exp_f32_e32 v22, v22
	v_exp_f32_e32 v23, v23
	s_nop 0
	v_pk_add_f32 v[22:23], v[22:23], 1.0 op_sel_hi:[1,0]
	v_rcp_f32_e32 v13, v20
	s_nop 0
	v_mul_f32_e32 v20, v12, v13
	v_rcp_f32_e32 v12, v23
	s_nop 0
	v_mul_f32_e32 v23, v15, v12
	v_rcp_f32_e32 v12, v22
	s_nop 0
	v_mul_f32_e32 v22, v14, v12

; DI float fexp(float x) { return __builtin_amdgcn_exp2f(x * LOG2E); }
; DI float sigmoid_f(float v) { return 1.f / (1.f + fexp(-v)); }
;   DI void operator()(int m, int n, float a, float b, float c, float d, float& ss) const {
;     if (n >= gl_start) {
;       const int j = n - gl_start;
;       if (j < 48) { float* g = gates + (long)m * 48 + j; g[0] = sigmoid_f(a); g[1] = sigmoid_f(b); g[2] = sigmoid_f(c); g[3] = sigmoid_f(d); }
;       return;
.LBB0_1298:
	v_cmp_gt_u32_e32 vcc, 48, v60
	s_and_saveexec_b64 s[4:5], vcc
	s_cbranch_execz .LBB0_1300
	v_mul_f32_e32 v8, 0xbfb8aa3b, v8
	v_mul_f32_e32 v9, 0xbfb8aa3b, v9
	v_exp_f32_e32 v8, v8
	v_exp_f32_e32 v9, v9
	v_mul_f32_e32 v10, 0xbfb8aa3b, v10
	v_mul_f32_e32 v11, 0xbfb8aa3b, v11
	v_exp_f32_e32 v10, v10
	v_pk_add_f32 v[8:9], v[8:9], 1.0 op_sel_hi:[1,0]
	v_exp_f32_e32 v11, v11
	s_nop 0
	v_pk_add_f32 v[10:11], v[10:11], 1.0 op_sel_hi:[1,0]
	v_mov_b32_e32 v61, v65
	v_lshl_add_u64 v[12:13], v[60:61], 2, v[18:19]
	v_rcp_f32_e32 v14, v9
	s_nop 0
	v_mul_f32_e32 v9, 1.0, v14
	v_rcp_f32_e32 v14, v8
	s_nop 0
	v_mul_f32_e32 v8, 1.0, v14
	v_rcp_f32_e32 v14, v11
	s_nop 0
	v_mul_f32_e32 v11, 1.0, v14
	v_rcp_f32_e32 v14, v10
	s_nop 0
	v_mul_f32_e32 v10, 1.0, v14
	flat_store_dwordx4 v[12:13], v[8:11]

; DI unsigned pack2(float a, float b) { v2f f = {a, b}; return __builtin_bit_cast(unsigned, __builtin_convertvector(f, v2bf)); }
; DI float fexp(float x) { return __builtin_amdgcn_exp2f(x * LOG2E); }
; DI float silu_f(float v) { return v / (1.f + fexp(-v)); }
;   DI void operator()(int m, int n, float a, float b, float c, float d, float& ss) const {
;     ...
;     if (n < q_end) { a *= qscale; b *= qscale; c *= qscale; d *= qscale; }
;     else if (n >= z_start) { a = silu_f(a); b = silu_f(b); c = silu_f(c); d = silu_f(d); }
;     ss += a * a + b * b + c * c + d * d;
;     u32x2 v; v.x = pack2(a, b); v.y = pack2(c, d);
;     *(u32x2*)(dst + (long)m * ld + n) = v;
.LBB0_1301:
	v_cmp_lt_i32_e32 vcc, s37, v74
	s_and_saveexec_b64 s[4:5], vcc
	s_xor_b64 s[4:5], exec, s[4:5]
	s_cbranch_execz .LBB0_1303
	v_mul_f32_e32 v12, 0xbfb8aa3b, v8
	v_mul_f32_e32 v13, 0xbfb8aa3b, v9
	v_exp_f32_e32 v12, v12
	v_exp_f32_e32 v13, v13
	s_nop 0
	v_pk_add_f32 v[12:13], v[12:13], 1.0 op_sel_hi:[1,0]
	s_nop 0
	v_rcp_f32_e32 v14, v13
	s_nop 0
	v_mul_f32_e32 v13, v9, v14
	v_mul_f32_e32 v14, 0xbfb8aa3b, v10
	v_mul_f32_e32 v15, 0xbfb8aa3b, v11
	v_exp_f32_e32 v14, v14
	v_exp_f32_e32 v15, v15
	s_nop 0
	v_pk_add_f32 v[14:15], v[14:15], 1.0 op_sel_hi:[1,0]
	v_rcp_f32_e32 v9, v12
	s_nop 0
	v_mul_f32_e32 v12, v8, v9
	v_rcp_f32_e32 v8, v15
	s_nop 0
	v_mul_f32_e32 v15, v11, v8
	v_rcp_f32_e32 v8, v14
	s_nop 0
	v_mul_f32_e32 v14, v10, v8

; DI float fexp(float x) { return __builtin_amdgcn_exp2f(x * LOG2E); }
; DI float sigmoid_f(float v) { return 1.f / (1.f + fexp(-v)); }
;   DI void operator()(int m, int n, float a, float b, float c, float d, float& ss) const {
;     if (n >= gl_start) {
;       const int j = n - gl_start;
;       if (j < 48) { float* g = gates + (long)m * 48 + j; g[0] = sigmoid_f(a); g[1] = sigmoid_f(b); g[2] = sigmoid_f(c); g[3] = sigmoid_f(d); }
;       return;
.LBB0_1306:
	v_cmp_gt_u32_e32 vcc, 48, v56
	s_and_saveexec_b64 s[4:5], vcc
	s_cbranch_execz .LBB0_1308
	v_mul_f32_e32 v4, 0xbfb8aa3b, v4
	v_mul_f32_e32 v5, 0xbfb8aa3b, v5
	v_exp_f32_e32 v4, v4
	v_exp_f32_e32 v5, v5
	v_mul_f32_e32 v6, 0xbfb8aa3b, v6
	v_mul_f32_e32 v7, 0xbfb8aa3b, v7
	v_exp_f32_e32 v6, v6
	v_pk_add_f32 v[4:5], v[4:5], 1.0 op_sel_hi:[1,0]
	v_exp_f32_e32 v7, v7
	s_nop 0
	v_pk_add_f32 v[6:7], v[6:7], 1.0 op_sel_hi:[1,0]
	v_mov_b32_e32 v57, v65
	v_lshl_add_u64 v[8:9], v[56:57], 2, v[18:19]
	v_rcp_f32_e32 v10, v5
	s_nop 0
	v_mul_f32_e32 v5, 1.0, v10
	v_rcp_f32_e32 v10, v4
	s_nop 0
	v_mul_f32_e32 v4, 1.0, v10
	v_rcp_f32_e32 v10, v7
	s_nop 0
	v_mul_f32_e32 v7, 1.0, v10
	v_rcp_f32_e32 v10, v6
	s_nop 0
	v_mul_f32_e32 v6, 1.0, v10
	flat_store_dwordx4 v[8:9], v[4:7]

; DI unsigned pack2(float a, float b) { v2f f = {a, b}; return __builtin_bit_cast(unsigned, __builtin_convertvector(f, v2bf)); }
; DI float fexp(float x) { return __builtin_amdgcn_exp2f(x * LOG2E); }
; DI float silu_f(float v) { return v / (1.f + fexp(-v)); }
;   DI void operator()(int m, int n, float a, float b, float c, float d, float& ss) const {
;     ...
;     if (n < q_end) { a *= qscale; b *= qscale; c *= qscale; d *= qscale; }
;     else if (n >= z_start) { a = silu_f(a); b = silu_f(b); c = silu_f(c); d = silu_f(d); }
;     ss += a * a + b * b + c * c + d * d;
;     u32x2 v; v.x = pack2(a, b); v.y = pack2(c, d);
;     *(u32x2*)(dst + (long)m * ld + n) = v;
.LBB0_1309:
	v_cmp_lt_i32_e32 vcc, s37, v72
	s_and_saveexec_b64 s[4:5], vcc
	s_xor_b64 s[4:5], exec, s[4:5]
	s_cbranch_execz .LBB0_1311
	v_mul_f32_e32 v8, 0xbfb8aa3b, v4
	v_mul_f32_e32 v9, 0xbfb8aa3b, v5
	v_exp_f32_e32 v8, v8
	v_exp_f32_e32 v9, v9
	s_nop 0
	v_pk_add_f32 v[8:9], v[8:9], 1.0 op_sel_hi:[1,0]
	s_nop 0
	v_rcp_f32_e32 v10, v9
	s_nop 0
	v_mul_f32_e32 v9, v5, v10
	v_mul_f32_e32 v10, 0xbfb8aa3b, v6
	v_mul_f32_e32 v11, 0xbfb8aa3b, v7
	v_exp_f32_e32 v10, v10
	v_exp_f32_e32 v11, v11
	s_nop 0
	v_pk_add_f32 v[10:11], v[10:11], 1.0 op_sel_hi:[1,0]
	v_rcp_f32_e32 v5, v8
	s_nop 0
	v_mul_f32_e32 v8, v4, v5
	v_rcp_f32_e32 v4, v11
	s_nop 0
	v_mul_f32_e32 v11, v7, v4
	v_rcp_f32_e32 v4, v10
	s_nop 0
	v_mul_f32_e32 v10, v6, v4

; DI unsigned pack2(float a, float b) { v2f f = {a, b}; return __builtin_bit_cast(unsigned, __builtin_convertvector(f, v2bf)); }
; DI float fexp(float x) { return __builtin_amdgcn_exp2f(x * LOG2E); }
; DI float silu_f(float v) { return v / (1.f + fexp(-v)); }
;   DI void operator()(int m, int n, float a, float b, float c, float d, float& ss) const {
;     ...
;     if (n < q_end) { a *= qscale; b *= qscale; c *= qscale; d *= qscale; }
;     else if (n >= z_start) { a = silu_f(a); b = silu_f(b); c = silu_f(c); d = silu_f(d); }
;     ss += a * a + b * b + c * c + d * d;
;     u32x2 v; v.x = pack2(a, b); v.y = pack2(c, d);
;     *(u32x2*)(dst + (long)m * ld + n) = v;
.LBB0_1314:
	v_cmp_lt_i32_e32 vcc, s37, v58
	s_and_saveexec_b64 s[4:5], vcc
	s_xor_b64 s[4:5], exec, s[4:5]
	s_cbranch_execz .LBB0_1316
	v_mul_f32_e32 v4, 0xbfb8aa3b, v0
	v_mul_f32_e32 v5, 0xbfb8aa3b, v1
	v_exp_f32_e32 v4, v4
	v_exp_f32_e32 v5, v5
	s_nop 0
	v_pk_add_f32 v[4:5], v[4:5], 1.0 op_sel_hi:[1,0]
	s_nop 0
	v_rcp_f32_e32 v6, v5
	s_nop 0
	v_mul_f32_e32 v5, v1, v6
	v_mul_f32_e32 v6, 0xbfb8aa3b, v2
	v_mul_f32_e32 v7, 0xbfb8aa3b, v3
	v_exp_f32_e32 v6, v6
	v_exp_f32_e32 v7, v7
	s_nop 0
	v_pk_add_f32 v[6:7], v[6:7], 1.0 op_sel_hi:[1,0]
	v_rcp_f32_e32 v1, v4
	s_nop 0
	v_mul_f32_e32 v4, v0, v1
	v_rcp_f32_e32 v0, v7
	s_nop 0
	v_mul_f32_e32 v7, v3, v0
	v_rcp_f32_e32 v0, v6
	s_nop 0
	v_mul_f32_e32 v6, v2, v0

; DI unsigned pack2(float a, float b) { v2f f = {a, b}; return __builtin_bit_cast(unsigned, __builtin_convertvector(f, v2bf)); }
; DI float fexp(float x) { return __builtin_amdgcn_exp2f(x * LOG2E); }
;   DI u32x2 pack(int, int, float a, float b, float c, float d, float&) const { u32x2 v; v.x = pack2(a, b); v.y = pack2(c, d); return v; }
; DI float silu_f(float v) { return v / (1.f + fexp(-v)); }
;   DI u32x2 pack(int m, int n, float a, float b, float c, float d, float& ss) const {
;     if (n < q_end) { a *= qscale; b *= qscale; c *= qscale; d *= qscale; }
;     else if (n >= z_start) { a = silu_f(a); b = silu_f(b); c = silu_f(c); d = silu_f(d); }
;     ss += a * a + b * b + c * c + d * d;
;     u32x2 v; v.x = pack2(a, b); v.y = pack2(c, d);
.LBB0_1320:
	s_andn2_saveexec_b64 s[30:31], s[12:13]
	s_cbranch_execz .LBB0_1171
	v_cmp_lt_i32_e64 s[4:5], s37, v64
	s_and_saveexec_b64 s[0:1], s[4:5]
	s_xor_b64 s[0:1], exec, s[0:1]
	s_cbranch_execz .LBB0_1324
	s_cmpk_lt_u32 s38, 0xc00
	s_cbranch_scc1 .LBB0_1324
	v_mul_f32_e32 v67, 0xbfb8aa3b, v60
	v_exp_f32_e32 v70, v67
	v_mul_f32_e32 v67, 0xbfb8aa3b, v61
	v_exp_f32_e32 v71, v67
	s_nop 0
	v_pk_add_f32 v[70:71], v[70:71], 1.0 op_sel_hi:[1,0]
	s_nop 0
	v_rcp_f32_e32 v67, v70
	s_nop 0
	v_mul_f32_e32 v60, v60, v67
	v_mul_f32_e32 v70, 0xbfb8aa3b, v62
	v_exp_f32_e32 v74, v70
	v_mul_f32_e32 v70, 0xbfb8aa3b, v63
	v_exp_f32_e32 v75, v70
	s_nop 0
	v_pk_add_f32 v[74:75], v[74:75], 1.0 op_sel_hi:[1,0]
	v_rcp_f32_e32 v67, v71
	s_nop 0
	v_mul_f32_e32 v61, v61, v67
	v_rcp_f32_e32 v67, v74
	s_nop 0
	v_mul_f32_e32 v62, v62, v67
	v_rcp_f32_e32 v67, v75
	s_nop 0
	v_mul_f32_e32 v63, v63, v67
.LBB0_1324:
	s_andn2_saveexec_b64 s[0:1], s[0:1]
	v_pk_mul_f32 v[60:61], v[60:61], s[28:29] op_sel_hi:[1,0]
	v_pk_mul_f32 v[62:63], v[62:63], s[28:29] op_sel_hi:[1,0]
	s_or_b64 exec, exec, s[0:1]
	v_or_b32_e32 v67, 16, v64
	v_cmp_lt_i32_e64 s[6:7], s37, v67
	s_and_saveexec_b64 s[0:1], s[6:7]
	s_xor_b64 s[0:1], exec, s[0:1]
	s_cbranch_execz .LBB0_1329
	s_cmpk_lt_u32 s38, 0xc00
	s_cbranch_scc1 .LBB0_1329
	v_mul_f32_e32 v67, 0xbfb8aa3b, v56
	v_exp_f32_e32 v70, v67
	v_mul_f32_e32 v67, 0xbfb8aa3b, v57
	v_exp_f32_e32 v71, v67
	s_nop 0
	v_pk_add_f32 v[70:71], v[70:71], 1.0 op_sel_hi:[1,0]
	s_nop 0
	v_rcp_f32_e32 v67, v70
	s_nop 0
	v_mul_f32_e32 v56, v56, v67
	v_mul_f32_e32 v70, 0xbfb8aa3b, v58
	v_exp_f32_e32 v74, v70
	v_mul_f32_e32 v70, 0xbfb8aa3b, v59
	v_exp_f32_e32 v75, v70
	s_nop 0
	v_pk_add_f32 v[74:75], v[74:75], 1.0 op_sel_hi:[1,0]
	v_rcp_f32_e32 v67, v71
	s_nop 0
	v_mul_f32_e32 v57, v57, v67
	v_rcp_f32_e32 v67, v74
	s_nop 0
	v_mul_f32_e32 v58, v58, v67
	v_rcp_f32_e32 v67, v75
	s_nop 0
	v_mul_f32_e32 v59, v59, v67
.LBB0_1329:
	s_andn2_saveexec_b64 s[0:1], s[0:1]
	v_pk_mul_f32 v[56:57], v[56:57], s[28:29] op_sel_hi:[1,0]
	v_pk_mul_f32 v[58:59], v[58:59], s[28:29] op_sel_hi:[1,0]
	s_or_b64 exec, exec, s[0:1]
	v_or_b32_e32 v67, 32, v64
	v_cmp_lt_i32_e64 s[8:9], s37, v67
	s_and_saveexec_b64 s[0:1], s[8:9]
	s_xor_b64 s[0:1], exec, s[0:1]
	s_cbranch_execz .LBB0_1334
	s_cmpk_lt_u32 s38, 0xc00
	s_cbranch_scc1 .LBB0_1334
	v_mul_f32_e32 v67, 0xbfb8aa3b, v52
	v_exp_f32_e32 v70, v67
	v_mul_f32_e32 v67, 0xbfb8aa3b, v53
	v_exp_f32_e32 v71, v67
	s_nop 0
	v_pk_add_f32 v[70:71], v[70:71], 1.0 op_sel_hi:[1,0]
	s_nop 0
	v_rcp_f32_e32 v67, v70
	s_nop 0
	v_mul_f32_e32 v52, v52, v67
	v_mul_f32_e32 v70, 0xbfb8aa3b, v54
	v_exp_f32_e32 v74, v70
	v_mul_f32_e32 v70, 0xbfb8aa3b, v55
	v_exp_f32_e32 v75, v70
	s_nop 0
	v_pk_add_f32 v[74:75], v[74:75], 1.0 op_sel_hi:[1,0]
	v_rcp_f32_e32 v67, v71
	s_nop 0
	v_mul_f32_e32 v53, v53, v67
	v_rcp_f32_e32 v67, v74
	s_nop 0
	v_mul_f32_e32 v54, v54, v67
	v_rcp_f32_e32 v67, v75
	s_nop 0
	v_mul_f32_e32 v55, v55, v67
.LBB0_1334:
	s_andn2_saveexec_b64 s[0:1], s[0:1]
	v_pk_mul_f32 v[52:53], v[52:53], s[28:29] op_sel_hi:[1,0]
	v_pk_mul_f32 v[54:55], v[54:55], s[28:29] op_sel_hi:[1,0]
	s_or_b64 exec, exec, s[0:1]
	v_or_b32_e32 v64, 48, v64
	v_cmp_lt_i32_e64 s[10:11], s37, v64
	s_and_saveexec_b64 s[0:1], s[10:11]
	s_xor_b64 s[0:1], exec, s[0:1]
	s_cbranch_execz .LBB0_1339
	s_cmpk_lt_u32 s38, 0xc00
	s_cbranch_scc1 .LBB0_1339
	v_mul_f32_e32 v64, 0xbfb8aa3b, v48
	v_exp_f32_e32 v70, v64
	v_mul_f32_e32 v64, 0xbfb8aa3b, v49
	v_exp_f32_e32 v71, v64
	s_nop 0
	v_pk_add_f32 v[70:71], v[70:71], 1.0 op_sel_hi:[1,0]
	s_nop 0
	v_rcp_f32_e32 v64, v70
	s_nop 0
	v_mul_f32_e32 v48, v48, v64
	v_mul_f32_e32 v70, 0xbfb8aa3b, v50
	v_exp_f32_e32 v74, v70
	v_mul_f32_e32 v70, 0xbfb8aa3b, v51
	v_exp_f32_e32 v75, v70
	s_nop 0
	v_pk_add_f32 v[74:75], v[74:75], 1.0 op_sel_hi:[1,0]
	v_rcp_f32_e32 v64, v71
	s_nop 0
	v_mul_f32_e32 v49, v49, v64
	v_rcp_f32_e32 v64, v74
	s_nop 0
	v_mul_f32_e32 v50, v50, v64
	v_rcp_f32_e32 v64, v75
	s_nop 0
	v_mul_f32_e32 v51, v51, v64

; DI unsigned pack2(float a, float b) { v2f f = {a, b}; return __builtin_bit_cast(unsigned, __builtin_convertvector(f, v2bf)); }
; DI float silu_f(float v) { return v / (1.f + fexp(-v)); }
;   DI u32x2 pack(int, int, float a, float b, float c, float d, float&) const { u32x2 v; v.x = pack2(a, b); v.y = pack2(c, d); return v; }
; template <class ARow, class Epi>
; DI void gemm_tile(const ARow& arow, long a_kstride, const u16* __restrict__ Bt, long ldb, int K, int m0, int n0,
;                   const Epi& epi, char* smem) {
;     ...
;       for (int ni = 0; ni < 4; ++ni) pk[ni] = epi.pack(m, nh + ni * 16 + fq * 4, acc[ni][mi][0], acc[ni][mi][1], acc[ni][mi][2], acc[ni][mi][3], ss);
;       epi.finish16(m, nh, ss);
;       u16* rp = epi.rowp(m) + nh;
; #pragma unroll
;       for (int pp = 0; pp < 2; ++pp) {
;         u32x2 a = pk[2 * pp], b = pk[2 * pp + 1];
;         const u32x2 rx = __builtin_amdgcn_permlane16_swap(a.x, b.x, false, false);
;         const u32x2 ry = __builtin_amdgcn_permlane16_swap(a.y, b.y, false, false);
;         const int nst = (fq & 1) ? ((2 * pp + 1) * 16 + (fq - 1) * 4) : ((2 * pp) * 16 + fq * 4);
;         *(u32x4*)(rp + nst) = (u32x4){rx[0], ry[0], rx[1], ry[1]};
;       }
;   DI u32x2 pack(int m, int n, float a, float b, float c, float d, float& ss) const {
;     if (n < q_end) { a *= qscale; b *= qscale; c *= qscale; d *= qscale; }
;     else if (n >= z_start) { a = silu_f(a); b = silu_f(b); c = silu_f(c); d = silu_f(d); }
;     ss += a * a + b * b + c * c + d * d;
;     u32x2 v; v.x = pack2(a, b); v.y = pack2(c, d);
.LBB0_1345:
	v_cvt_pk_bf16_f32 v75, v54, v55
	v_and_b32_e32 v54, 16, v83
	s_waitcnt lgkmcnt(0)
	v_ashrrev_i32_e32 v67, 31, v66
	v_cvt_pk_bf16_f32 v74, v52, v53
	v_lshlrev_b64 v[52:53], 13, v[66:67]
	v_add_u32_e32 v55, 12, v72
	v_cmp_eq_u32_e32 vcc, 0, v54
	v_ashrrev_i32_e32 v69, 31, v68
	v_lshl_add_u64 v[52:53], s[18:19], 0, v[52:53]
	v_cndmask_b32_e32 v54, v55, v72, vcc
	v_cvt_pk_bf16_f32 v76, v48, v49
	v_cvt_pk_bf16_f32 v77, v50, v51
	v_cvt_pk_bf16_f32 v50, v56, v57
	v_cvt_pk_bf16_f32 v51, v58, v59
	v_cvt_pk_bf16_f32 v48, v60, v61
	v_cvt_pk_bf16_f32 v49, v62, v63
	v_lshl_add_u64 v[52:53], v[68:69], 1, v[52:53]
	v_lshlrev_b32_e32 v64, 1, v54
	v_permlane16_swap_b32_e32 v48, v50
	v_permlane16_swap_b32_e32 v49, v51
	v_lshl_add_u64 v[54:55], v[52:53], 0, v[64:65]
	global_store_dwordx4 v[54:55], v[48:51], off
	v_permlane16_swap_b32_e32 v74, v76
	s_nop 0
	v_add_u32_e32 v48, 44, v72
	v_or_b32_e32 v49, 32, v72
	v_cndmask_b32_e32 v48, v48, v49, vcc
	v_lshlrev_b32_e32 v48, 1, v48
	v_mov_b32_e32 v49, v65
	v_permlane16_swap_b32_e32 v75, v77
	v_lshl_add_u64 v[50:51], v[52:53], 0, v[48:49]
	global_store_dwordx4 v[50:51], v[74:77], off
	s_and_saveexec_b64 s[0:1], s[4:5]
	s_xor_b64 s[0:1], exec, s[0:1]
	s_cbranch_execz .LBB0_1348
	s_cmpk_lt_u32 s38, 0xc00
	s_cbranch_scc1 .LBB0_1348
	v_mul_f32_e32 v49, 0xbfb8aa3b, v44
	v_exp_f32_e32 v50, v49
	v_mul_f32_e32 v49, 0xbfb8aa3b, v45
	v_exp_f32_e32 v51, v49
	s_nop 0
	v_pk_add_f32 v[50:51], v[50:51], 1.0 op_sel_hi:[1,0]
	s_nop 0
	v_rcp_f32_e32 v49, v50
	v_mul_f32_e32 v52, 0xbfb8aa3b, v46
	v_mul_f32_e32 v53, 0xbfb8aa3b, v47
	v_exp_f32_e32 v52, v52
	v_exp_f32_e32 v53, v53
	v_mul_f32_e32 v44, v44, v49
	v_pk_add_f32 v[52:53], v[52:53], 1.0 op_sel_hi:[1,0]
	v_rcp_f32_e32 v49, v51
	s_nop 0
	v_mul_f32_e32 v45, v45, v49
	v_rcp_f32_e32 v49, v52
	s_nop 0
	v_mul_f32_e32 v46, v46, v49
	v_rcp_f32_e32 v49, v53
	s_nop 0
	v_mul_f32_e32 v47, v47, v49
.LBB0_1348:
	s_andn2_saveexec_b64 s[0:1], s[0:1]
	v_pk_mul_f32 v[44:45], v[44:45], s[28:29] op_sel_hi:[1,0]
	v_pk_mul_f32 v[46:47], v[46:47], s[28:29] op_sel_hi:[1,0]
	s_or_b64 exec, exec, s[0:1]
	s_and_saveexec_b64 s[0:1], s[6:7]
	s_xor_b64 s[0:1], exec, s[0:1]
	s_cbranch_execz .LBB0_1353
	s_cmpk_lt_u32 s38, 0xc00
	s_cbranch_scc1 .LBB0_1353
	v_mul_f32_e32 v49, 0xbfb8aa3b, v40
	v_exp_f32_e32 v50, v49
	v_mul_f32_e32 v49, 0xbfb8aa3b, v41
	v_exp_f32_e32 v51, v49
	s_nop 0
	v_pk_add_f32 v[50:51], v[50:51], 1.0 op_sel_hi:[1,0]
	s_nop 0
	v_rcp_f32_e32 v49, v50
	v_mul_f32_e32 v52, 0xbfb8aa3b, v42
	v_mul_f32_e32 v53, 0xbfb8aa3b, v43
	v_exp_f32_e32 v52, v52
	v_exp_f32_e32 v53, v53
	v_mul_f32_e32 v40, v40, v49
	v_pk_add_f32 v[52:53], v[52:53], 1.0 op_sel_hi:[1,0]
	v_rcp_f32_e32 v49, v51
	s_nop 0
	v_mul_f32_e32 v41, v41, v49
	v_rcp_f32_e32 v49, v52
	s_nop 0
	v_mul_f32_e32 v42, v42, v49
	v_rcp_f32_e32 v49, v53
	s_nop 0
	v_mul_f32_e32 v43, v43, v49
.LBB0_1353:
	s_andn2_saveexec_b64 s[0:1], s[0:1]
	v_pk_mul_f32 v[40:41], v[40:41], s[28:29] op_sel_hi:[1,0]
	v_pk_mul_f32 v[42:43], v[42:43], s[28:29] op_sel_hi:[1,0]
	s_or_b64 exec, exec, s[0:1]
	s_and_saveexec_b64 s[0:1], s[8:9]
	s_xor_b64 s[0:1], exec, s[0:1]
	s_cbranch_execz .LBB0_1358
	s_cmpk_lt_u32 s38, 0xc00
	s_cbranch_scc1 .LBB0_1358
	v_mul_f32_e32 v49, 0xbfb8aa3b, v36
	v_exp_f32_e32 v50, v49
	v_mul_f32_e32 v49, 0xbfb8aa3b, v37
	v_exp_f32_e32 v51, v49
	s_nop 0
	v_pk_add_f32 v[50:51], v[50:51], 1.0 op_sel_hi:[1,0]
	s_nop 0
	v_rcp_f32_e32 v49, v50
	v_mul_f32_e32 v52, 0xbfb8aa3b, v38
	v_mul_f32_e32 v53, 0xbfb8aa3b, v39
	v_exp_f32_e32 v52, v52
	v_exp_f32_e32 v53, v53
	v_mul_f32_e32 v36, v36, v49
	v_pk_add_f32 v[52:53], v[52:53], 1.0 op_sel_hi:[1,0]
	v_rcp_f32_e32 v49, v51
	s_nop 0
	v_mul_f32_e32 v37, v37, v49
	v_rcp_f32_e32 v49, v52
	s_nop 0
	v_mul_f32_e32 v38, v38, v49
	v_rcp_f32_e32 v49, v53
	s_nop 0
	v_mul_f32_e32 v39, v39, v49
.LBB0_1358:
	s_andn2_saveexec_b64 s[0:1], s[0:1]
	v_pk_mul_f32 v[36:37], v[36:37], s[28:29] op_sel_hi:[1,0]
	v_pk_mul_f32 v[38:39], v[38:39], s[28:29] op_sel_hi:[1,0]
	s_or_b64 exec, exec, s[0:1]
	s_and_saveexec_b64 s[0:1], s[10:11]
	s_xor_b64 s[0:1], exec, s[0:1]
	s_cbranch_execz .LBB0_1363
	s_cmpk_lt_u32 s38, 0xc00
	s_cbranch_scc1 .LBB0_1363
	v_mul_f32_e32 v49, 0xbfb8aa3b, v32
	v_exp_f32_e32 v50, v49
	v_mul_f32_e32 v49, 0xbfb8aa3b, v33
	v_exp_f32_e32 v51, v49
	s_nop 0
	v_pk_add_f32 v[50:51], v[50:51], 1.0 op_sel_hi:[1,0]
	s_nop 0
	v_rcp_f32_e32 v49, v50
	v_mul_f32_e32 v52, 0xbfb8aa3b, v34
	v_mul_f32_e32 v53, 0xbfb8aa3b, v35
	v_exp_f32_e32 v52, v52
	v_exp_f32_e32 v53, v53
	v_mul_f32_e32 v32, v32, v49
	v_pk_add_f32 v[52:53], v[52:53], 1.0 op_sel_hi:[1,0]
	v_rcp_f32_e32 v49, v51
	s_nop 0
	v_mul_f32_e32 v33, v33, v49
	v_rcp_f32_e32 v49, v52
	s_nop 0
	v_mul_f32_e32 v34, v34, v49
	v_rcp_f32_e32 v49, v53
	s_nop 0
	v_mul_f32_e32 v35, v35, v49

; DI unsigned pack2(float a, float b) { v2f f = {a, b}; return __builtin_bit_cast(unsigned, __builtin_convertvector(f, v2bf)); }
; DI float silu_f(float v) { return v / (1.f + fexp(-v)); }
;   DI u32x2 pack(int, int, float a, float b, float c, float d, float&) const { u32x2 v; v.x = pack2(a, b); v.y = pack2(c, d); return v; }
; template <class ARow, class Epi>
; DI void gemm_tile(const ARow& arow, long a_kstride, const u16* __restrict__ Bt, long ldb, int K, int m0, int n0,
;                   const Epi& epi, char* smem) {
;     ...
;       for (int ni = 0; ni < 4; ++ni) pk[ni] = epi.pack(m, nh + ni * 16 + fq * 4, acc[ni][mi][0], acc[ni][mi][1], acc[ni][mi][2], acc[ni][mi][3], ss);
;       epi.finish16(m, nh, ss);
;       u16* rp = epi.rowp(m) + nh;
; #pragma unroll
;       for (int pp = 0; pp < 2; ++pp) {
;         u32x2 a = pk[2 * pp], b = pk[2 * pp + 1];
;         const u32x2 rx = __builtin_amdgcn_permlane16_swap(a.x, b.x, false, false);
;         const u32x2 ry = __builtin_amdgcn_permlane16_swap(a.y, b.y, false, false);
;         const int nst = (fq & 1) ? ((2 * pp + 1) * 16 + (fq - 1) * 4) : ((2 * pp) * 16 + fq * 4);
;         *(u32x4*)(rp + nst) = (u32x4){rx[0], ry[0], rx[1], ry[1]};
;       }
;   DI u32x2 pack(int m, int n, float a, float b, float c, float d, float& ss) const {
;     if (n < q_end) { a *= qscale; b *= qscale; c *= qscale; d *= qscale; }
;     else if (n >= z_start) { a = silu_f(a); b = silu_f(b); c = silu_f(c); d = silu_f(d); }
;     ss += a * a + b * b + c * c + d * d;
;     u32x2 v; v.x = pack2(a, b); v.y = pack2(c, d);
.LBB0_1369:
	v_or_b32_e32 v54, 16, v66
	v_ashrrev_i32_e32 v55, 31, v54
	s_waitcnt lgkmcnt(0)
	v_cvt_pk_bf16_f32 v50, v36, v37
	v_lshlrev_b64 v[36:37], 13, v[54:55]
	v_lshl_add_u64 v[36:37], s[18:19], 0, v[36:37]
	v_cvt_pk_bf16_f32 v52, v32, v33
	v_cvt_pk_bf16_f32 v53, v34, v35
	v_cvt_pk_bf16_f32 v34, v40, v41
	v_cvt_pk_bf16_f32 v35, v42, v43
	v_cvt_pk_bf16_f32 v32, v44, v45
	v_cvt_pk_bf16_f32 v33, v46, v47
	v_lshl_add_u64 v[36:37], v[68:69], 1, v[36:37]
	v_cvt_pk_bf16_f32 v51, v38, v39
	v_permlane16_swap_b32_e32 v32, v34
	v_permlane16_swap_b32_e32 v33, v35
	v_lshl_add_u64 v[38:39], v[36:37], 0, v[64:65]
	v_mov_b32_e32 v49, v65
	global_store_dwordx4 v[38:39], v[32:35], off
	v_permlane16_swap_b32_e32 v50, v52
	v_permlane16_swap_b32_e32 v51, v53
	v_lshl_add_u64 v[32:33], v[36:37], 0, v[48:49]
	global_store_dwordx4 v[32:33], v[50:53], off
	s_and_saveexec_b64 s[0:1], s[4:5]
	s_xor_b64 s[0:1], exec, s[0:1]
	s_cbranch_execz .LBB0_1372
	s_cmpk_lt_u32 s38, 0xc00
	s_cbranch_scc1 .LBB0_1372
	v_mul_f32_e32 v32, 0xbfb8aa3b, v28
	v_mul_f32_e32 v33, 0xbfb8aa3b, v29
	v_exp_f32_e32 v32, v32
	v_exp_f32_e32 v33, v33
	s_nop 0
	v_pk_add_f32 v[32:33], v[32:33], 1.0 op_sel_hi:[1,0]
	s_nop 0
	v_rcp_f32_e32 v34, v32
	s_nop 0
	v_mul_f32_e32 v28, v28, v34
	v_mul_f32_e32 v34, 0xbfb8aa3b, v30
	v_mul_f32_e32 v35, 0xbfb8aa3b, v31
	v_exp_f32_e32 v34, v34
	v_exp_f32_e32 v35, v35
	s_nop 0
	v_pk_add_f32 v[34:35], v[34:35], 1.0 op_sel_hi:[1,0]
	v_rcp_f32_e32 v32, v33
	s_nop 0
	v_mul_f32_e32 v29, v29, v32
	v_rcp_f32_e32 v32, v34
	s_nop 0
	v_mul_f32_e32 v30, v30, v32
	v_rcp_f32_e32 v32, v35
	s_nop 0
	v_mul_f32_e32 v31, v31, v32
.LBB0_1372:
	s_andn2_saveexec_b64 s[0:1], s[0:1]
	v_pk_mul_f32 v[28:29], v[28:29], s[28:29] op_sel_hi:[1,0]
	v_pk_mul_f32 v[30:31], v[30:31], s[28:29] op_sel_hi:[1,0]
	s_or_b64 exec, exec, s[0:1]
	s_and_saveexec_b64 s[0:1], s[6:7]
	s_xor_b64 s[0:1], exec, s[0:1]
	s_cbranch_execz .LBB0_1377
	s_cmpk_lt_u32 s38, 0xc00
	s_cbranch_scc1 .LBB0_1377
	v_mul_f32_e32 v32, 0xbfb8aa3b, v24
	v_mul_f32_e32 v33, 0xbfb8aa3b, v25
	v_exp_f32_e32 v32, v32
	v_exp_f32_e32 v33, v33
	s_nop 0
	v_pk_add_f32 v[32:33], v[32:33], 1.0 op_sel_hi:[1,0]
	s_nop 0
	v_rcp_f32_e32 v34, v32
	s_nop 0
	v_mul_f32_e32 v24, v24, v34
	v_mul_f32_e32 v34, 0xbfb8aa3b, v26
	v_mul_f32_e32 v35, 0xbfb8aa3b, v27
	v_exp_f32_e32 v34, v34
	v_exp_f32_e32 v35, v35
	s_nop 0
	v_pk_add_f32 v[34:35], v[34:35], 1.0 op_sel_hi:[1,0]
	v_rcp_f32_e32 v32, v33
	s_nop 0
	v_mul_f32_e32 v25, v25, v32
	v_rcp_f32_e32 v32, v34
	s_nop 0
	v_mul_f32_e32 v26, v26, v32
	v_rcp_f32_e32 v32, v35
	s_nop 0
	v_mul_f32_e32 v27, v27, v32
.LBB0_1377:
	s_andn2_saveexec_b64 s[0:1], s[0:1]
	v_pk_mul_f32 v[24:25], v[24:25], s[28:29] op_sel_hi:[1,0]
	v_pk_mul_f32 v[26:27], v[26:27], s[28:29] op_sel_hi:[1,0]
	s_or_b64 exec, exec, s[0:1]
	s_and_saveexec_b64 s[0:1], s[8:9]
	s_xor_b64 s[0:1], exec, s[0:1]
	s_cbranch_execz .LBB0_1382
	s_cmpk_lt_u32 s38, 0xc00
	s_cbranch_scc1 .LBB0_1382
	v_mul_f32_e32 v32, 0xbfb8aa3b, v20
	v_mul_f32_e32 v33, 0xbfb8aa3b, v21
	v_exp_f32_e32 v32, v32
	v_exp_f32_e32 v33, v33
	s_nop 0
	v_pk_add_f32 v[32:33], v[32:33], 1.0 op_sel_hi:[1,0]
	s_nop 0
	v_rcp_f32_e32 v34, v32
	s_nop 0
	v_mul_f32_e32 v20, v20, v34
	v_mul_f32_e32 v34, 0xbfb8aa3b, v22
	v_mul_f32_e32 v35, 0xbfb8aa3b, v23
	v_exp_f32_e32 v34, v34
	v_exp_f32_e32 v35, v35
	s_nop 0
	v_pk_add_f32 v[34:35], v[34:35], 1.0 op_sel_hi:[1,0]
	v_rcp_f32_e32 v32, v33
	s_nop 0
	v_mul_f32_e32 v21, v21, v32
	v_rcp_f32_e32 v32, v34
	s_nop 0
	v_mul_f32_e32 v22, v22, v32
	v_rcp_f32_e32 v32, v35
	s_nop 0
	v_mul_f32_e32 v23, v23, v32
.LBB0_1382:
	s_andn2_saveexec_b64 s[0:1], s[0:1]
	v_pk_mul_f32 v[20:21], v[20:21], s[28:29] op_sel_hi:[1,0]
	v_pk_mul_f32 v[22:23], v[22:23], s[28:29] op_sel_hi:[1,0]
	s_or_b64 exec, exec, s[0:1]
	s_and_saveexec_b64 s[0:1], s[10:11]
	s_xor_b64 s[0:1], exec, s[0:1]
	s_cbranch_execz .LBB0_1387
	s_cmpk_lt_u32 s38, 0xc00
	s_cbranch_scc1 .LBB0_1387
	v_mul_f32_e32 v32, 0xbfb8aa3b, v16
	v_mul_f32_e32 v33, 0xbfb8aa3b, v17
	v_exp_f32_e32 v32, v32
	v_exp_f32_e32 v33, v33
	s_nop 0
	v_pk_add_f32 v[32:33], v[32:33], 1.0 op_sel_hi:[1,0]
	s_nop 0
	v_rcp_f32_e32 v34, v32
	s_nop 0
	v_mul_f32_e32 v16, v16, v34
	v_mul_f32_e32 v34, 0xbfb8aa3b, v18
	v_mul_f32_e32 v35, 0xbfb8aa3b, v19
	v_exp_f32_e32 v34, v34
	v_exp_f32_e32 v35, v35
	s_nop 0
	v_pk_add_f32 v[34:35], v[34:35], 1.0 op_sel_hi:[1,0]
	v_rcp_f32_e32 v32, v33
	s_nop 0
	v_mul_f32_e32 v17, v17, v32
	v_rcp_f32_e32 v32, v34
	s_nop 0
	v_mul_f32_e32 v18, v18, v32
	v_rcp_f32_e32 v32, v35
	s_nop 0
	v_mul_f32_e32 v19, v19, v32

; DI unsigned pack2(float a, float b) { v2f f = {a, b}; return __builtin_bit_cast(unsigned, __builtin_convertvector(f, v2bf)); }
; DI float silu_f(float v) { return v / (1.f + fexp(-v)); }
;   DI u32x2 pack(int, int, float a, float b, float c, float d, float&) const { u32x2 v; v.x = pack2(a, b); v.y = pack2(c, d); return v; }
; template <class ARow, class Epi>
; DI void gemm_tile(const ARow& arow, long a_kstride, const u16* __restrict__ Bt, long ldb, int K, int m0, int n0,
;                   const Epi& epi, char* smem) {
;     ...
;       for (int ni = 0; ni < 4; ++ni) pk[ni] = epi.pack(m, nh + ni * 16 + fq * 4, acc[ni][mi][0], acc[ni][mi][1], acc[ni][mi][2], acc[ni][mi][3], ss);
;       epi.finish16(m, nh, ss);
;       u16* rp = epi.rowp(m) + nh;
; #pragma unroll
;       for (int pp = 0; pp < 2; ++pp) {
;         u32x2 a = pk[2 * pp], b = pk[2 * pp + 1];
;         const u32x2 rx = __builtin_amdgcn_permlane16_swap(a.x, b.x, false, false);
;         const u32x2 ry = __builtin_amdgcn_permlane16_swap(a.y, b.y, false, false);
;         const int nst = (fq & 1) ? ((2 * pp + 1) * 16 + (fq - 1) * 4) : ((2 * pp) * 16 + fq * 4);
;         *(u32x4*)(rp + nst) = (u32x4){rx[0], ry[0], rx[1], ry[1]};
;       }
;   DI u32x2 pack(int m, int n, float a, float b, float c, float d, float& ss) const {
;     if (n < q_end) { a *= qscale; b *= qscale; c *= qscale; d *= qscale; }
;     else if (n >= z_start) { a = silu_f(a); b = silu_f(b); c = silu_f(c); d = silu_f(d); }
;     ss += a * a + b * b + c * c + d * d;
;     u32x2 v; v.x = pack2(a, b); v.y = pack2(c, d);
.LBB0_1393:
	v_or_b32_e32 v36, 32, v66
	v_ashrrev_i32_e32 v37, 31, v36
	v_cvt_pk_bf16_f32 v32, v20, v21
	v_lshlrev_b64 v[20:21], 13, v[36:37]
	v_lshl_add_u64 v[20:21], s[18:19], 0, v[20:21]
	v_cvt_pk_bf16_f32 v34, v16, v17
	v_cvt_pk_bf16_f32 v35, v18, v19
	v_cvt_pk_bf16_f32 v18, v24, v25
	v_cvt_pk_bf16_f32 v19, v26, v27
	v_cvt_pk_bf16_f32 v16, v28, v29
	v_cvt_pk_bf16_f32 v17, v30, v31
	v_lshl_add_u64 v[20:21], v[68:69], 1, v[20:21]
	s_waitcnt lgkmcnt(0)
	v_cvt_pk_bf16_f32 v33, v22, v23
	v_permlane16_swap_b32_e32 v16, v18
	v_permlane16_swap_b32_e32 v17, v19
	v_lshl_add_u64 v[22:23], v[20:21], 0, v[64:65]
	v_mov_b32_e32 v49, v65
	global_store_dwordx4 v[22:23], v[16:19], off
	v_permlane16_swap_b32_e32 v32, v34
	v_permlane16_swap_b32_e32 v33, v35
	v_lshl_add_u64 v[16:17], v[20:21], 0, v[48:49]
	global_store_dwordx4 v[16:17], v[32:35], off
	s_and_saveexec_b64 s[0:1], s[4:5]
	s_xor_b64 s[0:1], exec, s[0:1]
	s_cbranch_execz .LBB0_1396
	s_cmpk_lt_u32 s38, 0xc00
	s_cbranch_scc1 .LBB0_1396
	v_mul_f32_e32 v16, 0xbfb8aa3b, v12
	v_mul_f32_e32 v17, 0xbfb8aa3b, v13
	v_exp_f32_e32 v16, v16
	v_exp_f32_e32 v17, v17
	s_nop 0
	v_pk_add_f32 v[16:17], v[16:17], 1.0 op_sel_hi:[1,0]
	s_nop 0
	v_rcp_f32_e32 v18, v16
	s_nop 0
	v_mul_f32_e32 v12, v12, v18
	v_mul_f32_e32 v18, 0xbfb8aa3b, v14
	v_mul_f32_e32 v19, 0xbfb8aa3b, v15
	v_exp_f32_e32 v18, v18
	v_exp_f32_e32 v19, v19
	s_nop 0
	v_pk_add_f32 v[18:19], v[18:19], 1.0 op_sel_hi:[1,0]
	v_rcp_f32_e32 v16, v17
	s_nop 0
	v_mul_f32_e32 v13, v13, v16
	v_rcp_f32_e32 v16, v18
	s_nop 0
	v_mul_f32_e32 v14, v14, v16
	v_rcp_f32_e32 v16, v19
	s_nop 0
	v_mul_f32_e32 v15, v15, v16
.LBB0_1396:
	s_andn2_saveexec_b64 s[0:1], s[0:1]
	v_pk_mul_f32 v[12:13], v[12:13], s[28:29] op_sel_hi:[1,0]
	v_pk_mul_f32 v[14:15], v[14:15], s[28:29] op_sel_hi:[1,0]
	s_or_b64 exec, exec, s[0:1]
	s_and_saveexec_b64 s[0:1], s[6:7]
	s_xor_b64 s[0:1], exec, s[0:1]
	s_cbranch_execz .LBB0_1401
	s_cmpk_lt_u32 s38, 0xc00
	s_cbranch_scc1 .LBB0_1401
	v_mul_f32_e32 v16, 0xbfb8aa3b, v8
	v_mul_f32_e32 v17, 0xbfb8aa3b, v9
	v_exp_f32_e32 v16, v16
	v_exp_f32_e32 v17, v17
	s_nop 0
	v_pk_add_f32 v[16:17], v[16:17], 1.0 op_sel_hi:[1,0]
	s_nop 0
	v_rcp_f32_e32 v18, v16
	s_nop 0
	v_mul_f32_e32 v8, v8, v18
	v_mul_f32_e32 v18, 0xbfb8aa3b, v10
	v_mul_f32_e32 v19, 0xbfb8aa3b, v11
	v_exp_f32_e32 v18, v18
	v_exp_f32_e32 v19, v19
	s_nop 0
	v_pk_add_f32 v[18:19], v[18:19], 1.0 op_sel_hi:[1,0]
	v_rcp_f32_e32 v16, v17
	s_nop 0
	v_mul_f32_e32 v9, v9, v16
	v_rcp_f32_e32 v16, v18
	s_nop 0
	v_mul_f32_e32 v10, v10, v16
	v_rcp_f32_e32 v16, v19
	s_nop 0
	v_mul_f32_e32 v11, v11, v16
.LBB0_1401:
	s_andn2_saveexec_b64 s[0:1], s[0:1]
	v_pk_mul_f32 v[8:9], v[8:9], s[28:29] op_sel_hi:[1,0]
	v_pk_mul_f32 v[10:11], v[10:11], s[28:29] op_sel_hi:[1,0]
	s_or_b64 exec, exec, s[0:1]
	s_and_saveexec_b64 s[0:1], s[8:9]
	s_xor_b64 s[0:1], exec, s[0:1]
	s_cbranch_execz .LBB0_1406
	s_cmpk_lt_u32 s38, 0xc00
	s_cbranch_scc1 .LBB0_1406
	v_mul_f32_e32 v16, 0xbfb8aa3b, v4
	v_mul_f32_e32 v17, 0xbfb8aa3b, v5
	v_exp_f32_e32 v16, v16
	v_exp_f32_e32 v17, v17
	s_nop 0
	v_pk_add_f32 v[16:17], v[16:17], 1.0 op_sel_hi:[1,0]
	s_nop 0
	v_rcp_f32_e32 v18, v16
	s_nop 0
	v_mul_f32_e32 v4, v4, v18
	v_mul_f32_e32 v18, 0xbfb8aa3b, v6
	v_mul_f32_e32 v19, 0xbfb8aa3b, v7
	v_exp_f32_e32 v18, v18
	v_exp_f32_e32 v19, v19
	s_nop 0
	v_pk_add_f32 v[18:19], v[18:19], 1.0 op_sel_hi:[1,0]
	v_rcp_f32_e32 v16, v17
	s_nop 0
	v_mul_f32_e32 v5, v5, v16
	v_rcp_f32_e32 v16, v18
	s_nop 0
	v_mul_f32_e32 v6, v6, v16
	v_rcp_f32_e32 v16, v19
	s_nop 0
	v_mul_f32_e32 v7, v7, v16
.LBB0_1406:
	s_andn2_saveexec_b64 s[0:1], s[0:1]
	v_pk_mul_f32 v[4:5], v[4:5], s[28:29] op_sel_hi:[1,0]
	v_pk_mul_f32 v[6:7], v[6:7], s[28:29] op_sel_hi:[1,0]
	s_or_b64 exec, exec, s[0:1]
	s_and_saveexec_b64 s[0:1], s[10:11]
	s_xor_b64 s[0:1], exec, s[0:1]
	s_cbranch_execz .LBB0_1411
	s_cmpk_lt_u32 s38, 0xc00
	s_cbranch_scc1 .LBB0_1411
	v_mul_f32_e32 v16, 0xbfb8aa3b, v0
	v_mul_f32_e32 v17, 0xbfb8aa3b, v1
	v_exp_f32_e32 v16, v16
	v_exp_f32_e32 v17, v17
	s_nop 0
	v_pk_add_f32 v[16:17], v[16:17], 1.0 op_sel_hi:[1,0]
	s_nop 0
	v_rcp_f32_e32 v18, v16
	s_nop 0
	v_mul_f32_e32 v0, v0, v18
	v_mul_f32_e32 v18, 0xbfb8aa3b, v2
	v_mul_f32_e32 v19, 0xbfb8aa3b, v3
	v_exp_f32_e32 v18, v18
	v_exp_f32_e32 v19, v19
	s_nop 0
	v_pk_add_f32 v[18:19], v[18:19], 1.0 op_sel_hi:[1,0]
	v_rcp_f32_e32 v16, v17
	s_nop 0
	v_mul_f32_e32 v1, v1, v16
	v_rcp_f32_e32 v16, v18
	s_nop 0
	v_mul_f32_e32 v2, v2, v16
	v_rcp_f32_e32 v16, v19
	s_nop 0
	v_mul_f32_e32 v3, v3, v16

; template <class ARow, class Epi>
; DI void gemm_tile(const ARow& arow, long a_kstride, const u16* __restrict__ Bt, long ldb, int K, int m0, int n0,
;                   const Epi& epi, char* smem) {
;     ...
;   for (int kt = 0; kt < KT; ++kt) {
;     const int cur = kt & 1;
;     if (kt + 1 < KT) GEMM_STAGE(cur ^ 1, kt + 1);
;     const char* sa = smem + cur * 32768 + wm * 64 * 128;
;     const char* sb = smem + cur * 32768 + 16384 + wn * 64 * 128;
; #pragma unroll
;     for (int ks = 0; ks < 2; ++ks) {
;       bf16x8 wf[4], af[4];
; #pragma unroll
;       for (int j = 0; j < 4; ++j) {
;         wf[j] = *(const bf16x8*)(sb + j * 2048 + foff[ks]);
;         af[j] = *(const bf16x8*)(sa + j * 2048 + foff[ks]);
;       }
; #pragma unroll
;       for (int ni = 0; ni < 4; ++ni)
; #pragma unroll
;         for (int mi = 0; mi < 4; ++mi) acc[ni][mi] = __builtin_amdgcn_mfma_f32_16x16x32_bf16(wf[ni], af[mi], acc[ni][mi], 0, 0, 0);
;     }
;     asm volatile("s_waitcnt vmcnt(0)" ::: "memory");
;     __syncthreads();
;   }
.LBB0_1702:
	s_and_b32 s6, s1, 0x8000
	s_xor_b32 s7, s6, 0x8000
	v_add_u32_e32 v108, s7, v90
	v_add_u32_e32 v91, s6, v88
	v_or_b32_e32 v116, s6, v89
	v_readfirstlane_b32 s6, v108
	v_add_u32_e32 v109, 0x4000, v108
	v_lshl_add_u64 v[92:93], v[66:67], 0, s[4:5]
	v_add_u32_e32 v110, 0x400, v108
	v_readfirstlane_b32 s7, v109
	s_mov_b32 m0, s6
	v_lshl_add_u64 v[94:95], v[68:69], 0, s[4:5]
	v_add_u32_e32 v111, 0x4400, v108
	v_readfirstlane_b32 s8, v110
	global_load_lds_dwordx4 v[92:93], off
	s_mov_b32 m0, s7
	v_lshl_add_u64 v[96:97], v[70:71], 0, s[4:5]
	v_add_u32_e32 v113, 0x800, v108
	v_readfirstlane_b32 s9, v111
	global_load_lds_dwordx4 v[94:95], off
	s_mov_b32 m0, s8
	v_lshl_add_u64 v[98:99], v[72:73], 0, s[4:5]
	v_add_u32_e32 v114, 0x4800, v108
	v_readfirstlane_b32 s10, v113
	global_load_lds_dwordx4 v[96:97], off
	s_mov_b32 m0, s9
	v_lshl_add_u64 v[100:101], v[74:75], 0, s[4:5]
	v_add_u32_e32 v115, 0xc00, v108
	v_readfirstlane_b32 s11, v114
	global_load_lds_dwordx4 v[98:99], off
	s_mov_b32 m0, s10
	v_lshl_add_u64 v[102:103], v[76:77], 0, s[4:5]
	v_add_u32_e32 v108, 0x4c00, v108
	v_readfirstlane_b32 s26, v115
	global_load_lds_dwordx4 v[100:101], off
	s_mov_b32 m0, s11
	v_lshl_add_u64 v[104:105], v[78:79], 0, s[4:5]
	v_readfirstlane_b32 s27, v108
	global_load_lds_dwordx4 v[102:103], off
	s_mov_b32 m0, s26
	v_lshl_add_u64 v[106:107], v[80:81], 0, s[4:5]
	global_load_lds_dwordx4 v[104:105], off
	s_mov_b32 m0, s27
	v_add_u32_e32 v117, v116, v87
	global_load_lds_dwordx4 v[106:107], off
	v_add_u32_e32 v112, v91, v87
	ds_read_b128 v[92:95], v117 offset:16384
	ds_read_b128 v[96:99], v112
	ds_read_b128 v[100:103], v117 offset:18432
	ds_read_b128 v[104:107], v112 offset:2048
	ds_read_b128 v[108:111], v112 offset:4096
	ds_read_b128 v[112:115], v112 offset:6144
	s_waitcnt lgkmcnt(0)
	v_mfma_f32_16x16x32_bf16 v[60:63], v[92:95], v[96:99], v[60:63]
	v_add_u32_e32 v116, v116, v86
	v_add_u32_e32 v91, v91, v86
	s_add_i32 s1, s1, 0x8000
	v_mfma_f32_16x16x32_bf16 v[56:59], v[92:95], v[104:107], v[56:59]
	s_add_u32 s4, s4, 0x80
	s_addc_u32 s5, s5, 0
	s_cmpk_eq_i32 s4, 0x780
	v_mfma_f32_16x16x32_bf16 v[48:51], v[92:95], v[108:111], v[48:51]
	v_mfma_f32_16x16x32_bf16 v[40:43], v[92:95], v[112:115], v[40:43]
	v_mfma_f32_16x16x32_bf16 v[36:39], v[100:103], v[96:99], v[36:39]
	v_mfma_f32_16x16x32_bf16 v[32:35], v[100:103], v[104:107], v[32:35]
	v_mfma_f32_16x16x32_bf16 v[28:31], v[100:103], v[108:111], v[28:31]
	v_mfma_f32_16x16x32_bf16 v[24:27], v[100:103], v[112:115], v[24:27]
	ds_read_b128 v[92:95], v117 offset:20480
	ds_read_b128 v[100:103], v117 offset:22528
	s_waitcnt lgkmcnt(0)
	v_mfma_f32_16x16x32_bf16 v[20:23], v[92:95], v[96:99], v[20:23]
	v_mfma_f32_16x16x32_bf16 v[16:19], v[92:95], v[104:107], v[16:19]
	v_mfma_f32_16x16x32_bf16 v[12:15], v[92:95], v[108:111], v[12:15]
	v_mfma_f32_16x16x32_bf16 v[8:11], v[92:95], v[112:115], v[8:11]
	ds_read_b128 v[92:95], v116 offset:16384
	v_mfma_f32_16x16x32_bf16 v[4:7], v[100:103], v[96:99], v[4:7]
	v_mfma_f32_16x16x32_bf16 v[0:3], v[100:103], v[104:107], v[0:3]
	v_mfma_f32_16x16x32_bf16 v[52:55], v[100:103], v[108:111], v[52:55]
	v_mfma_f32_16x16x32_bf16 v[44:47], v[100:103], v[112:115], v[44:47]
	ds_read_b128 v[96:99], v91
	ds_read_b128 v[100:103], v116 offset:18432
	ds_read_b128 v[104:107], v91 offset:2048
	ds_read_b128 v[108:111], v91 offset:4096
	ds_read_b128 v[112:115], v91 offset:6144
	s_waitcnt lgkmcnt(0)
	v_mfma_f32_16x16x32_bf16 v[60:63], v[92:95], v[96:99], v[60:63]
	v_mfma_f32_16x16x32_bf16 v[56:59], v[92:95], v[104:107], v[56:59]
	v_mfma_f32_16x16x32_bf16 v[48:51], v[92:95], v[108:111], v[48:51]
	v_mfma_f32_16x16x32_bf16 v[40:43], v[92:95], v[112:115], v[40:43]
	v_mfma_f32_16x16x32_bf16 v[36:39], v[100:103], v[96:99], v[36:39]
	v_mfma_f32_16x16x32_bf16 v[32:35], v[100:103], v[104:107], v[32:35]
	v_mfma_f32_16x16x32_bf16 v[28:31], v[100:103], v[108:111], v[28:31]
	v_mfma_f32_16x16x32_bf16 v[24:27], v[100:103], v[112:115], v[24:27]
	ds_read_b128 v[92:95], v116 offset:20480
	ds_read_b128 v[100:103], v116 offset:22528
	s_waitcnt vmcnt(0)
	s_waitcnt vmcnt(0) lgkmcnt(0)
	v_mfma_f32_16x16x32_bf16 v[20:23], v[92:95], v[96:99], v[20:23]
	s_barrier
	v_mfma_f32_16x16x32_bf16 v[16:19], v[92:95], v[104:107], v[16:19]
	v_mfma_f32_16x16x32_bf16 v[12:15], v[92:95], v[108:111], v[12:15]
	v_mfma_f32_16x16x32_bf16 v[8:11], v[92:95], v[112:115], v[8:11]
	v_mfma_f32_16x16x32_bf16 v[4:7], v[100:103], v[96:99], v[4:7]
	v_mfma_f32_16x16x32_bf16 v[0:3], v[100:103], v[104:107], v[0:3]
	v_mfma_f32_16x16x32_bf16 v[52:55], v[100:103], v[108:111], v[52:55]
	v_mfma_f32_16x16x32_bf16 v[44:47], v[100:103], v[112:115], v[44:47]
	s_cbranch_scc0 .LBB0_1702
; DI float sigmoid_f(float v) { return 1.f / (1.f + fexp(-v)); }
;   DI void operator()(int m, int n, float a, float b, float c, float d, float& ss) const { u32x2 v; v.x = pack2(a, b); v.y = pack2(c, d); *(u32x2*)(y + (long)m * 1024 + n) = v; }
; template <class ARow, class Epi>
; DI void gemm_tile(const ARow& arow, long a_kstride, const u16* __restrict__ Bt, long ldb, int K, int m0, int n0,
;                   const Epi& epi, char* smem) {
;     ...
;   for (int kt = 0; kt < KT; ++kt) {
;     const int cur = kt & 1;
;     if (kt + 1 < KT) GEMM_STAGE(cur ^ 1, kt + 1);
;     const char* sa = smem + cur * 32768 + wm * 64 * 128;
;     const char* sb = smem + cur * 32768 + 16384 + wn * 64 * 128;
; #pragma unroll
;     for (int ks = 0; ks < 2; ++ks) {
;       bf16x8 wf[4], af[4];
; #pragma unroll
;       for (int j = 0; j < 4; ++j) {
;         wf[j] = *(const bf16x8*)(sb + j * 2048 + foff[ks]);
;         af[j] = *(const bf16x8*)(sa + j * 2048 + foff[ks]);
;       }
; #pragma unroll
;       for (int ni = 0; ni < 4; ++ni)
; #pragma unroll
;         for (int mi = 0; mi < 4; ++mi) acc[ni][mi] = __builtin_amdgcn_mfma_f32_16x16x32_bf16(wf[ni], af[mi], acc[ni][mi], 0, 0, 0);
;     }
;     asm volatile("s_waitcnt vmcnt(0)" ::: "memory");
;     __syncthreads();
;   }
;     ...
;   const int nh = n0 + wn * 64;
;   if (epi.packed(nh)) {
;   DI void operator()(int m, int n, float a, float b, float c, float d, float& ss) const {
;     if (n >= gl_start) {
;       const int j = n - gl_start;
;       if (j < 48) { float* g = gates + (long)m * 48 + j; g[0] = sigmoid_f(a); g[1] = sigmoid_f(b); g[2] = sigmoid_f(c); g[3] = sigmoid_f(d); }
;       return;
	v_add_u32_e32 v106, v89, v87
	ds_read_b128 v[66:69], v106 offset:49152
	v_add_u32_e32 v87, v88, v87
	ds_read_b128 v[70:73], v87 offset:32768
	ds_read_b128 v[74:77], v87 offset:34816
	ds_read_b128 v[78:81], v87 offset:36864
	ds_read_b128 v[90:93], v87 offset:38912
	v_add_u32_e32 v114, v89, v86
	s_waitcnt lgkmcnt(3)
	v_mfma_f32_16x16x32_bf16 v[60:63], v[66:69], v[70:73], v[60:63]
	s_waitcnt lgkmcnt(2)
	v_mfma_f32_16x16x32_bf16 v[56:59], v[66:69], v[74:77], v[56:59]
	s_waitcnt lgkmcnt(1)
	v_mfma_f32_16x16x32_bf16 v[48:51], v[66:69], v[78:81], v[48:51]
	s_waitcnt lgkmcnt(0)
	v_mfma_f32_16x16x32_bf16 v[40:43], v[66:69], v[90:93], v[40:43]
	ds_read_b128 v[66:69], v106 offset:51200
	s_waitcnt lgkmcnt(0)
	v_mfma_f32_16x16x32_bf16 v[36:39], v[66:69], v[70:73], v[36:39]
	v_mfma_f32_16x16x32_bf16 v[32:35], v[66:69], v[74:77], v[32:35]
	v_mfma_f32_16x16x32_bf16 v[94:97], v[66:69], v[78:81], v[28:31]
	v_mfma_f32_16x16x32_bf16 v[66:69], v[66:69], v[90:93], v[24:27]
	s_nop 2
	ds_read_b128 v[24:27], v106 offset:53248
	s_waitcnt lgkmcnt(0)
	v_mfma_f32_16x16x32_bf16 v[102:105], v[24:27], v[90:93], v[8:11]
	s_nop 2
	ds_read_b128 v[8:11], v106 offset:55296
	v_mfma_f32_16x16x32_bf16 v[20:23], v[24:27], v[70:73], v[20:23]
	s_waitcnt lgkmcnt(0)
	v_mfma_f32_16x16x32_bf16 v[70:73], v[8:11], v[70:73], v[4:7]
	s_nop 2
	ds_read_b128 v[4:7], v114 offset:49152
	v_mfma_f32_16x16x32_bf16 v[98:101], v[24:27], v[78:81], v[12:15]
	s_nop 2
	v_add_u32_e32 v12, v88, v86
	v_mfma_f32_16x16x32_bf16 v[16:19], v[24:27], v[74:77], v[16:19]
	ds_read_b128 v[86:89], v12 offset:32768
	ds_read_b128 v[106:109], v12 offset:36864
	ds_read_b128 v[110:113], v12 offset:38912
	v_mfma_f32_16x16x32_bf16 v[0:3], v[8:11], v[74:77], v[0:3]
	v_mfma_f32_16x16x32_bf16 v[74:77], v[8:11], v[78:81], v[52:55]
	v_mfma_f32_16x16x32_bf16 v[78:81], v[8:11], v[90:93], v[44:47]
	ds_read_b128 v[90:93], v12 offset:34816
	s_waitcnt lgkmcnt(3)
	v_mfma_f32_16x16x32_bf16 v[60:63], v[4:7], v[86:89], v[60:63]
	s_waitcnt lgkmcnt(0)
	v_mfma_f32_16x16x32_bf16 v[44:47], v[4:7], v[90:93], v[56:59]
	v_mfma_f32_16x16x32_bf16 v[28:31], v[4:7], v[106:109], v[48:51]
	v_mfma_f32_16x16x32_bf16 v[12:15], v[4:7], v[110:113], v[40:43]
	ds_read_b128 v[4:7], v114 offset:51200
	s_waitcnt lgkmcnt(0)
	v_mfma_f32_16x16x32_bf16 v[56:59], v[4:7], v[86:89], v[36:39]
	v_mfma_f32_16x16x32_bf16 v[40:43], v[4:7], v[90:93], v[32:35]
	v_mfma_f32_16x16x32_bf16 v[24:27], v[4:7], v[106:109], v[94:97]
	v_mfma_f32_16x16x32_bf16 v[8:11], v[4:7], v[110:113], v[66:69]
	ds_read_b128 v[4:7], v114 offset:53248
	s_nop 0
	ds_read_b128 v[94:97], v114 offset:55296
	s_waitcnt vmcnt(0)
	s_waitcnt lgkmcnt(0)
	v_mfma_f32_16x16x32_bf16 v[32:35], v[94:97], v[90:93], v[0:3]
	s_nop 2
	v_or_b32_e32 v0, s0, v64
	v_lshl_or_b32 v66, v84, 6, s35
	v_lshlrev_b32_e32 v68, 2, v83
	v_mfma_f32_16x16x32_bf16 v[52:55], v[4:7], v[86:89], v[20:23]
	v_cmp_lt_i32_e32 vcc, s30, v66
	v_or_b32_e32 v64, v66, v68
	v_mfma_f32_16x16x32_bf16 v[36:39], v[4:7], v[90:93], v[16:19]
	s_barrier
	v_mfma_f32_16x16x32_bf16 v[20:23], v[4:7], v[106:109], v[98:101]
	v_mfma_f32_16x16x32_bf16 v[4:7], v[4:7], v[110:113], v[102:105]
	v_mfma_f32_16x16x32_bf16 v[48:51], v[94:97], v[86:89], v[70:73]
	v_mfma_f32_16x16x32_bf16 v[16:19], v[94:97], v[106:109], v[74:77]
	s_nop 2
	v_lshl_add_u32 v74, v85, 6, v0
	v_mfma_f32_16x16x32_bf16 v[0:3], v[94:97], v[110:113], v[78:81]
	s_and_saveexec_b64 s[0:1], vcc
	s_xor_b64 s[26:27], exec, s[0:1]
	s_cbranch_execz .LBB0_1849
	v_mad_i64_i32 v[68:69], s[0:1], v74, s31, 0
	v_cmp_lt_i32_e64 s[4:5], s30, v64
	v_add_u32_e32 v66, -2.0, v64
	s_and_saveexec_b64 s[0:1], s[4:5]
	s_xor_b64 s[0:1], exec, s[0:1]
	s_cbranch_execz .LBB0_1708
	v_cmp_gt_u32_e32 vcc, 48, v66
	s_and_saveexec_b64 s[6:7], vcc
	s_cbranch_execz .LBB0_1707
	v_mul_f32_e32 v60, 0xbfb8aa3b, v60
	v_mul_f32_e32 v61, 0xbfb8aa3b, v61
	v_exp_f32_e32 v60, v60
	v_exp_f32_e32 v61, v61
	v_mov_b32_e32 v67, v65
	v_lshl_add_u64 v[70:71], v[66:67], 2, v[68:69]
	v_mul_f32_e32 v62, 0xbfb8aa3b, v62
	v_pk_add_f32 v[60:61], v[60:61], 1.0 op_sel_hi:[1,0]
	v_mul_f32_e32 v63, 0xbfb8aa3b, v63
	v_exp_f32_e32 v62, v62
	v_exp_f32_e32 v63, v63
	v_rcp_f32_e32 v67, v61
	s_nop 0
	v_mul_f32_e32 v61, 1.0, v67
	v_pk_add_f32 v[62:63], v[62:63], 1.0 op_sel_hi:[1,0]
	v_rcp_f32_e32 v67, v60
	s_nop 0
	v_mul_f32_e32 v60, 1.0, v67
	v_rcp_f32_e32 v67, v63
	s_nop 0
	v_mul_f32_e32 v63, 1.0, v67
	v_rcp_f32_e32 v67, v62
	s_nop 0
	v_mul_f32_e32 v62, 1.0, v67
	flat_store_dwordx4 v[70:71], v[60:63]

; DI unsigned pack2(float a, float b) { v2f f = {a, b}; return __builtin_bit_cast(unsigned, __builtin_convertvector(f, v2bf)); }
; DI float fexp(float x) { return __builtin_amdgcn_exp2f(x * LOG2E); }
; DI float silu_f(float v) { return v / (1.f + fexp(-v)); }
;   DI void operator()(int m, int n, float a, float b, float c, float d, float& ss) const {
;     ...
;     if (n < q_end) { a *= qscale; b *= qscale; c *= qscale; d *= qscale; }
;     else if (n >= z_start) { a = silu_f(a); b = silu_f(b); c = silu_f(c); d = silu_f(d); }
;     ss += a * a + b * b + c * c + d * d;
;     u32x2 v; v.x = pack2(a, b); v.y = pack2(c, d);
;     *(u32x2*)(dst + (long)m * ld + n) = v;
.LBB0_1708:
	s_andn2_saveexec_b64 s[0:1], s[0:1]
	s_cbranch_execz .LBB0_1714
	v_cmp_lt_i32_e32 vcc, s33, v64
	s_and_saveexec_b64 s[6:7], vcc
	s_xor_b64 s[6:7], exec, s[6:7]
	s_cbranch_execz .LBB0_1711
	v_mul_f32_e32 v67, 0xbfb8aa3b, v60
	v_exp_f32_e32 v70, v67
	v_mul_f32_e32 v67, 0xbfb8aa3b, v61
	v_exp_f32_e32 v71, v67
	s_nop 0
	v_pk_add_f32 v[70:71], v[70:71], 1.0 op_sel_hi:[1,0]
	s_nop 0
	v_rcp_f32_e32 v67, v71
	v_mul_f32_e32 v72, 0xbfb8aa3b, v62
	v_mul_f32_e32 v73, 0xbfb8aa3b, v63
	v_exp_f32_e32 v72, v72
	v_exp_f32_e32 v73, v73
	v_mul_f32_e32 v71, v61, v67
	v_pk_add_f32 v[72:73], v[72:73], 1.0 op_sel_hi:[1,0]
	v_rcp_f32_e32 v61, v70
	s_nop 0
	v_mul_f32_e32 v70, v60, v61
	v_rcp_f32_e32 v60, v73
	s_nop 0
	v_mul_f32_e32 v73, v63, v60
	v_rcp_f32_e32 v60, v72
	s_nop 0
	v_mul_f32_e32 v72, v62, v60

; DI float fexp(float x) { return __builtin_amdgcn_exp2f(x * LOG2E); }
; DI float sigmoid_f(float v) { return 1.f / (1.f + fexp(-v)); }
;   DI void operator()(int m, int n, float a, float b, float c, float d, float& ss) const {
;     if (n >= gl_start) {
;       const int j = n - gl_start;
;       if (j < 48) { float* g = gates + (long)m * 48 + j; g[0] = sigmoid_f(a); g[1] = sigmoid_f(b); g[2] = sigmoid_f(c); g[3] = sigmoid_f(d); }
;       return;
.LBB0_1714:
	s_or_b64 exec, exec, s[0:1]
	v_or_b32_e32 v72, 16, v64
	v_cmp_lt_i32_e64 s[6:7], s30, v72
	v_add_u32_e32 v60, 0xc0000010, v64
	s_and_saveexec_b64 s[0:1], s[6:7]
	s_xor_b64 s[0:1], exec, s[0:1]
	s_cbranch_execz .LBB0_1718
	v_cmp_gt_u32_e32 vcc, 48, v60
	s_and_saveexec_b64 s[8:9], vcc
	s_cbranch_execz .LBB0_1717
	v_mul_f32_e32 v56, 0xbfb8aa3b, v56
	v_mul_f32_e32 v57, 0xbfb8aa3b, v57
	v_exp_f32_e32 v56, v56
	v_exp_f32_e32 v57, v57
	v_mov_b32_e32 v61, v65
	v_lshl_add_u64 v[62:63], v[60:61], 2, v[68:69]
	v_mul_f32_e32 v58, 0xbfb8aa3b, v58
	v_pk_add_f32 v[56:57], v[56:57], 1.0 op_sel_hi:[1,0]
	v_mul_f32_e32 v59, 0xbfb8aa3b, v59
	v_exp_f32_e32 v58, v58
	v_exp_f32_e32 v59, v59
	v_rcp_f32_e32 v61, v57
	s_nop 0
	v_mul_f32_e32 v57, 1.0, v61
	v_pk_add_f32 v[58:59], v[58:59], 1.0 op_sel_hi:[1,0]
	v_rcp_f32_e32 v61, v56
	s_nop 0
	v_mul_f32_e32 v56, 1.0, v61
	v_rcp_f32_e32 v61, v59
	s_nop 0
	v_mul_f32_e32 v59, 1.0, v61
	v_rcp_f32_e32 v61, v58
	s_nop 0
	v_mul_f32_e32 v58, 1.0, v61
	flat_store_dwordx4 v[62:63], v[56:59]

; DI unsigned pack2(float a, float b) { v2f f = {a, b}; return __builtin_bit_cast(unsigned, __builtin_convertvector(f, v2bf)); }
; DI float fexp(float x) { return __builtin_amdgcn_exp2f(x * LOG2E); }
; DI float silu_f(float v) { return v / (1.f + fexp(-v)); }
;   DI void operator()(int m, int n, float a, float b, float c, float d, float& ss) const {
;     ...
;     if (n < q_end) { a *= qscale; b *= qscale; c *= qscale; d *= qscale; }
;     else if (n >= z_start) { a = silu_f(a); b = silu_f(b); c = silu_f(c); d = silu_f(d); }
;     ss += a * a + b * b + c * c + d * d;
;     u32x2 v; v.x = pack2(a, b); v.y = pack2(c, d);
;     *(u32x2*)(dst + (long)m * ld + n) = v;
.LBB0_1718:
	s_andn2_saveexec_b64 s[0:1], s[0:1]
	s_cbranch_execz .LBB0_1724
	v_cmp_lt_i32_e32 vcc, s33, v72
	s_and_saveexec_b64 s[8:9], vcc
	s_xor_b64 s[8:9], exec, s[8:9]
	s_cbranch_execz .LBB0_1721
	v_mul_f32_e32 v61, 0xbfb8aa3b, v56
	v_exp_f32_e32 v62, v61
	v_mul_f32_e32 v61, 0xbfb8aa3b, v57
	v_exp_f32_e32 v63, v61
	s_nop 0
	v_pk_add_f32 v[62:63], v[62:63], 1.0 op_sel_hi:[1,0]
	s_nop 0
	v_rcp_f32_e32 v61, v63
	v_mul_f32_e32 v67, 0xbfb8aa3b, v58
	v_exp_f32_e32 v70, v67
	v_mul_f32_e32 v67, 0xbfb8aa3b, v59
	v_exp_f32_e32 v71, v67
	v_mul_f32_e32 v63, v57, v61
	v_pk_add_f32 v[70:71], v[70:71], 1.0 op_sel_hi:[1,0]
	v_rcp_f32_e32 v57, v62
	s_nop 0
	v_mul_f32_e32 v62, v56, v57
	v_rcp_f32_e32 v56, v71
	s_nop 0
	v_mul_f32_e32 v71, v59, v56
	v_rcp_f32_e32 v56, v70
	s_nop 0
	v_mul_f32_e32 v70, v58, v56

; DI float fexp(float x) { return __builtin_amdgcn_exp2f(x * LOG2E); }
; DI float sigmoid_f(float v) { return 1.f / (1.f + fexp(-v)); }
;   DI void operator()(int m, int n, float a, float b, float c, float d, float& ss) const {
;     if (n >= gl_start) {
;       const int j = n - gl_start;
;       if (j < 48) { float* g = gates + (long)m * 48 + j; g[0] = sigmoid_f(a); g[1] = sigmoid_f(b); g[2] = sigmoid_f(c); g[3] = sigmoid_f(d); }
;       return;
.LBB0_1724:
	s_or_b64 exec, exec, s[0:1]
	v_or_b32_e32 v70, 32, v64
	v_cmp_lt_i32_e64 s[8:9], s30, v70
	v_add_u32_e32 v56, 0xc0000020, v64
	s_and_saveexec_b64 s[0:1], s[8:9]
	s_xor_b64 s[0:1], exec, s[0:1]
	s_cbranch_execz .LBB0_1728
	v_cmp_gt_u32_e32 vcc, 48, v56
	s_and_saveexec_b64 s[10:11], vcc
	s_cbranch_execz .LBB0_1727
	v_mul_f32_e32 v52, 0xbfb8aa3b, v52
	v_mul_f32_e32 v53, 0xbfb8aa3b, v53
	v_exp_f32_e32 v52, v52
	v_exp_f32_e32 v53, v53
	v_mov_b32_e32 v57, v65
	v_lshl_add_u64 v[58:59], v[56:57], 2, v[68:69]
	v_mul_f32_e32 v54, 0xbfb8aa3b, v54
	v_pk_add_f32 v[52:53], v[52:53], 1.0 op_sel_hi:[1,0]
	v_mul_f32_e32 v55, 0xbfb8aa3b, v55
	v_exp_f32_e32 v54, v54
	v_exp_f32_e32 v55, v55
	v_rcp_f32_e32 v57, v53
	s_nop 0
	v_mul_f32_e32 v53, 1.0, v57
	v_pk_add_f32 v[54:55], v[54:55], 1.0 op_sel_hi:[1,0]
	v_rcp_f32_e32 v57, v52
	s_nop 0
	v_mul_f32_e32 v52, 1.0, v57
	v_rcp_f32_e32 v57, v55
	s_nop 0
	v_mul_f32_e32 v55, 1.0, v57
	v_rcp_f32_e32 v57, v54
	s_nop 0
	v_mul_f32_e32 v54, 1.0, v57
	flat_store_dwordx4 v[58:59], v[52:55]

; DI unsigned pack2(float a, float b) { v2f f = {a, b}; return __builtin_bit_cast(unsigned, __builtin_convertvector(f, v2bf)); }
; DI float fexp(float x) { return __builtin_amdgcn_exp2f(x * LOG2E); }
; DI float silu_f(float v) { return v / (1.f + fexp(-v)); }
;   DI void operator()(int m, int n, float a, float b, float c, float d, float& ss) const {
;     ...
;     if (n < q_end) { a *= qscale; b *= qscale; c *= qscale; d *= qscale; }
;     else if (n >= z_start) { a = silu_f(a); b = silu_f(b); c = silu_f(c); d = silu_f(d); }
;     ss += a * a + b * b + c * c + d * d;
;     u32x2 v; v.x = pack2(a, b); v.y = pack2(c, d);
;     *(u32x2*)(dst + (long)m * ld + n) = v;
.LBB0_1728:
	s_andn2_saveexec_b64 s[0:1], s[0:1]
	s_cbranch_execz .LBB0_1734
	v_cmp_lt_i32_e32 vcc, s33, v70
	s_and_saveexec_b64 s[10:11], vcc
	s_xor_b64 s[10:11], exec, s[10:11]
	s_cbranch_execz .LBB0_1731
	v_mul_f32_e32 v57, 0xbfb8aa3b, v52
	v_exp_f32_e32 v58, v57
	v_mul_f32_e32 v57, 0xbfb8aa3b, v53
	v_exp_f32_e32 v59, v57
	s_nop 0
	v_pk_add_f32 v[58:59], v[58:59], 1.0 op_sel_hi:[1,0]
	s_nop 0
	v_rcp_f32_e32 v57, v59
	v_mul_f32_e32 v61, 0xbfb8aa3b, v54
	v_exp_f32_e32 v62, v61
	v_mul_f32_e32 v61, 0xbfb8aa3b, v55
	v_exp_f32_e32 v63, v61
	v_mul_f32_e32 v59, v53, v57
	v_pk_add_f32 v[62:63], v[62:63], 1.0 op_sel_hi:[1,0]
	v_rcp_f32_e32 v53, v58
	s_nop 0
	v_mul_f32_e32 v58, v52, v53
	v_rcp_f32_e32 v52, v63
	s_nop 0
	v_mul_f32_e32 v63, v55, v52
	v_rcp_f32_e32 v52, v62
	s_nop 0
	v_mul_f32_e32 v62, v54, v52

; DI unsigned pack2(float a, float b) { v2f f = {a, b}; return __builtin_bit_cast(unsigned, __builtin_convertvector(f, v2bf)); }
; DI float fexp(float x) { return __builtin_amdgcn_exp2f(x * LOG2E); }
; DI float sigmoid_f(float v) { return 1.f / (1.f + fexp(-v)); }
;   DI void operator()(int m, int n, float a, float b, float c, float d, float& ss) const { u32x2 v; v.x = pack2(a, b); v.y = pack2(c, d); *(u32x2*)(y + (long)m * 1024 + n) = v; }
; DI float silu_f(float v) { return v / (1.f + fexp(-v)); }
;   DI void operator()(int m, int n, float a, float b, float c, float d, float& ss) const {
;     if (n >= gl_start) {
;       const int j = n - gl_start;
;       if (j < 48) { float* g = gates + (long)m * 48 + j; g[0] = sigmoid_f(a); g[1] = sigmoid_f(b); g[2] = sigmoid_f(c); g[3] = sigmoid_f(d); }
;       return;
;     }
;     if (n < q_end) { a *= qscale; b *= qscale; c *= qscale; d *= qscale; }
;     else if (n >= z_start) { a = silu_f(a); b = silu_f(b); c = silu_f(c); d = silu_f(d); }
;     ss += a * a + b * b + c * c + d * d;
;     u32x2 v; v.x = pack2(a, b); v.y = pack2(c, d);
;     *(u32x2*)(dst + (long)m * ld + n) = v;
.LBB0_1734:
	s_or_b64 exec, exec, s[0:1]
	v_or_b32_e32 v58, 48, v64
	v_cmp_gt_i32_e64 s[10:11], 2.0, v58
	s_and_saveexec_b64 s[0:1], s[10:11]
	s_cbranch_execz .LBB0_1740
	v_cmp_lt_i32_e32 vcc, s33, v58
	s_and_saveexec_b64 s[28:29], vcc
	s_xor_b64 s[28:29], exec, s[28:29]
	s_cbranch_execz .LBB0_1737
	v_mul_f32_e32 v52, 0xbfb8aa3b, v48
	v_mul_f32_e32 v53, 0xbfb8aa3b, v49
	v_exp_f32_e32 v52, v52
	v_exp_f32_e32 v53, v53
	s_nop 0
	v_pk_add_f32 v[52:53], v[52:53], 1.0 op_sel_hi:[1,0]
	s_nop 0
	v_rcp_f32_e32 v54, v53
	s_nop 0
	v_mul_f32_e32 v53, v49, v54
	v_mul_f32_e32 v54, 0xbfb8aa3b, v50
	v_mul_f32_e32 v55, 0xbfb8aa3b, v51
	v_exp_f32_e32 v54, v54
	v_exp_f32_e32 v55, v55
	s_nop 0
	v_pk_add_f32 v[54:55], v[54:55], 1.0 op_sel_hi:[1,0]
	v_rcp_f32_e32 v49, v52
	s_nop 0
	v_mul_f32_e32 v52, v48, v49
	v_rcp_f32_e32 v48, v55
	s_nop 0
	v_mul_f32_e32 v55, v51, v48
	v_rcp_f32_e32 v48, v54
	s_nop 0
	v_mul_f32_e32 v54, v50, v48

; DI float fexp(float x) { return __builtin_amdgcn_exp2f(x * LOG2E); }
; DI float sigmoid_f(float v) { return 1.f / (1.f + fexp(-v)); }
;   DI void operator()(int m, int n, float a, float b, float c, float d, float& ss) const {
;     if (n >= gl_start) {
;       const int j = n - gl_start;
;       if (j < 48) { float* g = gates + (long)m * 48 + j; g[0] = sigmoid_f(a); g[1] = sigmoid_f(b); g[2] = sigmoid_f(c); g[3] = sigmoid_f(d); }
;       return;
.LBB0_1747:
	v_cmp_gt_u32_e32 vcc, 48, v66
	s_and_saveexec_b64 s[28:29], vcc
	s_cbranch_execz .LBB0_1749
	v_mul_f32_e32 v44, 0xbfb8aa3b, v44
	v_mul_f32_e32 v45, 0xbfb8aa3b, v45
	v_exp_f32_e32 v44, v44
	v_exp_f32_e32 v45, v45
	v_mul_f32_e32 v46, 0xbfb8aa3b, v46
	v_mul_f32_e32 v47, 0xbfb8aa3b, v47
	v_exp_f32_e32 v46, v46
	v_pk_add_f32 v[44:45], v[44:45], 1.0 op_sel_hi:[1,0]
	v_exp_f32_e32 v47, v47
	s_nop 0
	v_pk_add_f32 v[46:47], v[46:47], 1.0 op_sel_hi:[1,0]
	v_mov_b32_e32 v67, v65
	v_lshl_add_u64 v[50:51], v[66:67], 2, v[48:49]
	v_rcp_f32_e32 v52, v45
	s_nop 0
	v_mul_f32_e32 v45, 1.0, v52
	v_rcp_f32_e32 v52, v44
	s_nop 0
	v_mul_f32_e32 v44, 1.0, v52
	v_rcp_f32_e32 v52, v47
	s_nop 0
	v_mul_f32_e32 v47, 1.0, v52
	v_rcp_f32_e32 v52, v46
	s_nop 0
	v_mul_f32_e32 v46, 1.0, v52
	flat_store_dwordx4 v[50:51], v[44:47]

; DI unsigned pack2(float a, float b) { v2f f = {a, b}; return __builtin_bit_cast(unsigned, __builtin_convertvector(f, v2bf)); }
; DI float fexp(float x) { return __builtin_amdgcn_exp2f(x * LOG2E); }
; DI float silu_f(float v) { return v / (1.f + fexp(-v)); }
;   DI void operator()(int m, int n, float a, float b, float c, float d, float& ss) const {
;     ...
;     if (n < q_end) { a *= qscale; b *= qscale; c *= qscale; d *= qscale; }
;     else if (n >= z_start) { a = silu_f(a); b = silu_f(b); c = silu_f(c); d = silu_f(d); }
;     ss += a * a + b * b + c * c + d * d;
;     u32x2 v; v.x = pack2(a, b); v.y = pack2(c, d);
;     *(u32x2*)(dst + (long)m * ld + n) = v;
.LBB0_1750:
	v_cmp_lt_i32_e32 vcc, s33, v64
	s_and_saveexec_b64 s[28:29], vcc
	s_xor_b64 s[28:29], exec, s[28:29]
	s_cbranch_execz .LBB0_1752
	v_mul_f32_e32 v50, 0xbfb8aa3b, v44
	v_mul_f32_e32 v51, 0xbfb8aa3b, v45
	v_exp_f32_e32 v50, v50
	v_exp_f32_e32 v51, v51
	s_nop 0
	v_pk_add_f32 v[50:51], v[50:51], 1.0 op_sel_hi:[1,0]
	s_nop 0
	v_rcp_f32_e32 v52, v51
	s_nop 0
	v_mul_f32_e32 v51, v45, v52
	v_mul_f32_e32 v52, 0xbfb8aa3b, v46
	v_mul_f32_e32 v53, 0xbfb8aa3b, v47
	v_exp_f32_e32 v52, v52
	v_exp_f32_e32 v53, v53
	s_nop 0
	v_pk_add_f32 v[52:53], v[52:53], 1.0 op_sel_hi:[1,0]
	v_rcp_f32_e32 v45, v50
	s_nop 0
	v_mul_f32_e32 v50, v44, v45
	v_rcp_f32_e32 v44, v53
	s_nop 0
	v_mul_f32_e32 v53, v47, v44
	v_rcp_f32_e32 v44, v52
	s_nop 0
	v_mul_f32_e32 v52, v46, v44

; DI float fexp(float x) { return __builtin_amdgcn_exp2f(x * LOG2E); }
; DI float sigmoid_f(float v) { return 1.f / (1.f + fexp(-v)); }
;   DI void operator()(int m, int n, float a, float b, float c, float d, float& ss) const {
;     if (n >= gl_start) {
;       const int j = n - gl_start;
;       if (j < 48) { float* g = gates + (long)m * 48 + j; g[0] = sigmoid_f(a); g[1] = sigmoid_f(b); g[2] = sigmoid_f(c); g[3] = sigmoid_f(d); }
;       return;
.LBB0_1755:
	v_cmp_gt_u32_e32 vcc, 48, v60
	s_and_saveexec_b64 s[28:29], vcc
	s_cbranch_execz .LBB0_1757
	v_mul_f32_e32 v40, 0xbfb8aa3b, v40
	v_mul_f32_e32 v41, 0xbfb8aa3b, v41
	v_exp_f32_e32 v40, v40
	v_exp_f32_e32 v41, v41
	v_mul_f32_e32 v42, 0xbfb8aa3b, v42
	v_mul_f32_e32 v43, 0xbfb8aa3b, v43
	v_exp_f32_e32 v42, v42
	v_pk_add_f32 v[40:41], v[40:41], 1.0 op_sel_hi:[1,0]
	v_exp_f32_e32 v43, v43
	s_nop 0
	v_pk_add_f32 v[42:43], v[42:43], 1.0 op_sel_hi:[1,0]
	v_mov_b32_e32 v61, v65
	v_lshl_add_u64 v[44:45], v[60:61], 2, v[48:49]
	v_rcp_f32_e32 v46, v41
	s_nop 0
	v_mul_f32_e32 v41, 1.0, v46
	v_rcp_f32_e32 v46, v40
	s_nop 0
	v_mul_f32_e32 v40, 1.0, v46
	v_rcp_f32_e32 v46, v43
	s_nop 0
	v_mul_f32_e32 v43, 1.0, v46
	v_rcp_f32_e32 v46, v42
	s_nop 0
	v_mul_f32_e32 v42, 1.0, v46
	flat_store_dwordx4 v[44:45], v[40:43]

; DI unsigned pack2(float a, float b) { v2f f = {a, b}; return __builtin_bit_cast(unsigned, __builtin_convertvector(f, v2bf)); }
; DI float fexp(float x) { return __builtin_amdgcn_exp2f(x * LOG2E); }
; DI float silu_f(float v) { return v / (1.f + fexp(-v)); }
;   DI void operator()(int m, int n, float a, float b, float c, float d, float& ss) const {
;     ...
;     if (n < q_end) { a *= qscale; b *= qscale; c *= qscale; d *= qscale; }
;     else if (n >= z_start) { a = silu_f(a); b = silu_f(b); c = silu_f(c); d = silu_f(d); }
;     ss += a * a + b * b + c * c + d * d;
;     u32x2 v; v.x = pack2(a, b); v.y = pack2(c, d);
;     *(u32x2*)(dst + (long)m * ld + n) = v;
.LBB0_1758:
	v_cmp_lt_i32_e32 vcc, s33, v72
	s_and_saveexec_b64 s[28:29], vcc
	s_xor_b64 s[28:29], exec, s[28:29]
	s_cbranch_execz .LBB0_1760
	v_mul_f32_e32 v44, 0xbfb8aa3b, v40
	v_mul_f32_e32 v45, 0xbfb8aa3b, v41
	v_exp_f32_e32 v44, v44
	v_exp_f32_e32 v45, v45
	s_nop 0
	v_pk_add_f32 v[44:45], v[44:45], 1.0 op_sel_hi:[1,0]
	s_nop 0
	v_rcp_f32_e32 v46, v45
	s_nop 0
	v_mul_f32_e32 v45, v41, v46
	v_mul_f32_e32 v46, 0xbfb8aa3b, v42
	v_mul_f32_e32 v47, 0xbfb8aa3b, v43
	v_exp_f32_e32 v46, v46
	v_exp_f32_e32 v47, v47
	s_nop 0
	v_pk_add_f32 v[46:47], v[46:47], 1.0 op_sel_hi:[1,0]
	v_rcp_f32_e32 v41, v44
	s_nop 0
	v_mul_f32_e32 v44, v40, v41
	v_rcp_f32_e32 v40, v47
	s_nop 0
	v_mul_f32_e32 v47, v43, v40
	v_rcp_f32_e32 v40, v46
	s_nop 0
	v_mul_f32_e32 v46, v42, v40

; DI float fexp(float x) { return __builtin_amdgcn_exp2f(x * LOG2E); }
; DI float sigmoid_f(float v) { return 1.f / (1.f + fexp(-v)); }
;   DI void operator()(int m, int n, float a, float b, float c, float d, float& ss) const {
;     if (n >= gl_start) {
;       const int j = n - gl_start;
;       if (j < 48) { float* g = gates + (long)m * 48 + j; g[0] = sigmoid_f(a); g[1] = sigmoid_f(b); g[2] = sigmoid_f(c); g[3] = sigmoid_f(d); }
;       return;
.LBB0_1763:
	v_cmp_gt_u32_e32 vcc, 48, v56
	s_and_saveexec_b64 s[28:29], vcc
	s_cbranch_execz .LBB0_1765
	v_mul_f32_e32 v36, 0xbfb8aa3b, v36
	v_mul_f32_e32 v37, 0xbfb8aa3b, v37
	v_exp_f32_e32 v36, v36
	v_exp_f32_e32 v37, v37
	v_mul_f32_e32 v38, 0xbfb8aa3b, v38
	v_mul_f32_e32 v39, 0xbfb8aa3b, v39
	v_exp_f32_e32 v38, v38
	v_pk_add_f32 v[36:37], v[36:37], 1.0 op_sel_hi:[1,0]
	v_exp_f32_e32 v39, v39
	s_nop 0
	v_pk_add_f32 v[38:39], v[38:39], 1.0 op_sel_hi:[1,0]
	v_mov_b32_e32 v57, v65
	v_lshl_add_u64 v[40:41], v[56:57], 2, v[48:49]
	v_rcp_f32_e32 v42, v37
	s_nop 0
	v_mul_f32_e32 v37, 1.0, v42
	v_rcp_f32_e32 v42, v36
	s_nop 0
	v_mul_f32_e32 v36, 1.0, v42
	v_rcp_f32_e32 v42, v39
	s_nop 0
	v_mul_f32_e32 v39, 1.0, v42
	v_rcp_f32_e32 v42, v38
	s_nop 0
	v_mul_f32_e32 v38, 1.0, v42
	flat_store_dwordx4 v[40:41], v[36:39]

; DI unsigned pack2(float a, float b) { v2f f = {a, b}; return __builtin_bit_cast(unsigned, __builtin_convertvector(f, v2bf)); }
; DI float fexp(float x) { return __builtin_amdgcn_exp2f(x * LOG2E); }
; DI float silu_f(float v) { return v / (1.f + fexp(-v)); }
;   DI void operator()(int m, int n, float a, float b, float c, float d, float& ss) const {
;     ...
;     if (n < q_end) { a *= qscale; b *= qscale; c *= qscale; d *= qscale; }
;     else if (n >= z_start) { a = silu_f(a); b = silu_f(b); c = silu_f(c); d = silu_f(d); }
;     ss += a * a + b * b + c * c + d * d;
;     u32x2 v; v.x = pack2(a, b); v.y = pack2(c, d);
;     *(u32x2*)(dst + (long)m * ld + n) = v;
.LBB0_1766:
	v_cmp_lt_i32_e32 vcc, s33, v70
	s_and_saveexec_b64 s[28:29], vcc
	s_xor_b64 s[28:29], exec, s[28:29]
	s_cbranch_execz .LBB0_1768
	v_mul_f32_e32 v40, 0xbfb8aa3b, v36
	v_mul_f32_e32 v41, 0xbfb8aa3b, v37
	v_exp_f32_e32 v40, v40
	v_exp_f32_e32 v41, v41
	s_nop 0
	v_pk_add_f32 v[40:41], v[40:41], 1.0 op_sel_hi:[1,0]
	s_nop 0
	v_rcp_f32_e32 v42, v41
	s_nop 0
	v_mul_f32_e32 v41, v37, v42
	v_mul_f32_e32 v42, 0xbfb8aa3b, v38
	v_mul_f32_e32 v43, 0xbfb8aa3b, v39
	v_exp_f32_e32 v42, v42
	v_exp_f32_e32 v43, v43
	s_nop 0
	v_pk_add_f32 v[42:43], v[42:43], 1.0 op_sel_hi:[1,0]
	v_rcp_f32_e32 v37, v40
	s_nop 0
	v_mul_f32_e32 v40, v36, v37
	v_rcp_f32_e32 v36, v43
	s_nop 0
	v_mul_f32_e32 v43, v39, v36
	v_rcp_f32_e32 v36, v42
	s_nop 0
	v_mul_f32_e32 v42, v38, v36

; DI unsigned pack2(float a, float b) { v2f f = {a, b}; return __builtin_bit_cast(unsigned, __builtin_convertvector(f, v2bf)); }
; DI float fexp(float x) { return __builtin_amdgcn_exp2f(x * LOG2E); }
; DI float silu_f(float v) { return v / (1.f + fexp(-v)); }
;   DI void operator()(int m, int n, float a, float b, float c, float d, float& ss) const {
;     ...
;     if (n < q_end) { a *= qscale; b *= qscale; c *= qscale; d *= qscale; }
;     else if (n >= z_start) { a = silu_f(a); b = silu_f(b); c = silu_f(c); d = silu_f(d); }
;     ss += a * a + b * b + c * c + d * d;
;     u32x2 v; v.x = pack2(a, b); v.y = pack2(c, d);
;     *(u32x2*)(dst + (long)m * ld + n) = v;
.LBB0_1771:
	v_cmp_lt_i32_e32 vcc, s33, v58
	s_and_saveexec_b64 s[28:29], vcc
	s_xor_b64 s[28:29], exec, s[28:29]
	s_cbranch_execz .LBB0_1773
	v_mul_f32_e32 v36, 0xbfb8aa3b, v32
	v_mul_f32_e32 v37, 0xbfb8aa3b, v33
	v_exp_f32_e32 v36, v36
	v_exp_f32_e32 v37, v37
	s_nop 0
	v_pk_add_f32 v[36:37], v[36:37], 1.0 op_sel_hi:[1,0]
	s_nop 0
	v_rcp_f32_e32 v38, v37
	s_nop 0
	v_mul_f32_e32 v37, v33, v38
	v_mul_f32_e32 v38, 0xbfb8aa3b, v34
	v_mul_f32_e32 v39, 0xbfb8aa3b, v35
	v_exp_f32_e32 v38, v38
	v_exp_f32_e32 v39, v39
	s_nop 0
	v_pk_add_f32 v[38:39], v[38:39], 1.0 op_sel_hi:[1,0]
	v_rcp_f32_e32 v33, v36
	s_nop 0
	v_mul_f32_e32 v36, v32, v33
	v_rcp_f32_e32 v32, v39
	s_nop 0
	v_mul_f32_e32 v39, v35, v32
	v_rcp_f32_e32 v32, v38
	s_nop 0
	v_mul_f32_e32 v38, v34, v32

; DI float fexp(float x) { return __builtin_amdgcn_exp2f(x * LOG2E); }
; DI float sigmoid_f(float v) { return 1.f / (1.f + fexp(-v)); }
;   DI void operator()(int m, int n, float a, float b, float c, float d, float& ss) const {
;     if (n >= gl_start) {
;       const int j = n - gl_start;
;       if (j < 48) { float* g = gates + (long)m * 48 + j; g[0] = sigmoid_f(a); g[1] = sigmoid_f(b); g[2] = sigmoid_f(c); g[3] = sigmoid_f(d); }
;       return;
.LBB0_1783:
	v_cmp_gt_u32_e32 vcc, 48, v66
	s_and_saveexec_b64 s[28:29], vcc
	s_cbranch_execz .LBB0_1785
	v_mul_f32_e32 v28, 0xbfb8aa3b, v28
	v_mul_f32_e32 v29, 0xbfb8aa3b, v29
	v_exp_f32_e32 v28, v28
	v_exp_f32_e32 v29, v29
	v_mul_f32_e32 v30, 0xbfb8aa3b, v30
	v_mul_f32_e32 v31, 0xbfb8aa3b, v31
	v_exp_f32_e32 v30, v30
	v_pk_add_f32 v[28:29], v[28:29], 1.0 op_sel_hi:[1,0]
	v_exp_f32_e32 v31, v31
	s_nop 0
	v_pk_add_f32 v[30:31], v[30:31], 1.0 op_sel_hi:[1,0]
	v_mov_b32_e32 v67, v65
	v_lshl_add_u64 v[34:35], v[66:67], 2, v[32:33]
	v_rcp_f32_e32 v36, v29
	s_nop 0
	v_mul_f32_e32 v29, 1.0, v36
	v_rcp_f32_e32 v36, v28
	s_nop 0
	v_mul_f32_e32 v28, 1.0, v36
	v_rcp_f32_e32 v36, v31
	s_nop 0
	v_mul_f32_e32 v31, 1.0, v36
	v_rcp_f32_e32 v36, v30
	s_nop 0
	v_mul_f32_e32 v30, 1.0, v36
	flat_store_dwordx4 v[34:35], v[28:31]

; DI unsigned pack2(float a, float b) { v2f f = {a, b}; return __builtin_bit_cast(unsigned, __builtin_convertvector(f, v2bf)); }
; DI float fexp(float x) { return __builtin_amdgcn_exp2f(x * LOG2E); }
; DI float silu_f(float v) { return v / (1.f + fexp(-v)); }
;   DI void operator()(int m, int n, float a, float b, float c, float d, float& ss) const {
;     ...
;     if (n < q_end) { a *= qscale; b *= qscale; c *= qscale; d *= qscale; }
;     else if (n >= z_start) { a = silu_f(a); b = silu_f(b); c = silu_f(c); d = silu_f(d); }
;     ss += a * a + b * b + c * c + d * d;
;     u32x2 v; v.x = pack2(a, b); v.y = pack2(c, d);
;     *(u32x2*)(dst + (long)m * ld + n) = v;
.LBB0_1786:
	v_cmp_lt_i32_e32 vcc, s33, v64
	s_and_saveexec_b64 s[28:29], vcc
	s_xor_b64 s[28:29], exec, s[28:29]
	s_cbranch_execz .LBB0_1788
	v_mul_f32_e32 v34, 0xbfb8aa3b, v28
	v_mul_f32_e32 v35, 0xbfb8aa3b, v29
	v_exp_f32_e32 v34, v34
	v_exp_f32_e32 v35, v35
	s_nop 0
	v_pk_add_f32 v[34:35], v[34:35], 1.0 op_sel_hi:[1,0]
	s_nop 0
	v_rcp_f32_e32 v36, v35
	s_nop 0
	v_mul_f32_e32 v35, v29, v36
	v_mul_f32_e32 v36, 0xbfb8aa3b, v30
	v_mul_f32_e32 v37, 0xbfb8aa3b, v31
	v_exp_f32_e32 v36, v36
	v_exp_f32_e32 v37, v37
	s_nop 0
	v_pk_add_f32 v[36:37], v[36:37], 1.0 op_sel_hi:[1,0]
	v_rcp_f32_e32 v29, v34
	s_nop 0
	v_mul_f32_e32 v34, v28, v29
	v_rcp_f32_e32 v28, v37
	s_nop 0
	v_mul_f32_e32 v37, v31, v28
	v_rcp_f32_e32 v28, v36
	s_nop 0
	v_mul_f32_e32 v36, v30, v28

; DI float fexp(float x) { return __builtin_amdgcn_exp2f(x * LOG2E); }
; DI float sigmoid_f(float v) { return 1.f / (1.f + fexp(-v)); }
;   DI void operator()(int m, int n, float a, float b, float c, float d, float& ss) const {
;     if (n >= gl_start) {
;       const int j = n - gl_start;
;       if (j < 48) { float* g = gates + (long)m * 48 + j; g[0] = sigmoid_f(a); g[1] = sigmoid_f(b); g[2] = sigmoid_f(c); g[3] = sigmoid_f(d); }
;       return;
.LBB0_1791:
	v_cmp_gt_u32_e32 vcc, 48, v60
	s_and_saveexec_b64 s[28:29], vcc
	s_cbranch_execz .LBB0_1793
	v_mul_f32_e32 v24, 0xbfb8aa3b, v24
	v_mul_f32_e32 v25, 0xbfb8aa3b, v25
	v_exp_f32_e32 v24, v24
	v_exp_f32_e32 v25, v25
	v_mul_f32_e32 v26, 0xbfb8aa3b, v26
	v_mul_f32_e32 v27, 0xbfb8aa3b, v27
	v_exp_f32_e32 v26, v26
	v_pk_add_f32 v[24:25], v[24:25], 1.0 op_sel_hi:[1,0]
	v_exp_f32_e32 v27, v27
	s_nop 0
	v_pk_add_f32 v[26:27], v[26:27], 1.0 op_sel_hi:[1,0]
	v_mov_b32_e32 v61, v65
	v_lshl_add_u64 v[28:29], v[60:61], 2, v[32:33]
	v_rcp_f32_e32 v30, v25
	s_nop 0
	v_mul_f32_e32 v25, 1.0, v30
	v_rcp_f32_e32 v30, v24
	s_nop 0
	v_mul_f32_e32 v24, 1.0, v30
	v_rcp_f32_e32 v30, v27
	s_nop 0
	v_mul_f32_e32 v27, 1.0, v30
	v_rcp_f32_e32 v30, v26
	s_nop 0
	v_mul_f32_e32 v26, 1.0, v30
	flat_store_dwordx4 v[28:29], v[24:27]

; DI unsigned pack2(float a, float b) { v2f f = {a, b}; return __builtin_bit_cast(unsigned, __builtin_convertvector(f, v2bf)); }
; DI float fexp(float x) { return __builtin_amdgcn_exp2f(x * LOG2E); }
; DI float silu_f(float v) { return v / (1.f + fexp(-v)); }
;   DI void operator()(int m, int n, float a, float b, float c, float d, float& ss) const {
;     ...
;     if (n < q_end) { a *= qscale; b *= qscale; c *= qscale; d *= qscale; }
;     else if (n >= z_start) { a = silu_f(a); b = silu_f(b); c = silu_f(c); d = silu_f(d); }
;     ss += a * a + b * b + c * c + d * d;
;     u32x2 v; v.x = pack2(a, b); v.y = pack2(c, d);
;     *(u32x2*)(dst + (long)m * ld + n) = v;
.LBB0_1794:
	v_cmp_lt_i32_e32 vcc, s33, v72
	s_and_saveexec_b64 s[28:29], vcc
	s_xor_b64 s[28:29], exec, s[28:29]
	s_cbranch_execz .LBB0_1796
	v_mul_f32_e32 v28, 0xbfb8aa3b, v24
	v_mul_f32_e32 v29, 0xbfb8aa3b, v25
	v_exp_f32_e32 v28, v28
	v_exp_f32_e32 v29, v29
	s_nop 0
	v_pk_add_f32 v[28:29], v[28:29], 1.0 op_sel_hi:[1,0]
	s_nop 0
	v_rcp_f32_e32 v30, v29
	s_nop 0
	v_mul_f32_e32 v29, v25, v30
	v_mul_f32_e32 v30, 0xbfb8aa3b, v26
	v_mul_f32_e32 v31, 0xbfb8aa3b, v27
	v_exp_f32_e32 v30, v30
	v_exp_f32_e32 v31, v31
	s_nop 0
	v_pk_add_f32 v[30:31], v[30:31], 1.0 op_sel_hi:[1,0]
	v_rcp_f32_e32 v25, v28
	s_nop 0
	v_mul_f32_e32 v28, v24, v25
	v_rcp_f32_e32 v24, v31
	s_nop 0
	v_mul_f32_e32 v31, v27, v24
	v_rcp_f32_e32 v24, v30
	s_nop 0
	v_mul_f32_e32 v30, v26, v24

; DI float fexp(float x) { return __builtin_amdgcn_exp2f(x * LOG2E); }
; DI float sigmoid_f(float v) { return 1.f / (1.f + fexp(-v)); }
;   DI void operator()(int m, int n, float a, float b, float c, float d, float& ss) const {
;     if (n >= gl_start) {
;       const int j = n - gl_start;
;       if (j < 48) { float* g = gates + (long)m * 48 + j; g[0] = sigmoid_f(a); g[1] = sigmoid_f(b); g[2] = sigmoid_f(c); g[3] = sigmoid_f(d); }
;       return;
.LBB0_1799:
	v_cmp_gt_u32_e32 vcc, 48, v56
	s_and_saveexec_b64 s[28:29], vcc
	s_cbranch_execz .LBB0_1801
	v_mul_f32_e32 v20, 0xbfb8aa3b, v20
	v_mul_f32_e32 v21, 0xbfb8aa3b, v21
	v_exp_f32_e32 v20, v20
	v_exp_f32_e32 v21, v21
	v_mul_f32_e32 v22, 0xbfb8aa3b, v22
	v_mul_f32_e32 v23, 0xbfb8aa3b, v23
	v_exp_f32_e32 v22, v22
	v_pk_add_f32 v[20:21], v[20:21], 1.0 op_sel_hi:[1,0]
	v_exp_f32_e32 v23, v23
	s_nop 0
	v_pk_add_f32 v[22:23], v[22:23], 1.0 op_sel_hi:[1,0]
	v_mov_b32_e32 v57, v65
	v_lshl_add_u64 v[24:25], v[56:57], 2, v[32:33]
	v_rcp_f32_e32 v26, v21
	s_nop 0
	v_mul_f32_e32 v21, 1.0, v26
	v_rcp_f32_e32 v26, v20
	s_nop 0
	v_mul_f32_e32 v20, 1.0, v26
	v_rcp_f32_e32 v26, v23
	s_nop 0
	v_mul_f32_e32 v23, 1.0, v26
	v_rcp_f32_e32 v26, v22
	s_nop 0
	v_mul_f32_e32 v22, 1.0, v26
	flat_store_dwordx4 v[24:25], v[20:23]

; DI unsigned pack2(float a, float b) { v2f f = {a, b}; return __builtin_bit_cast(unsigned, __builtin_convertvector(f, v2bf)); }
; DI float fexp(float x) { return __builtin_amdgcn_exp2f(x * LOG2E); }
; DI float silu_f(float v) { return v / (1.f + fexp(-v)); }
;   DI void operator()(int m, int n, float a, float b, float c, float d, float& ss) const {
;     ...
;     if (n < q_end) { a *= qscale; b *= qscale; c *= qscale; d *= qscale; }
;     else if (n >= z_start) { a = silu_f(a); b = silu_f(b); c = silu_f(c); d = silu_f(d); }
;     ss += a * a + b * b + c * c + d * d;
;     u32x2 v; v.x = pack2(a, b); v.y = pack2(c, d);
;     *(u32x2*)(dst + (long)m * ld + n) = v;
.LBB0_1802:
	v_cmp_lt_i32_e32 vcc, s33, v70
	s_and_saveexec_b64 s[28:29], vcc
	s_xor_b64 s[28:29], exec, s[28:29]
	s_cbranch_execz .LBB0_1804
	v_mul_f32_e32 v24, 0xbfb8aa3b, v20
	v_mul_f32_e32 v25, 0xbfb8aa3b, v21
	v_exp_f32_e32 v24, v24
	v_exp_f32_e32 v25, v25
	s_nop 0
	v_pk_add_f32 v[24:25], v[24:25], 1.0 op_sel_hi:[1,0]
	s_nop 0
	v_rcp_f32_e32 v26, v25
	s_nop 0
	v_mul_f32_e32 v25, v21, v26
	v_mul_f32_e32 v26, 0xbfb8aa3b, v22
	v_mul_f32_e32 v27, 0xbfb8aa3b, v23
	v_exp_f32_e32 v26, v26
	v_exp_f32_e32 v27, v27
	s_nop 0
	v_pk_add_f32 v[26:27], v[26:27], 1.0 op_sel_hi:[1,0]
	v_rcp_f32_e32 v21, v24
	s_nop 0
	v_mul_f32_e32 v24, v20, v21
	v_rcp_f32_e32 v20, v27
	s_nop 0
	v_mul_f32_e32 v27, v23, v20
	v_rcp_f32_e32 v20, v26
	s_nop 0
	v_mul_f32_e32 v26, v22, v20

; DI unsigned pack2(float a, float b) { v2f f = {a, b}; return __builtin_bit_cast(unsigned, __builtin_convertvector(f, v2bf)); }
; DI float fexp(float x) { return __builtin_amdgcn_exp2f(x * LOG2E); }
; DI float silu_f(float v) { return v / (1.f + fexp(-v)); }
;   DI void operator()(int m, int n, float a, float b, float c, float d, float& ss) const {
;     ...
;     if (n < q_end) { a *= qscale; b *= qscale; c *= qscale; d *= qscale; }
;     else if (n >= z_start) { a = silu_f(a); b = silu_f(b); c = silu_f(c); d = silu_f(d); }
;     ss += a * a + b * b + c * c + d * d;
;     u32x2 v; v.x = pack2(a, b); v.y = pack2(c, d);
;     *(u32x2*)(dst + (long)m * ld + n) = v;
.LBB0_1807:
	v_cmp_lt_i32_e32 vcc, s33, v58
	s_and_saveexec_b64 s[28:29], vcc
	s_xor_b64 s[28:29], exec, s[28:29]
	s_cbranch_execz .LBB0_1809
	v_mul_f32_e32 v20, 0xbfb8aa3b, v16
	v_mul_f32_e32 v21, 0xbfb8aa3b, v17
	v_exp_f32_e32 v20, v20
	v_exp_f32_e32 v21, v21
	s_nop 0
	v_pk_add_f32 v[20:21], v[20:21], 1.0 op_sel_hi:[1,0]
	s_nop 0
	v_rcp_f32_e32 v22, v21
	s_nop 0
	v_mul_f32_e32 v21, v17, v22
	v_mul_f32_e32 v22, 0xbfb8aa3b, v18
	v_mul_f32_e32 v23, 0xbfb8aa3b, v19
	v_exp_f32_e32 v22, v22
	v_exp_f32_e32 v23, v23
	s_nop 0
	v_pk_add_f32 v[22:23], v[22:23], 1.0 op_sel_hi:[1,0]
	v_rcp_f32_e32 v17, v20
	s_nop 0
	v_mul_f32_e32 v20, v16, v17
	v_rcp_f32_e32 v16, v23
	s_nop 0
	v_mul_f32_e32 v23, v19, v16
	v_rcp_f32_e32 v16, v22
	s_nop 0
	v_mul_f32_e32 v22, v18, v16

; DI float fexp(float x) { return __builtin_amdgcn_exp2f(x * LOG2E); }
; DI float sigmoid_f(float v) { return 1.f / (1.f + fexp(-v)); }
;   DI void operator()(int m, int n, float a, float b, float c, float d, float& ss) const {
;     if (n >= gl_start) {
;       const int j = n - gl_start;
;       if (j < 48) { float* g = gates + (long)m * 48 + j; g[0] = sigmoid_f(a); g[1] = sigmoid_f(b); g[2] = sigmoid_f(c); g[3] = sigmoid_f(d); }
;       return;
.LBB0_1819:
	v_cmp_gt_u32_e32 vcc, 48, v66
	s_and_saveexec_b64 s[4:5], vcc
	s_cbranch_execz .LBB0_1821
	v_mul_f32_e32 v12, 0xbfb8aa3b, v12
	v_mul_f32_e32 v13, 0xbfb8aa3b, v13
	v_exp_f32_e32 v12, v12
	v_exp_f32_e32 v13, v13
	v_mul_f32_e32 v14, 0xbfb8aa3b, v14
	v_mul_f32_e32 v15, 0xbfb8aa3b, v15
	v_exp_f32_e32 v14, v14
	v_pk_add_f32 v[12:13], v[12:13], 1.0 op_sel_hi:[1,0]
	v_exp_f32_e32 v15, v15
	s_nop 0
	v_pk_add_f32 v[14:15], v[14:15], 1.0 op_sel_hi:[1,0]
	v_mov_b32_e32 v67, v65
	v_lshl_add_u64 v[18:19], v[66:67], 2, v[16:17]
	v_rcp_f32_e32 v20, v13
	s_nop 0
	v_mul_f32_e32 v13, 1.0, v20
	v_rcp_f32_e32 v20, v12
	s_nop 0
	v_mul_f32_e32 v12, 1.0, v20
	v_rcp_f32_e32 v20, v15
	s_nop 0
	v_mul_f32_e32 v15, 1.0, v20
	v_rcp_f32_e32 v20, v14
	s_nop 0
	v_mul_f32_e32 v14, 1.0, v20
	flat_store_dwordx4 v[18:19], v[12:15]

; DI unsigned pack2(float a, float b) { v2f f = {a, b}; return __builtin_bit_cast(unsigned, __builtin_convertvector(f, v2bf)); }
; DI float fexp(float x) { return __builtin_amdgcn_exp2f(x * LOG2E); }
; DI float silu_f(float v) { return v / (1.f + fexp(-v)); }
;   DI void operator()(int m, int n, float a, float b, float c, float d, float& ss) const {
;     ...
;     if (n < q_end) { a *= qscale; b *= qscale; c *= qscale; d *= qscale; }
;     else if (n >= z_start) { a = silu_f(a); b = silu_f(b); c = silu_f(c); d = silu_f(d); }
;     ss += a * a + b * b + c * c + d * d;
;     u32x2 v; v.x = pack2(a, b); v.y = pack2(c, d);
;     *(u32x2*)(dst + (long)m * ld + n) = v;
.LBB0_1822:
	v_cmp_lt_i32_e32 vcc, s33, v64
	s_and_saveexec_b64 s[4:5], vcc
	s_xor_b64 s[4:5], exec, s[4:5]
	s_cbranch_execz .LBB0_1824
	v_mul_f32_e32 v18, 0xbfb8aa3b, v12
	v_mul_f32_e32 v19, 0xbfb8aa3b, v13
	v_exp_f32_e32 v18, v18
	v_exp_f32_e32 v19, v19
	s_nop 0
	v_pk_add_f32 v[18:19], v[18:19], 1.0 op_sel_hi:[1,0]
	s_nop 0
	v_rcp_f32_e32 v20, v19
	s_nop 0
	v_mul_f32_e32 v19, v13, v20
	v_mul_f32_e32 v20, 0xbfb8aa3b, v14
	v_mul_f32_e32 v21, 0xbfb8aa3b, v15
	v_exp_f32_e32 v20, v20
	v_exp_f32_e32 v21, v21
	s_nop 0
	v_pk_add_f32 v[20:21], v[20:21], 1.0 op_sel_hi:[1,0]
	v_rcp_f32_e32 v13, v18
	s_nop 0
	v_mul_f32_e32 v18, v12, v13
	v_rcp_f32_e32 v12, v21
	s_nop 0
	v_mul_f32_e32 v21, v15, v12
	v_rcp_f32_e32 v12, v20
	s_nop 0
	v_mul_f32_e32 v20, v14, v12

; DI float fexp(float x) { return __builtin_amdgcn_exp2f(x * LOG2E); }
; DI float sigmoid_f(float v) { return 1.f / (1.f + fexp(-v)); }
;   DI void operator()(int m, int n, float a, float b, float c, float d, float& ss) const {
;     if (n >= gl_start) {
;       const int j = n - gl_start;
;       if (j < 48) { float* g = gates + (long)m * 48 + j; g[0] = sigmoid_f(a); g[1] = sigmoid_f(b); g[2] = sigmoid_f(c); g[3] = sigmoid_f(d); }
;       return;
.LBB0_1827:
	v_cmp_gt_u32_e32 vcc, 48, v60
	s_and_saveexec_b64 s[4:5], vcc
	s_cbranch_execz .LBB0_1829
	v_mul_f32_e32 v8, 0xbfb8aa3b, v8
	v_mul_f32_e32 v9, 0xbfb8aa3b, v9
	v_exp_f32_e32 v8, v8
	v_exp_f32_e32 v9, v9
	v_mul_f32_e32 v10, 0xbfb8aa3b, v10
	v_mul_f32_e32 v11, 0xbfb8aa3b, v11
	v_exp_f32_e32 v10, v10
	v_pk_add_f32 v[8:9], v[8:9], 1.0 op_sel_hi:[1,0]
	v_exp_f32_e32 v11, v11
	s_nop 0
	v_pk_add_f32 v[10:11], v[10:11], 1.0 op_sel_hi:[1,0]
	v_mov_b32_e32 v61, v65
	v_lshl_add_u64 v[12:13], v[60:61], 2, v[16:17]
	v_rcp_f32_e32 v14, v9
	s_nop 0
	v_mul_f32_e32 v9, 1.0, v14
	v_rcp_f32_e32 v14, v8
	s_nop 0
	v_mul_f32_e32 v8, 1.0, v14
	v_rcp_f32_e32 v14, v11
	s_nop 0
	v_mul_f32_e32 v11, 1.0, v14
	v_rcp_f32_e32 v14, v10
	s_nop 0
	v_mul_f32_e32 v10, 1.0, v14
	flat_store_dwordx4 v[12:13], v[8:11]

; DI unsigned pack2(float a, float b) { v2f f = {a, b}; return __builtin_bit_cast(unsigned, __builtin_convertvector(f, v2bf)); }
; DI float fexp(float x) { return __builtin_amdgcn_exp2f(x * LOG2E); }
; DI float silu_f(float v) { return v / (1.f + fexp(-v)); }
;   DI void operator()(int m, int n, float a, float b, float c, float d, float& ss) const {
;     ...
;     if (n < q_end) { a *= qscale; b *= qscale; c *= qscale; d *= qscale; }
;     else if (n >= z_start) { a = silu_f(a); b = silu_f(b); c = silu_f(c); d = silu_f(d); }
;     ss += a * a + b * b + c * c + d * d;
;     u32x2 v; v.x = pack2(a, b); v.y = pack2(c, d);
;     *(u32x2*)(dst + (long)m * ld + n) = v;
.LBB0_1830:
	v_cmp_lt_i32_e32 vcc, s33, v72
	s_and_saveexec_b64 s[4:5], vcc
	s_xor_b64 s[4:5], exec, s[4:5]
	s_cbranch_execz .LBB0_1832
	v_mul_f32_e32 v12, 0xbfb8aa3b, v8
	v_mul_f32_e32 v13, 0xbfb8aa3b, v9
	v_exp_f32_e32 v12, v12
	v_exp_f32_e32 v13, v13
	s_nop 0
	v_pk_add_f32 v[12:13], v[12:13], 1.0 op_sel_hi:[1,0]
	s_nop 0
	v_rcp_f32_e32 v14, v13
	s_nop 0
	v_mul_f32_e32 v13, v9, v14
	v_mul_f32_e32 v14, 0xbfb8aa3b, v10
	v_mul_f32_e32 v15, 0xbfb8aa3b, v11
	v_exp_f32_e32 v14, v14
	v_exp_f32_e32 v15, v15
	s_nop 0
	v_pk_add_f32 v[14:15], v[14:15], 1.0 op_sel_hi:[1,0]
	v_rcp_f32_e32 v9, v12
	s_nop 0
	v_mul_f32_e32 v12, v8, v9
	v_rcp_f32_e32 v8, v15
	s_nop 0
	v_mul_f32_e32 v15, v11, v8
	v_rcp_f32_e32 v8, v14
	s_nop 0
	v_mul_f32_e32 v14, v10, v8

; DI float fexp(float x) { return __builtin_amdgcn_exp2f(x * LOG2E); }
; DI float sigmoid_f(float v) { return 1.f / (1.f + fexp(-v)); }
;   DI void operator()(int m, int n, float a, float b, float c, float d, float& ss) const {
;     if (n >= gl_start) {
;       const int j = n - gl_start;
;       if (j < 48) { float* g = gates + (long)m * 48 + j; g[0] = sigmoid_f(a); g[1] = sigmoid_f(b); g[2] = sigmoid_f(c); g[3] = sigmoid_f(d); }
;       return;
.LBB0_1835:
	v_cmp_gt_u32_e32 vcc, 48, v56
	s_and_saveexec_b64 s[4:5], vcc
	s_cbranch_execz .LBB0_1837
	v_mul_f32_e32 v4, 0xbfb8aa3b, v4
	v_mul_f32_e32 v5, 0xbfb8aa3b, v5
	v_exp_f32_e32 v4, v4
	v_exp_f32_e32 v5, v5
	v_mul_f32_e32 v6, 0xbfb8aa3b, v6
	v_mul_f32_e32 v7, 0xbfb8aa3b, v7
	v_exp_f32_e32 v6, v6
	v_pk_add_f32 v[4:5], v[4:5], 1.0 op_sel_hi:[1,0]
	v_exp_f32_e32 v7, v7
	s_nop 0
	v_pk_add_f32 v[6:7], v[6:7], 1.0 op_sel_hi:[1,0]
	v_mov_b32_e32 v57, v65
	v_lshl_add_u64 v[8:9], v[56:57], 2, v[16:17]
	v_rcp_f32_e32 v10, v5
	s_nop 0
	v_mul_f32_e32 v5, 1.0, v10
	v_rcp_f32_e32 v10, v4
	s_nop 0
	v_mul_f32_e32 v4, 1.0, v10
	v_rcp_f32_e32 v10, v7
	s_nop 0
	v_mul_f32_e32 v7, 1.0, v10
	v_rcp_f32_e32 v10, v6
	s_nop 0
	v_mul_f32_e32 v6, 1.0, v10
	flat_store_dwordx4 v[8:9], v[4:7]

; DI unsigned pack2(float a, float b) { v2f f = {a, b}; return __builtin_bit_cast(unsigned, __builtin_convertvector(f, v2bf)); }
; DI float fexp(float x) { return __builtin_amdgcn_exp2f(x * LOG2E); }
; DI float silu_f(float v) { return v / (1.f + fexp(-v)); }
;   DI void operator()(int m, int n, float a, float b, float c, float d, float& ss) const {
;     ...
;     if (n < q_end) { a *= qscale; b *= qscale; c *= qscale; d *= qscale; }
;     else if (n >= z_start) { a = silu_f(a); b = silu_f(b); c = silu_f(c); d = silu_f(d); }
;     ss += a * a + b * b + c * c + d * d;
;     u32x2 v; v.x = pack2(a, b); v.y = pack2(c, d);
;     *(u32x2*)(dst + (long)m * ld + n) = v;
.LBB0_1838:
	v_cmp_lt_i32_e32 vcc, s33, v70
	s_and_saveexec_b64 s[4:5], vcc
	s_xor_b64 s[4:5], exec, s[4:5]
	s_cbranch_execz .LBB0_1840
	v_mul_f32_e32 v8, 0xbfb8aa3b, v4
	v_mul_f32_e32 v9, 0xbfb8aa3b, v5
	v_exp_f32_e32 v8, v8
	v_exp_f32_e32 v9, v9
	s_nop 0
	v_pk_add_f32 v[8:9], v[8:9], 1.0 op_sel_hi:[1,0]
	s_nop 0
	v_rcp_f32_e32 v10, v9
	s_nop 0
	v_mul_f32_e32 v9, v5, v10
	v_mul_f32_e32 v10, 0xbfb8aa3b, v6
	v_mul_f32_e32 v11, 0xbfb8aa3b, v7
	v_exp_f32_e32 v10, v10
	v_exp_f32_e32 v11, v11
	s_nop 0
	v_pk_add_f32 v[10:11], v[10:11], 1.0 op_sel_hi:[1,0]
	v_rcp_f32_e32 v5, v8
	s_nop 0
	v_mul_f32_e32 v8, v4, v5
	v_rcp_f32_e32 v4, v11
	s_nop 0
	v_mul_f32_e32 v11, v7, v4
	v_rcp_f32_e32 v4, v10
	s_nop 0
	v_mul_f32_e32 v10, v6, v4

; DI unsigned pack2(float a, float b) { v2f f = {a, b}; return __builtin_bit_cast(unsigned, __builtin_convertvector(f, v2bf)); }
; DI float fexp(float x) { return __builtin_amdgcn_exp2f(x * LOG2E); }
; DI float silu_f(float v) { return v / (1.f + fexp(-v)); }
;   DI void operator()(int m, int n, float a, float b, float c, float d, float& ss) const {
;     ...
;     if (n < q_end) { a *= qscale; b *= qscale; c *= qscale; d *= qscale; }
;     else if (n >= z_start) { a = silu_f(a); b = silu_f(b); c = silu_f(c); d = silu_f(d); }
;     ss += a * a + b * b + c * c + d * d;
;     u32x2 v; v.x = pack2(a, b); v.y = pack2(c, d);
;     *(u32x2*)(dst + (long)m * ld + n) = v;
.LBB0_1843:
	v_cmp_lt_i32_e32 vcc, s33, v58
	s_and_saveexec_b64 s[4:5], vcc
	s_xor_b64 s[4:5], exec, s[4:5]
	s_cbranch_execz .LBB0_1845
	v_mul_f32_e32 v4, 0xbfb8aa3b, v0
	v_mul_f32_e32 v5, 0xbfb8aa3b, v1
	v_exp_f32_e32 v4, v4
	v_exp_f32_e32 v5, v5
	s_nop 0
	v_pk_add_f32 v[4:5], v[4:5], 1.0 op_sel_hi:[1,0]
	s_nop 0
	v_rcp_f32_e32 v6, v5
	s_nop 0
	v_mul_f32_e32 v5, v1, v6
	v_mul_f32_e32 v6, 0xbfb8aa3b, v2
	v_mul_f32_e32 v7, 0xbfb8aa3b, v3
	v_exp_f32_e32 v6, v6
	v_exp_f32_e32 v7, v7
	s_nop 0
	v_pk_add_f32 v[6:7], v[6:7], 1.0 op_sel_hi:[1,0]
	v_rcp_f32_e32 v1, v4
	s_nop 0
	v_mul_f32_e32 v4, v0, v1
	v_rcp_f32_e32 v0, v7
	s_nop 0
	v_mul_f32_e32 v7, v3, v0
	v_rcp_f32_e32 v0, v6
	s_nop 0
	v_mul_f32_e32 v6, v2, v0

; DI unsigned pack2(float a, float b) { v2f f = {a, b}; return __builtin_bit_cast(unsigned, __builtin_convertvector(f, v2bf)); }
; DI float silu_f(float v) { return v / (1.f + fexp(-v)); }
;   DI u32x2 pack(int, int, float a, float b, float c, float d, float&) const { u32x2 v; v.x = pack2(a, b); v.y = pack2(c, d); return v; }
; template <class ARow, class Epi>
; DI void gemm_tile(const ARow& arow, long a_kstride, const u16* __restrict__ Bt, long ldb, int K, int m0, int n0,
;                   const Epi& epi, char* smem) {
;     ...
;     for (int mi = 0; mi < 4; ++mi) {
;       const int m = m0 + wm * 64 + mi * 16 + fr;
;       float ss = 0.f;
;       u32x2 pk[4];
; #pragma unroll
;       for (int ni = 0; ni < 4; ++ni) pk[ni] = epi.pack(m, nh + ni * 16 + fq * 4, acc[ni][mi][0], acc[ni][mi][1], acc[ni][mi][2], acc[ni][mi][3], ss);
;       epi.finish16(m, nh, ss);
;       u16* rp = epi.rowp(m) + nh;
; #pragma unroll
;       for (int pp = 0; pp < 2; ++pp) {
;         u32x2 a = pk[2 * pp], b = pk[2 * pp + 1];
;         const u32x2 rx = __builtin_amdgcn_permlane16_swap(a.x, b.x, false, false);
;         const u32x2 ry = __builtin_amdgcn_permlane16_swap(a.y, b.y, false, false);
;         const int nst = (fq & 1) ? ((2 * pp + 1) * 16 + (fq - 1) * 4) : ((2 * pp) * 16 + fq * 4);
;         *(u32x4*)(rp + nst) = (u32x4){rx[0], ry[0], rx[1], ry[1]};
;       }
;   DI u32x2 pack(int m, int n, float a, float b, float c, float d, float& ss) const {
;     if (n < q_end) { a *= qscale; b *= qscale; c *= qscale; d *= qscale; }
;     else if (n >= z_start) { a = silu_f(a); b = silu_f(b); c = silu_f(c); d = silu_f(d); }
;     ss += a * a + b * b + c * c + d * d;
;     u32x2 v; v.x = pack2(a, b); v.y = pack2(c, d);
;     return v;
.LBB0_1849:
	s_andn2_saveexec_b64 s[26:27], s[26:27]
	s_cbranch_execz .LBB0_1700
	v_cmp_lt_i32_e64 s[4:5], s33, v64
	s_and_saveexec_b64 s[0:1], s[4:5]
	s_xor_b64 s[0:1], exec, s[0:1]
	s_cbranch_execz .LBB0_1853
	s_cmpk_lt_u32 s35, 0xa00
	s_cbranch_scc1 .LBB0_1853
	v_mul_f32_e32 v67, 0xbfb8aa3b, v60
	v_exp_f32_e32 v70, v67
	v_mul_f32_e32 v67, 0xbfb8aa3b, v61
	v_exp_f32_e32 v71, v67
	s_nop 0
	v_pk_add_f32 v[70:71], v[70:71], 1.0 op_sel_hi:[1,0]
	s_nop 0
	v_rcp_f32_e32 v67, v70
	s_nop 0
	v_mul_f32_e32 v60, v60, v67
	v_mul_f32_e32 v70, 0xbfb8aa3b, v62
	v_exp_f32_e32 v72, v70
	v_mul_f32_e32 v70, 0xbfb8aa3b, v63
	v_exp_f32_e32 v73, v70
	s_nop 0
	v_pk_add_f32 v[72:73], v[72:73], 1.0 op_sel_hi:[1,0]
	v_rcp_f32_e32 v67, v71
	s_nop 0
	v_mul_f32_e32 v61, v61, v67
	v_rcp_f32_e32 v67, v72
	s_nop 0
	v_mul_f32_e32 v62, v62, v67
	v_rcp_f32_e32 v67, v73
	s_nop 0
	v_mul_f32_e32 v63, v63, v67
.LBB0_1853:
	s_andn2_saveexec_b64 s[0:1], s[0:1]
	v_pk_mul_f32 v[60:61], v[60:61], s[24:25] op_sel_hi:[1,0]
	v_pk_mul_f32 v[62:63], v[62:63], s[24:25] op_sel_hi:[1,0]
	s_or_b64 exec, exec, s[0:1]
	v_or_b32_e32 v67, 16, v64
	v_cmp_lt_i32_e64 s[6:7], s33, v67
	s_and_saveexec_b64 s[0:1], s[6:7]
	s_xor_b64 s[0:1], exec, s[0:1]
	s_cbranch_execz .LBB0_1858
	s_cmpk_lt_u32 s35, 0xa00
	s_cbranch_scc1 .LBB0_1858
	v_mul_f32_e32 v67, 0xbfb8aa3b, v56
	v_exp_f32_e32 v70, v67
	v_mul_f32_e32 v67, 0xbfb8aa3b, v57
	v_exp_f32_e32 v71, v67
	s_nop 0
	v_pk_add_f32 v[70:71], v[70:71], 1.0 op_sel_hi:[1,0]
	s_nop 0
	v_rcp_f32_e32 v67, v70
	s_nop 0
	v_mul_f32_e32 v56, v56, v67
	v_mul_f32_e32 v70, 0xbfb8aa3b, v58
	v_exp_f32_e32 v72, v70
	v_mul_f32_e32 v70, 0xbfb8aa3b, v59
	v_exp_f32_e32 v73, v70
	s_nop 0
	v_pk_add_f32 v[72:73], v[72:73], 1.0 op_sel_hi:[1,0]
	v_rcp_f32_e32 v67, v71
	s_nop 0
	v_mul_f32_e32 v57, v57, v67
	v_rcp_f32_e32 v67, v72
	s_nop 0
	v_mul_f32_e32 v58, v58, v67
	v_rcp_f32_e32 v67, v73
	s_nop 0
	v_mul_f32_e32 v59, v59, v67
.LBB0_1858:
	s_andn2_saveexec_b64 s[0:1], s[0:1]
	v_pk_mul_f32 v[56:57], v[56:57], s[24:25] op_sel_hi:[1,0]
	v_pk_mul_f32 v[58:59], v[58:59], s[24:25] op_sel_hi:[1,0]
	s_or_b64 exec, exec, s[0:1]
	v_or_b32_e32 v67, 32, v64
	v_cmp_lt_i32_e64 s[8:9], s33, v67
	s_and_saveexec_b64 s[0:1], s[8:9]
	s_xor_b64 s[0:1], exec, s[0:1]
	s_cbranch_execz .LBB0_1863
	s_cmpk_lt_u32 s35, 0xa00
	s_cbranch_scc1 .LBB0_1863
	v_mul_f32_e32 v67, 0xbfb8aa3b, v52
	v_exp_f32_e32 v70, v67
	v_mul_f32_e32 v67, 0xbfb8aa3b, v53
	v_exp_f32_e32 v71, v67
	s_nop 0
	v_pk_add_f32 v[70:71], v[70:71], 1.0 op_sel_hi:[1,0]
	s_nop 0
	v_rcp_f32_e32 v67, v70
	s_nop 0
	v_mul_f32_e32 v52, v52, v67
	v_mul_f32_e32 v70, 0xbfb8aa3b, v54
	v_exp_f32_e32 v72, v70
	v_mul_f32_e32 v70, 0xbfb8aa3b, v55
	v_exp_f32_e32 v73, v70
	s_nop 0
	v_pk_add_f32 v[72:73], v[72:73], 1.0 op_sel_hi:[1,0]
	v_rcp_f32_e32 v67, v71
	s_nop 0
	v_mul_f32_e32 v53, v53, v67
	v_rcp_f32_e32 v67, v72
	s_nop 0
	v_mul_f32_e32 v54, v54, v67
	v_rcp_f32_e32 v67, v73
	s_nop 0
	v_mul_f32_e32 v55, v55, v67
.LBB0_1863:
	s_andn2_saveexec_b64 s[0:1], s[0:1]
	v_pk_mul_f32 v[52:53], v[52:53], s[24:25] op_sel_hi:[1,0]
	v_pk_mul_f32 v[54:55], v[54:55], s[24:25] op_sel_hi:[1,0]
	s_or_b64 exec, exec, s[0:1]
	v_or_b32_e32 v64, 48, v64
	v_cmp_lt_i32_e64 s[10:11], s33, v64
	s_and_saveexec_b64 s[0:1], s[10:11]
	s_xor_b64 s[0:1], exec, s[0:1]
	s_cbranch_execz .LBB0_1868
	s_cmpk_lt_u32 s35, 0xa00
	s_cbranch_scc1 .LBB0_1868
	v_mul_f32_e32 v64, 0xbfb8aa3b, v48
	v_exp_f32_e32 v70, v64
	v_mul_f32_e32 v64, 0xbfb8aa3b, v49
	v_exp_f32_e32 v71, v64
	s_nop 0
	v_pk_add_f32 v[70:71], v[70:71], 1.0 op_sel_hi:[1,0]
	s_nop 0
	v_rcp_f32_e32 v64, v70
	s_nop 0
	v_mul_f32_e32 v48, v48, v64
	v_mul_f32_e32 v70, 0xbfb8aa3b, v50
	v_exp_f32_e32 v72, v70
	v_mul_f32_e32 v70, 0xbfb8aa3b, v51
	v_exp_f32_e32 v73, v70
	s_nop 0
	v_pk_add_f32 v[72:73], v[72:73], 1.0 op_sel_hi:[1,0]
	v_rcp_f32_e32 v64, v71
	s_nop 0
	v_mul_f32_e32 v49, v49, v64
	v_rcp_f32_e32 v64, v72
	s_nop 0
	v_mul_f32_e32 v50, v50, v64
	v_rcp_f32_e32 v64, v73
	s_nop 0
	v_mul_f32_e32 v51, v51, v64
.LBB0_1868:
	s_andn2_saveexec_b64 s[0:1], s[0:1]
	v_pk_mul_f32 v[48:49], v[48:49], s[24:25] op_sel_hi:[1,0]
	v_pk_mul_f32 v[50:51], v[50:51], s[24:25] op_sel_hi:[1,0]
	s_or_b64 exec, exec, s[0:1]
	v_cvt_pk_bf16_f32 v52, v52, v53
	v_cvt_pk_bf16_f32 v53, v54, v55
	v_cvt_pk_bf16_f32 v54, v48, v49
	v_mov_b64_e32 v[48:49], s[14:15]
	v_cvt_pk_bf16_f32 v72, v56, v57
	v_ashrrev_i32_e32 v67, 31, v66
	v_and_b32_e32 v56, 16, v82
	v_mad_i64_i32 v[48:49], s[0:1], v74, s34, v[48:49]
	v_cvt_pk_bf16_f32 v55, v50, v51
	v_lshl_add_u64 v[50:51], v[66:67], 1, v[48:49]
	v_add_u32_e32 v48, 12, v68
	v_cmp_eq_u32_e32 vcc, 0, v56
	v_cvt_pk_bf16_f32 v73, v58, v59
	v_cvt_pk_bf16_f32 v70, v60, v61
	v_cndmask_b32_e32 v48, v48, v68, vcc
	v_cvt_pk_bf16_f32 v71, v62, v63
	v_lshlrev_b32_e32 v64, 1, v48
	v_permlane16_swap_b32_e32 v70, v72
	v_permlane16_swap_b32_e32 v71, v73
	v_lshl_add_u64 v[48:49], v[50:51], 0, v[64:65]
	global_store_dwordx4 v[48:49], v[70:73], off
	v_add_u32_e32 v48, 44, v68
	v_or_b32_e32 v49, 32, v68
	v_cndmask_b32_e32 v48, v48, v49, vcc
	v_lshlrev_b32_e32 v48, 1, v48
	v_mov_b32_e32 v49, v65
	v_permlane16_swap_b32_e32 v52, v54
	v_permlane16_swap_b32_e32 v53, v55
	v_lshl_add_u64 v[50:51], v[50:51], 0, v[48:49]
	global_store_dwordx4 v[50:51], v[52:55], off
	s_and_saveexec_b64 s[0:1], s[4:5]
	s_xor_b64 s[0:1], exec, s[0:1]
	s_cbranch_execz .LBB0_1873
	s_cmpk_lt_u32 s35, 0xa00
	s_cbranch_scc1 .LBB0_1873
	v_mul_f32_e32 v49, 0xbfb8aa3b, v44
	v_exp_f32_e32 v50, v49
	v_mul_f32_e32 v49, 0xbfb8aa3b, v45
	v_exp_f32_e32 v51, v49
	s_nop 0
	v_pk_add_f32 v[50:51], v[50:51], 1.0 op_sel_hi:[1,0]
	s_nop 0
	v_rcp_f32_e32 v49, v50
	v_mul_f32_e32 v52, 0xbfb8aa3b, v46
	v_mul_f32_e32 v53, 0xbfb8aa3b, v47
	v_exp_f32_e32 v52, v52
	v_exp_f32_e32 v53, v53
	v_mul_f32_e32 v44, v44, v49
	v_pk_add_f32 v[52:53], v[52:53], 1.0 op_sel_hi:[1,0]
	v_rcp_f32_e32 v49, v51
	s_nop 0
	v_mul_f32_e32 v45, v45, v49
	v_rcp_f32_e32 v49, v52
	s_nop 0
	v_mul_f32_e32 v46, v46, v49
	v_rcp_f32_e32 v49, v53
	s_nop 0
	v_mul_f32_e32 v47, v47, v49
; DI unsigned pack2(float a, float b) { v2f f = {a, b}; return __builtin_bit_cast(unsigned, __builtin_convertvector(f, v2bf)); }
; DI float silu_f(float v) { return v / (1.f + fexp(-v)); }
;   DI u32x2 pack(int, int, float a, float b, float c, float d, float&) const { u32x2 v; v.x = pack2(a, b); v.y = pack2(c, d); return v; }
; template <class ARow, class Epi>
; DI void gemm_tile(const ARow& arow, long a_kstride, const u16* __restrict__ Bt, long ldb, int K, int m0, int n0,
;                   const Epi& epi, char* smem) {
;     ...
;     for (int mi = 0; mi < 4; ++mi) {
;       const int m = m0 + wm * 64 + mi * 16 + fr;
;       float ss = 0.f;
;       u32x2 pk[4];
; #pragma unroll
;       for (int ni = 0; ni < 4; ++ni) pk[ni] = epi.pack(m, nh + ni * 16 + fq * 4, acc[ni][mi][0], acc[ni][mi][1], acc[ni][mi][2], acc[ni][mi][3], ss);
;       epi.finish16(m, nh, ss);
;       u16* rp = epi.rowp(m) + nh;
; #pragma unroll
;       for (int pp = 0; pp < 2; ++pp) {
;         u32x2 a = pk[2 * pp], b = pk[2 * pp + 1];
;         const u32x2 rx = __builtin_amdgcn_permlane16_swap(a.x, b.x, false, false);
;         const u32x2 ry = __builtin_amdgcn_permlane16_swap(a.y, b.y, false, false);
;         const int nst = (fq & 1) ? ((2 * pp + 1) * 16 + (fq - 1) * 4) : ((2 * pp) * 16 + fq * 4);
;         *(u32x4*)(rp + nst) = (u32x4){rx[0], ry[0], rx[1], ry[1]};
;       }
;   DI u32x2 pack(int m, int n, float a, float b, float c, float d, float& ss) const {
;     if (n < q_end) { a *= qscale; b *= qscale; c *= qscale; d *= qscale; }
;     else if (n >= z_start) { a = silu_f(a); b = silu_f(b); c = silu_f(c); d = silu_f(d); }
;     ss += a * a + b * b + c * c + d * d;
;     u32x2 v; v.x = pack2(a, b); v.y = pack2(c, d);
;     return v;
.LBB0_1873:
	s_andn2_saveexec_b64 s[0:1], s[0:1]
	v_pk_mul_f32 v[44:45], v[44:45], s[24:25] op_sel_hi:[1,0]
	v_pk_mul_f32 v[46:47], v[46:47], s[24:25] op_sel_hi:[1,0]
	s_or_b64 exec, exec, s[0:1]
	s_and_saveexec_b64 s[0:1], s[6:7]
	s_xor_b64 s[0:1], exec, s[0:1]
	s_cbranch_execz .LBB0_1878
	s_cmpk_lt_u32 s35, 0xa00
	s_cbranch_scc1 .LBB0_1878
	v_mul_f32_e32 v49, 0xbfb8aa3b, v40
	v_exp_f32_e32 v50, v49
	v_mul_f32_e32 v49, 0xbfb8aa3b, v41
	v_exp_f32_e32 v51, v49
	s_nop 0
	v_pk_add_f32 v[50:51], v[50:51], 1.0 op_sel_hi:[1,0]
	s_nop 0
	v_rcp_f32_e32 v49, v50
	v_mul_f32_e32 v52, 0xbfb8aa3b, v42
	v_mul_f32_e32 v53, 0xbfb8aa3b, v43
	v_exp_f32_e32 v52, v52
	v_exp_f32_e32 v53, v53
	v_mul_f32_e32 v40, v40, v49
	v_pk_add_f32 v[52:53], v[52:53], 1.0 op_sel_hi:[1,0]
	v_rcp_f32_e32 v49, v51
	s_nop 0
	v_mul_f32_e32 v41, v41, v49
	v_rcp_f32_e32 v49, v52
	s_nop 0
	v_mul_f32_e32 v42, v42, v49
	v_rcp_f32_e32 v49, v53
	s_nop 0
	v_mul_f32_e32 v43, v43, v49
.LBB0_1878:
	s_andn2_saveexec_b64 s[0:1], s[0:1]
	v_pk_mul_f32 v[40:41], v[40:41], s[24:25] op_sel_hi:[1,0]
	v_pk_mul_f32 v[42:43], v[42:43], s[24:25] op_sel_hi:[1,0]
	s_or_b64 exec, exec, s[0:1]
	s_and_saveexec_b64 s[0:1], s[8:9]
	s_xor_b64 s[0:1], exec, s[0:1]
	s_cbranch_execz .LBB0_1883
	s_cmpk_lt_u32 s35, 0xa00
	s_cbranch_scc1 .LBB0_1883
	v_mul_f32_e32 v49, 0xbfb8aa3b, v36
	v_exp_f32_e32 v50, v49
	v_mul_f32_e32 v49, 0xbfb8aa3b, v37
	v_exp_f32_e32 v51, v49
	s_nop 0
	v_pk_add_f32 v[50:51], v[50:51], 1.0 op_sel_hi:[1,0]
	s_nop 0
	v_rcp_f32_e32 v49, v50
	v_mul_f32_e32 v52, 0xbfb8aa3b, v38
	v_mul_f32_e32 v53, 0xbfb8aa3b, v39
	v_exp_f32_e32 v52, v52
	v_exp_f32_e32 v53, v53
	v_mul_f32_e32 v36, v36, v49
	v_pk_add_f32 v[52:53], v[52:53], 1.0 op_sel_hi:[1,0]
	v_rcp_f32_e32 v49, v51
	s_nop 0
	v_mul_f32_e32 v37, v37, v49
	v_rcp_f32_e32 v49, v52
	s_nop 0
	v_mul_f32_e32 v38, v38, v49
	v_rcp_f32_e32 v49, v53
	s_nop 0
	v_mul_f32_e32 v39, v39, v49
.LBB0_1883:
	s_andn2_saveexec_b64 s[0:1], s[0:1]
	v_pk_mul_f32 v[36:37], v[36:37], s[24:25] op_sel_hi:[1,0]
	v_pk_mul_f32 v[38:39], v[38:39], s[24:25] op_sel_hi:[1,0]
	s_or_b64 exec, exec, s[0:1]
	s_and_saveexec_b64 s[0:1], s[10:11]
	s_xor_b64 s[0:1], exec, s[0:1]
	s_cbranch_execz .LBB0_1888
	s_cmpk_lt_u32 s35, 0xa00
	s_cbranch_scc1 .LBB0_1888
	v_mul_f32_e32 v49, 0xbfb8aa3b, v32
	v_exp_f32_e32 v50, v49
	v_mul_f32_e32 v49, 0xbfb8aa3b, v33
	v_exp_f32_e32 v51, v49
	s_nop 0
	v_pk_add_f32 v[50:51], v[50:51], 1.0 op_sel_hi:[1,0]
	s_nop 0
	v_rcp_f32_e32 v49, v50
	v_mul_f32_e32 v52, 0xbfb8aa3b, v34
	v_mul_f32_e32 v53, 0xbfb8aa3b, v35
	v_exp_f32_e32 v52, v52
	v_exp_f32_e32 v53, v53
	v_mul_f32_e32 v32, v32, v49
	v_pk_add_f32 v[52:53], v[52:53], 1.0 op_sel_hi:[1,0]
	v_rcp_f32_e32 v49, v51
	s_nop 0
	v_mul_f32_e32 v33, v33, v49
	v_rcp_f32_e32 v49, v52
	s_nop 0
	v_mul_f32_e32 v34, v34, v49
	v_rcp_f32_e32 v49, v53
	s_nop 0
	v_mul_f32_e32 v35, v35, v49
.LBB0_1888:
	s_andn2_saveexec_b64 s[0:1], s[0:1]
	v_pk_mul_f32 v[32:33], v[32:33], s[24:25] op_sel_hi:[1,0]
	v_pk_mul_f32 v[34:35], v[34:35], s[24:25] op_sel_hi:[1,0]
	s_or_b64 exec, exec, s[0:1]
	v_cvt_pk_bf16_f32 v36, v36, v37
	v_cvt_pk_bf16_f32 v37, v38, v39
	v_cvt_pk_bf16_f32 v38, v32, v33
	v_cvt_pk_bf16_f32 v39, v34, v35
	v_or_b32_e32 v34, 16, v74
	v_mov_b64_e32 v[32:33], s[14:15]
	v_mad_i64_i32 v[32:33], s[0:1], v34, s34, v[32:33]
	v_cvt_pk_bf16_f32 v52, v40, v41
	v_cvt_pk_bf16_f32 v53, v42, v43
	v_cvt_pk_bf16_f32 v50, v44, v45
	v_cvt_pk_bf16_f32 v51, v46, v47
	v_lshl_add_u64 v[32:33], v[66:67], 1, v[32:33]
	v_mov_b32_e32 v49, v65
	v_permlane16_swap_b32_e32 v50, v52
	v_permlane16_swap_b32_e32 v51, v53
	v_lshl_add_u64 v[34:35], v[32:33], 0, v[64:65]
	v_permlane16_swap_b32_e32 v36, v38
	v_permlane16_swap_b32_e32 v37, v39
	v_lshl_add_u64 v[32:33], v[32:33], 0, v[48:49]
	global_store_dwordx4 v[34:35], v[50:53], off
	global_store_dwordx4 v[32:33], v[36:39], off
	s_and_saveexec_b64 s[0:1], s[4:5]
	s_xor_b64 s[0:1], exec, s[0:1]
	s_cbranch_execz .LBB0_1893
	s_cmpk_lt_u32 s35, 0xa00
	s_cbranch_scc1 .LBB0_1893
	v_mul_f32_e32 v32, 0xbfb8aa3b, v28
	v_mul_f32_e32 v33, 0xbfb8aa3b, v29
	v_exp_f32_e32 v32, v32
	v_exp_f32_e32 v33, v33
	s_nop 0
	v_pk_add_f32 v[32:33], v[32:33], 1.0 op_sel_hi:[1,0]
	s_nop 0
	v_rcp_f32_e32 v34, v32
	s_nop 0
	v_mul_f32_e32 v28, v28, v34
	v_mul_f32_e32 v34, 0xbfb8aa3b, v30
	v_mul_f32_e32 v35, 0xbfb8aa3b, v31
	v_exp_f32_e32 v34, v34
	v_exp_f32_e32 v35, v35
	s_nop 0
	v_pk_add_f32 v[34:35], v[34:35], 1.0 op_sel_hi:[1,0]
	v_rcp_f32_e32 v32, v33
	s_nop 0
	v_mul_f32_e32 v29, v29, v32
	v_rcp_f32_e32 v32, v34
	s_nop 0
	v_mul_f32_e32 v30, v30, v32
	v_rcp_f32_e32 v32, v35
	s_nop 0
	v_mul_f32_e32 v31, v31, v32
.LBB0_1893:
	s_andn2_saveexec_b64 s[0:1], s[0:1]
	v_pk_mul_f32 v[28:29], v[28:29], s[24:25] op_sel_hi:[1,0]
	v_pk_mul_f32 v[30:31], v[30:31], s[24:25] op_sel_hi:[1,0]
	s_or_b64 exec, exec, s[0:1]
	s_and_saveexec_b64 s[0:1], s[6:7]
	s_xor_b64 s[0:1], exec, s[0:1]
	s_cbranch_execz .LBB0_1898
	s_cmpk_lt_u32 s35, 0xa00
	s_cbranch_scc1 .LBB0_1898
	v_mul_f32_e32 v32, 0xbfb8aa3b, v24
	v_mul_f32_e32 v33, 0xbfb8aa3b, v25
	v_exp_f32_e32 v32, v32
	v_exp_f32_e32 v33, v33
	s_nop 0
	v_pk_add_f32 v[32:33], v[32:33], 1.0 op_sel_hi:[1,0]
	s_nop 0
	v_rcp_f32_e32 v34, v32
	s_nop 0
	v_mul_f32_e32 v24, v24, v34
	v_mul_f32_e32 v34, 0xbfb8aa3b, v26
	v_mul_f32_e32 v35, 0xbfb8aa3b, v27
	v_exp_f32_e32 v34, v34
	v_exp_f32_e32 v35, v35
	s_nop 0
	v_pk_add_f32 v[34:35], v[34:35], 1.0 op_sel_hi:[1,0]
	v_rcp_f32_e32 v32, v33
	s_nop 0
	v_mul_f32_e32 v25, v25, v32
	v_rcp_f32_e32 v32, v34
	s_nop 0
	v_mul_f32_e32 v26, v26, v32
	v_rcp_f32_e32 v32, v35
	s_nop 0
	v_mul_f32_e32 v27, v27, v32
; DI unsigned pack2(float a, float b) { v2f f = {a, b}; return __builtin_bit_cast(unsigned, __builtin_convertvector(f, v2bf)); }
; DI float silu_f(float v) { return v / (1.f + fexp(-v)); }
;   DI u32x2 pack(int, int, float a, float b, float c, float d, float&) const { u32x2 v; v.x = pack2(a, b); v.y = pack2(c, d); return v; }
; template <class ARow, class Epi>
; DI void gemm_tile(const ARow& arow, long a_kstride, const u16* __restrict__ Bt, long ldb, int K, int m0, int n0,
;                   const Epi& epi, char* smem) {
;     ...
;     for (int mi = 0; mi < 4; ++mi) {
;       const int m = m0 + wm * 64 + mi * 16 + fr;
;       float ss = 0.f;
;       u32x2 pk[4];
; #pragma unroll
;       for (int ni = 0; ni < 4; ++ni) pk[ni] = epi.pack(m, nh + ni * 16 + fq * 4, acc[ni][mi][0], acc[ni][mi][1], acc[ni][mi][2], acc[ni][mi][3], ss);
;       epi.finish16(m, nh, ss);
;       u16* rp = epi.rowp(m) + nh;
; #pragma unroll
;       for (int pp = 0; pp < 2; ++pp) {
;         u32x2 a = pk[2 * pp], b = pk[2 * pp + 1];
;         const u32x2 rx = __builtin_amdgcn_permlane16_swap(a.x, b.x, false, false);
;         const u32x2 ry = __builtin_amdgcn_permlane16_swap(a.y, b.y, false, false);
;         const int nst = (fq & 1) ? ((2 * pp + 1) * 16 + (fq - 1) * 4) : ((2 * pp) * 16 + fq * 4);
;         *(u32x4*)(rp + nst) = (u32x4){rx[0], ry[0], rx[1], ry[1]};
;       }
;   DI u32x2 pack(int m, int n, float a, float b, float c, float d, float& ss) const {
;     if (n < q_end) { a *= qscale; b *= qscale; c *= qscale; d *= qscale; }
;     else if (n >= z_start) { a = silu_f(a); b = silu_f(b); c = silu_f(c); d = silu_f(d); }
;     ss += a * a + b * b + c * c + d * d;
;     u32x2 v; v.x = pack2(a, b); v.y = pack2(c, d);
;     return v;
.LBB0_1898:
	s_andn2_saveexec_b64 s[0:1], s[0:1]
	v_pk_mul_f32 v[24:25], v[24:25], s[24:25] op_sel_hi:[1,0]
	v_pk_mul_f32 v[26:27], v[26:27], s[24:25] op_sel_hi:[1,0]
	s_or_b64 exec, exec, s[0:1]
	s_and_saveexec_b64 s[0:1], s[8:9]
	s_xor_b64 s[0:1], exec, s[0:1]
	s_cbranch_execz .LBB0_1903
	s_cmpk_lt_u32 s35, 0xa00
	s_cbranch_scc1 .LBB0_1903
	v_mul_f32_e32 v32, 0xbfb8aa3b, v20
	v_mul_f32_e32 v33, 0xbfb8aa3b, v21
	v_exp_f32_e32 v32, v32
	v_exp_f32_e32 v33, v33
	s_nop 0
	v_pk_add_f32 v[32:33], v[32:33], 1.0 op_sel_hi:[1,0]
	s_nop 0
	v_rcp_f32_e32 v34, v32
	s_nop 0
	v_mul_f32_e32 v20, v20, v34
	v_mul_f32_e32 v34, 0xbfb8aa3b, v22
	v_mul_f32_e32 v35, 0xbfb8aa3b, v23
	v_exp_f32_e32 v34, v34
	v_exp_f32_e32 v35, v35
	s_nop 0
	v_pk_add_f32 v[34:35], v[34:35], 1.0 op_sel_hi:[1,0]
	v_rcp_f32_e32 v32, v33
	s_nop 0
	v_mul_f32_e32 v21, v21, v32
	v_rcp_f32_e32 v32, v34
	s_nop 0
	v_mul_f32_e32 v22, v22, v32
	v_rcp_f32_e32 v32, v35
	s_nop 0
	v_mul_f32_e32 v23, v23, v32
.LBB0_1903:
	s_andn2_saveexec_b64 s[0:1], s[0:1]
	v_pk_mul_f32 v[20:21], v[20:21], s[24:25] op_sel_hi:[1,0]
	v_pk_mul_f32 v[22:23], v[22:23], s[24:25] op_sel_hi:[1,0]
	s_or_b64 exec, exec, s[0:1]
	s_and_saveexec_b64 s[0:1], s[10:11]
	s_xor_b64 s[0:1], exec, s[0:1]
	s_cbranch_execz .LBB0_1908
	s_cmpk_lt_u32 s35, 0xa00
	s_cbranch_scc1 .LBB0_1908
	v_mul_f32_e32 v32, 0xbfb8aa3b, v16
	v_mul_f32_e32 v33, 0xbfb8aa3b, v17
	v_exp_f32_e32 v32, v32
	v_exp_f32_e32 v33, v33
	s_nop 0
	v_pk_add_f32 v[32:33], v[32:33], 1.0 op_sel_hi:[1,0]
	s_nop 0
	v_rcp_f32_e32 v34, v32
	s_nop 0
	v_mul_f32_e32 v16, v16, v34
	v_mul_f32_e32 v34, 0xbfb8aa3b, v18
	v_mul_f32_e32 v35, 0xbfb8aa3b, v19
	v_exp_f32_e32 v34, v34
	v_exp_f32_e32 v35, v35
	s_nop 0
	v_pk_add_f32 v[34:35], v[34:35], 1.0 op_sel_hi:[1,0]
	v_rcp_f32_e32 v32, v33
	s_nop 0
	v_mul_f32_e32 v17, v17, v32
	v_rcp_f32_e32 v32, v34
	s_nop 0
	v_mul_f32_e32 v18, v18, v32
	v_rcp_f32_e32 v32, v35
	s_nop 0
	v_mul_f32_e32 v19, v19, v32
.LBB0_1908:
	s_andn2_saveexec_b64 s[0:1], s[0:1]
	v_pk_mul_f32 v[16:17], v[16:17], s[24:25] op_sel_hi:[1,0]
	v_pk_mul_f32 v[18:19], v[18:19], s[24:25] op_sel_hi:[1,0]
	s_or_b64 exec, exec, s[0:1]
	v_cvt_pk_bf16_f32 v20, v20, v21
	v_cvt_pk_bf16_f32 v21, v22, v23
	v_cvt_pk_bf16_f32 v22, v16, v17
	v_cvt_pk_bf16_f32 v23, v18, v19
	v_or_b32_e32 v18, 32, v74
	v_mov_b64_e32 v[16:17], s[14:15]
	v_mad_i64_i32 v[16:17], s[0:1], v18, s34, v[16:17]
	v_cvt_pk_bf16_f32 v34, v24, v25
	v_cvt_pk_bf16_f32 v35, v26, v27
	v_cvt_pk_bf16_f32 v32, v28, v29
	v_cvt_pk_bf16_f32 v33, v30, v31
	v_lshl_add_u64 v[16:17], v[66:67], 1, v[16:17]
	v_mov_b32_e32 v49, v65
	v_permlane16_swap_b32_e32 v32, v34
	v_permlane16_swap_b32_e32 v33, v35
	v_lshl_add_u64 v[18:19], v[16:17], 0, v[64:65]
	v_permlane16_swap_b32_e32 v20, v22
	v_permlane16_swap_b32_e32 v21, v23
	v_lshl_add_u64 v[16:17], v[16:17], 0, v[48:49]
	global_store_dwordx4 v[18:19], v[32:35], off
	global_store_dwordx4 v[16:17], v[20:23], off
	s_and_saveexec_b64 s[0:1], s[4:5]
	s_xor_b64 s[0:1], exec, s[0:1]
	s_cbranch_execz .LBB0_1913
	s_cmpk_lt_u32 s35, 0xa00
	s_cbranch_scc1 .LBB0_1913
	v_mul_f32_e32 v16, 0xbfb8aa3b, v12
	v_mul_f32_e32 v17, 0xbfb8aa3b, v13
	v_exp_f32_e32 v16, v16
	v_exp_f32_e32 v17, v17
	s_nop 0
	v_pk_add_f32 v[16:17], v[16:17], 1.0 op_sel_hi:[1,0]
	s_nop 0
	v_rcp_f32_e32 v18, v16
	s_nop 0
	v_mul_f32_e32 v12, v12, v18
	v_mul_f32_e32 v18, 0xbfb8aa3b, v14
	v_mul_f32_e32 v19, 0xbfb8aa3b, v15
	v_exp_f32_e32 v18, v18
	v_exp_f32_e32 v19, v19
	s_nop 0
	v_pk_add_f32 v[18:19], v[18:19], 1.0 op_sel_hi:[1,0]
	v_rcp_f32_e32 v16, v17
	s_nop 0
	v_mul_f32_e32 v13, v13, v16
	v_rcp_f32_e32 v16, v18
	s_nop 0
	v_mul_f32_e32 v14, v14, v16
	v_rcp_f32_e32 v16, v19
	s_nop 0
	v_mul_f32_e32 v15, v15, v16
.LBB0_1913:
	s_andn2_saveexec_b64 s[0:1], s[0:1]
	v_pk_mul_f32 v[12:13], v[12:13], s[24:25] op_sel_hi:[1,0]
	v_pk_mul_f32 v[14:15], v[14:15], s[24:25] op_sel_hi:[1,0]
	s_or_b64 exec, exec, s[0:1]
	s_and_saveexec_b64 s[0:1], s[6:7]
	s_xor_b64 s[0:1], exec, s[0:1]
	s_cbranch_execz .LBB0_1918
	s_cmpk_lt_u32 s35, 0xa00
	s_cbranch_scc1 .LBB0_1918
	v_mul_f32_e32 v16, 0xbfb8aa3b, v8
	v_mul_f32_e32 v17, 0xbfb8aa3b, v9
	v_exp_f32_e32 v16, v16
	v_exp_f32_e32 v17, v17
	s_nop 0
	v_pk_add_f32 v[16:17], v[16:17], 1.0 op_sel_hi:[1,0]
	s_nop 0
	v_rcp_f32_e32 v18, v16
	s_nop 0
	v_mul_f32_e32 v8, v8, v18
	v_mul_f32_e32 v18, 0xbfb8aa3b, v10
	v_mul_f32_e32 v19, 0xbfb8aa3b, v11
	v_exp_f32_e32 v18, v18
	v_exp_f32_e32 v19, v19
	s_nop 0
	v_pk_add_f32 v[18:19], v[18:19], 1.0 op_sel_hi:[1,0]
	v_rcp_f32_e32 v16, v17
	s_nop 0
	v_mul_f32_e32 v9, v9, v16
	v_rcp_f32_e32 v16, v18
	s_nop 0
	v_mul_f32_e32 v10, v10, v16
	v_rcp_f32_e32 v16, v19
	s_nop 0
	v_mul_f32_e32 v11, v11, v16
.LBB0_1918:
	s_andn2_saveexec_b64 s[0:1], s[0:1]
	v_pk_mul_f32 v[8:9], v[8:9], s[24:25] op_sel_hi:[1,0]
	v_pk_mul_f32 v[10:11], v[10:11], s[24:25] op_sel_hi:[1,0]
	s_or_b64 exec, exec, s[0:1]
	s_and_saveexec_b64 s[0:1], s[8:9]
	s_xor_b64 s[0:1], exec, s[0:1]
	s_cbranch_execz .LBB0_1923
	s_cmpk_lt_u32 s35, 0xa00
	s_cbranch_scc1 .LBB0_1923
	v_mul_f32_e32 v16, 0xbfb8aa3b, v4
	v_mul_f32_e32 v17, 0xbfb8aa3b, v5
	v_exp_f32_e32 v16, v16
	v_exp_f32_e32 v17, v17
	s_nop 0
	v_pk_add_f32 v[16:17], v[16:17], 1.0 op_sel_hi:[1,0]
	s_nop 0
	v_rcp_f32_e32 v18, v16
	s_nop 0
	v_mul_f32_e32 v4, v4, v18
	v_mul_f32_e32 v18, 0xbfb8aa3b, v6
	v_mul_f32_e32 v19, 0xbfb8aa3b, v7
	v_exp_f32_e32 v18, v18
	v_exp_f32_e32 v19, v19
	s_nop 0
	v_pk_add_f32 v[18:19], v[18:19], 1.0 op_sel_hi:[1,0]
	v_rcp_f32_e32 v16, v17
	s_nop 0
	v_mul_f32_e32 v5, v5, v16
	v_rcp_f32_e32 v16, v18
	s_nop 0
	v_mul_f32_e32 v6, v6, v16
	v_rcp_f32_e32 v16, v19
	s_nop 0
	v_mul_f32_e32 v7, v7, v16
.LBB0_1923:
	s_andn2_saveexec_b64 s[0:1], s[0:1]
	v_pk_mul_f32 v[4:5], v[4:5], s[24:25] op_sel_hi:[1,0]
	v_pk_mul_f32 v[6:7], v[6:7], s[24:25] op_sel_hi:[1,0]
	s_or_b64 exec, exec, s[0:1]
	s_and_saveexec_b64 s[0:1], s[10:11]
	s_xor_b64 s[0:1], exec, s[0:1]
	s_cbranch_execz .LBB0_1928
	s_cmpk_lt_u32 s35, 0xa00
	s_cbranch_scc1 .LBB0_1928
	v_mul_f32_e32 v16, 0xbfb8aa3b, v0
	v_mul_f32_e32 v17, 0xbfb8aa3b, v1
	v_exp_f32_e32 v16, v16
	v_exp_f32_e32 v17, v17
	s_nop 0
	v_pk_add_f32 v[16:17], v[16:17], 1.0 op_sel_hi:[1,0]
	s_nop 0
	v_rcp_f32_e32 v18, v16
	s_nop 0
	v_mul_f32_e32 v0, v0, v18
	v_mul_f32_e32 v18, 0xbfb8aa3b, v2
	v_mul_f32_e32 v19, 0xbfb8aa3b, v3
	v_exp_f32_e32 v18, v18
	v_exp_f32_e32 v19, v19
	s_nop 0
	v_pk_add_f32 v[18:19], v[18:19], 1.0 op_sel_hi:[1,0]
	v_rcp_f32_e32 v16, v17
	s_nop 0
	v_mul_f32_e32 v1, v1, v16
	v_rcp_f32_e32 v16, v18
	s_nop 0
	v_mul_f32_e32 v2, v2, v16
	v_rcp_f32_e32 v16, v19
	s_nop 0
	v_mul_f32_e32 v3, v3, v16

; template <class ARow, class Epi>
; DI void gemm_tile(const ARow& arow, long a_kstride, const u16* __restrict__ Bt, long ldb, int K, int m0, int n0,
;                   const Epi& epi, char* smem) {
;     ...
;   for (int kt = 0; kt < KT; ++kt) {
;     const int cur = kt & 1;
;     if (kt + 1 < KT) GEMM_STAGE(cur ^ 1, kt + 1);
;     const char* sa = smem + cur * 32768 + wm * 64 * 128;
;     const char* sb = smem + cur * 32768 + 16384 + wn * 64 * 128;
; #pragma unroll
;     for (int ks = 0; ks < 2; ++ks) {
;       bf16x8 wf[4], af[4];
; #pragma unroll
;       for (int j = 0; j < 4; ++j) {
;         wf[j] = *(const bf16x8*)(sb + j * 2048 + foff[ks]);
;         af[j] = *(const bf16x8*)(sa + j * 2048 + foff[ks]);
;       }
; #pragma unroll
;       for (int ni = 0; ni < 4; ++ni)
; #pragma unroll
;         for (int mi = 0; mi < 4; ++mi) acc[ni][mi] = __builtin_amdgcn_mfma_f32_16x16x32_bf16(wf[ni], af[mi], acc[ni][mi], 0, 0, 0);
;     }
;     asm volatile("s_waitcnt vmcnt(0)" ::: "memory");
;     __syncthreads();
;   }
.LBB0_2314:
	s_and_b32 s6, s1, 0x8000
	s_xor_b32 s7, s6, 0x8000
	v_add_u32_e32 v108, s7, v90
	v_add_u32_e32 v91, s6, v88
	v_or_b32_e32 v116, s6, v89
	v_readfirstlane_b32 s6, v108
	v_add_u32_e32 v109, 0x4000, v108
	v_lshl_add_u64 v[92:93], v[66:67], 0, s[4:5]
	v_add_u32_e32 v110, 0x400, v108
	v_readfirstlane_b32 s7, v109
	s_mov_b32 m0, s6
	v_lshl_add_u64 v[94:95], v[68:69], 0, s[4:5]
	v_add_u32_e32 v111, 0x4400, v108
	v_readfirstlane_b32 s8, v110
	global_load_lds_dwordx4 v[92:93], off
	s_mov_b32 m0, s7
	v_lshl_add_u64 v[96:97], v[70:71], 0, s[4:5]
	v_add_u32_e32 v113, 0x800, v108
	v_readfirstlane_b32 s9, v111
	global_load_lds_dwordx4 v[94:95], off
	s_mov_b32 m0, s8
	v_lshl_add_u64 v[98:99], v[72:73], 0, s[4:5]
	v_add_u32_e32 v114, 0x4800, v108
	v_readfirstlane_b32 s10, v113
	global_load_lds_dwordx4 v[96:97], off
	s_mov_b32 m0, s9
	v_lshl_add_u64 v[100:101], v[74:75], 0, s[4:5]
	v_add_u32_e32 v115, 0xc00, v108
	v_readfirstlane_b32 s11, v114
	global_load_lds_dwordx4 v[98:99], off
	s_mov_b32 m0, s10
	v_lshl_add_u64 v[102:103], v[76:77], 0, s[4:5]
	v_add_u32_e32 v108, 0x4c00, v108
	v_readfirstlane_b32 s26, v115
	global_load_lds_dwordx4 v[100:101], off
	s_mov_b32 m0, s11
	v_lshl_add_u64 v[104:105], v[78:79], 0, s[4:5]
	v_readfirstlane_b32 s27, v108
	global_load_lds_dwordx4 v[102:103], off
	s_mov_b32 m0, s26
	v_lshl_add_u64 v[106:107], v[80:81], 0, s[4:5]
	global_load_lds_dwordx4 v[104:105], off
	s_mov_b32 m0, s27
	v_add_u32_e32 v117, v116, v87
	global_load_lds_dwordx4 v[106:107], off
	v_add_u32_e32 v112, v91, v87
	ds_read_b128 v[92:95], v117 offset:16384
	ds_read_b128 v[96:99], v112
	ds_read_b128 v[100:103], v117 offset:18432
	ds_read_b128 v[104:107], v112 offset:2048
	ds_read_b128 v[108:111], v112 offset:4096
	ds_read_b128 v[112:115], v112 offset:6144
	s_waitcnt lgkmcnt(0)
	v_mfma_f32_16x16x32_bf16 v[60:63], v[92:95], v[96:99], v[60:63]
	v_add_u32_e32 v116, v116, v86
	v_add_u32_e32 v91, v91, v86
	s_add_i32 s1, s1, 0x8000
	v_mfma_f32_16x16x32_bf16 v[56:59], v[92:95], v[104:107], v[56:59]
	s_add_u32 s4, s4, 0x80
	s_addc_u32 s5, s5, 0
	s_cmpk_eq_i32 s4, 0x780
	v_mfma_f32_16x16x32_bf16 v[48:51], v[92:95], v[108:111], v[48:51]
	v_mfma_f32_16x16x32_bf16 v[40:43], v[92:95], v[112:115], v[40:43]
	v_mfma_f32_16x16x32_bf16 v[36:39], v[100:103], v[96:99], v[36:39]
	v_mfma_f32_16x16x32_bf16 v[32:35], v[100:103], v[104:107], v[32:35]
	v_mfma_f32_16x16x32_bf16 v[28:31], v[100:103], v[108:111], v[28:31]
	v_mfma_f32_16x16x32_bf16 v[24:27], v[100:103], v[112:115], v[24:27]
	ds_read_b128 v[92:95], v117 offset:20480
	ds_read_b128 v[100:103], v117 offset:22528
	s_waitcnt lgkmcnt(0)
	v_mfma_f32_16x16x32_bf16 v[20:23], v[92:95], v[96:99], v[20:23]
	v_mfma_f32_16x16x32_bf16 v[16:19], v[92:95], v[104:107], v[16:19]
	v_mfma_f32_16x16x32_bf16 v[12:15], v[92:95], v[108:111], v[12:15]
	v_mfma_f32_16x16x32_bf16 v[8:11], v[92:95], v[112:115], v[8:11]
	ds_read_b128 v[92:95], v116 offset:16384
	v_mfma_f32_16x16x32_bf16 v[4:7], v[100:103], v[96:99], v[4:7]
	v_mfma_f32_16x16x32_bf16 v[0:3], v[100:103], v[104:107], v[0:3]
	v_mfma_f32_16x16x32_bf16 v[52:55], v[100:103], v[108:111], v[52:55]
	v_mfma_f32_16x16x32_bf16 v[44:47], v[100:103], v[112:115], v[44:47]
	ds_read_b128 v[96:99], v91
	ds_read_b128 v[100:103], v116 offset:18432
	ds_read_b128 v[104:107], v91 offset:2048
	ds_read_b128 v[108:111], v91 offset:4096
	ds_read_b128 v[112:115], v91 offset:6144
	s_waitcnt lgkmcnt(0)
	v_mfma_f32_16x16x32_bf16 v[60:63], v[92:95], v[96:99], v[60:63]
	v_mfma_f32_16x16x32_bf16 v[56:59], v[92:95], v[104:107], v[56:59]
	v_mfma_f32_16x16x32_bf16 v[48:51], v[92:95], v[108:111], v[48:51]
	v_mfma_f32_16x16x32_bf16 v[40:43], v[92:95], v[112:115], v[40:43]
	v_mfma_f32_16x16x32_bf16 v[36:39], v[100:103], v[96:99], v[36:39]
	v_mfma_f32_16x16x32_bf16 v[32:35], v[100:103], v[104:107], v[32:35]
	v_mfma_f32_16x16x32_bf16 v[28:31], v[100:103], v[108:111], v[28:31]
	v_mfma_f32_16x16x32_bf16 v[24:27], v[100:103], v[112:115], v[24:27]
	ds_read_b128 v[92:95], v116 offset:20480
	ds_read_b128 v[100:103], v116 offset:22528
	s_waitcnt vmcnt(0)
	s_waitcnt vmcnt(0) lgkmcnt(0)
	v_mfma_f32_16x16x32_bf16 v[20:23], v[92:95], v[96:99], v[20:23]
	s_barrier
	v_mfma_f32_16x16x32_bf16 v[16:19], v[92:95], v[104:107], v[16:19]
	v_mfma_f32_16x16x32_bf16 v[12:15], v[92:95], v[108:111], v[12:15]
	v_mfma_f32_16x16x32_bf16 v[8:11], v[92:95], v[112:115], v[8:11]
	v_mfma_f32_16x16x32_bf16 v[4:7], v[100:103], v[96:99], v[4:7]
	v_mfma_f32_16x16x32_bf16 v[0:3], v[100:103], v[104:107], v[0:3]
	v_mfma_f32_16x16x32_bf16 v[52:55], v[100:103], v[108:111], v[52:55]
	v_mfma_f32_16x16x32_bf16 v[44:47], v[100:103], v[112:115], v[44:47]
	s_cbranch_scc0 .LBB0_2314
; DI float sigmoid_f(float v) { return 1.f / (1.f + fexp(-v)); }
;   DI void operator()(int m, int n, float a, float b, float c, float d, float& ss) const { u32x2 v; v.x = pack2(a, b); v.y = pack2(c, d); *(u32x2*)(y + (long)m * 1024 + n) = v; }
; template <class ARow, class Epi>
; DI void gemm_tile(const ARow& arow, long a_kstride, const u16* __restrict__ Bt, long ldb, int K, int m0, int n0,
;                   const Epi& epi, char* smem) {
;     ...
;   for (int kt = 0; kt < KT; ++kt) {
;     const int cur = kt & 1;
;     if (kt + 1 < KT) GEMM_STAGE(cur ^ 1, kt + 1);
;     const char* sa = smem + cur * 32768 + wm * 64 * 128;
;     const char* sb = smem + cur * 32768 + 16384 + wn * 64 * 128;
; #pragma unroll
;     for (int ks = 0; ks < 2; ++ks) {
;       bf16x8 wf[4], af[4];
; #pragma unroll
;       for (int j = 0; j < 4; ++j) {
;         wf[j] = *(const bf16x8*)(sb + j * 2048 + foff[ks]);
;         af[j] = *(const bf16x8*)(sa + j * 2048 + foff[ks]);
;       }
; #pragma unroll
;       for (int ni = 0; ni < 4; ++ni)
; #pragma unroll
;         for (int mi = 0; mi < 4; ++mi) acc[ni][mi] = __builtin_amdgcn_mfma_f32_16x16x32_bf16(wf[ni], af[mi], acc[ni][mi], 0, 0, 0);
;     }
;     asm volatile("s_waitcnt vmcnt(0)" ::: "memory");
;     __syncthreads();
;   }
;   DI void operator()(int m, int n, float a, float b, float c, float d, float& ss) const {
;     if (n >= gl_start) {
;       const int j = n - gl_start;
;       if (j < 48) { float* g = gates + (long)m * 48 + j; g[0] = sigmoid_f(a); g[1] = sigmoid_f(b); g[2] = sigmoid_f(c); g[3] = sigmoid_f(d); }
;       return;
	v_add_u32_e32 v106, v89, v87
	ds_read_b128 v[66:69], v106 offset:49152
	v_add_u32_e32 v87, v88, v87
	ds_read_b128 v[70:73], v87 offset:32768
	ds_read_b128 v[74:77], v87 offset:34816
	ds_read_b128 v[78:81], v87 offset:36864
	ds_read_b128 v[90:93], v87 offset:38912
	v_add_u32_e32 v114, v89, v86
	s_waitcnt lgkmcnt(3)
	v_mfma_f32_16x16x32_bf16 v[60:63], v[66:69], v[70:73], v[60:63]
	s_waitcnt lgkmcnt(2)
	v_mfma_f32_16x16x32_bf16 v[56:59], v[66:69], v[74:77], v[56:59]
	s_waitcnt lgkmcnt(1)
	v_mfma_f32_16x16x32_bf16 v[48:51], v[66:69], v[78:81], v[48:51]
	s_waitcnt lgkmcnt(0)
	v_mfma_f32_16x16x32_bf16 v[40:43], v[66:69], v[90:93], v[40:43]
	ds_read_b128 v[66:69], v106 offset:51200
	s_waitcnt lgkmcnt(0)
	v_mfma_f32_16x16x32_bf16 v[36:39], v[66:69], v[70:73], v[36:39]
	v_mfma_f32_16x16x32_bf16 v[32:35], v[66:69], v[74:77], v[32:35]
	v_mfma_f32_16x16x32_bf16 v[94:97], v[66:69], v[78:81], v[28:31]
	v_mfma_f32_16x16x32_bf16 v[66:69], v[66:69], v[90:93], v[24:27]
	s_nop 2
	ds_read_b128 v[24:27], v106 offset:53248
	s_waitcnt lgkmcnt(0)
	v_mfma_f32_16x16x32_bf16 v[102:105], v[24:27], v[90:93], v[8:11]
	s_nop 2
	ds_read_b128 v[8:11], v106 offset:55296
	v_mfma_f32_16x16x32_bf16 v[20:23], v[24:27], v[70:73], v[20:23]
	s_waitcnt lgkmcnt(0)
	v_mfma_f32_16x16x32_bf16 v[70:73], v[8:11], v[70:73], v[4:7]
	s_nop 2
	ds_read_b128 v[4:7], v114 offset:49152
	v_mfma_f32_16x16x32_bf16 v[98:101], v[24:27], v[78:81], v[12:15]
	s_nop 2
	v_add_u32_e32 v12, v88, v86
	v_mfma_f32_16x16x32_bf16 v[16:19], v[24:27], v[74:77], v[16:19]
	ds_read_b128 v[86:89], v12 offset:32768
	ds_read_b128 v[106:109], v12 offset:36864
	ds_read_b128 v[110:113], v12 offset:38912
	v_mfma_f32_16x16x32_bf16 v[0:3], v[8:11], v[74:77], v[0:3]
	v_mfma_f32_16x16x32_bf16 v[74:77], v[8:11], v[78:81], v[52:55]
	v_mfma_f32_16x16x32_bf16 v[78:81], v[8:11], v[90:93], v[44:47]
	ds_read_b128 v[90:93], v12 offset:34816
	s_waitcnt lgkmcnt(3)
	v_mfma_f32_16x16x32_bf16 v[60:63], v[4:7], v[86:89], v[60:63]
	s_waitcnt lgkmcnt(0)
	v_mfma_f32_16x16x32_bf16 v[44:47], v[4:7], v[90:93], v[56:59]
	v_mfma_f32_16x16x32_bf16 v[28:31], v[4:7], v[106:109], v[48:51]
	v_mfma_f32_16x16x32_bf16 v[12:15], v[4:7], v[110:113], v[40:43]
	ds_read_b128 v[4:7], v114 offset:51200
	s_waitcnt lgkmcnt(0)
	v_mfma_f32_16x16x32_bf16 v[56:59], v[4:7], v[86:89], v[36:39]
	v_mfma_f32_16x16x32_bf16 v[40:43], v[4:7], v[90:93], v[32:35]
	v_mfma_f32_16x16x32_bf16 v[24:27], v[4:7], v[106:109], v[94:97]
	v_mfma_f32_16x16x32_bf16 v[8:11], v[4:7], v[110:113], v[66:69]
	ds_read_b128 v[4:7], v114 offset:53248
	s_nop 0
	ds_read_b128 v[94:97], v114 offset:55296
	s_waitcnt vmcnt(0)
	s_waitcnt lgkmcnt(0)
	v_mfma_f32_16x16x32_bf16 v[32:35], v[94:97], v[90:93], v[0:3]
	s_nop 2
	v_or_b32_e32 v0, s0, v64
	v_lshl_add_u32 v66, v85, 6, v0
	v_lshl_or_b32 v68, v84, 6, s34
	v_mfma_f32_16x16x32_bf16 v[52:55], v[4:7], v[86:89], v[20:23]
	v_cmp_lt_i32_e32 vcc, s30, v68
	s_barrier
	v_mfma_f32_16x16x32_bf16 v[36:39], v[4:7], v[90:93], v[16:19]
	v_mfma_f32_16x16x32_bf16 v[20:23], v[4:7], v[106:109], v[98:101]
	v_mfma_f32_16x16x32_bf16 v[4:7], v[4:7], v[110:113], v[102:105]
	v_mfma_f32_16x16x32_bf16 v[48:51], v[94:97], v[86:89], v[70:73]
	v_mfma_f32_16x16x32_bf16 v[16:19], v[94:97], v[106:109], v[74:77]
	s_nop 1
	v_lshlrev_b32_e32 v70, 2, v83
	v_or_b32_e32 v64, v68, v70
	v_mfma_f32_16x16x32_bf16 v[0:3], v[94:97], v[110:113], v[78:81]
	s_and_saveexec_b64 s[0:1], vcc
	s_xor_b64 s[26:27], exec, s[0:1]
	s_cbranch_execz .LBB0_2461
	v_mad_i64_i32 v[70:71], s[0:1], v66, s31, 0
	v_cmp_lt_i32_e64 s[4:5], s30, v64
	v_add_u32_e32 v68, -2.0, v64
	s_and_saveexec_b64 s[0:1], s[4:5]
	s_xor_b64 s[0:1], exec, s[0:1]
	s_cbranch_execz .LBB0_2320
	v_cmp_gt_u32_e32 vcc, 48, v68
	s_and_saveexec_b64 s[6:7], vcc
	s_cbranch_execz .LBB0_2319
	v_mul_f32_e32 v60, 0xbfb8aa3b, v60
	v_mul_f32_e32 v61, 0xbfb8aa3b, v61
	v_exp_f32_e32 v60, v60
	v_exp_f32_e32 v61, v61
	v_mov_b32_e32 v69, v65
	v_lshl_add_u64 v[72:73], v[68:69], 2, v[70:71]
	v_mul_f32_e32 v62, 0xbfb8aa3b, v62
	v_pk_add_f32 v[60:61], v[60:61], 1.0 op_sel_hi:[1,0]
	v_mul_f32_e32 v63, 0xbfb8aa3b, v63
	v_exp_f32_e32 v62, v62
	v_exp_f32_e32 v63, v63
	v_rcp_f32_e32 v67, v61
	s_nop 0
	v_mul_f32_e32 v61, 1.0, v67
	v_pk_add_f32 v[62:63], v[62:63], 1.0 op_sel_hi:[1,0]
	v_rcp_f32_e32 v67, v60
	s_nop 0
	v_mul_f32_e32 v60, 1.0, v67
	v_rcp_f32_e32 v67, v63
	s_nop 0
	v_mul_f32_e32 v63, 1.0, v67
	v_rcp_f32_e32 v67, v62
	s_nop 0
	v_mul_f32_e32 v62, 1.0, v67
	flat_store_dwordx4 v[72:73], v[60:63]

; DI unsigned pack2(float a, float b) { v2f f = {a, b}; return __builtin_bit_cast(unsigned, __builtin_convertvector(f, v2bf)); }
; DI float fexp(float x) { return __builtin_amdgcn_exp2f(x * LOG2E); }
; DI float silu_f(float v) { return v / (1.f + fexp(-v)); }
;   DI void operator()(int m, int n, float a, float b, float c, float d, float& ss) const {
;     ...
;     if (n < q_end) { a *= qscale; b *= qscale; c *= qscale; d *= qscale; }
;     else if (n >= z_start) { a = silu_f(a); b = silu_f(b); c = silu_f(c); d = silu_f(d); }
;     ss += a * a + b * b + c * c + d * d;
;     u32x2 v; v.x = pack2(a, b); v.y = pack2(c, d);
;     *(u32x2*)(dst + (long)m * ld + n) = v;
.LBB0_2320:
	s_or_saveexec_b64 s[0:1], s[0:1]
	v_ashrrev_i32_e32 v67, 31, v66
	s_xor_b64 exec, exec, s[0:1]
	s_cbranch_execz .LBB0_2326
	v_cmp_lt_i32_e32 vcc, s33, v64
	s_and_saveexec_b64 s[6:7], vcc
	s_xor_b64 s[6:7], exec, s[6:7]
	s_cbranch_execz .LBB0_2323
	v_mul_f32_e32 v69, 0xbfb8aa3b, v60
	v_exp_f32_e32 v72, v69
	v_mul_f32_e32 v69, 0xbfb8aa3b, v61
	v_exp_f32_e32 v73, v69
	s_nop 0
	v_pk_add_f32 v[72:73], v[72:73], 1.0 op_sel_hi:[1,0]
	s_nop 0
	v_rcp_f32_e32 v69, v73
	v_mul_f32_e32 v74, 0xbfb8aa3b, v62
	v_mul_f32_e32 v75, 0xbfb8aa3b, v63
	v_exp_f32_e32 v74, v74
	v_exp_f32_e32 v75, v75
	v_mul_f32_e32 v73, v61, v69
	v_pk_add_f32 v[74:75], v[74:75], 1.0 op_sel_hi:[1,0]
	v_rcp_f32_e32 v61, v72
	s_nop 0
	v_mul_f32_e32 v72, v60, v61
	v_rcp_f32_e32 v60, v75
	s_nop 0
	v_mul_f32_e32 v75, v63, v60
	v_rcp_f32_e32 v60, v74
	s_nop 0
	v_mul_f32_e32 v74, v62, v60

; DI float fexp(float x) { return __builtin_amdgcn_exp2f(x * LOG2E); }
; DI float sigmoid_f(float v) { return 1.f / (1.f + fexp(-v)); }
;   DI void operator()(int m, int n, float a, float b, float c, float d, float& ss) const {
;     if (n >= gl_start) {
;       const int j = n - gl_start;
;       if (j < 48) { float* g = gates + (long)m * 48 + j; g[0] = sigmoid_f(a); g[1] = sigmoid_f(b); g[2] = sigmoid_f(c); g[3] = sigmoid_f(d); }
;       return;
.LBB0_2326:
	s_or_b64 exec, exec, s[0:1]
	v_or_b32_e32 v74, 16, v64
	v_cmp_lt_i32_e64 s[6:7], s30, v74
	v_add_u32_e32 v60, 0xc0000010, v64
	s_and_saveexec_b64 s[0:1], s[6:7]
	s_xor_b64 s[0:1], exec, s[0:1]
	s_cbranch_execz .LBB0_2330
	v_cmp_gt_u32_e32 vcc, 48, v60
	s_and_saveexec_b64 s[8:9], vcc
	s_cbranch_execz .LBB0_2329
	v_mul_f32_e32 v56, 0xbfb8aa3b, v56
	v_mul_f32_e32 v57, 0xbfb8aa3b, v57
	v_exp_f32_e32 v56, v56
	v_exp_f32_e32 v57, v57
	v_mov_b32_e32 v61, v65
	v_lshl_add_u64 v[62:63], v[60:61], 2, v[70:71]
	v_mul_f32_e32 v58, 0xbfb8aa3b, v58
	v_pk_add_f32 v[56:57], v[56:57], 1.0 op_sel_hi:[1,0]
	v_mul_f32_e32 v59, 0xbfb8aa3b, v59
	v_exp_f32_e32 v58, v58
	v_exp_f32_e32 v59, v59
	v_rcp_f32_e32 v61, v57
	s_nop 0
	v_mul_f32_e32 v57, 1.0, v61
	v_pk_add_f32 v[58:59], v[58:59], 1.0 op_sel_hi:[1,0]
	v_rcp_f32_e32 v61, v56
	s_nop 0
	v_mul_f32_e32 v56, 1.0, v61
	v_rcp_f32_e32 v61, v59
	s_nop 0
	v_mul_f32_e32 v59, 1.0, v61
	v_rcp_f32_e32 v61, v58
	s_nop 0
	v_mul_f32_e32 v58, 1.0, v61
	flat_store_dwordx4 v[62:63], v[56:59]

; DI unsigned pack2(float a, float b) { v2f f = {a, b}; return __builtin_bit_cast(unsigned, __builtin_convertvector(f, v2bf)); }
; DI float fexp(float x) { return __builtin_amdgcn_exp2f(x * LOG2E); }
; DI float silu_f(float v) { return v / (1.f + fexp(-v)); }
;   DI void operator()(int m, int n, float a, float b, float c, float d, float& ss) const {
;     ...
;     if (n < q_end) { a *= qscale; b *= qscale; c *= qscale; d *= qscale; }
;     else if (n >= z_start) { a = silu_f(a); b = silu_f(b); c = silu_f(c); d = silu_f(d); }
;     ss += a * a + b * b + c * c + d * d;
;     u32x2 v; v.x = pack2(a, b); v.y = pack2(c, d);
;     *(u32x2*)(dst + (long)m * ld + n) = v;
.LBB0_2330:
	s_andn2_saveexec_b64 s[0:1], s[0:1]
	s_cbranch_execz .LBB0_2336
	v_cmp_lt_i32_e32 vcc, s33, v74
	s_and_saveexec_b64 s[8:9], vcc
	s_xor_b64 s[8:9], exec, s[8:9]
	s_cbranch_execz .LBB0_2333
	v_mul_f32_e32 v61, 0xbfb8aa3b, v56
	v_exp_f32_e32 v62, v61
	v_mul_f32_e32 v61, 0xbfb8aa3b, v57
	v_exp_f32_e32 v63, v61
	s_nop 0
	v_pk_add_f32 v[62:63], v[62:63], 1.0 op_sel_hi:[1,0]
	s_nop 0
	v_rcp_f32_e32 v61, v63
	v_mul_f32_e32 v69, 0xbfb8aa3b, v58
	v_exp_f32_e32 v72, v69
	v_mul_f32_e32 v69, 0xbfb8aa3b, v59
	v_exp_f32_e32 v73, v69
	v_mul_f32_e32 v63, v57, v61
	v_pk_add_f32 v[72:73], v[72:73], 1.0 op_sel_hi:[1,0]
	v_rcp_f32_e32 v57, v62
	s_nop 0
	v_mul_f32_e32 v62, v56, v57
	v_rcp_f32_e32 v56, v73
	s_nop 0
	v_mul_f32_e32 v73, v59, v56
	v_rcp_f32_e32 v56, v72
	s_nop 0
	v_mul_f32_e32 v72, v58, v56

; DI float fexp(float x) { return __builtin_amdgcn_exp2f(x * LOG2E); }
; DI float sigmoid_f(float v) { return 1.f / (1.f + fexp(-v)); }
;   DI void operator()(int m, int n, float a, float b, float c, float d, float& ss) const {
;     if (n >= gl_start) {
;       const int j = n - gl_start;
;       if (j < 48) { float* g = gates + (long)m * 48 + j; g[0] = sigmoid_f(a); g[1] = sigmoid_f(b); g[2] = sigmoid_f(c); g[3] = sigmoid_f(d); }
;       return;
.LBB0_2336:
	s_or_b64 exec, exec, s[0:1]
	v_or_b32_e32 v72, 32, v64
	v_cmp_lt_i32_e64 s[8:9], s30, v72
	v_add_u32_e32 v56, 0xc0000020, v64
	s_and_saveexec_b64 s[0:1], s[8:9]
	s_xor_b64 s[0:1], exec, s[0:1]
	s_cbranch_execz .LBB0_2340
	v_cmp_gt_u32_e32 vcc, 48, v56
	s_and_saveexec_b64 s[10:11], vcc
	s_cbranch_execz .LBB0_2339
	v_mul_f32_e32 v52, 0xbfb8aa3b, v52
	v_mul_f32_e32 v53, 0xbfb8aa3b, v53
	v_exp_f32_e32 v52, v52
	v_exp_f32_e32 v53, v53
	v_mov_b32_e32 v57, v65
	v_lshl_add_u64 v[58:59], v[56:57], 2, v[70:71]
	v_mul_f32_e32 v54, 0xbfb8aa3b, v54
	v_pk_add_f32 v[52:53], v[52:53], 1.0 op_sel_hi:[1,0]
	v_mul_f32_e32 v55, 0xbfb8aa3b, v55
	v_exp_f32_e32 v54, v54
	v_exp_f32_e32 v55, v55
	v_rcp_f32_e32 v57, v53
	s_nop 0
	v_mul_f32_e32 v53, 1.0, v57
	v_pk_add_f32 v[54:55], v[54:55], 1.0 op_sel_hi:[1,0]
	v_rcp_f32_e32 v57, v52
	s_nop 0
	v_mul_f32_e32 v52, 1.0, v57
	v_rcp_f32_e32 v57, v55
	s_nop 0
	v_mul_f32_e32 v55, 1.0, v57
	v_rcp_f32_e32 v57, v54
	s_nop 0
	v_mul_f32_e32 v54, 1.0, v57
	flat_store_dwordx4 v[58:59], v[52:55]

; DI unsigned pack2(float a, float b) { v2f f = {a, b}; return __builtin_bit_cast(unsigned, __builtin_convertvector(f, v2bf)); }
; DI float fexp(float x) { return __builtin_amdgcn_exp2f(x * LOG2E); }
; DI float silu_f(float v) { return v / (1.f + fexp(-v)); }
;   DI void operator()(int m, int n, float a, float b, float c, float d, float& ss) const {
;     ...
;     if (n < q_end) { a *= qscale; b *= qscale; c *= qscale; d *= qscale; }
;     else if (n >= z_start) { a = silu_f(a); b = silu_f(b); c = silu_f(c); d = silu_f(d); }
;     ss += a * a + b * b + c * c + d * d;
;     u32x2 v; v.x = pack2(a, b); v.y = pack2(c, d);
;     *(u32x2*)(dst + (long)m * ld + n) = v;
.LBB0_2340:
	s_andn2_saveexec_b64 s[0:1], s[0:1]
	s_cbranch_execz .LBB0_2346
	v_cmp_lt_i32_e32 vcc, s33, v72
	s_and_saveexec_b64 s[10:11], vcc
	s_xor_b64 s[10:11], exec, s[10:11]
	s_cbranch_execz .LBB0_2343
	v_mul_f32_e32 v57, 0xbfb8aa3b, v52
	v_exp_f32_e32 v58, v57
	v_mul_f32_e32 v57, 0xbfb8aa3b, v53
	v_exp_f32_e32 v59, v57
	s_nop 0
	v_pk_add_f32 v[58:59], v[58:59], 1.0 op_sel_hi:[1,0]
	s_nop 0
	v_rcp_f32_e32 v57, v59
	v_mul_f32_e32 v61, 0xbfb8aa3b, v54
	v_exp_f32_e32 v62, v61
	v_mul_f32_e32 v61, 0xbfb8aa3b, v55
	v_exp_f32_e32 v63, v61
	v_mul_f32_e32 v59, v53, v57
	v_pk_add_f32 v[62:63], v[62:63], 1.0 op_sel_hi:[1,0]
	v_rcp_f32_e32 v53, v58
	s_nop 0
	v_mul_f32_e32 v58, v52, v53
	v_rcp_f32_e32 v52, v63
	s_nop 0
	v_mul_f32_e32 v63, v55, v52
	v_rcp_f32_e32 v52, v62
	s_nop 0
	v_mul_f32_e32 v62, v54, v52

; DI float fexp(float x) { return __builtin_amdgcn_exp2f(x * LOG2E); }
; DI float sigmoid_f(float v) { return 1.f / (1.f + fexp(-v)); }
;   DI void operator()(int m, int n, float a, float b, float c, float d, float& ss) const {
;     if (n >= gl_start) {
;       const int j = n - gl_start;
;       if (j < 48) { float* g = gates + (long)m * 48 + j; g[0] = sigmoid_f(a); g[1] = sigmoid_f(b); g[2] = sigmoid_f(c); g[3] = sigmoid_f(d); }
;       return;
.LBB0_2359:
	v_cmp_gt_u32_e32 vcc, 48, v68
	s_and_saveexec_b64 s[28:29], vcc
	s_cbranch_execz .LBB0_2361
	v_mul_f32_e32 v44, 0xbfb8aa3b, v44
	v_mul_f32_e32 v45, 0xbfb8aa3b, v45
	v_exp_f32_e32 v44, v44
	v_exp_f32_e32 v45, v45
	v_mul_f32_e32 v46, 0xbfb8aa3b, v46
	v_mul_f32_e32 v47, 0xbfb8aa3b, v47
	v_exp_f32_e32 v46, v46
	v_pk_add_f32 v[44:45], v[44:45], 1.0 op_sel_hi:[1,0]
	v_exp_f32_e32 v47, v47
	s_nop 0
	v_pk_add_f32 v[46:47], v[46:47], 1.0 op_sel_hi:[1,0]
	v_mov_b32_e32 v69, v65
	v_lshl_add_u64 v[52:53], v[68:69], 2, v[50:51]
	v_rcp_f32_e32 v49, v45
	s_nop 0
	v_mul_f32_e32 v45, 1.0, v49
	v_rcp_f32_e32 v49, v44
	s_nop 0
	v_mul_f32_e32 v44, 1.0, v49
	v_rcp_f32_e32 v49, v47
	s_nop 0
	v_mul_f32_e32 v47, 1.0, v49
	v_rcp_f32_e32 v49, v46
	s_nop 0
	v_mul_f32_e32 v46, 1.0, v49
	flat_store_dwordx4 v[52:53], v[44:47]

; DI unsigned pack2(float a, float b) { v2f f = {a, b}; return __builtin_bit_cast(unsigned, __builtin_convertvector(f, v2bf)); }
; DI float fexp(float x) { return __builtin_amdgcn_exp2f(x * LOG2E); }
; DI float flog(float x) { return __builtin_amdgcn_logf(x) * 0.6931471805599453f; }
; DI float silu_f(float v) { return v / (1.f + fexp(-v)); }
;   DI void operator()(int m, int n, float a, float b, float c, float d, float& ss) const {
;     ...
;     if (n < q_end) { a *= qscale; b *= qscale; c *= qscale; d *= qscale; }
;     else if (n >= z_start) { a = silu_f(a); b = silu_f(b); c = silu_f(c); d = silu_f(d); }
;     ss += a * a + b * b + c * c + d * d;
;     u32x2 v; v.x = pack2(a, b); v.y = pack2(c, d);
;     *(u32x2*)(dst + (long)m * ld + n) = v;
.LBB0_2362:
	v_cmp_lt_i32_e32 vcc, s33, v64
	s_and_saveexec_b64 s[28:29], vcc
	s_xor_b64 s[28:29], exec, s[28:29]
	s_cbranch_execz .LBB0_2364
	v_mul_f32_e32 v52, 0xbfb8aa3b, v44
	v_mul_f32_e32 v53, 0xbfb8aa3b, v45
	v_exp_f32_e32 v52, v52
	v_exp_f32_e32 v53, v53
	s_nop 0
	v_pk_add_f32 v[52:53], v[52:53], 1.0 op_sel_hi:[1,0]
	s_nop 0
	v_rcp_f32_e32 v54, v53
	s_nop 0
	v_mul_f32_e32 v53, v45, v54
	v_mul_f32_e32 v54, 0xbfb8aa3b, v46
	v_mul_f32_e32 v55, 0xbfb8aa3b, v47
	v_exp_f32_e32 v54, v54
	v_exp_f32_e32 v55, v55
	s_nop 0
	v_pk_add_f32 v[54:55], v[54:55], 1.0 op_sel_hi:[1,0]
	v_rcp_f32_e32 v45, v52
	s_nop 0
	v_mul_f32_e32 v52, v44, v45
	v_rcp_f32_e32 v44, v55
	s_nop 0
	v_mul_f32_e32 v55, v47, v44
	v_rcp_f32_e32 v44, v54
	s_nop 0
	v_mul_f32_e32 v54, v46, v44

; DI float fexp(float x) { return __builtin_amdgcn_exp2f(x * LOG2E); }
; DI float sigmoid_f(float v) { return 1.f / (1.f + fexp(-v)); }
;   DI void operator()(int m, int n, float a, float b, float c, float d, float& ss) const {
;     if (n >= gl_start) {
;       const int j = n - gl_start;
;       if (j < 48) { float* g = gates + (long)m * 48 + j; g[0] = sigmoid_f(a); g[1] = sigmoid_f(b); g[2] = sigmoid_f(c); g[3] = sigmoid_f(d); }
;       return;
.LBB0_2367:
	v_cmp_gt_u32_e32 vcc, 48, v60
	s_and_saveexec_b64 s[28:29], vcc
	s_cbranch_execz .LBB0_2369
	v_mul_f32_e32 v40, 0xbfb8aa3b, v40
	v_mul_f32_e32 v41, 0xbfb8aa3b, v41
	v_exp_f32_e32 v40, v40
	v_exp_f32_e32 v41, v41
	v_mul_f32_e32 v42, 0xbfb8aa3b, v42
	v_mul_f32_e32 v43, 0xbfb8aa3b, v43
	v_exp_f32_e32 v42, v42
	v_pk_add_f32 v[40:41], v[40:41], 1.0 op_sel_hi:[1,0]
	v_exp_f32_e32 v43, v43
	s_nop 0
	v_pk_add_f32 v[42:43], v[42:43], 1.0 op_sel_hi:[1,0]
	v_mov_b32_e32 v61, v65
	v_lshl_add_u64 v[44:45], v[60:61], 2, v[50:51]
	v_rcp_f32_e32 v46, v41
	s_nop 0
	v_mul_f32_e32 v41, 1.0, v46
	v_rcp_f32_e32 v46, v40
	s_nop 0
	v_mul_f32_e32 v40, 1.0, v46
	v_rcp_f32_e32 v46, v43
	s_nop 0
	v_mul_f32_e32 v43, 1.0, v46
	v_rcp_f32_e32 v46, v42
	s_nop 0
	v_mul_f32_e32 v42, 1.0, v46
	flat_store_dwordx4 v[44:45], v[40:43]

; DI unsigned pack2(float a, float b) { v2f f = {a, b}; return __builtin_bit_cast(unsigned, __builtin_convertvector(f, v2bf)); }
; DI float fexp(float x) { return __builtin_amdgcn_exp2f(x * LOG2E); }
; DI float flog(float x) { return __builtin_amdgcn_logf(x) * 0.6931471805599453f; }
; DI float silu_f(float v) { return v / (1.f + fexp(-v)); }
;   DI void operator()(int m, int n, float a, float b, float c, float d, float& ss) const {
;     ...
;     if (n < q_end) { a *= qscale; b *= qscale; c *= qscale; d *= qscale; }
;     else if (n >= z_start) { a = silu_f(a); b = silu_f(b); c = silu_f(c); d = silu_f(d); }
;     ss += a * a + b * b + c * c + d * d;
;     u32x2 v; v.x = pack2(a, b); v.y = pack2(c, d);
;     *(u32x2*)(dst + (long)m * ld + n) = v;
.LBB0_2370:
	v_cmp_lt_i32_e32 vcc, s33, v74
	s_and_saveexec_b64 s[28:29], vcc
	s_xor_b64 s[28:29], exec, s[28:29]
	s_cbranch_execz .LBB0_2372
	v_mul_f32_e32 v44, 0xbfb8aa3b, v40
	v_mul_f32_e32 v45, 0xbfb8aa3b, v41
	v_exp_f32_e32 v44, v44
	v_exp_f32_e32 v45, v45
	s_nop 0
	v_pk_add_f32 v[44:45], v[44:45], 1.0 op_sel_hi:[1,0]
	s_nop 0
	v_rcp_f32_e32 v46, v45
	s_nop 0
	v_mul_f32_e32 v45, v41, v46
	v_mul_f32_e32 v46, 0xbfb8aa3b, v42
	v_mul_f32_e32 v47, 0xbfb8aa3b, v43
	v_exp_f32_e32 v46, v46
	v_exp_f32_e32 v47, v47
	s_nop 0
	v_pk_add_f32 v[46:47], v[46:47], 1.0 op_sel_hi:[1,0]
	v_rcp_f32_e32 v41, v44
	s_nop 0
	v_mul_f32_e32 v44, v40, v41
	v_rcp_f32_e32 v40, v47
	s_nop 0
	v_mul_f32_e32 v47, v43, v40
	v_rcp_f32_e32 v40, v46
	s_nop 0
	v_mul_f32_e32 v46, v42, v40

; DI float fexp(float x) { return __builtin_amdgcn_exp2f(x * LOG2E); }
; DI float sigmoid_f(float v) { return 1.f / (1.f + fexp(-v)); }
;   DI void operator()(int m, int n, float a, float b, float c, float d, float& ss) const {
;     if (n >= gl_start) {
;       const int j = n - gl_start;
;       if (j < 48) { float* g = gates + (long)m * 48 + j; g[0] = sigmoid_f(a); g[1] = sigmoid_f(b); g[2] = sigmoid_f(c); g[3] = sigmoid_f(d); }
;       return;
.LBB0_2375:
	v_cmp_gt_u32_e32 vcc, 48, v56
	s_and_saveexec_b64 s[28:29], vcc
	s_cbranch_execz .LBB0_2377
	v_mul_f32_e32 v36, 0xbfb8aa3b, v36
	v_mul_f32_e32 v37, 0xbfb8aa3b, v37
	v_exp_f32_e32 v36, v36
	v_exp_f32_e32 v37, v37
	v_mul_f32_e32 v38, 0xbfb8aa3b, v38
	v_mul_f32_e32 v39, 0xbfb8aa3b, v39
	v_exp_f32_e32 v38, v38
	v_pk_add_f32 v[36:37], v[36:37], 1.0 op_sel_hi:[1,0]
	v_exp_f32_e32 v39, v39
	s_nop 0
	v_pk_add_f32 v[38:39], v[38:39], 1.0 op_sel_hi:[1,0]
	v_mov_b32_e32 v57, v65
	v_lshl_add_u64 v[40:41], v[56:57], 2, v[50:51]
	v_rcp_f32_e32 v42, v37
	s_nop 0
	v_mul_f32_e32 v37, 1.0, v42
	v_rcp_f32_e32 v42, v36
	s_nop 0
	v_mul_f32_e32 v36, 1.0, v42
	v_rcp_f32_e32 v42, v39
	s_nop 0
	v_mul_f32_e32 v39, 1.0, v42
	v_rcp_f32_e32 v42, v38
	s_nop 0
	v_mul_f32_e32 v38, 1.0, v42
	flat_store_dwordx4 v[40:41], v[36:39]

; DI unsigned pack2(float a, float b) { v2f f = {a, b}; return __builtin_bit_cast(unsigned, __builtin_convertvector(f, v2bf)); }
; DI float fexp(float x) { return __builtin_amdgcn_exp2f(x * LOG2E); }
; DI float flog(float x) { return __builtin_amdgcn_logf(x) * 0.6931471805599453f; }
; DI float silu_f(float v) { return v / (1.f + fexp(-v)); }
;   DI void operator()(int m, int n, float a, float b, float c, float d, float& ss) const {
;     ...
;     if (n < q_end) { a *= qscale; b *= qscale; c *= qscale; d *= qscale; }
;     else if (n >= z_start) { a = silu_f(a); b = silu_f(b); c = silu_f(c); d = silu_f(d); }
;     ss += a * a + b * b + c * c + d * d;
;     u32x2 v; v.x = pack2(a, b); v.y = pack2(c, d);
;     *(u32x2*)(dst + (long)m * ld + n) = v;
.LBB0_2378:
	v_cmp_lt_i32_e32 vcc, s33, v72
	s_and_saveexec_b64 s[28:29], vcc
	s_xor_b64 s[28:29], exec, s[28:29]
	s_cbranch_execz .LBB0_2380
	v_mul_f32_e32 v40, 0xbfb8aa3b, v36
	v_mul_f32_e32 v41, 0xbfb8aa3b, v37
	v_exp_f32_e32 v40, v40
	v_exp_f32_e32 v41, v41
	s_nop 0
	v_pk_add_f32 v[40:41], v[40:41], 1.0 op_sel_hi:[1,0]
	s_nop 0
	v_rcp_f32_e32 v42, v41
	s_nop 0
	v_mul_f32_e32 v41, v37, v42
	v_mul_f32_e32 v42, 0xbfb8aa3b, v38
	v_mul_f32_e32 v43, 0xbfb8aa3b, v39
	v_exp_f32_e32 v42, v42
	v_exp_f32_e32 v43, v43
	s_nop 0
	v_pk_add_f32 v[42:43], v[42:43], 1.0 op_sel_hi:[1,0]
	v_rcp_f32_e32 v37, v40
	s_nop 0
	v_mul_f32_e32 v40, v36, v37
	v_rcp_f32_e32 v36, v43
	s_nop 0
	v_mul_f32_e32 v43, v39, v36
	v_rcp_f32_e32 v36, v42
	s_nop 0
	v_mul_f32_e32 v42, v38, v36

; DI float fexp(float x) { return __builtin_amdgcn_exp2f(x * LOG2E); }
; DI float sigmoid_f(float v) { return 1.f / (1.f + fexp(-v)); }
;   DI void operator()(int m, int n, float a, float b, float c, float d, float& ss) const {
;     if (n >= gl_start) {
;       const int j = n - gl_start;
;       if (j < 48) { float* g = gates + (long)m * 48 + j; g[0] = sigmoid_f(a); g[1] = sigmoid_f(b); g[2] = sigmoid_f(c); g[3] = sigmoid_f(d); }
;       return;
.LBB0_2395:
	v_cmp_gt_u32_e32 vcc, 48, v68
	s_and_saveexec_b64 s[28:29], vcc
	s_cbranch_execz .LBB0_2397
	v_mul_f32_e32 v28, 0xbfb8aa3b, v28
	v_mul_f32_e32 v29, 0xbfb8aa3b, v29
	v_exp_f32_e32 v28, v28
	v_exp_f32_e32 v29, v29
	v_mul_f32_e32 v30, 0xbfb8aa3b, v30
	v_mul_f32_e32 v31, 0xbfb8aa3b, v31
	v_exp_f32_e32 v30, v30
	v_pk_add_f32 v[28:29], v[28:29], 1.0 op_sel_hi:[1,0]
	v_exp_f32_e32 v31, v31
	s_nop 0
	v_pk_add_f32 v[30:31], v[30:31], 1.0 op_sel_hi:[1,0]
	v_mov_b32_e32 v69, v65
	v_lshl_add_u64 v[36:37], v[68:69], 2, v[34:35]
	v_rcp_f32_e32 v33, v29
	s_nop 0
	v_mul_f32_e32 v29, 1.0, v33
	v_rcp_f32_e32 v33, v28
	s_nop 0
	v_mul_f32_e32 v28, 1.0, v33
	v_rcp_f32_e32 v33, v31
	s_nop 0
	v_mul_f32_e32 v31, 1.0, v33
	v_rcp_f32_e32 v33, v30
	s_nop 0
	v_mul_f32_e32 v30, 1.0, v33
	flat_store_dwordx4 v[36:37], v[28:31]

; DI unsigned pack2(float a, float b) { v2f f = {a, b}; return __builtin_bit_cast(unsigned, __builtin_convertvector(f, v2bf)); }
; DI float fexp(float x) { return __builtin_amdgcn_exp2f(x * LOG2E); }
; DI float flog(float x) { return __builtin_amdgcn_logf(x) * 0.6931471805599453f; }
; DI float silu_f(float v) { return v / (1.f + fexp(-v)); }
;   DI void operator()(int m, int n, float a, float b, float c, float d, float& ss) const {
;     ...
;     if (n < q_end) { a *= qscale; b *= qscale; c *= qscale; d *= qscale; }
;     else if (n >= z_start) { a = silu_f(a); b = silu_f(b); c = silu_f(c); d = silu_f(d); }
;     ss += a * a + b * b + c * c + d * d;
;     u32x2 v; v.x = pack2(a, b); v.y = pack2(c, d);
;     *(u32x2*)(dst + (long)m * ld + n) = v;
.LBB0_2398:
	v_cmp_lt_i32_e32 vcc, s33, v64
	s_and_saveexec_b64 s[28:29], vcc
	s_xor_b64 s[28:29], exec, s[28:29]
	s_cbranch_execz .LBB0_2400
	v_mul_f32_e32 v36, 0xbfb8aa3b, v28
	v_mul_f32_e32 v37, 0xbfb8aa3b, v29
	v_exp_f32_e32 v36, v36
	v_exp_f32_e32 v37, v37
	s_nop 0
	v_pk_add_f32 v[36:37], v[36:37], 1.0 op_sel_hi:[1,0]
	s_nop 0
	v_rcp_f32_e32 v38, v37
	s_nop 0
	v_mul_f32_e32 v37, v29, v38
	v_mul_f32_e32 v38, 0xbfb8aa3b, v30
	v_mul_f32_e32 v39, 0xbfb8aa3b, v31
	v_exp_f32_e32 v38, v38
	v_exp_f32_e32 v39, v39
	s_nop 0
	v_pk_add_f32 v[38:39], v[38:39], 1.0 op_sel_hi:[1,0]
	v_rcp_f32_e32 v29, v36
	s_nop 0
	v_mul_f32_e32 v36, v28, v29
	v_rcp_f32_e32 v28, v39
	s_nop 0
	v_mul_f32_e32 v39, v31, v28
	v_rcp_f32_e32 v28, v38
	s_nop 0
	v_mul_f32_e32 v38, v30, v28

; DI float fexp(float x) { return __builtin_amdgcn_exp2f(x * LOG2E); }
; DI float sigmoid_f(float v) { return 1.f / (1.f + fexp(-v)); }
;   DI void operator()(int m, int n, float a, float b, float c, float d, float& ss) const {
;     if (n >= gl_start) {
;       const int j = n - gl_start;
;       if (j < 48) { float* g = gates + (long)m * 48 + j; g[0] = sigmoid_f(a); g[1] = sigmoid_f(b); g[2] = sigmoid_f(c); g[3] = sigmoid_f(d); }
;       return;
.LBB0_2403:
	v_cmp_gt_u32_e32 vcc, 48, v60
	s_and_saveexec_b64 s[28:29], vcc
	s_cbranch_execz .LBB0_2405
	v_mul_f32_e32 v24, 0xbfb8aa3b, v24
	v_mul_f32_e32 v25, 0xbfb8aa3b, v25
	v_exp_f32_e32 v24, v24
	v_exp_f32_e32 v25, v25
	v_mul_f32_e32 v26, 0xbfb8aa3b, v26
	v_mul_f32_e32 v27, 0xbfb8aa3b, v27
	v_exp_f32_e32 v26, v26
	v_pk_add_f32 v[24:25], v[24:25], 1.0 op_sel_hi:[1,0]
	v_exp_f32_e32 v27, v27
	s_nop 0
	v_pk_add_f32 v[26:27], v[26:27], 1.0 op_sel_hi:[1,0]
	v_mov_b32_e32 v61, v65
	v_lshl_add_u64 v[28:29], v[60:61], 2, v[34:35]
	v_rcp_f32_e32 v30, v25
	s_nop 0
	v_mul_f32_e32 v25, 1.0, v30
	v_rcp_f32_e32 v30, v24
	s_nop 0
	v_mul_f32_e32 v24, 1.0, v30
	v_rcp_f32_e32 v30, v27
	s_nop 0
	v_mul_f32_e32 v27, 1.0, v30
	v_rcp_f32_e32 v30, v26
	s_nop 0
	v_mul_f32_e32 v26, 1.0, v30
	flat_store_dwordx4 v[28:29], v[24:27]

; DI unsigned pack2(float a, float b) { v2f f = {a, b}; return __builtin_bit_cast(unsigned, __builtin_convertvector(f, v2bf)); }
; DI float fexp(float x) { return __builtin_amdgcn_exp2f(x * LOG2E); }
; DI float flog(float x) { return __builtin_amdgcn_logf(x) * 0.6931471805599453f; }
; DI float silu_f(float v) { return v / (1.f + fexp(-v)); }
;   DI void operator()(int m, int n, float a, float b, float c, float d, float& ss) const {
;     ...
;     if (n < q_end) { a *= qscale; b *= qscale; c *= qscale; d *= qscale; }
;     else if (n >= z_start) { a = silu_f(a); b = silu_f(b); c = silu_f(c); d = silu_f(d); }
;     ss += a * a + b * b + c * c + d * d;
;     u32x2 v; v.x = pack2(a, b); v.y = pack2(c, d);
;     *(u32x2*)(dst + (long)m * ld + n) = v;
.LBB0_2406:
	v_cmp_lt_i32_e32 vcc, s33, v74
	s_and_saveexec_b64 s[28:29], vcc
	s_xor_b64 s[28:29], exec, s[28:29]
	s_cbranch_execz .LBB0_2408
	v_mul_f32_e32 v28, 0xbfb8aa3b, v24
	v_mul_f32_e32 v29, 0xbfb8aa3b, v25
	v_exp_f32_e32 v28, v28
	v_exp_f32_e32 v29, v29
	s_nop 0
	v_pk_add_f32 v[28:29], v[28:29], 1.0 op_sel_hi:[1,0]
	s_nop 0
	v_rcp_f32_e32 v30, v29
	s_nop 0
	v_mul_f32_e32 v29, v25, v30
	v_mul_f32_e32 v30, 0xbfb8aa3b, v26
	v_mul_f32_e32 v31, 0xbfb8aa3b, v27
	v_exp_f32_e32 v30, v30
	v_exp_f32_e32 v31, v31
	s_nop 0
	v_pk_add_f32 v[30:31], v[30:31], 1.0 op_sel_hi:[1,0]
	v_rcp_f32_e32 v25, v28
	s_nop 0
	v_mul_f32_e32 v28, v24, v25
	v_rcp_f32_e32 v24, v31
	s_nop 0
	v_mul_f32_e32 v31, v27, v24
	v_rcp_f32_e32 v24, v30
	s_nop 0
	v_mul_f32_e32 v30, v26, v24

; DI float fexp(float x) { return __builtin_amdgcn_exp2f(x * LOG2E); }
; DI float sigmoid_f(float v) { return 1.f / (1.f + fexp(-v)); }
;   DI void operator()(int m, int n, float a, float b, float c, float d, float& ss) const {
;     if (n >= gl_start) {
;       const int j = n - gl_start;
;       if (j < 48) { float* g = gates + (long)m * 48 + j; g[0] = sigmoid_f(a); g[1] = sigmoid_f(b); g[2] = sigmoid_f(c); g[3] = sigmoid_f(d); }
;       return;
.LBB0_2411:
	v_cmp_gt_u32_e32 vcc, 48, v56
	s_and_saveexec_b64 s[28:29], vcc
	s_cbranch_execz .LBB0_2413
	v_mul_f32_e32 v20, 0xbfb8aa3b, v20
	v_mul_f32_e32 v21, 0xbfb8aa3b, v21
	v_exp_f32_e32 v20, v20
	v_exp_f32_e32 v21, v21
	v_mul_f32_e32 v22, 0xbfb8aa3b, v22
	v_mul_f32_e32 v23, 0xbfb8aa3b, v23
	v_exp_f32_e32 v22, v22
	v_pk_add_f32 v[20:21], v[20:21], 1.0 op_sel_hi:[1,0]
	v_exp_f32_e32 v23, v23
	s_nop 0
	v_pk_add_f32 v[22:23], v[22:23], 1.0 op_sel_hi:[1,0]
	v_mov_b32_e32 v57, v65
	v_lshl_add_u64 v[24:25], v[56:57], 2, v[34:35]
	v_rcp_f32_e32 v26, v21
	s_nop 0
	v_mul_f32_e32 v21, 1.0, v26
	v_rcp_f32_e32 v26, v20
	s_nop 0
	v_mul_f32_e32 v20, 1.0, v26
	v_rcp_f32_e32 v26, v23
	s_nop 0
	v_mul_f32_e32 v23, 1.0, v26
	v_rcp_f32_e32 v26, v22
	s_nop 0
	v_mul_f32_e32 v22, 1.0, v26
	flat_store_dwordx4 v[24:25], v[20:23]

; DI unsigned pack2(float a, float b) { v2f f = {a, b}; return __builtin_bit_cast(unsigned, __builtin_convertvector(f, v2bf)); }
; DI float fexp(float x) { return __builtin_amdgcn_exp2f(x * LOG2E); }
; DI float flog(float x) { return __builtin_amdgcn_logf(x) * 0.6931471805599453f; }
; DI float silu_f(float v) { return v / (1.f + fexp(-v)); }
;   DI void operator()(int m, int n, float a, float b, float c, float d, float& ss) const {
;     ...
;     if (n < q_end) { a *= qscale; b *= qscale; c *= qscale; d *= qscale; }
;     else if (n >= z_start) { a = silu_f(a); b = silu_f(b); c = silu_f(c); d = silu_f(d); }
;     ss += a * a + b * b + c * c + d * d;
;     u32x2 v; v.x = pack2(a, b); v.y = pack2(c, d);
;     *(u32x2*)(dst + (long)m * ld + n) = v;
.LBB0_2414:
	v_cmp_lt_i32_e32 vcc, s33, v72
	s_and_saveexec_b64 s[28:29], vcc
	s_xor_b64 s[28:29], exec, s[28:29]
	s_cbranch_execz .LBB0_2416
	v_mul_f32_e32 v24, 0xbfb8aa3b, v20
	v_mul_f32_e32 v25, 0xbfb8aa3b, v21
	v_exp_f32_e32 v24, v24
	v_exp_f32_e32 v25, v25
	s_nop 0
	v_pk_add_f32 v[24:25], v[24:25], 1.0 op_sel_hi:[1,0]
	s_nop 0
	v_rcp_f32_e32 v26, v25
	s_nop 0
	v_mul_f32_e32 v25, v21, v26
	v_mul_f32_e32 v26, 0xbfb8aa3b, v22
	v_mul_f32_e32 v27, 0xbfb8aa3b, v23
	v_exp_f32_e32 v26, v26
	v_exp_f32_e32 v27, v27
	s_nop 0
	v_pk_add_f32 v[26:27], v[26:27], 1.0 op_sel_hi:[1,0]
	v_rcp_f32_e32 v21, v24
	s_nop 0
	v_mul_f32_e32 v24, v20, v21
	v_rcp_f32_e32 v20, v27
	s_nop 0
	v_mul_f32_e32 v27, v23, v20
	v_rcp_f32_e32 v20, v26
	s_nop 0
	v_mul_f32_e32 v26, v22, v20

; DI unsigned pack2(float a, float b) { v2f f = {a, b}; return __builtin_bit_cast(unsigned, __builtin_convertvector(f, v2bf)); }
; DI float fexp(float x) { return __builtin_amdgcn_exp2f(x * LOG2E); }
; DI float flog(float x) { return __builtin_amdgcn_logf(x) * 0.6931471805599453f; }
; DI float silu_f(float v) { return v / (1.f + fexp(-v)); }
;   DI void operator()(int m, int n, float a, float b, float c, float d, float& ss) const {
;     ...
;     if (n < q_end) { a *= qscale; b *= qscale; c *= qscale; d *= qscale; }
;     else if (n >= z_start) { a = silu_f(a); b = silu_f(b); c = silu_f(c); d = silu_f(d); }
;     ss += a * a + b * b + c * c + d * d;
;     u32x2 v; v.x = pack2(a, b); v.y = pack2(c, d);
;     *(u32x2*)(dst + (long)m * ld + n) = v;
.LBB0_2434:
	v_cmp_lt_i32_e32 vcc, s33, v64
	s_and_saveexec_b64 s[4:5], vcc
	s_xor_b64 s[4:5], exec, s[4:5]
	s_cbranch_execz .LBB0_2436
	v_mul_f32_e32 v20, 0xbfb8aa3b, v12
	v_mul_f32_e32 v21, 0xbfb8aa3b, v13
	v_exp_f32_e32 v20, v20
	v_exp_f32_e32 v21, v21
	s_nop 0
	v_pk_add_f32 v[20:21], v[20:21], 1.0 op_sel_hi:[1,0]
	s_nop 0
	v_rcp_f32_e32 v22, v21
	s_nop 0
	v_mul_f32_e32 v21, v13, v22
	v_mul_f32_e32 v22, 0xbfb8aa3b, v14
	v_mul_f32_e32 v23, 0xbfb8aa3b, v15
	v_exp_f32_e32 v22, v22
	v_exp_f32_e32 v23, v23
	s_nop 0
	v_pk_add_f32 v[22:23], v[22:23], 1.0 op_sel_hi:[1,0]
	v_rcp_f32_e32 v13, v20
	s_nop 0
	v_mul_f32_e32 v20, v12, v13
	v_rcp_f32_e32 v12, v23
	s_nop 0
	v_mul_f32_e32 v23, v15, v12
	v_rcp_f32_e32 v12, v22
	s_nop 0
	v_mul_f32_e32 v22, v14, v12

; DI unsigned pack2(float a, float b) { v2f f = {a, b}; return __builtin_bit_cast(unsigned, __builtin_convertvector(f, v2bf)); }
; DI float fexp(float x) { return __builtin_amdgcn_exp2f(x * LOG2E); }
; DI float flog(float x) { return __builtin_amdgcn_logf(x) * 0.6931471805599453f; }
; DI float silu_f(float v) { return v / (1.f + fexp(-v)); }
;   DI void operator()(int m, int n, float a, float b, float c, float d, float& ss) const {
;     ...
;     if (n < q_end) { a *= qscale; b *= qscale; c *= qscale; d *= qscale; }
;     else if (n >= z_start) { a = silu_f(a); b = silu_f(b); c = silu_f(c); d = silu_f(d); }
;     ss += a * a + b * b + c * c + d * d;
;     u32x2 v; v.x = pack2(a, b); v.y = pack2(c, d);
;     *(u32x2*)(dst + (long)m * ld + n) = v;
.LBB0_2442:
	v_cmp_lt_i32_e32 vcc, s33, v74
	s_and_saveexec_b64 s[4:5], vcc
	s_xor_b64 s[4:5], exec, s[4:5]
	s_cbranch_execz .LBB0_2444
	v_mul_f32_e32 v12, 0xbfb8aa3b, v8
	v_mul_f32_e32 v13, 0xbfb8aa3b, v9
	v_exp_f32_e32 v12, v12
	v_exp_f32_e32 v13, v13
	s_nop 0
	v_pk_add_f32 v[12:13], v[12:13], 1.0 op_sel_hi:[1,0]
	s_nop 0
	v_rcp_f32_e32 v14, v13
	s_nop 0
	v_mul_f32_e32 v13, v9, v14
	v_mul_f32_e32 v14, 0xbfb8aa3b, v10
	v_mul_f32_e32 v15, 0xbfb8aa3b, v11
	v_exp_f32_e32 v14, v14
	v_exp_f32_e32 v15, v15
	s_nop 0
	v_pk_add_f32 v[14:15], v[14:15], 1.0 op_sel_hi:[1,0]
	v_rcp_f32_e32 v9, v12
	s_nop 0
	v_mul_f32_e32 v12, v8, v9
	v_rcp_f32_e32 v8, v15
	s_nop 0
	v_mul_f32_e32 v15, v11, v8
	v_rcp_f32_e32 v8, v14
	s_nop 0
	v_mul_f32_e32 v14, v10, v8

; DI unsigned pack2(float a, float b) { v2f f = {a, b}; return __builtin_bit_cast(unsigned, __builtin_convertvector(f, v2bf)); }
; DI float fexp(float x) { return __builtin_amdgcn_exp2f(x * LOG2E); }
; DI float flog(float x) { return __builtin_amdgcn_logf(x) * 0.6931471805599453f; }
; DI float silu_f(float v) { return v / (1.f + fexp(-v)); }
;   DI void operator()(int m, int n, float a, float b, float c, float d, float& ss) const {
;     ...
;     if (n < q_end) { a *= qscale; b *= qscale; c *= qscale; d *= qscale; }
;     else if (n >= z_start) { a = silu_f(a); b = silu_f(b); c = silu_f(c); d = silu_f(d); }
;     ss += a * a + b * b + c * c + d * d;
;     u32x2 v; v.x = pack2(a, b); v.y = pack2(c, d);
;     *(u32x2*)(dst + (long)m * ld + n) = v;
.LBB0_2450:
	v_cmp_lt_i32_e32 vcc, s33, v72
	s_and_saveexec_b64 s[4:5], vcc
	s_xor_b64 s[4:5], exec, s[4:5]
	s_cbranch_execz .LBB0_2452
	v_mul_f32_e32 v8, 0xbfb8aa3b, v4
	v_mul_f32_e32 v9, 0xbfb8aa3b, v5
	v_exp_f32_e32 v8, v8
	v_exp_f32_e32 v9, v9
	s_nop 0
	v_pk_add_f32 v[8:9], v[8:9], 1.0 op_sel_hi:[1,0]
	s_nop 0
	v_rcp_f32_e32 v10, v9
	s_nop 0
	v_mul_f32_e32 v9, v5, v10
	v_mul_f32_e32 v10, 0xbfb8aa3b, v6
	v_mul_f32_e32 v11, 0xbfb8aa3b, v7
	v_exp_f32_e32 v10, v10
	v_exp_f32_e32 v11, v11
	s_nop 0
	v_pk_add_f32 v[10:11], v[10:11], 1.0 op_sel_hi:[1,0]
	v_rcp_f32_e32 v5, v8
	s_nop 0
	v_mul_f32_e32 v8, v4, v5
	v_rcp_f32_e32 v4, v11
	s_nop 0
	v_mul_f32_e32 v11, v7, v4
	v_rcp_f32_e32 v4, v10
	s_nop 0
	v_mul_f32_e32 v10, v6, v4

; DI unsigned pack2(float a, float b) { v2f f = {a, b}; return __builtin_bit_cast(unsigned, __builtin_convertvector(f, v2bf)); }
; DI float silu_f(float v) { return v / (1.f + fexp(-v)); }
;   DI u32x2 pack(int, int, float a, float b, float c, float d, float&) const { u32x2 v; v.x = pack2(a, b); v.y = pack2(c, d); return v; }
; template <class ARow, class Epi>
; DI void gemm_tile(const ARow& arow, long a_kstride, const u16* __restrict__ Bt, long ldb, int K, int m0, int n0,
;                   const Epi& epi, char* smem) {
;     ...
;     for (int mi = 0; mi < 4; ++mi) {
;       const int m = m0 + wm * 64 + mi * 16 + fr;
;       float ss = 0.f;
;       u32x2 pk[4];
; #pragma unroll
;       for (int ni = 0; ni < 4; ++ni) pk[ni] = epi.pack(m, nh + ni * 16 + fq * 4, acc[ni][mi][0], acc[ni][mi][1], acc[ni][mi][2], acc[ni][mi][3], ss);
;       epi.finish16(m, nh, ss);
;       u16* rp = epi.rowp(m) + nh;
; #pragma unroll
;       for (int pp = 0; pp < 2; ++pp) {
;         u32x2 a = pk[2 * pp], b = pk[2 * pp + 1];
;         const u32x2 rx = __builtin_amdgcn_permlane16_swap(a.x, b.x, false, false);
;         const u32x2 ry = __builtin_amdgcn_permlane16_swap(a.y, b.y, false, false);
;         const int nst = (fq & 1) ? ((2 * pp + 1) * 16 + (fq - 1) * 4) : ((2 * pp) * 16 + fq * 4);
;         *(u32x4*)(rp + nst) = (u32x4){rx[0], ry[0], rx[1], ry[1]};
;       }
;   DI u32x2 pack(int m, int n, float a, float b, float c, float d, float& ss) const {
;     if (n < q_end) { a *= qscale; b *= qscale; c *= qscale; d *= qscale; }
;     else if (n >= z_start) { a = silu_f(a); b = silu_f(b); c = silu_f(c); d = silu_f(d); }
;     ss += a * a + b * b + c * c + d * d;
;     u32x2 v; v.x = pack2(a, b); v.y = pack2(c, d);
;     return v;
;   }
.LBB0_2461:
	s_andn2_saveexec_b64 s[26:27], s[26:27]
	s_cbranch_execz .LBB0_2312
	v_cmp_lt_i32_e64 s[4:5], s33, v64
	s_and_saveexec_b64 s[0:1], s[4:5]
	s_xor_b64 s[0:1], exec, s[0:1]
	s_cbranch_execz .LBB0_2465
	s_cmpk_lt_u32 s34, 0xc00
	s_cbranch_scc1 .LBB0_2465
	v_mul_f32_e32 v67, 0xbfb8aa3b, v60
	v_exp_f32_e32 v72, v67
	v_mul_f32_e32 v67, 0xbfb8aa3b, v61
	v_exp_f32_e32 v73, v67
	s_nop 0
	v_pk_add_f32 v[72:73], v[72:73], 1.0 op_sel_hi:[1,0]
	s_nop 0
	v_rcp_f32_e32 v67, v72
	s_nop 0
	v_mul_f32_e32 v60, v60, v67
	v_mul_f32_e32 v72, 0xbfb8aa3b, v62
	v_exp_f32_e32 v74, v72
	v_mul_f32_e32 v72, 0xbfb8aa3b, v63
	v_exp_f32_e32 v75, v72
	s_nop 0
	v_pk_add_f32 v[74:75], v[74:75], 1.0 op_sel_hi:[1,0]
	v_rcp_f32_e32 v67, v73
	s_nop 0
	v_mul_f32_e32 v61, v61, v67
	v_rcp_f32_e32 v67, v74
	s_nop 0
	v_mul_f32_e32 v62, v62, v67
	v_rcp_f32_e32 v67, v75
	s_nop 0
	v_mul_f32_e32 v63, v63, v67
.LBB0_2465:
	s_andn2_saveexec_b64 s[0:1], s[0:1]
	v_pk_mul_f32 v[60:61], v[60:61], s[24:25] op_sel_hi:[1,0]
	v_pk_mul_f32 v[62:63], v[62:63], s[24:25] op_sel_hi:[1,0]
	s_or_b64 exec, exec, s[0:1]
	v_or_b32_e32 v67, 16, v64
	v_cmp_lt_i32_e64 s[6:7], s33, v67
	s_and_saveexec_b64 s[0:1], s[6:7]
	s_xor_b64 s[0:1], exec, s[0:1]
	s_cbranch_execz .LBB0_2470
	s_cmpk_lt_u32 s34, 0xc00
	s_cbranch_scc1 .LBB0_2470
	v_mul_f32_e32 v67, 0xbfb8aa3b, v56
	v_exp_f32_e32 v72, v67
	v_mul_f32_e32 v67, 0xbfb8aa3b, v57
	v_exp_f32_e32 v73, v67
	s_nop 0
	v_pk_add_f32 v[72:73], v[72:73], 1.0 op_sel_hi:[1,0]
	s_nop 0
	v_rcp_f32_e32 v67, v72
	s_nop 0
	v_mul_f32_e32 v56, v56, v67
	v_mul_f32_e32 v72, 0xbfb8aa3b, v58
	v_exp_f32_e32 v74, v72
	v_mul_f32_e32 v72, 0xbfb8aa3b, v59
	v_exp_f32_e32 v75, v72
	s_nop 0
	v_pk_add_f32 v[74:75], v[74:75], 1.0 op_sel_hi:[1,0]
	v_rcp_f32_e32 v67, v73
	s_nop 0
	v_mul_f32_e32 v57, v57, v67
	v_rcp_f32_e32 v67, v74
	s_nop 0
	v_mul_f32_e32 v58, v58, v67
	v_rcp_f32_e32 v67, v75
	s_nop 0
	v_mul_f32_e32 v59, v59, v67
.LBB0_2470:
	s_andn2_saveexec_b64 s[0:1], s[0:1]
	v_pk_mul_f32 v[56:57], v[56:57], s[24:25] op_sel_hi:[1,0]
	v_pk_mul_f32 v[58:59], v[58:59], s[24:25] op_sel_hi:[1,0]
	s_or_b64 exec, exec, s[0:1]
	v_or_b32_e32 v67, 32, v64
	v_cmp_lt_i32_e64 s[8:9], s33, v67
	s_and_saveexec_b64 s[0:1], s[8:9]
	s_xor_b64 s[0:1], exec, s[0:1]
	s_cbranch_execz .LBB0_2475
	s_cmpk_lt_u32 s34, 0xc00
	s_cbranch_scc1 .LBB0_2475
	v_mul_f32_e32 v67, 0xbfb8aa3b, v52
	v_exp_f32_e32 v72, v67
	v_mul_f32_e32 v67, 0xbfb8aa3b, v53
	v_exp_f32_e32 v73, v67
	s_nop 0
	v_pk_add_f32 v[72:73], v[72:73], 1.0 op_sel_hi:[1,0]
	s_nop 0
	v_rcp_f32_e32 v67, v72
	s_nop 0
	v_mul_f32_e32 v52, v52, v67
	v_mul_f32_e32 v72, 0xbfb8aa3b, v54
	v_exp_f32_e32 v74, v72
	v_mul_f32_e32 v72, 0xbfb8aa3b, v55
	v_exp_f32_e32 v75, v72
	s_nop 0
	v_pk_add_f32 v[74:75], v[74:75], 1.0 op_sel_hi:[1,0]
	v_rcp_f32_e32 v67, v73
	s_nop 0
	v_mul_f32_e32 v53, v53, v67
	v_rcp_f32_e32 v67, v74
	s_nop 0
	v_mul_f32_e32 v54, v54, v67
	v_rcp_f32_e32 v67, v75
	s_nop 0
	v_mul_f32_e32 v55, v55, v67
.LBB0_2475:
	s_andn2_saveexec_b64 s[0:1], s[0:1]
	v_pk_mul_f32 v[52:53], v[52:53], s[24:25] op_sel_hi:[1,0]
	v_pk_mul_f32 v[54:55], v[54:55], s[24:25] op_sel_hi:[1,0]
	s_or_b64 exec, exec, s[0:1]
	v_or_b32_e32 v64, 48, v64
	v_cmp_lt_i32_e64 s[10:11], s33, v64
	s_and_saveexec_b64 s[0:1], s[10:11]
	s_xor_b64 s[0:1], exec, s[0:1]
	s_cbranch_execz .LBB0_2480
	s_cmpk_lt_u32 s34, 0xc00
	s_cbranch_scc1 .LBB0_2480
	v_mul_f32_e32 v64, 0xbfb8aa3b, v48
	v_exp_f32_e32 v72, v64
	v_mul_f32_e32 v64, 0xbfb8aa3b, v49
	v_exp_f32_e32 v73, v64
	s_nop 0
	v_pk_add_f32 v[72:73], v[72:73], 1.0 op_sel_hi:[1,0]
	s_nop 0
	v_rcp_f32_e32 v64, v72
	v_mul_f32_e32 v71, 0xbfb8aa3b, v50
	v_exp_f32_e32 v74, v71
	v_mul_f32_e32 v71, 0xbfb8aa3b, v51
	v_mul_f32_e32 v48, v48, v64
	v_exp_f32_e32 v75, v71
	s_nop 0
	v_pk_add_f32 v[74:75], v[74:75], 1.0 op_sel_hi:[1,0]
	v_rcp_f32_e32 v64, v73
	s_nop 0
	v_mul_f32_e32 v49, v49, v64
	v_rcp_f32_e32 v64, v74
	s_nop 0
	v_mul_f32_e32 v50, v50, v64
	v_rcp_f32_e32 v64, v75
	s_nop 0
	v_mul_f32_e32 v51, v51, v64
.LBB0_2480:
	s_andn2_saveexec_b64 s[0:1], s[0:1]
	v_pk_mul_f32 v[48:49], v[48:49], s[24:25] op_sel_hi:[1,0]
	v_pk_mul_f32 v[50:51], v[50:51], s[24:25] op_sel_hi:[1,0]
	s_or_b64 exec, exec, s[0:1]
	v_ashrrev_i32_e32 v67, 31, v66
	v_cvt_pk_bf16_f32 v52, v52, v53
	v_cvt_pk_bf16_f32 v53, v54, v55
	v_cvt_pk_bf16_f32 v54, v48, v49
	v_lshlrev_b64 v[48:49], 13, v[66:67]
	v_cvt_pk_bf16_f32 v74, v56, v57
	v_ashrrev_i32_e32 v69, 31, v68
	v_and_b32_e32 v56, 16, v82
	v_lshl_add_u64 v[48:49], s[14:15], 0, v[48:49]
	v_cvt_pk_bf16_f32 v55, v50, v51
	v_lshl_add_u64 v[50:51], v[68:69], 1, v[48:49]
	v_add_u32_e32 v48, 12, v70
	v_cmp_eq_u32_e32 vcc, 0, v56
	v_cvt_pk_bf16_f32 v75, v58, v59
	v_cvt_pk_bf16_f32 v72, v60, v61
	v_cndmask_b32_e32 v48, v48, v70, vcc
	v_cvt_pk_bf16_f32 v73, v62, v63
	v_lshlrev_b32_e32 v64, 1, v48
	v_permlane16_swap_b32_e32 v72, v74
	v_permlane16_swap_b32_e32 v73, v75
	v_lshl_add_u64 v[48:49], v[50:51], 0, v[64:65]
	global_store_dwordx4 v[48:49], v[72:75], off
	v_add_u32_e32 v48, 44, v70
	v_or_b32_e32 v49, 32, v70
	v_cndmask_b32_e32 v48, v48, v49, vcc
	v_lshlrev_b32_e32 v48, 1, v48
	v_mov_b32_e32 v49, v65
	v_permlane16_swap_b32_e32 v52, v54
	v_permlane16_swap_b32_e32 v53, v55
	v_lshl_add_u64 v[50:51], v[50:51], 0, v[48:49]
	global_store_dwordx4 v[50:51], v[52:55], off
	s_and_saveexec_b64 s[0:1], s[4:5]
	s_xor_b64 s[0:1], exec, s[0:1]
	s_cbranch_execz .LBB0_2485
	s_cmpk_lt_u32 s34, 0xc00
	s_cbranch_scc1 .LBB0_2485
	v_mul_f32_e32 v49, 0xbfb8aa3b, v44
	v_exp_f32_e32 v50, v49
	v_mul_f32_e32 v49, 0xbfb8aa3b, v45
	v_exp_f32_e32 v51, v49
	s_nop 0
	v_pk_add_f32 v[50:51], v[50:51], 1.0 op_sel_hi:[1,0]
	s_nop 0
	v_rcp_f32_e32 v49, v50
	v_mul_f32_e32 v52, 0xbfb8aa3b, v46
	v_mul_f32_e32 v53, 0xbfb8aa3b, v47
	v_exp_f32_e32 v52, v52
	v_exp_f32_e32 v53, v53
	v_mul_f32_e32 v44, v44, v49
	v_pk_add_f32 v[52:53], v[52:53], 1.0 op_sel_hi:[1,0]
	v_rcp_f32_e32 v49, v51
	s_nop 0
	v_mul_f32_e32 v45, v45, v49
	v_rcp_f32_e32 v49, v52
	s_nop 0
	v_mul_f32_e32 v46, v46, v49
	v_rcp_f32_e32 v49, v53
	s_nop 0
	v_mul_f32_e32 v47, v47, v49
; DI unsigned pack2(float a, float b) { v2f f = {a, b}; return __builtin_bit_cast(unsigned, __builtin_convertvector(f, v2bf)); }
; DI float silu_f(float v) { return v / (1.f + fexp(-v)); }
;   DI u32x2 pack(int, int, float a, float b, float c, float d, float&) const { u32x2 v; v.x = pack2(a, b); v.y = pack2(c, d); return v; }
; template <class ARow, class Epi>
; DI void gemm_tile(const ARow& arow, long a_kstride, const u16* __restrict__ Bt, long ldb, int K, int m0, int n0,
;                   const Epi& epi, char* smem) {
;     ...
;     for (int mi = 0; mi < 4; ++mi) {
;       const int m = m0 + wm * 64 + mi * 16 + fr;
;       float ss = 0.f;
;       u32x2 pk[4];
; #pragma unroll
;       for (int ni = 0; ni < 4; ++ni) pk[ni] = epi.pack(m, nh + ni * 16 + fq * 4, acc[ni][mi][0], acc[ni][mi][1], acc[ni][mi][2], acc[ni][mi][3], ss);
;       epi.finish16(m, nh, ss);
;       u16* rp = epi.rowp(m) + nh;
; #pragma unroll
;       for (int pp = 0; pp < 2; ++pp) {
;         u32x2 a = pk[2 * pp], b = pk[2 * pp + 1];
;         const u32x2 rx = __builtin_amdgcn_permlane16_swap(a.x, b.x, false, false);
;         const u32x2 ry = __builtin_amdgcn_permlane16_swap(a.y, b.y, false, false);
;         const int nst = (fq & 1) ? ((2 * pp + 1) * 16 + (fq - 1) * 4) : ((2 * pp) * 16 + fq * 4);
;         *(u32x4*)(rp + nst) = (u32x4){rx[0], ry[0], rx[1], ry[1]};
;       }
;   DI u32x2 pack(int m, int n, float a, float b, float c, float d, float& ss) const {
;     if (n < q_end) { a *= qscale; b *= qscale; c *= qscale; d *= qscale; }
;     else if (n >= z_start) { a = silu_f(a); b = silu_f(b); c = silu_f(c); d = silu_f(d); }
;     ss += a * a + b * b + c * c + d * d;
;     u32x2 v; v.x = pack2(a, b); v.y = pack2(c, d);
;     return v;
;   }
.LBB0_2485:
	s_andn2_saveexec_b64 s[0:1], s[0:1]
	v_pk_mul_f32 v[44:45], v[44:45], s[24:25] op_sel_hi:[1,0]
	v_pk_mul_f32 v[46:47], v[46:47], s[24:25] op_sel_hi:[1,0]
	s_or_b64 exec, exec, s[0:1]
	s_and_saveexec_b64 s[0:1], s[6:7]
	s_xor_b64 s[0:1], exec, s[0:1]
	s_cbranch_execz .LBB0_2490
	s_cmpk_lt_u32 s34, 0xc00
	s_cbranch_scc1 .LBB0_2490
	v_mul_f32_e32 v49, 0xbfb8aa3b, v40
	v_exp_f32_e32 v50, v49
	v_mul_f32_e32 v49, 0xbfb8aa3b, v41
	v_exp_f32_e32 v51, v49
	s_nop 0
	v_pk_add_f32 v[50:51], v[50:51], 1.0 op_sel_hi:[1,0]
	s_nop 0
	v_rcp_f32_e32 v49, v50
	v_mul_f32_e32 v52, 0xbfb8aa3b, v42
	v_mul_f32_e32 v53, 0xbfb8aa3b, v43
	v_exp_f32_e32 v52, v52
	v_exp_f32_e32 v53, v53
	v_mul_f32_e32 v40, v40, v49
	v_pk_add_f32 v[52:53], v[52:53], 1.0 op_sel_hi:[1,0]
	v_rcp_f32_e32 v49, v51
	s_nop 0
	v_mul_f32_e32 v41, v41, v49
	v_rcp_f32_e32 v49, v52
	s_nop 0
	v_mul_f32_e32 v42, v42, v49
	v_rcp_f32_e32 v49, v53
	s_nop 0
	v_mul_f32_e32 v43, v43, v49
.LBB0_2490:
	s_andn2_saveexec_b64 s[0:1], s[0:1]
	v_pk_mul_f32 v[40:41], v[40:41], s[24:25] op_sel_hi:[1,0]
	v_pk_mul_f32 v[42:43], v[42:43], s[24:25] op_sel_hi:[1,0]
	s_or_b64 exec, exec, s[0:1]
	s_and_saveexec_b64 s[0:1], s[8:9]
	s_xor_b64 s[0:1], exec, s[0:1]
	s_cbranch_execz .LBB0_2495
	s_cmpk_lt_u32 s34, 0xc00
	s_cbranch_scc1 .LBB0_2495
	v_mul_f32_e32 v49, 0xbfb8aa3b, v36
	v_exp_f32_e32 v50, v49
	v_mul_f32_e32 v49, 0xbfb8aa3b, v37
	v_exp_f32_e32 v51, v49
	s_nop 0
	v_pk_add_f32 v[50:51], v[50:51], 1.0 op_sel_hi:[1,0]
	s_nop 0
	v_rcp_f32_e32 v49, v50
	v_mul_f32_e32 v52, 0xbfb8aa3b, v38
	v_mul_f32_e32 v53, 0xbfb8aa3b, v39
	v_exp_f32_e32 v52, v52
	v_exp_f32_e32 v53, v53
	v_mul_f32_e32 v36, v36, v49
	v_pk_add_f32 v[52:53], v[52:53], 1.0 op_sel_hi:[1,0]
	v_rcp_f32_e32 v49, v51
	s_nop 0
	v_mul_f32_e32 v37, v37, v49
	v_rcp_f32_e32 v49, v52
	s_nop 0
	v_mul_f32_e32 v38, v38, v49
	v_rcp_f32_e32 v49, v53
	s_nop 0
	v_mul_f32_e32 v39, v39, v49
.LBB0_2495:
	s_andn2_saveexec_b64 s[0:1], s[0:1]
	v_pk_mul_f32 v[36:37], v[36:37], s[24:25] op_sel_hi:[1,0]
	v_pk_mul_f32 v[38:39], v[38:39], s[24:25] op_sel_hi:[1,0]
	s_or_b64 exec, exec, s[0:1]
	s_and_saveexec_b64 s[0:1], s[10:11]
	s_xor_b64 s[0:1], exec, s[0:1]
	s_cbranch_execz .LBB0_2500
	s_cmpk_lt_u32 s34, 0xc00
	s_cbranch_scc1 .LBB0_2500
	v_mul_f32_e32 v49, 0xbfb8aa3b, v32
	v_exp_f32_e32 v50, v49
	v_mul_f32_e32 v49, 0xbfb8aa3b, v33
	v_exp_f32_e32 v51, v49
	s_nop 0
	v_pk_add_f32 v[50:51], v[50:51], 1.0 op_sel_hi:[1,0]
	s_nop 0
	v_rcp_f32_e32 v49, v50
	v_mul_f32_e32 v52, 0xbfb8aa3b, v34
	v_mul_f32_e32 v53, 0xbfb8aa3b, v35
	v_exp_f32_e32 v52, v52
	v_exp_f32_e32 v53, v53
	v_mul_f32_e32 v32, v32, v49
	v_pk_add_f32 v[52:53], v[52:53], 1.0 op_sel_hi:[1,0]
	v_rcp_f32_e32 v49, v51
	s_nop 0
	v_mul_f32_e32 v33, v33, v49
	v_rcp_f32_e32 v49, v52
	s_nop 0
	v_mul_f32_e32 v34, v34, v49
	v_rcp_f32_e32 v49, v53
	s_nop 0
	v_mul_f32_e32 v35, v35, v49
.LBB0_2500:
	s_andn2_saveexec_b64 s[0:1], s[0:1]
	v_pk_mul_f32 v[32:33], v[32:33], s[24:25] op_sel_hi:[1,0]
	v_pk_mul_f32 v[34:35], v[34:35], s[24:25] op_sel_hi:[1,0]
	s_or_b64 exec, exec, s[0:1]
	v_cvt_pk_bf16_f32 v36, v36, v37
	v_cvt_pk_bf16_f32 v37, v38, v39
	v_cvt_pk_bf16_f32 v38, v32, v33
	v_or_b32_e32 v32, 16, v66
	v_ashrrev_i32_e32 v33, 31, v32
	v_lshlrev_b64 v[32:33], 13, v[32:33]
	v_lshl_add_u64 v[32:33], s[14:15], 0, v[32:33]
	v_cvt_pk_bf16_f32 v52, v40, v41
	v_cvt_pk_bf16_f32 v53, v42, v43
	v_cvt_pk_bf16_f32 v50, v44, v45
	v_cvt_pk_bf16_f32 v51, v46, v47
	v_cvt_pk_bf16_f32 v39, v34, v35
	v_lshl_add_u64 v[32:33], v[68:69], 1, v[32:33]
	v_mov_b32_e32 v49, v65
	v_permlane16_swap_b32_e32 v50, v52
	v_permlane16_swap_b32_e32 v51, v53
	v_lshl_add_u64 v[34:35], v[32:33], 0, v[64:65]
	v_permlane16_swap_b32_e32 v36, v38
	v_permlane16_swap_b32_e32 v37, v39
	v_lshl_add_u64 v[32:33], v[32:33], 0, v[48:49]
	global_store_dwordx4 v[34:35], v[50:53], off
	global_store_dwordx4 v[32:33], v[36:39], off
	s_and_saveexec_b64 s[0:1], s[4:5]
	s_xor_b64 s[0:1], exec, s[0:1]
	s_cbranch_execz .LBB0_2505
	s_cmpk_lt_u32 s34, 0xc00
	s_cbranch_scc1 .LBB0_2505
	v_mul_f32_e32 v32, 0xbfb8aa3b, v28
	v_mul_f32_e32 v33, 0xbfb8aa3b, v29
	v_exp_f32_e32 v32, v32
	v_exp_f32_e32 v33, v33
	s_nop 0
	v_pk_add_f32 v[32:33], v[32:33], 1.0 op_sel_hi:[1,0]
	s_nop 0
	v_rcp_f32_e32 v34, v32
	s_nop 0
	v_mul_f32_e32 v28, v28, v34
	v_mul_f32_e32 v34, 0xbfb8aa3b, v30
	v_mul_f32_e32 v35, 0xbfb8aa3b, v31
	v_exp_f32_e32 v34, v34
	v_exp_f32_e32 v35, v35
	s_nop 0
	v_pk_add_f32 v[34:35], v[34:35], 1.0 op_sel_hi:[1,0]
	v_rcp_f32_e32 v32, v33
	s_nop 0
	v_mul_f32_e32 v29, v29, v32
	v_rcp_f32_e32 v32, v34
	s_nop 0
	v_mul_f32_e32 v30, v30, v32
	v_rcp_f32_e32 v32, v35
	s_nop 0
	v_mul_f32_e32 v31, v31, v32
.LBB0_2505:
	s_andn2_saveexec_b64 s[0:1], s[0:1]
	v_pk_mul_f32 v[28:29], v[28:29], s[24:25] op_sel_hi:[1,0]
	v_pk_mul_f32 v[30:31], v[30:31], s[24:25] op_sel_hi:[1,0]
	s_or_b64 exec, exec, s[0:1]
	s_and_saveexec_b64 s[0:1], s[6:7]
	s_xor_b64 s[0:1], exec, s[0:1]
	s_cbranch_execz .LBB0_2510
	s_cmpk_lt_u32 s34, 0xc00
	s_cbranch_scc1 .LBB0_2510
	v_mul_f32_e32 v32, 0xbfb8aa3b, v24
	v_mul_f32_e32 v33, 0xbfb8aa3b, v25
	v_exp_f32_e32 v32, v32
	v_exp_f32_e32 v33, v33
	s_nop 0
	v_pk_add_f32 v[32:33], v[32:33], 1.0 op_sel_hi:[1,0]
	s_nop 0
	v_rcp_f32_e32 v34, v32
	s_nop 0
	v_mul_f32_e32 v24, v24, v34
	v_mul_f32_e32 v34, 0xbfb8aa3b, v26
	v_mul_f32_e32 v35, 0xbfb8aa3b, v27
	v_exp_f32_e32 v34, v34
	v_exp_f32_e32 v35, v35
	s_nop 0
	v_pk_add_f32 v[34:35], v[34:35], 1.0 op_sel_hi:[1,0]
	v_rcp_f32_e32 v32, v33
	s_nop 0
	v_mul_f32_e32 v25, v25, v32
	v_rcp_f32_e32 v32, v34
	s_nop 0
	v_mul_f32_e32 v26, v26, v32
	v_rcp_f32_e32 v32, v35
	s_nop 0
	v_mul_f32_e32 v27, v27, v32
; DI unsigned pack2(float a, float b) { v2f f = {a, b}; return __builtin_bit_cast(unsigned, __builtin_convertvector(f, v2bf)); }
; DI float silu_f(float v) { return v / (1.f + fexp(-v)); }
;   DI u32x2 pack(int, int, float a, float b, float c, float d, float&) const { u32x2 v; v.x = pack2(a, b); v.y = pack2(c, d); return v; }
; template <class ARow, class Epi>
; DI void gemm_tile(const ARow& arow, long a_kstride, const u16* __restrict__ Bt, long ldb, int K, int m0, int n0,
;                   const Epi& epi, char* smem) {
;     ...
;     for (int mi = 0; mi < 4; ++mi) {
;       const int m = m0 + wm * 64 + mi * 16 + fr;
;       float ss = 0.f;
;       u32x2 pk[4];
; #pragma unroll
;       for (int ni = 0; ni < 4; ++ni) pk[ni] = epi.pack(m, nh + ni * 16 + fq * 4, acc[ni][mi][0], acc[ni][mi][1], acc[ni][mi][2], acc[ni][mi][3], ss);
;       epi.finish16(m, nh, ss);
;       u16* rp = epi.rowp(m) + nh;
; #pragma unroll
;       for (int pp = 0; pp < 2; ++pp) {
;         u32x2 a = pk[2 * pp], b = pk[2 * pp + 1];
;         const u32x2 rx = __builtin_amdgcn_permlane16_swap(a.x, b.x, false, false);
;         const u32x2 ry = __builtin_amdgcn_permlane16_swap(a.y, b.y, false, false);
;         const int nst = (fq & 1) ? ((2 * pp + 1) * 16 + (fq - 1) * 4) : ((2 * pp) * 16 + fq * 4);
;         *(u32x4*)(rp + nst) = (u32x4){rx[0], ry[0], rx[1], ry[1]};
;       }
;   DI u32x2 pack(int m, int n, float a, float b, float c, float d, float& ss) const {
;     if (n < q_end) { a *= qscale; b *= qscale; c *= qscale; d *= qscale; }
;     else if (n >= z_start) { a = silu_f(a); b = silu_f(b); c = silu_f(c); d = silu_f(d); }
;     ss += a * a + b * b + c * c + d * d;
;     u32x2 v; v.x = pack2(a, b); v.y = pack2(c, d);
;     return v;
;   }
.LBB0_2510:
	s_andn2_saveexec_b64 s[0:1], s[0:1]
	v_pk_mul_f32 v[24:25], v[24:25], s[24:25] op_sel_hi:[1,0]
	v_pk_mul_f32 v[26:27], v[26:27], s[24:25] op_sel_hi:[1,0]
	s_or_b64 exec, exec, s[0:1]
	s_and_saveexec_b64 s[0:1], s[8:9]
	s_xor_b64 s[0:1], exec, s[0:1]
	s_cbranch_execz .LBB0_2515
	s_cmpk_lt_u32 s34, 0xc00
	s_cbranch_scc1 .LBB0_2515
	v_mul_f32_e32 v32, 0xbfb8aa3b, v20
	v_mul_f32_e32 v33, 0xbfb8aa3b, v21
	v_exp_f32_e32 v32, v32
	v_exp_f32_e32 v33, v33
	s_nop 0
	v_pk_add_f32 v[32:33], v[32:33], 1.0 op_sel_hi:[1,0]
	s_nop 0
	v_rcp_f32_e32 v34, v32
	s_nop 0
	v_mul_f32_e32 v20, v20, v34
	v_mul_f32_e32 v34, 0xbfb8aa3b, v22
	v_mul_f32_e32 v35, 0xbfb8aa3b, v23
	v_exp_f32_e32 v34, v34
	v_exp_f32_e32 v35, v35
	s_nop 0
	v_pk_add_f32 v[34:35], v[34:35], 1.0 op_sel_hi:[1,0]
	v_rcp_f32_e32 v32, v33
	s_nop 0
	v_mul_f32_e32 v21, v21, v32
	v_rcp_f32_e32 v32, v34
	s_nop 0
	v_mul_f32_e32 v22, v22, v32
	v_rcp_f32_e32 v32, v35
	s_nop 0
	v_mul_f32_e32 v23, v23, v32
.LBB0_2515:
	s_andn2_saveexec_b64 s[0:1], s[0:1]
	v_pk_mul_f32 v[20:21], v[20:21], s[24:25] op_sel_hi:[1,0]
	v_pk_mul_f32 v[22:23], v[22:23], s[24:25] op_sel_hi:[1,0]
	s_or_b64 exec, exec, s[0:1]
	s_and_saveexec_b64 s[0:1], s[10:11]
	s_xor_b64 s[0:1], exec, s[0:1]
	s_cbranch_execz .LBB0_2520
	s_cmpk_lt_u32 s34, 0xc00
	s_cbranch_scc1 .LBB0_2520
	v_mul_f32_e32 v32, 0xbfb8aa3b, v16
	v_mul_f32_e32 v33, 0xbfb8aa3b, v17
	v_exp_f32_e32 v32, v32
	v_exp_f32_e32 v33, v33
	s_nop 0
	v_pk_add_f32 v[32:33], v[32:33], 1.0 op_sel_hi:[1,0]
	s_nop 0
	v_rcp_f32_e32 v34, v32
	s_nop 0
	v_mul_f32_e32 v16, v16, v34
	v_mul_f32_e32 v34, 0xbfb8aa3b, v18
	v_mul_f32_e32 v35, 0xbfb8aa3b, v19
	v_exp_f32_e32 v34, v34
	v_exp_f32_e32 v35, v35
	s_nop 0
	v_pk_add_f32 v[34:35], v[34:35], 1.0 op_sel_hi:[1,0]
	v_rcp_f32_e32 v32, v33
	s_nop 0
	v_mul_f32_e32 v17, v17, v32
	v_rcp_f32_e32 v32, v34
	s_nop 0
	v_mul_f32_e32 v18, v18, v32
	v_rcp_f32_e32 v32, v35
	s_nop 0
	v_mul_f32_e32 v19, v19, v32
.LBB0_2520:
	s_andn2_saveexec_b64 s[0:1], s[0:1]
	v_pk_mul_f32 v[16:17], v[16:17], s[24:25] op_sel_hi:[1,0]
	v_pk_mul_f32 v[18:19], v[18:19], s[24:25] op_sel_hi:[1,0]
	s_or_b64 exec, exec, s[0:1]
	v_cvt_pk_bf16_f32 v20, v20, v21
	v_cvt_pk_bf16_f32 v21, v22, v23
	v_cvt_pk_bf16_f32 v22, v16, v17
	v_or_b32_e32 v16, 32, v66
	v_ashrrev_i32_e32 v17, 31, v16
	v_lshlrev_b64 v[16:17], 13, v[16:17]
	v_lshl_add_u64 v[16:17], s[14:15], 0, v[16:17]
	v_cvt_pk_bf16_f32 v34, v24, v25
	v_cvt_pk_bf16_f32 v35, v26, v27
	v_cvt_pk_bf16_f32 v32, v28, v29
	v_cvt_pk_bf16_f32 v33, v30, v31
	v_cvt_pk_bf16_f32 v23, v18, v19
	v_lshl_add_u64 v[16:17], v[68:69], 1, v[16:17]
	v_mov_b32_e32 v49, v65
	v_permlane16_swap_b32_e32 v32, v34
	v_permlane16_swap_b32_e32 v33, v35
	v_lshl_add_u64 v[18:19], v[16:17], 0, v[64:65]
	v_permlane16_swap_b32_e32 v20, v22
	v_permlane16_swap_b32_e32 v21, v23
	v_lshl_add_u64 v[16:17], v[16:17], 0, v[48:49]
	global_store_dwordx4 v[18:19], v[32:35], off
	global_store_dwordx4 v[16:17], v[20:23], off
	s_and_saveexec_b64 s[0:1], s[4:5]
	s_xor_b64 s[0:1], exec, s[0:1]
	s_cbranch_execz .LBB0_2525
	s_cmpk_lt_u32 s34, 0xc00
	s_cbranch_scc1 .LBB0_2525
	v_mul_f32_e32 v16, 0xbfb8aa3b, v12
	v_mul_f32_e32 v17, 0xbfb8aa3b, v13
	v_exp_f32_e32 v16, v16
	v_exp_f32_e32 v17, v17
	s_nop 0
	v_pk_add_f32 v[16:17], v[16:17], 1.0 op_sel_hi:[1,0]
	s_nop 0
	v_rcp_f32_e32 v18, v16
	s_nop 0
	v_mul_f32_e32 v12, v12, v18
	v_mul_f32_e32 v18, 0xbfb8aa3b, v14
	v_mul_f32_e32 v19, 0xbfb8aa3b, v15
	v_exp_f32_e32 v18, v18
	v_exp_f32_e32 v19, v19
	s_nop 0
	v_pk_add_f32 v[18:19], v[18:19], 1.0 op_sel_hi:[1,0]
	v_rcp_f32_e32 v16, v17
	s_nop 0
	v_mul_f32_e32 v13, v13, v16
	v_rcp_f32_e32 v16, v18
	s_nop 0
	v_mul_f32_e32 v14, v14, v16
	v_rcp_f32_e32 v16, v19
	s_nop 0
	v_mul_f32_e32 v15, v15, v16
.LBB0_2525:
	s_andn2_saveexec_b64 s[0:1], s[0:1]
	v_pk_mul_f32 v[12:13], v[12:13], s[24:25] op_sel_hi:[1,0]
	v_pk_mul_f32 v[14:15], v[14:15], s[24:25] op_sel_hi:[1,0]
	s_or_b64 exec, exec, s[0:1]
	s_and_saveexec_b64 s[0:1], s[6:7]
	s_xor_b64 s[0:1], exec, s[0:1]
	s_cbranch_execz .LBB0_2530
	s_cmpk_lt_u32 s34, 0xc00
	s_cbranch_scc1 .LBB0_2530
	v_mul_f32_e32 v16, 0xbfb8aa3b, v8
	v_mul_f32_e32 v17, 0xbfb8aa3b, v9
	v_exp_f32_e32 v16, v16
	v_exp_f32_e32 v17, v17
	s_nop 0
	v_pk_add_f32 v[16:17], v[16:17], 1.0 op_sel_hi:[1,0]
	s_nop 0
	v_rcp_f32_e32 v18, v16
	s_nop 0
	v_mul_f32_e32 v8, v8, v18
	v_mul_f32_e32 v18, 0xbfb8aa3b, v10
	v_mul_f32_e32 v19, 0xbfb8aa3b, v11
	v_exp_f32_e32 v18, v18
	v_exp_f32_e32 v19, v19
	s_nop 0
	v_pk_add_f32 v[18:19], v[18:19], 1.0 op_sel_hi:[1,0]
	v_rcp_f32_e32 v16, v17
	s_nop 0
	v_mul_f32_e32 v9, v9, v16
	v_rcp_f32_e32 v16, v18
	s_nop 0
	v_mul_f32_e32 v10, v10, v16
	v_rcp_f32_e32 v16, v19
	s_nop 0
	v_mul_f32_e32 v11, v11, v16
.LBB0_2530:
	s_andn2_saveexec_b64 s[0:1], s[0:1]
	v_pk_mul_f32 v[8:9], v[8:9], s[24:25] op_sel_hi:[1,0]
	v_pk_mul_f32 v[10:11], v[10:11], s[24:25] op_sel_hi:[1,0]
	s_or_b64 exec, exec, s[0:1]
	s_and_saveexec_b64 s[0:1], s[8:9]
	s_xor_b64 s[0:1], exec, s[0:1]
	s_cbranch_execz .LBB0_2535
	s_cmpk_lt_u32 s34, 0xc00
	s_cbranch_scc1 .LBB0_2535
	v_mul_f32_e32 v16, 0xbfb8aa3b, v4
	v_mul_f32_e32 v17, 0xbfb8aa3b, v5
	v_exp_f32_e32 v16, v16
	v_exp_f32_e32 v17, v17
	s_nop 0
	v_pk_add_f32 v[16:17], v[16:17], 1.0 op_sel_hi:[1,0]
	s_nop 0
	v_rcp_f32_e32 v18, v16
	s_nop 0
	v_mul_f32_e32 v4, v4, v18
	v_mul_f32_e32 v18, 0xbfb8aa3b, v6
	v_mul_f32_e32 v19, 0xbfb8aa3b, v7
	v_exp_f32_e32 v18, v18
	v_exp_f32_e32 v19, v19
	s_nop 0
	v_pk_add_f32 v[18:19], v[18:19], 1.0 op_sel_hi:[1,0]
	v_rcp_f32_e32 v16, v17
	s_nop 0
	v_mul_f32_e32 v5, v5, v16
	v_rcp_f32_e32 v16, v18
	s_nop 0
	v_mul_f32_e32 v6, v6, v16
	v_rcp_f32_e32 v16, v19
	s_nop 0
	v_mul_f32_e32 v7, v7, v16
.LBB0_2535:
	s_andn2_saveexec_b64 s[0:1], s[0:1]
	v_pk_mul_f32 v[4:5], v[4:5], s[24:25] op_sel_hi:[1,0]
	v_pk_mul_f32 v[6:7], v[6:7], s[24:25] op_sel_hi:[1,0]
	s_or_b64 exec, exec, s[0:1]
	s_and_saveexec_b64 s[0:1], s[10:11]
	s_xor_b64 s[0:1], exec, s[0:1]
	s_cbranch_execz .LBB0_2540
	s_cmpk_lt_u32 s34, 0xc00
	s_cbranch_scc1 .LBB0_2540
	v_mul_f32_e32 v16, 0xbfb8aa3b, v0
	v_mul_f32_e32 v17, 0xbfb8aa3b, v1
	v_exp_f32_e32 v16, v16
	v_exp_f32_e32 v17, v17
	s_nop 0
	v_pk_add_f32 v[16:17], v[16:17], 1.0 op_sel_hi:[1,0]
	s_nop 0
	v_rcp_f32_e32 v18, v16
	s_nop 0
	v_mul_f32_e32 v0, v0, v18
	v_mul_f32_e32 v18, 0xbfb8aa3b, v2
	v_mul_f32_e32 v19, 0xbfb8aa3b, v3
	v_exp_f32_e32 v18, v18
	v_exp_f32_e32 v19, v19
	s_nop 0
	v_pk_add_f32 v[18:19], v[18:19], 1.0 op_sel_hi:[1,0]
	v_rcp_f32_e32 v16, v17
	s_nop 0
	v_mul_f32_e32 v1, v1, v16
	v_rcp_f32_e32 v16, v18
	s_nop 0
	v_mul_f32_e32 v2, v2, v16
	v_rcp_f32_e32 v16, v19
	s_nop 0
	v_mul_f32_e32 v3, v3, v16
